# g2 plus s_setprio toggles removed from the GEMM K-loops
# speedup vs baseline: 1.0058x; 1.0035x over previous
; #define PG8_STAGE(bufoff, gbase, voff) do { _Pragma("unroll") for (int _i = 0; _i < 2; ++_i) \
;         __builtin_amdgcn_global_load_lds((const unsigned*)((const char*)(gbase) + (voff)[_i]), (LAS unsigned*)(lds + (bufoff) + ldsw + _i * 8192), 16, 0, 0); } while (0)
; #define PG8_LDA(dst, b, h) do { _Pragma("unroll") for (int m = 0; m < 4; ++m) _Pragma("unroll") for (int k = 0; k < 2; ++k) dst[m][k] = *(const LAS bf16x8*)(lds + PG8_SA(b, h) + aoff + m * 2048 + k * 1024); } while (0)
; #define PG8_LDB(dst, b, h) do { _Pragma("unroll") for (int n = 0; n < 2; ++n) _Pragma("unroll") for (int k = 0; k < 2; ++k) dst[n][k] = *(const LAS bf16x8*)(lds + PG8_SB(b, h) + boff + n * 2048 + k * 1024); } while (0)
; #define PG8_MMA(ai, bj, At, Bt) do { __builtin_amdgcn_s_setprio(1); _Pragma("unroll") for (int m = 0; m < 4; ++m) _Pragma("unroll") for (int n = 0; n < 2; ++n) _Pragma("unroll") for (int k = 0; k < 2; ++k) \
;         acc[ai][bj][m][n] = __builtin_amdgcn_mfma_f32_16x16x32_bf16(Bt[n][k], At[m][k], acc[ai][bj][m][n], 0, 0, 0); __builtin_amdgcn_s_setprio(0); } while (0)
; #define PG8_WAIT_L(n) asm volatile("s_waitcnt lgkmcnt(" #n ")" ::: "memory")
; #define PG8_BAR __builtin_amdgcn_s_barrier()
; #define PG8_SCHED __builtin_amdgcn_sched_barrier(0)
; template <class Epi>
; __device__ __forceinline__ void gemm_phase(LAS unsigned char* lds, const Gemm g, const StaticOrder& S, const Epi& E) {
;     ...
;         for (int t = 0; t < nt; t += 2) {
;             const bool last = (t == nt - 2);
;             const char* a1 = cA + (size_t)(t + 1) * kstep;
;             const char* a2 = last ? nA : cA + (size_t)(t + 2) * kstep; const char* b2 = last ? nB : cB + (size_t)(t + 2) * kstep;
;             const char* a3 = a2 + kstep; const char* b3 = b2 + kstep;
;             PG8_LDB(B0, 0, 0); PG8_SCHED; PG8_LDA(At, 0, 0); PG8_STAGE(PG8_SA(1, 1), a1 + hA, voffA);
;             PG8_WAIT_L(8); PG8_BAR; PG8_WAIT_L(0); PG8_MMA(0, 0, At, B0); PG8_BAR; PG8_SCHED;
;             PG8_LDB(B1, 0, 1); PG8_STAGE(PG8_SB(0, 0), b2, voffB);
;             PG8_BAR; PG8_WAIT_L(0); PG8_MMA(0, 1, At, B1); PG8_BAR;
;             PG8_LDA(At, 0, 1); PG8_STAGE(PG8_SA(0, 0), a2, voffA);
;             PG8_BAR; PG8_WAIT_L(0); PG8_MMA(1, 0, At, B0); PG8_BAR; PG8_SCHED;
.LBB0_281:
	s_add_u32 s16, s12, 0xfffc0080
	s_addc_u32 s17, s13, -1
	s_add_i32 s26, 0, 0x10000
	v_add_u32_e32 v139, s26, v137
	ds_read_b128 v[140:143], v139
	ds_read_b128 v[146:149], v139 offset:1024
	ds_read_b128 v[150:153], v139 offset:2048
	ds_read_b128 v[154:157], v139 offset:3072
	s_cmp_eq_u32 s78, 12
	s_cselect_b32 s21, s72, s17
	s_cselect_b32 s20, s76, s16
	s_cselect_b32 s17, s7, s77
	s_cselect_b32 s16, s24, s25
	v_lshl_add_u64 v[186:187], s[12:13], 0, v[132:133]
	s_add_i32 m0, s61, 0xc000
	ds_read_b128 v[158:161], v138
	ds_read_b128 v[162:165], v138 offset:1024
	ds_read_b128 v[166:169], v138 offset:2048
	ds_read_b128 v[170:173], v138 offset:3072
	ds_read_b128 v[174:177], v138 offset:4096
	ds_read_b128 v[178:181], v138 offset:5120
	ds_read_b128 v[182:185], v138 offset:6144
	ds_read_b128 v[196:199], v138 offset:7168
	global_load_lds_dwordx4 v[186:187], off
	s_add_i32 m0, s61, 0xe000
	v_lshl_add_u64 v[186:187], s[12:13], 0, v[134:135]
	global_load_lds_dwordx4 v[186:187], off
	s_waitcnt lgkmcnt(8)
	s_barrier
	s_waitcnt lgkmcnt(0)
	v_mfma_f32_16x16x32_bf16 v[120:123], v[140:143], v[158:161], v[120:123]
	v_mfma_f32_16x16x32_bf16 v[124:127], v[150:153], v[158:161], v[124:127]
	v_mfma_f32_16x16x32_bf16 v[104:107], v[140:143], v[166:169], v[104:107]
	v_mfma_f32_16x16x32_bf16 v[108:111], v[150:153], v[166:169], v[108:111]
	v_mfma_f32_16x16x32_bf16 v[88:91], v[140:143], v[174:177], v[88:91]
	v_mfma_f32_16x16x32_bf16 v[92:95], v[150:153], v[174:177], v[92:95]
	v_mfma_f32_16x16x32_bf16 v[72:75], v[140:143], v[182:185], v[72:75]
	v_mfma_f32_16x16x32_bf16 v[76:79], v[150:153], v[182:185], v[76:79]
	v_mfma_f32_16x16x32_bf16 v[120:123], v[146:149], v[162:165], v[120:123]
	v_mfma_f32_16x16x32_bf16 v[124:127], v[154:157], v[162:165], v[124:127]
	v_mfma_f32_16x16x32_bf16 v[104:107], v[146:149], v[170:173], v[104:107]
	v_mfma_f32_16x16x32_bf16 v[108:111], v[154:157], v[170:173], v[108:111]
	v_mfma_f32_16x16x32_bf16 v[88:91], v[146:149], v[178:181], v[88:91]
	v_mfma_f32_16x16x32_bf16 v[92:95], v[154:157], v[178:181], v[92:95]
	v_mfma_f32_16x16x32_bf16 v[72:75], v[146:149], v[196:199], v[72:75]
	v_mfma_f32_16x16x32_bf16 v[76:79], v[154:157], v[196:199], v[76:79]
	s_barrier
	s_add_i32 s28, 0, 0x14000
	s_add_i32 s26, s26, s35
	v_add_u32_e32 v139, s28, v137
	v_lshl_add_u64 v[186:187], s[16:17], 0, v[130:131]
	s_mov_b32 m0, s26
	ds_read_b128 v[200:203], v139
	ds_read_b128 v[204:207], v139 offset:1024
	ds_read_b128 v[214:217], v139 offset:2048
	ds_read_b128 v[218:221], v139 offset:3072
	global_load_lds_dwordx4 v[186:187], off
	s_add_i32 m0, s26, 0x2000
	v_lshl_add_u64 v[188:189], s[16:17], 0, v[128:129]
	global_load_lds_dwordx4 v[188:189], off
	s_barrier
	s_waitcnt lgkmcnt(0)
	v_mfma_f32_16x16x32_bf16 v[112:115], v[200:203], v[158:161], v[112:115]
	v_mfma_f32_16x16x32_bf16 v[116:119], v[214:217], v[158:161], v[116:119]
	v_mfma_f32_16x16x32_bf16 v[96:99], v[200:203], v[166:169], v[96:99]
	v_mfma_f32_16x16x32_bf16 v[100:103], v[214:217], v[166:169], v[100:103]
	v_mfma_f32_16x16x32_bf16 v[80:83], v[200:203], v[174:177], v[80:83]
	v_mfma_f32_16x16x32_bf16 v[84:87], v[214:217], v[174:177], v[84:87]
	v_mfma_f32_16x16x32_bf16 v[64:67], v[200:203], v[182:185], v[64:67]
	v_mfma_f32_16x16x32_bf16 v[68:71], v[214:217], v[182:185], v[68:71]
	v_mfma_f32_16x16x32_bf16 v[112:115], v[204:207], v[162:165], v[112:115]
	v_mfma_f32_16x16x32_bf16 v[116:119], v[218:221], v[162:165], v[116:119]
	v_mfma_f32_16x16x32_bf16 v[96:99], v[204:207], v[170:173], v[96:99]
	v_mfma_f32_16x16x32_bf16 v[100:103], v[218:221], v[170:173], v[100:103]
	v_mfma_f32_16x16x32_bf16 v[80:83], v[204:207], v[178:181], v[80:83]
	v_mfma_f32_16x16x32_bf16 v[84:87], v[218:221], v[178:181], v[84:87]
	v_mfma_f32_16x16x32_bf16 v[64:67], v[204:207], v[196:199], v[64:67]
	v_mfma_f32_16x16x32_bf16 v[68:71], v[218:221], v[196:199], v[68:71]
	s_mov_b32 m0, s61
	v_lshl_add_u64 v[192:193], s[20:21], 0, v[130:131]
	s_barrier
	ds_read_b128 v[158:161], v138 offset:16384
	ds_read_b128 v[162:165], v138 offset:17408
	ds_read_b128 v[166:169], v138 offset:18432
	ds_read_b128 v[170:173], v138 offset:19456
	ds_read_b128 v[174:177], v138 offset:20480
	ds_read_b128 v[178:181], v138 offset:21504
	ds_read_b128 v[182:185], v138 offset:22528
	ds_read_b128 v[196:199], v138 offset:23552
	global_load_lds_dwordx4 v[192:193], off
	s_mov_b32 m0, s62
	v_lshl_add_u64 v[222:223], s[20:21], 0, v[128:129]
	global_load_lds_dwordx4 v[222:223], off
	s_barrier
	s_waitcnt lgkmcnt(0)
	v_mfma_f32_16x16x32_bf16 v[56:59], v[140:143], v[158:161], v[56:59]
	v_mfma_f32_16x16x32_bf16 v[60:63], v[150:153], v[158:161], v[60:63]
	v_mfma_f32_16x16x32_bf16 v[40:43], v[140:143], v[166:169], v[40:43]
	v_mfma_f32_16x16x32_bf16 v[44:47], v[150:153], v[166:169], v[44:47]
	v_mfma_f32_16x16x32_bf16 v[24:27], v[140:143], v[174:177], v[24:27]
	v_mfma_f32_16x16x32_bf16 v[28:31], v[150:153], v[174:177], v[28:31]
	v_mfma_f32_16x16x32_bf16 v[8:11], v[140:143], v[182:185], v[8:11]
	v_mfma_f32_16x16x32_bf16 v[12:15], v[150:153], v[182:185], v[12:15]
	v_mfma_f32_16x16x32_bf16 v[56:59], v[146:149], v[162:165], v[56:59]
	v_mfma_f32_16x16x32_bf16 v[60:63], v[154:157], v[162:165], v[60:63]
	v_mfma_f32_16x16x32_bf16 v[40:43], v[146:149], v[170:173], v[40:43]
	v_mfma_f32_16x16x32_bf16 v[44:47], v[154:157], v[170:173], v[44:47]
	v_mfma_f32_16x16x32_bf16 v[24:27], v[146:149], v[178:181], v[24:27]
	v_mfma_f32_16x16x32_bf16 v[28:31], v[154:157], v[178:181], v[28:31]
	v_mfma_f32_16x16x32_bf16 v[8:11], v[146:149], v[196:199], v[8:11]
	v_mfma_f32_16x16x32_bf16 v[12:15], v[154:157], v[196:199], v[12:15]
	s_barrier
; #define PG8_STAGE(bufoff, gbase, voff) do { _Pragma("unroll") for (int _i = 0; _i < 2; ++_i) \
;         __builtin_amdgcn_global_load_lds((const unsigned*)((const char*)(gbase) + (voff)[_i]), (LAS unsigned*)(lds + (bufoff) + ldsw + _i * 8192), 16, 0, 0); } while (0)
; #define PG8_LDA(dst, b, h) do { _Pragma("unroll") for (int m = 0; m < 4; ++m) _Pragma("unroll") for (int k = 0; k < 2; ++k) dst[m][k] = *(const LAS bf16x8*)(lds + PG8_SA(b, h) + aoff + m * 2048 + k * 1024); } while (0)
; #define PG8_LDB(dst, b, h) do { _Pragma("unroll") for (int n = 0; n < 2; ++n) _Pragma("unroll") for (int k = 0; k < 2; ++k) dst[n][k] = *(const LAS bf16x8*)(lds + PG8_SB(b, h) + boff + n * 2048 + k * 1024); } while (0)
; #define PG8_MMA(ai, bj, At, Bt) do { __builtin_amdgcn_s_setprio(1); _Pragma("unroll") for (int m = 0; m < 4; ++m) _Pragma("unroll") for (int n = 0; n < 2; ++n) _Pragma("unroll") for (int k = 0; k < 2; ++k) \
;         acc[ai][bj][m][n] = __builtin_amdgcn_mfma_f32_16x16x32_bf16(Bt[n][k], At[m][k], acc[ai][bj][m][n], 0, 0, 0); __builtin_amdgcn_s_setprio(0); } while (0)
; #define PG8_WAIT_V(n) asm volatile("s_waitcnt vmcnt(" #n ")" ::: "memory")
; #define PG8_WAIT_L(n) asm volatile("s_waitcnt lgkmcnt(" #n ")" ::: "memory")
; #define PG8_BAR __builtin_amdgcn_s_barrier()
; #define PG8_SCHED __builtin_amdgcn_sched_barrier(0)
; template <class Epi>
; __device__ __forceinline__ void gemm_phase(LAS unsigned char* lds, const Gemm g, const StaticOrder& S, const Epi& E) {
;     ...
;             PG8_STAGE(PG8_SB(0, 1), b2 + hB, voffB);
;             PG8_WAIT_V(6); PG8_BAR; PG8_MMA(1, 1, At, B1); PG8_BAR;
;             PG8_LDB(B0, 1, 0); PG8_SCHED; PG8_LDA(At, 1, 0); PG8_STAGE(PG8_SA(0, 1), a2 + hA, voffA);
;             PG8_WAIT_L(8); PG8_BAR; PG8_WAIT_L(0); PG8_MMA(0, 0, At, B0); PG8_BAR; PG8_SCHED;
;             PG8_LDB(B1, 1, 1); PG8_STAGE(PG8_SB(1, 0), b3, voffB);
;             PG8_BAR; PG8_WAIT_L(0); PG8_MMA(0, 1, At, B1); PG8_BAR;
;             PG8_LDA(At, 1, 1); PG8_STAGE(PG8_SA(1, 0), a3, voffA);
;             PG8_BAR; PG8_WAIT_L(0); PG8_MMA(1, 0, At, B0); PG8_BAR; PG8_SCHED;
	s_add_u32 s26, s16, 0x40000
	s_addc_u32 s27, s17, 0
	s_add_i32 s28, s28, s35
	s_mov_b32 m0, s28
	v_lshl_add_u64 v[140:141], s[26:27], 0, v[130:131]
	global_load_lds_dwordx4 v[140:141], off
	s_add_i32 m0, s28, 0x2000
	v_lshl_add_u64 v[140:141], s[26:27], 0, v[128:129]
	global_load_lds_dwordx4 v[140:141], off
	s_waitcnt vmcnt(6)
	s_barrier
	v_mfma_f32_16x16x32_bf16 v[48:51], v[200:203], v[158:161], v[48:51]
	v_mfma_f32_16x16x32_bf16 v[52:55], v[214:217], v[158:161], v[52:55]
	v_mfma_f32_16x16x32_bf16 v[32:35], v[200:203], v[166:169], v[32:35]
	v_mfma_f32_16x16x32_bf16 v[36:39], v[214:217], v[166:169], v[36:39]
	v_mfma_f32_16x16x32_bf16 v[16:19], v[200:203], v[174:177], v[16:19]
	v_mfma_f32_16x16x32_bf16 v[20:23], v[214:217], v[174:177], v[20:23]
	v_mfma_f32_16x16x32_bf16 v[0:3], v[200:203], v[182:185], v[0:3]
	v_mfma_f32_16x16x32_bf16 v[4:7], v[214:217], v[182:185], v[4:7]
	v_mfma_f32_16x16x32_bf16 v[48:51], v[204:207], v[162:165], v[48:51]
	v_mfma_f32_16x16x32_bf16 v[52:55], v[218:221], v[162:165], v[52:55]
	v_mfma_f32_16x16x32_bf16 v[32:35], v[204:207], v[170:173], v[32:35]
	v_mfma_f32_16x16x32_bf16 v[36:39], v[218:221], v[170:173], v[36:39]
	v_mfma_f32_16x16x32_bf16 v[16:19], v[204:207], v[178:181], v[16:19]
	v_mfma_f32_16x16x32_bf16 v[20:23], v[218:221], v[178:181], v[20:23]
	v_mfma_f32_16x16x32_bf16 v[0:3], v[204:207], v[196:199], v[0:3]
	v_mfma_f32_16x16x32_bf16 v[4:7], v[218:221], v[196:199], v[4:7]
	s_add_i32 s26, 0, 0x18000
	v_add_u32_e32 v139, s26, v137
	s_barrier
	ds_read_b128 v[140:143], v139
	ds_read_b128 v[146:149], v139 offset:1024
	ds_read_b128 v[150:153], v139 offset:2048
	ds_read_b128 v[154:157], v139 offset:3072
	s_add_u32 s20, s20, 0x40000
	s_addc_u32 s21, s21, 0
	s_mov_b32 m0, s63
	v_lshl_add_u64 v[200:201], s[20:21], 0, v[130:131]
	ds_read_b128 v[158:161], v138 offset:32768
	ds_read_b128 v[162:165], v138 offset:33792
	ds_read_b128 v[166:169], v138 offset:34816
	ds_read_b128 v[170:173], v138 offset:35840
	ds_read_b128 v[174:177], v138 offset:36864
	ds_read_b128 v[178:181], v138 offset:37888
	ds_read_b128 v[182:185], v138 offset:38912
	ds_read_b128 v[196:199], v138 offset:39936
	global_load_lds_dwordx4 v[200:201], off
	s_mov_b32 m0, s64
	v_lshl_add_u64 v[200:201], s[20:21], 0, v[128:129]
	global_load_lds_dwordx4 v[200:201], off
	s_waitcnt lgkmcnt(8)
	s_barrier
	s_waitcnt lgkmcnt(0)
	v_mfma_f32_16x16x32_bf16 v[120:123], v[140:143], v[158:161], v[120:123]
	v_mfma_f32_16x16x32_bf16 v[124:127], v[150:153], v[158:161], v[124:127]
	v_mfma_f32_16x16x32_bf16 v[104:107], v[140:143], v[166:169], v[104:107]
	v_mfma_f32_16x16x32_bf16 v[108:111], v[150:153], v[166:169], v[108:111]
	v_mfma_f32_16x16x32_bf16 v[88:91], v[140:143], v[174:177], v[88:91]
	v_mfma_f32_16x16x32_bf16 v[92:95], v[150:153], v[174:177], v[92:95]
	v_mfma_f32_16x16x32_bf16 v[72:75], v[140:143], v[182:185], v[72:75]
	v_mfma_f32_16x16x32_bf16 v[76:79], v[150:153], v[182:185], v[76:79]
	v_mfma_f32_16x16x32_bf16 v[120:123], v[146:149], v[162:165], v[120:123]
	v_mfma_f32_16x16x32_bf16 v[124:127], v[154:157], v[162:165], v[124:127]
	v_mfma_f32_16x16x32_bf16 v[104:107], v[146:149], v[170:173], v[104:107]
	v_mfma_f32_16x16x32_bf16 v[108:111], v[154:157], v[170:173], v[108:111]
	v_mfma_f32_16x16x32_bf16 v[88:91], v[146:149], v[178:181], v[88:91]
	v_mfma_f32_16x16x32_bf16 v[92:95], v[154:157], v[178:181], v[92:95]
	v_mfma_f32_16x16x32_bf16 v[72:75], v[146:149], v[196:199], v[72:75]
	v_mfma_f32_16x16x32_bf16 v[76:79], v[154:157], v[196:199], v[76:79]
	s_barrier
	s_add_i32 s20, 0, 0x1c000
	s_add_i32 s21, s26, s35
	v_add_u32_e32 v139, s20, v137
	v_lshl_add_u64 v[186:187], v[186:187], 0, s[88:89]
	s_mov_b32 m0, s21
	ds_read_b128 v[200:203], v139
	ds_read_b128 v[204:207], v139 offset:1024
	ds_read_b128 v[214:217], v139 offset:2048
	ds_read_b128 v[218:221], v139 offset:3072
	global_load_lds_dwordx4 v[186:187], off
	s_add_i32 m0, s21, 0x2000
	v_lshl_add_u64 v[186:187], v[188:189], 0, s[88:89]
	global_load_lds_dwordx4 v[186:187], off
	s_barrier
	s_waitcnt lgkmcnt(0)
	v_mfma_f32_16x16x32_bf16 v[112:115], v[200:203], v[158:161], v[112:115]
	v_mfma_f32_16x16x32_bf16 v[116:119], v[214:217], v[158:161], v[116:119]
	v_mfma_f32_16x16x32_bf16 v[96:99], v[200:203], v[166:169], v[96:99]
	v_mfma_f32_16x16x32_bf16 v[100:103], v[214:217], v[166:169], v[100:103]
	v_mfma_f32_16x16x32_bf16 v[80:83], v[200:203], v[174:177], v[80:83]
	v_mfma_f32_16x16x32_bf16 v[84:87], v[214:217], v[174:177], v[84:87]
	v_mfma_f32_16x16x32_bf16 v[64:67], v[200:203], v[182:185], v[64:67]
	v_mfma_f32_16x16x32_bf16 v[68:71], v[214:217], v[182:185], v[68:71]
	v_mfma_f32_16x16x32_bf16 v[112:115], v[204:207], v[162:165], v[112:115]
	v_mfma_f32_16x16x32_bf16 v[116:119], v[218:221], v[162:165], v[116:119]
	v_mfma_f32_16x16x32_bf16 v[96:99], v[204:207], v[170:173], v[96:99]
	v_mfma_f32_16x16x32_bf16 v[100:103], v[218:221], v[170:173], v[100:103]
	v_mfma_f32_16x16x32_bf16 v[80:83], v[204:207], v[178:181], v[80:83]
	v_mfma_f32_16x16x32_bf16 v[84:87], v[218:221], v[178:181], v[84:87]
	v_mfma_f32_16x16x32_bf16 v[64:67], v[204:207], v[196:199], v[64:67]
	v_mfma_f32_16x16x32_bf16 v[68:71], v[218:221], v[196:199], v[68:71]
	s_mov_b32 m0, s65
	v_lshl_add_u64 v[186:187], v[192:193], 0, s[88:89]
	s_barrier
	ds_read_b128 v[158:161], v138 offset:49152
	ds_read_b128 v[162:165], v138 offset:50176
	ds_read_b128 v[166:169], v138 offset:51200
	ds_read_b128 v[170:173], v138 offset:52224
	ds_read_b128 v[174:177], v138 offset:53248
	ds_read_b128 v[178:181], v138 offset:54272
	ds_read_b128 v[182:185], v138 offset:55296
	ds_read_b128 v[196:199], v138 offset:56320
	global_load_lds_dwordx4 v[186:187], off
	s_mov_b32 m0, s68
	v_lshl_add_u64 v[186:187], v[222:223], 0, s[88:89]
	global_load_lds_dwordx4 v[186:187], off
	s_barrier
; __device__ __forceinline__ unsigned pk2(float lo, float hi) { unsigned r; asm("v_cvt_pk_bf16_f32 %0, %1, %2" : "=v"(r) : "v"(lo), "v"(hi)); return r; }
; #define PG8_STAGE(bufoff, gbase, voff) do { _Pragma("unroll") for (int _i = 0; _i < 2; ++_i) \
;         __builtin_amdgcn_global_load_lds((const unsigned*)((const char*)(gbase) + (voff)[_i]), (LAS unsigned*)(lds + (bufoff) + ldsw + _i * 8192), 16, 0, 0); } while (0)
; #define PG8_MMA(ai, bj, At, Bt) do { __builtin_amdgcn_s_setprio(1); _Pragma("unroll") for (int m = 0; m < 4; ++m) _Pragma("unroll") for (int n = 0; n < 2; ++n) _Pragma("unroll") for (int k = 0; k < 2; ++k) \
;         acc[ai][bj][m][n] = __builtin_amdgcn_mfma_f32_16x16x32_bf16(Bt[n][k], At[m][k], acc[ai][bj][m][n], 0, 0, 0); __builtin_amdgcn_s_setprio(0); } while (0)
; #define PG8_WAIT_V(n) asm volatile("s_waitcnt vmcnt(" #n ")" ::: "memory")
; #define PG8_WAIT_L(n) asm volatile("s_waitcnt lgkmcnt(" #n ")" ::: "memory")
; #define PG8_BAR __builtin_amdgcn_s_barrier()
; #define PG8_SCHED __builtin_amdgcn_sched_barrier(0)
; template <class Epi>
; __device__ __forceinline__ void gemm_phase(LAS unsigned char* lds, const Gemm g, const StaticOrder& S, const Epi& E) {
;     ...
;             PG8_BAR; PG8_WAIT_L(0); PG8_MMA(1, 0, At, B0); PG8_BAR; PG8_SCHED;
;             PG8_STAGE(PG8_SB(1, 1), b3 + hB, voffB);
;             PG8_WAIT_V(6); PG8_BAR; PG8_MMA(1, 1, At, B1); PG8_BAR;
;         }
;     static __device__ __forceinline__ float sg(float g, float u) { return (g * u) * __builtin_amdgcn_rcpf(1.f + __builtin_amdgcn_exp2f(-g)); }
;     __device__ __forceinline__ void operator()(const f32x4 (&acc)[2][2][4][2], const Unit& u, int wr, int wc, int fr, int fq) const {
; #pragma unroll
;         for (int ai = 0; ai < 2; ++ai)
; #pragma unroll
;             for (int m = 0; m < 4; ++m) {
;                 const int row = u.pm * BM + ai * HALF + wr * 64 + m * 16 + fr;
;                 const f32x4 g0 = acc[ai][0][m][0], u0 = acc[ai][0][m][1], g1 = acc[ai][1][m][0], u1 = acc[ai][1][m][1];
;                 u32x4 o; o.x = pk2(sg(g0[0], u0[0]), sg(g0[1], u0[1])); o.y = pk2(sg(g0[2], u0[2]), sg(g0[3], u0[3]));
;                 o.z = pk2(sg(g1[0], u1[0]), sg(g1[1], u1[1])); o.w = pk2(sg(g1[2], u1[2]), sg(g1[3], u1[3]));
;                 *(u32x4*)(O + (size_t)row * DFF + u.pn * 128 + wc * 32 + fq * 8) = o;
;             }
	s_waitcnt lgkmcnt(0)
	v_mfma_f32_16x16x32_bf16 v[56:59], v[140:143], v[158:161], v[56:59]
	v_mfma_f32_16x16x32_bf16 v[60:63], v[150:153], v[158:161], v[60:63]
	v_mfma_f32_16x16x32_bf16 v[40:43], v[140:143], v[166:169], v[40:43]
	v_mfma_f32_16x16x32_bf16 v[44:47], v[150:153], v[166:169], v[44:47]
	v_mfma_f32_16x16x32_bf16 v[24:27], v[140:143], v[174:177], v[24:27]
	v_mfma_f32_16x16x32_bf16 v[28:31], v[150:153], v[174:177], v[28:31]
	v_mfma_f32_16x16x32_bf16 v[8:11], v[140:143], v[182:185], v[8:11]
	v_mfma_f32_16x16x32_bf16 v[12:15], v[150:153], v[182:185], v[12:15]
	v_mfma_f32_16x16x32_bf16 v[56:59], v[146:149], v[162:165], v[56:59]
	v_mfma_f32_16x16x32_bf16 v[60:63], v[154:157], v[162:165], v[60:63]
	v_mfma_f32_16x16x32_bf16 v[40:43], v[146:149], v[170:173], v[40:43]
	v_mfma_f32_16x16x32_bf16 v[44:47], v[154:157], v[170:173], v[44:47]
	v_mfma_f32_16x16x32_bf16 v[24:27], v[146:149], v[178:181], v[24:27]
	v_mfma_f32_16x16x32_bf16 v[28:31], v[154:157], v[178:181], v[28:31]
	v_mfma_f32_16x16x32_bf16 v[8:11], v[146:149], v[196:199], v[8:11]
	v_mfma_f32_16x16x32_bf16 v[12:15], v[154:157], v[196:199], v[12:15]
	s_barrier
	s_add_u32 s16, s16, 0x40080
	s_addc_u32 s17, s17, 0
	s_add_i32 s20, s20, s35
	s_mov_b32 m0, s20
	v_lshl_add_u64 v[140:141], s[16:17], 0, v[130:131]
	global_load_lds_dwordx4 v[140:141], off
	s_add_i32 m0, s20, 0x2000
	v_lshl_add_u64 v[140:141], s[16:17], 0, v[128:129]
	global_load_lds_dwordx4 v[140:141], off
	s_waitcnt vmcnt(6)
	s_barrier
	v_mfma_f32_16x16x32_bf16 v[48:51], v[200:203], v[158:161], v[48:51]
	v_mfma_f32_16x16x32_bf16 v[52:55], v[214:217], v[158:161], v[52:55]
	v_mfma_f32_16x16x32_bf16 v[32:35], v[200:203], v[166:169], v[32:35]
	v_mfma_f32_16x16x32_bf16 v[36:39], v[214:217], v[166:169], v[36:39]
	v_mfma_f32_16x16x32_bf16 v[16:19], v[200:203], v[174:177], v[16:19]
	v_mfma_f32_16x16x32_bf16 v[20:23], v[214:217], v[174:177], v[20:23]
	v_mfma_f32_16x16x32_bf16 v[0:3], v[200:203], v[182:185], v[0:3]
	v_mfma_f32_16x16x32_bf16 v[4:7], v[214:217], v[182:185], v[4:7]
	v_mfma_f32_16x16x32_bf16 v[48:51], v[204:207], v[162:165], v[48:51]
	v_mfma_f32_16x16x32_bf16 v[52:55], v[218:221], v[162:165], v[52:55]
	v_mfma_f32_16x16x32_bf16 v[32:35], v[204:207], v[170:173], v[32:35]
	v_mfma_f32_16x16x32_bf16 v[36:39], v[218:221], v[170:173], v[36:39]
	v_mfma_f32_16x16x32_bf16 v[16:19], v[204:207], v[178:181], v[16:19]
	v_mfma_f32_16x16x32_bf16 v[20:23], v[218:221], v[178:181], v[20:23]
	v_mfma_f32_16x16x32_bf16 v[0:3], v[204:207], v[196:199], v[0:3]
	v_mfma_f32_16x16x32_bf16 v[4:7], v[218:221], v[196:199], v[4:7]
	s_add_i32 s78, s78, 2
	s_add_u32 s12, s12, 0x100
	s_addc_u32 s13, s13, 0
	s_add_u32 s25, s25, 0x100
	s_addc_u32 s77, s77, 0
	s_cmp_gt_u32 s78, 13
	s_barrier
	s_cbranch_scc0 .LBB0_281
	v_mul_f32_e32 v124, v120, v124
	v_exp_f32_e64 v120, -v120
	v_mul_f32_e32 v108, v104, v108
	v_exp_f32_e64 v104, -v104
	v_mul_f32_e32 v92, v88, v92
	v_add_f32_e32 v120, 1.0, v120
	v_rcp_f32_e32 v120, v120
	v_add_f32_e32 v104, 1.0, v104
	v_rcp_f32_e32 v104, v104
	v_exp_f32_e64 v88, -v88
	v_mul_f32_e32 v120, v124, v120
	v_mul_f32_e32 v124, v121, v125
	v_exp_f32_e64 v121, -v121
	v_mul_f32_e32 v104, v108, v104
	v_mul_f32_e32 v108, v105, v109
	v_exp_f32_e64 v105, -v105
	v_add_f32_e32 v121, 1.0, v121
	v_rcp_f32_e32 v121, v121
	v_add_f32_e32 v88, 1.0, v88
	v_rcp_f32_e32 v88, v88
	v_mul_f32_e32 v76, v72, v76
	v_exp_f32_e64 v72, -v72
	v_mul_f32_e32 v121, v124, v121
	v_cvt_pk_bf16_f32 v120, v120, v121
	v_mul_f32_e32 v121, v122, v126
	v_exp_f32_e64 v122, -v122
	v_mul_f32_e32 v116, v112, v116
	v_exp_f32_e64 v112, -v112
	v_add_f32_e32 v105, 1.0, v105
	v_rcp_f32_e32 v105, v105
	v_mul_f32_e32 v88, v92, v88
	v_mul_f32_e32 v92, v89, v93
	v_exp_f32_e64 v89, -v89
	v_add_f32_e32 v72, 1.0, v72
	v_rcp_f32_e32 v72, v72
	v_mul_f32_e32 v60, v56, v60
	v_exp_f32_e64 v56, -v56
	v_add_f32_e32 v122, 1.0, v122
	v_add_f32_e32 v112, 1.0, v112
	v_rcp_f32_e32 v122, v122
	v_rcp_f32_e32 v112, v112
	v_mul_f32_e32 v105, v108, v105
	v_add_f32_e32 v89, 1.0, v89
	v_cvt_pk_bf16_f32 v104, v104, v105
	v_mul_f32_e32 v105, v106, v110
	v_exp_f32_e64 v106, -v106
	v_mul_f32_e32 v100, v96, v100
	v_exp_f32_e64 v96, -v96
	v_rcp_f32_e32 v89, v89
	v_mul_f32_e32 v72, v76, v72
	v_mul_f32_e32 v76, v73, v77
	v_exp_f32_e64 v73, -v73
	v_add_f32_e32 v56, 1.0, v56
	v_rcp_f32_e32 v56, v56
	v_mul_f32_e32 v44, v40, v44
	v_exp_f32_e64 v40, -v40
	v_mul_f32_e32 v121, v121, v122
	v_mul_f32_e32 v122, v123, v127
	v_exp_f32_e64 v123, -v123
	v_mul_f32_e32 v112, v116, v112
	v_mul_f32_e32 v116, v113, v117
	v_exp_f32_e64 v113, -v113
	v_add_f32_e32 v106, 1.0, v106
	v_add_f32_e32 v96, 1.0, v96
	v_mul_f32_e32 v89, v92, v89
	v_add_f32_e32 v73, 1.0, v73
	v_rcp_f32_e32 v106, v106
	v_rcp_f32_e32 v96, v96
	v_cvt_pk_bf16_f32 v88, v88, v89
	v_mul_f32_e32 v89, v90, v94
	v_exp_f32_e64 v90, -v90
	v_mul_f32_e32 v84, v80, v84
	v_exp_f32_e64 v80, -v80
	v_rcp_f32_e32 v73, v73
	v_mul_f32_e32 v56, v60, v56
	v_mul_f32_e32 v60, v57, v61
	v_exp_f32_e64 v57, -v57
	v_add_f32_e32 v40, 1.0, v40
	v_rcp_f32_e32 v40, v40
	v_mul_f32_e32 v28, v24, v28
	v_exp_f32_e64 v24, -v24
	v_add_f32_e32 v123, 1.0, v123
	v_add_f32_e32 v113, 1.0, v113
	v_rcp_f32_e32 v123, v123
	v_rcp_f32_e32 v113, v113
	v_mul_f32_e32 v105, v105, v106
	v_mul_f32_e32 v106, v107, v111
	v_exp_f32_e64 v107, -v107
	v_mul_f32_e32 v96, v100, v96
	v_mul_f32_e32 v100, v97, v101
	v_exp_f32_e64 v97, -v97
	v_add_f32_e32 v90, 1.0, v90
	v_add_f32_e32 v80, 1.0, v80
	v_mul_f32_e32 v73, v76, v73
	v_add_f32_e32 v57, 1.0, v57
	v_rcp_f32_e32 v90, v90
	v_rcp_f32_e32 v80, v80
	v_cvt_pk_bf16_f32 v72, v72, v73
	v_mul_f32_e32 v73, v74, v78
	v_exp_f32_e64 v74, -v74
	v_mul_f32_e32 v68, v64, v68
	v_exp_f32_e64 v64, -v64
; __device__ __forceinline__ unsigned pk2(float lo, float hi) { unsigned r; asm("v_cvt_pk_bf16_f32 %0, %1, %2" : "=v"(r) : "v"(lo), "v"(hi)); return r; }
;     static __device__ __forceinline__ float sg(float g, float u) { return (g * u) * __builtin_amdgcn_rcpf(1.f + __builtin_amdgcn_exp2f(-g)); }
;     __device__ __forceinline__ void operator()(const f32x4 (&acc)[2][2][4][2], const Unit& u, int wr, int wc, int fr, int fq) const {
; #pragma unroll
;         for (int ai = 0; ai < 2; ++ai)
; #pragma unroll
;             for (int m = 0; m < 4; ++m) {
;                 const int row = u.pm * BM + ai * HALF + wr * 64 + m * 16 + fr;
;                 const f32x4 g0 = acc[ai][0][m][0], u0 = acc[ai][0][m][1], g1 = acc[ai][1][m][0], u1 = acc[ai][1][m][1];
;                 u32x4 o; o.x = pk2(sg(g0[0], u0[0]), sg(g0[1], u0[1])); o.y = pk2(sg(g0[2], u0[2]), sg(g0[3], u0[3]));
;                 o.z = pk2(sg(g1[0], u1[0]), sg(g1[1], u1[1])); o.w = pk2(sg(g1[2], u1[2]), sg(g1[3], u1[3]));
;                 *(u32x4*)(O + (size_t)row * DFF + u.pn * 128 + wc * 32 + fq * 8) = o;
;             }
	v_rcp_f32_e32 v57, v57
	v_mul_f32_e32 v40, v44, v40
	v_mul_f32_e32 v44, v41, v45
	v_exp_f32_e64 v41, -v41
	v_add_f32_e32 v24, 1.0, v24
	v_rcp_f32_e32 v24, v24
	v_mul_f32_e32 v12, v8, v12
	v_exp_f32_e64 v8, -v8
	v_mul_f32_e32 v122, v122, v123
	v_mul_f32_e32 v113, v116, v113
	v_cvt_pk_bf16_f32 v121, v121, v122
	v_cvt_pk_bf16_f32 v122, v112, v113
	v_exp_f32_e64 v113, -v114
	v_add_f32_e32 v107, 1.0, v107
	v_add_f32_e32 v97, 1.0, v97
	v_mul_f32_e32 v112, v114, v118
	v_exp_f32_e64 v114, -v115
	v_rcp_f32_e32 v107, v107
	v_rcp_f32_e32 v97, v97
	v_mul_f32_e32 v89, v89, v90
	v_mul_f32_e32 v90, v91, v95
	v_exp_f32_e64 v91, -v91
	v_mul_f32_e32 v80, v84, v80
	v_mul_f32_e32 v84, v81, v85
	v_exp_f32_e64 v81, -v81
	v_add_f32_e32 v74, 1.0, v74
	v_add_f32_e32 v64, 1.0, v64
	v_mul_f32_e32 v57, v60, v57
	v_add_f32_e32 v41, 1.0, v41
	v_rcp_f32_e32 v74, v74
	v_rcp_f32_e32 v64, v64
	v_cvt_pk_bf16_f32 v56, v56, v57
	v_mul_f32_e32 v57, v58, v62
	v_exp_f32_e64 v58, -v58
	v_mul_f32_e32 v52, v48, v52
	v_exp_f32_e64 v48, -v48
	v_rcp_f32_e32 v41, v41
	v_mul_f32_e32 v24, v28, v24
	v_mul_f32_e32 v28, v25, v29
	v_exp_f32_e64 v25, -v25
	v_add_f32_e32 v8, 1.0, v8
	v_rcp_f32_e32 v8, v8
	v_add_f32_e32 v113, 1.0, v113
	v_rcp_f32_e32 v113, v113
	v_add_f32_e32 v114, 1.0, v114
	v_mul_f32_e32 v106, v106, v107
	v_mul_f32_e32 v97, v100, v97
	v_add_f32_e32 v91, 1.0, v91
	v_add_f32_e32 v81, 1.0, v81
	v_rcp_f32_e32 v114, v114
	v_cvt_pk_bf16_f32 v105, v105, v106
	v_cvt_pk_bf16_f32 v106, v96, v97
	v_exp_f32_e64 v97, -v98
	v_rcp_f32_e32 v91, v91
	v_rcp_f32_e32 v81, v81
	v_mul_f32_e32 v73, v73, v74
	v_mul_f32_e32 v74, v75, v79
	v_exp_f32_e64 v75, -v75
	v_mul_f32_e32 v64, v68, v64
	v_mul_f32_e32 v68, v65, v69
	v_exp_f32_e64 v65, -v65
	v_add_f32_e32 v58, 1.0, v58
	v_add_f32_e32 v48, 1.0, v48
	v_mul_f32_e32 v41, v44, v41
	v_add_f32_e32 v25, 1.0, v25
	v_mul_f32_e32 v96, v98, v102
	v_exp_f32_e64 v98, -v99
	v_rcp_f32_e32 v58, v58
	v_rcp_f32_e32 v48, v48
	v_cvt_pk_bf16_f32 v40, v40, v41
	v_mul_f32_e32 v41, v42, v46
	v_exp_f32_e64 v42, -v42
	v_mul_f32_e32 v36, v32, v36
	v_exp_f32_e64 v32, -v32
	v_rcp_f32_e32 v25, v25
	v_mul_f32_e32 v8, v12, v8
	v_mul_f32_e32 v12, v9, v13
	v_exp_f32_e64 v9, -v9
	v_mul_f32_e32 v112, v112, v113
	v_mul_f32_e32 v113, v115, v119
	s_lshl_b32 s12, s15, 7
	v_mul_f32_e32 v113, v113, v114
	v_add_f32_e32 v97, 1.0, v97
	v_mul_f32_e32 v90, v90, v91
	v_mul_f32_e32 v81, v84, v81
	v_add_f32_e32 v75, 1.0, v75
	v_add_f32_e32 v65, 1.0, v65
	v_lshl_add_u32 v139, s71, 8, v136
	s_ashr_i32 s13, s12, 31
	v_cvt_pk_bf16_f32 v123, v112, v113
	v_mov_b64_e32 v[112:113], s[4:5]
	v_rcp_f32_e32 v97, v97
	v_add_f32_e32 v98, 1.0, v98
	v_cvt_pk_bf16_f32 v89, v89, v90
	v_cvt_pk_bf16_f32 v90, v80, v81
	v_exp_f32_e64 v81, -v82
	v_rcp_f32_e32 v75, v75
	v_rcp_f32_e32 v65, v65
	v_mul_f32_e32 v57, v57, v58
	v_mul_f32_e32 v58, v59, v63
	v_exp_f32_e64 v59, -v59
	v_mul_f32_e32 v48, v52, v48
	v_mul_f32_e32 v52, v49, v53
	v_exp_f32_e64 v49, -v49
	v_add_f32_e32 v42, 1.0, v42
	v_add_f32_e32 v32, 1.0, v32
	v_mul_f32_e32 v25, v28, v25
	v_add_f32_e32 v9, 1.0, v9
	v_mad_i64_i32 v[114:115], s[16:17], v139, s33, v[112:113]
	s_lshl_b64 s[12:13], s[12:13], 1
	v_rcp_f32_e32 v98, v98
	v_mul_f32_e32 v80, v82, v86
	v_exp_f32_e64 v82, -v83
	v_rcp_f32_e32 v42, v42
	v_rcp_f32_e32 v32, v32
	v_cvt_pk_bf16_f32 v24, v24, v25
	v_mul_f32_e32 v25, v26, v30
	v_exp_f32_e64 v26, -v26
	v_mul_f32_e32 v20, v16, v20
	v_exp_f32_e64 v16, -v16
	v_rcp_f32_e32 v9, v9
	v_lshl_add_u64 v[114:115], v[114:115], 0, s[12:13]
	v_lshl_add_u64 v[114:115], v[114:115], 0, s[66:67]
	v_lshl_add_u64 v[114:115], v[114:115], 0, v[144:145]
	v_mul_f32_e32 v96, v96, v97
	v_mul_f32_e32 v97, v99, v103
	v_add_f32_e32 v81, 1.0, v81
	v_mul_f32_e32 v74, v74, v75
	v_mul_f32_e32 v65, v68, v65
	v_add_f32_e32 v59, 1.0, v59
	v_add_f32_e32 v49, 1.0, v49
	global_store_dwordx4 v[114:115], v[120:123], off
	v_or_b32_e32 v114, 16, v139
	v_mul_f32_e32 v97, v97, v98
	v_rcp_f32_e32 v81, v81
	v_add_f32_e32 v82, 1.0, v82
	v_cvt_pk_bf16_f32 v73, v73, v74
	v_cvt_pk_bf16_f32 v74, v64, v65
	v_exp_f32_e64 v65, -v66
	v_rcp_f32_e32 v59, v59
	v_rcp_f32_e32 v49, v49
	v_mul_f32_e32 v41, v41, v42
	v_mul_f32_e32 v42, v43, v47
	v_exp_f32_e64 v43, -v43
	v_mul_f32_e32 v32, v36, v32
	v_mul_f32_e32 v36, v33, v37
	v_exp_f32_e64 v33, -v33
	v_add_f32_e32 v26, 1.0, v26
	v_add_f32_e32 v16, 1.0, v16
	v_mul_f32_e32 v9, v12, v9
	v_cvt_pk_bf16_f32 v107, v96, v97
	v_mad_i64_i32 v[96:97], s[16:17], v114, s33, v[112:113]
	v_rcp_f32_e32 v82, v82
	v_mul_f32_e32 v64, v66, v70
	v_exp_f32_e64 v66, -v67
	v_rcp_f32_e32 v26, v26
	v_rcp_f32_e32 v16, v16
	v_cvt_pk_bf16_f32 v8, v8, v9
	v_mul_f32_e32 v9, v10, v14
	v_exp_f32_e64 v10, -v10
	v_mul_f32_e32 v4, v0, v4
	v_exp_f32_e64 v0, -v0
	v_lshl_add_u64 v[96:97], v[96:97], 0, s[12:13]
	v_lshl_add_u64 v[96:97], v[96:97], 0, s[66:67]
; __device__ __forceinline__ unsigned pk2(float lo, float hi) { unsigned r; asm("v_cvt_pk_bf16_f32 %0, %1, %2" : "=v"(r) : "v"(lo), "v"(hi)); return r; }
; #define PG8_WAIT_V(n) asm volatile("s_waitcnt vmcnt(" #n ")" ::: "memory")
; #define PG8_BAR __builtin_amdgcn_s_barrier()
;     static __device__ __forceinline__ float sg(float g, float u) { return (g * u) * __builtin_amdgcn_rcpf(1.f + __builtin_amdgcn_exp2f(-g)); }
; template <class Epi>
; __device__ __forceinline__ void gemm_phase(LAS unsigned char* lds, const Gemm g, const StaticOrder& S, const Epi& E) {
;     ...
;         E(acc, cur, wr, wc, fr, fq);
;         if (!has_next) break;
; #pragma unroll
;         for (int a = 0; a < 2; ++a)
; #pragma unroll
;             for (int b = 0; b < 2; ++b)
; #pragma unroll
;                 for (int m = 0; m < 4; ++m)
; #pragma unroll
;                     for (int n = 0; n < 2; ++n) acc[a][b][m][n] = (f32x4){0.f, 0.f, 0.f, 0.f};
;         cur = nxt; cA = nA; cB = nB; ++ui;
;     }
;     PG8_WAIT_V(0);
;     if (wr == 0) PG8_BAR;
;     __device__ __forceinline__ void operator()(const f32x4 (&acc)[2][2][4][2], const Unit& u, int wr, int wc, int fr, int fq) const {
; #pragma unroll
;         for (int ai = 0; ai < 2; ++ai)
; #pragma unroll
;             for (int m = 0; m < 4; ++m) {
;                 const int row = u.pm * BM + ai * HALF + wr * 64 + m * 16 + fr;
;                 const f32x4 g0 = acc[ai][0][m][0], u0 = acc[ai][0][m][1], g1 = acc[ai][1][m][0], u1 = acc[ai][1][m][1];
;                 u32x4 o; o.x = pk2(sg(g0[0], u0[0]), sg(g0[1], u0[1])); o.y = pk2(sg(g0[2], u0[2]), sg(g0[3], u0[3]));
;                 o.z = pk2(sg(g1[0], u1[0]), sg(g1[1], u1[1])); o.w = pk2(sg(g1[2], u1[2]), sg(g1[3], u1[3]));
;                 *(u32x4*)(O + (size_t)row * DFF + u.pn * 128 + wc * 32 + fq * 8) = o;
;             }
	v_lshl_add_u64 v[96:97], v[96:97], 0, v[144:145]
	v_mul_f32_e32 v80, v80, v81
	v_mul_f32_e32 v81, v83, v87
	v_add_f32_e32 v65, 1.0, v65
	v_mul_f32_e32 v58, v58, v59
	v_mul_f32_e32 v49, v52, v49
	v_add_f32_e32 v43, 1.0, v43
	v_add_f32_e32 v33, 1.0, v33
	global_store_dwordx4 v[96:97], v[104:107], off
	v_or_b32_e32 v96, 32, v139
	v_mul_f32_e32 v81, v81, v82
	v_rcp_f32_e32 v65, v65
	v_add_f32_e32 v66, 1.0, v66
	v_cvt_pk_bf16_f32 v57, v57, v58
	v_cvt_pk_bf16_f32 v58, v48, v49
	v_exp_f32_e64 v49, -v50
	v_rcp_f32_e32 v43, v43
	v_rcp_f32_e32 v33, v33
	v_mul_f32_e32 v25, v25, v26
	v_mul_f32_e32 v26, v27, v31
	v_exp_f32_e64 v27, -v27
	v_mul_f32_e32 v16, v20, v16
	v_mul_f32_e32 v20, v17, v21
	v_exp_f32_e64 v17, -v17
	v_add_f32_e32 v10, 1.0, v10
	v_add_f32_e32 v0, 1.0, v0
	v_cvt_pk_bf16_f32 v91, v80, v81
	v_mad_i64_i32 v[80:81], s[16:17], v96, s33, v[112:113]
	v_rcp_f32_e32 v66, v66
	v_mul_f32_e32 v48, v50, v54
	v_exp_f32_e64 v50, -v51
	v_rcp_f32_e32 v10, v10
	v_rcp_f32_e32 v0, v0
	v_lshl_add_u64 v[80:81], v[80:81], 0, s[12:13]
	v_lshl_add_u64 v[80:81], v[80:81], 0, s[66:67]
	v_lshl_add_u64 v[80:81], v[80:81], 0, v[144:145]
	v_mul_f32_e32 v64, v64, v65
	v_mul_f32_e32 v65, v67, v71
	v_add_f32_e32 v49, 1.0, v49
	v_mul_f32_e32 v42, v42, v43
	v_mul_f32_e32 v33, v36, v33
	v_add_f32_e32 v27, 1.0, v27
	v_add_f32_e32 v17, 1.0, v17
	global_store_dwordx4 v[80:81], v[88:91], off
	v_or_b32_e32 v80, 48, v139
	v_mul_f32_e32 v65, v65, v66
	v_rcp_f32_e32 v49, v49
	v_add_f32_e32 v50, 1.0, v50
	v_cvt_pk_bf16_f32 v41, v41, v42
	v_cvt_pk_bf16_f32 v42, v32, v33
	v_exp_f32_e64 v33, -v34
	v_rcp_f32_e32 v27, v27
	v_rcp_f32_e32 v17, v17
	v_mul_f32_e32 v9, v9, v10
	v_mul_f32_e32 v10, v11, v15
	v_exp_f32_e64 v11, -v11
	v_mul_f32_e32 v0, v4, v0
	v_mul_f32_e32 v4, v1, v5
	v_exp_f32_e64 v1, -v1
	v_cvt_pk_bf16_f32 v75, v64, v65
	v_mad_i64_i32 v[64:65], s[16:17], v80, s33, v[112:113]
	v_rcp_f32_e32 v50, v50
	v_mul_f32_e32 v32, v34, v38
	v_exp_f32_e64 v34, -v35
	v_lshl_add_u64 v[64:65], v[64:65], 0, s[12:13]
	v_lshl_add_u64 v[64:65], v[64:65], 0, s[66:67]
	v_lshl_add_u64 v[64:65], v[64:65], 0, v[144:145]
	v_mul_f32_e32 v48, v48, v49
	v_mul_f32_e32 v49, v51, v55
	v_add_f32_e32 v33, 1.0, v33
	v_mul_f32_e32 v26, v26, v27
	v_mul_f32_e32 v17, v20, v17
	v_add_f32_e32 v11, 1.0, v11
	v_add_f32_e32 v1, 1.0, v1
	global_store_dwordx4 v[64:65], v[72:75], off
	v_add_u32_e32 v64, 0x80, v139
	v_mul_f32_e32 v49, v49, v50
	v_rcp_f32_e32 v33, v33
	v_add_f32_e32 v34, 1.0, v34
	v_cvt_pk_bf16_f32 v25, v25, v26
	v_cvt_pk_bf16_f32 v26, v16, v17
	v_exp_f32_e64 v17, -v18
	v_rcp_f32_e32 v11, v11
	v_rcp_f32_e32 v1, v1
	v_cvt_pk_bf16_f32 v59, v48, v49
	v_mad_i64_i32 v[48:49], s[16:17], v64, s33, v[112:113]
	v_rcp_f32_e32 v34, v34
	v_mul_f32_e32 v16, v18, v22
	v_exp_f32_e64 v18, -v19
	v_lshl_add_u64 v[48:49], v[48:49], 0, s[12:13]
	v_lshl_add_u64 v[48:49], v[48:49], 0, s[66:67]
	v_lshl_add_u64 v[48:49], v[48:49], 0, v[144:145]
	v_mul_f32_e32 v32, v32, v33
	v_mul_f32_e32 v33, v35, v39
	v_add_f32_e32 v17, 1.0, v17
	v_mul_f32_e32 v10, v10, v11
	v_mul_f32_e32 v1, v4, v1
	global_store_dwordx4 v[48:49], v[56:59], off
	v_add_u32_e32 v48, 0x90, v139
	v_mul_f32_e32 v33, v33, v34
	v_rcp_f32_e32 v17, v17
	v_add_f32_e32 v18, 1.0, v18
	v_cvt_pk_bf16_f32 v9, v9, v10
	v_cvt_pk_bf16_f32 v10, v0, v1
	v_exp_f32_e64 v1, -v2
	v_cvt_pk_bf16_f32 v43, v32, v33
	v_mad_i64_i32 v[32:33], s[16:17], v48, s33, v[112:113]
	v_rcp_f32_e32 v18, v18
	v_mul_f32_e32 v0, v2, v6
	v_exp_f32_e64 v2, -v3
	v_lshl_add_u64 v[32:33], v[32:33], 0, s[12:13]
	v_lshl_add_u64 v[32:33], v[32:33], 0, s[66:67]
	v_lshl_add_u64 v[32:33], v[32:33], 0, v[144:145]
	v_mul_f32_e32 v16, v16, v17
	v_mul_f32_e32 v17, v19, v23
	v_add_f32_e32 v1, 1.0, v1
	global_store_dwordx4 v[32:33], v[40:43], off
	v_add_u32_e32 v32, 0xa0, v139
	v_mul_f32_e32 v17, v17, v18
	v_rcp_f32_e32 v1, v1
	v_add_f32_e32 v2, 1.0, v2
	v_cvt_pk_bf16_f32 v27, v16, v17
	v_mad_i64_i32 v[16:17], s[16:17], v32, s33, v[112:113]
	v_rcp_f32_e32 v2, v2
	v_lshl_add_u64 v[16:17], v[16:17], 0, s[12:13]
	v_lshl_add_u64 v[16:17], v[16:17], 0, s[66:67]
	v_lshl_add_u64 v[16:17], v[16:17], 0, v[144:145]
	v_mul_f32_e32 v0, v0, v1
	v_mul_f32_e32 v1, v3, v7
	global_store_dwordx4 v[16:17], v[24:27], off
	v_add_u32_e32 v16, 0xb0, v139
	v_mul_f32_e32 v1, v1, v2
	v_cvt_pk_bf16_f32 v11, v0, v1
	v_mad_i64_i32 v[0:1], s[16:17], v16, s33, v[112:113]
	v_lshl_add_u64 v[0:1], v[0:1], 0, s[12:13]
	v_lshl_add_u64 v[0:1], v[0:1], 0, s[66:67]
	v_lshl_add_u64 v[0:1], v[0:1], 0, v[144:145]
	s_and_b64 vcc, exec, s[0:1]
	s_mov_b32 s15, s6
	s_mov_b32 s71, s70
	s_mov_b64 s[16:17], s[10:11]
	s_mov_b64 s[12:13], s[8:9]
	global_store_dwordx4 v[0:1], v[8:11], off
	s_cbranch_vccz .LBB0_278
	s_waitcnt vmcnt(0)
	s_cmpk_gt_u32 s3, 0xff
	s_cbranch_scc1 .LBB0_285
	s_barrier

; #define PG8_STAGE(bufoff, gbase, voff) do { _Pragma("unroll") for (int _i = 0; _i < 2; ++_i) \
;         __builtin_amdgcn_global_load_lds((const unsigned*)((const char*)(gbase) + (voff)[_i]), (LAS unsigned*)(lds + (bufoff) + ldsw + _i * 8192), 16, 0, 0); } while (0)
; #define PG8_LDA(dst, b, h) do { _Pragma("unroll") for (int m = 0; m < 4; ++m) _Pragma("unroll") for (int k = 0; k < 2; ++k) dst[m][k] = *(const LAS bf16x8*)(lds + PG8_SA(b, h) + aoff + m * 2048 + k * 1024); } while (0)
; #define PG8_LDB(dst, b, h) do { _Pragma("unroll") for (int n = 0; n < 2; ++n) _Pragma("unroll") for (int k = 0; k < 2; ++k) dst[n][k] = *(const LAS bf16x8*)(lds + PG8_SB(b, h) + boff + n * 2048 + k * 1024); } while (0)
; #define PG8_MMA(ai, bj, At, Bt) do { __builtin_amdgcn_s_setprio(1); _Pragma("unroll") for (int m = 0; m < 4; ++m) _Pragma("unroll") for (int n = 0; n < 2; ++n) _Pragma("unroll") for (int k = 0; k < 2; ++k) \
;         acc[ai][bj][m][n] = __builtin_amdgcn_mfma_f32_16x16x32_bf16(Bt[n][k], At[m][k], acc[ai][bj][m][n], 0, 0, 0); __builtin_amdgcn_s_setprio(0); } while (0)
; #define PG8_WAIT_L(n) asm volatile("s_waitcnt lgkmcnt(" #n ")" ::: "memory")
; #define PG8_BAR __builtin_amdgcn_s_barrier()
; #define PG8_SCHED __builtin_amdgcn_sched_barrier(0)
; template <class Epi>
; __device__ __forceinline__ void gemm_phase(LAS unsigned char* lds, const Gemm g, const StaticOrder& S, const Epi& E) {
;     ...
;         for (int t = 0; t < nt; t += 2) {
;             const bool last = (t == nt - 2);
;             const char* a1 = cA + (size_t)(t + 1) * kstep;
;             const char* a2 = last ? nA : cA + (size_t)(t + 2) * kstep; const char* b2 = last ? nB : cB + (size_t)(t + 2) * kstep;
;             const char* a3 = a2 + kstep; const char* b3 = b2 + kstep;
;             PG8_LDB(B0, 0, 0); PG8_SCHED; PG8_LDA(At, 0, 0); PG8_STAGE(PG8_SA(1, 1), a1 + hA, voffA);
;             PG8_WAIT_L(8); PG8_BAR; PG8_WAIT_L(0); PG8_MMA(0, 0, At, B0); PG8_BAR; PG8_SCHED;
;             PG8_LDB(B1, 0, 1); PG8_STAGE(PG8_SB(0, 0), b2, voffB);
;             PG8_BAR; PG8_WAIT_L(0); PG8_MMA(0, 1, At, B1); PG8_BAR;
;             PG8_LDA(At, 0, 1); PG8_STAGE(PG8_SA(0, 0), a2, voffA);
;             PG8_BAR; PG8_WAIT_L(0); PG8_MMA(1, 0, At, B0); PG8_BAR; PG8_SCHED;
.LBB0_349:
	s_add_u32 s12, s10, 0x100
	s_addc_u32 s13, s11, 0
	s_add_i32 s26, 0, 0x10000
	v_add_u32_e32 v142, s26, v139
	ds_read_b128 v[134:137], v142
	ds_read_b128 v[146:149], v142 offset:1024
	ds_read_b128 v[150:153], v142 offset:2048
	ds_read_b128 v[154:157], v142 offset:3072
	s_cmp_eq_u32 s72, 40
	s_cselect_b32 s21, s5, s13
	s_cselect_b32 s20, s4, s12
	s_cselect_b32 s17, s7, s25
	s_cselect_b32 s16, s6, s24
	v_lshl_add_u64 v[142:143], s[10:11], 0, v[130:131]
	s_add_i32 m0, s61, 0xc000
	ds_read_b128 v[158:161], v141
	ds_read_b128 v[162:165], v141 offset:1024
	ds_read_b128 v[166:169], v141 offset:2048
	ds_read_b128 v[170:173], v141 offset:3072
	ds_read_b128 v[174:177], v141 offset:4096
	ds_read_b128 v[178:181], v141 offset:5120
	ds_read_b128 v[182:185], v141 offset:6144
	ds_read_b128 v[196:199], v141 offset:7168
	global_load_lds_dwordx4 v[142:143], off
	s_add_i32 m0, s61, 0xe000
	v_lshl_add_u64 v[142:143], s[10:11], 0, v[132:133]
	global_load_lds_dwordx4 v[142:143], off
	s_waitcnt lgkmcnt(8)
	s_barrier
	s_waitcnt lgkmcnt(0)
	v_mfma_f32_16x16x32_bf16 v[124:127], v[134:137], v[158:161], v[124:127]
	v_mfma_f32_16x16x32_bf16 v[120:123], v[150:153], v[158:161], v[120:123]
	v_mfma_f32_16x16x32_bf16 v[116:119], v[134:137], v[166:169], v[116:119]
	v_mfma_f32_16x16x32_bf16 v[108:111], v[150:153], v[166:169], v[108:111]
	v_mfma_f32_16x16x32_bf16 v[100:103], v[134:137], v[174:177], v[100:103]
	v_mfma_f32_16x16x32_bf16 v[92:95], v[150:153], v[174:177], v[92:95]
	v_mfma_f32_16x16x32_bf16 v[84:87], v[134:137], v[182:185], v[84:87]
	v_mfma_f32_16x16x32_bf16 v[76:79], v[150:153], v[182:185], v[76:79]
	v_mfma_f32_16x16x32_bf16 v[124:127], v[146:149], v[162:165], v[124:127]
	v_mfma_f32_16x16x32_bf16 v[120:123], v[154:157], v[162:165], v[120:123]
	v_mfma_f32_16x16x32_bf16 v[116:119], v[146:149], v[170:173], v[116:119]
	v_mfma_f32_16x16x32_bf16 v[108:111], v[154:157], v[170:173], v[108:111]
	v_mfma_f32_16x16x32_bf16 v[100:103], v[146:149], v[178:181], v[100:103]
	v_mfma_f32_16x16x32_bf16 v[92:95], v[154:157], v[178:181], v[92:95]
	v_mfma_f32_16x16x32_bf16 v[84:87], v[146:149], v[196:199], v[84:87]
	v_mfma_f32_16x16x32_bf16 v[76:79], v[154:157], v[196:199], v[76:79]
	s_barrier
	s_add_i32 s27, 0, 0x14000
	v_add_u32_e32 v142, s27, v139
	s_add_i32 s10, s26, s35
	ds_read_b128 v[200:203], v142
	ds_read_b128 v[204:207], v142 offset:1024
	ds_read_b128 v[214:217], v142 offset:2048
	ds_read_b128 v[218:221], v142 offset:3072
	v_lshl_add_u64 v[142:143], s[16:17], 0, v[144:145]
	s_mov_b32 m0, s10
	v_lshl_add_u64 v[186:187], s[16:17], 0, v[128:129]
	global_load_lds_dwordx4 v[142:143], off
	s_add_i32 m0, s10, 0x2000
	s_nop 0
	global_load_lds_dwordx4 v[186:187], off
	s_barrier
	s_waitcnt lgkmcnt(0)
	v_mfma_f32_16x16x32_bf16 v[112:115], v[200:203], v[158:161], v[112:115]
	v_mfma_f32_16x16x32_bf16 v[104:107], v[214:217], v[158:161], v[104:107]
	v_mfma_f32_16x16x32_bf16 v[96:99], v[200:203], v[166:169], v[96:99]
	v_mfma_f32_16x16x32_bf16 v[88:91], v[214:217], v[166:169], v[88:91]
	v_mfma_f32_16x16x32_bf16 v[80:83], v[200:203], v[174:177], v[80:83]
	v_mfma_f32_16x16x32_bf16 v[72:75], v[214:217], v[174:177], v[72:75]
	v_mfma_f32_16x16x32_bf16 v[68:71], v[200:203], v[182:185], v[68:71]
	v_mfma_f32_16x16x32_bf16 v[64:67], v[214:217], v[182:185], v[64:67]
	v_mfma_f32_16x16x32_bf16 v[112:115], v[204:207], v[162:165], v[112:115]
	v_mfma_f32_16x16x32_bf16 v[104:107], v[218:221], v[162:165], v[104:107]
	v_mfma_f32_16x16x32_bf16 v[96:99], v[204:207], v[170:173], v[96:99]
	v_mfma_f32_16x16x32_bf16 v[88:91], v[218:221], v[170:173], v[88:91]
	v_mfma_f32_16x16x32_bf16 v[80:83], v[204:207], v[178:181], v[80:83]
	v_mfma_f32_16x16x32_bf16 v[72:75], v[218:221], v[178:181], v[72:75]
	v_mfma_f32_16x16x32_bf16 v[68:71], v[204:207], v[196:199], v[68:71]
	v_mfma_f32_16x16x32_bf16 v[64:67], v[218:221], v[196:199], v[64:67]
	s_mov_b32 m0, s61
	v_lshl_add_u64 v[188:189], s[20:21], 0, v[144:145]
	s_barrier
	ds_read_b128 v[158:161], v141 offset:16384
	ds_read_b128 v[162:165], v141 offset:17408
	ds_read_b128 v[166:169], v141 offset:18432
	ds_read_b128 v[170:173], v141 offset:19456
	ds_read_b128 v[174:177], v141 offset:20480
	ds_read_b128 v[178:181], v141 offset:21504
	ds_read_b128 v[182:185], v141 offset:22528
	ds_read_b128 v[196:199], v141 offset:23552
	global_load_lds_dwordx4 v[188:189], off
	s_mov_b32 m0, s62
	v_lshl_add_u64 v[192:193], s[20:21], 0, v[128:129]
	global_load_lds_dwordx4 v[192:193], off
	s_barrier
	s_waitcnt lgkmcnt(0)
	v_mfma_f32_16x16x32_bf16 v[60:63], v[134:137], v[158:161], v[60:63]
	v_mfma_f32_16x16x32_bf16 v[56:59], v[150:153], v[158:161], v[56:59]
	v_mfma_f32_16x16x32_bf16 v[52:55], v[134:137], v[166:169], v[52:55]
	v_mfma_f32_16x16x32_bf16 v[44:47], v[150:153], v[166:169], v[44:47]
	v_mfma_f32_16x16x32_bf16 v[36:39], v[134:137], v[174:177], v[36:39]
	v_mfma_f32_16x16x32_bf16 v[28:31], v[150:153], v[174:177], v[28:31]
	v_mfma_f32_16x16x32_bf16 v[20:23], v[134:137], v[182:185], v[20:23]
	v_mfma_f32_16x16x32_bf16 v[12:15], v[150:153], v[182:185], v[12:15]
	v_mfma_f32_16x16x32_bf16 v[60:63], v[146:149], v[162:165], v[60:63]
	v_mfma_f32_16x16x32_bf16 v[56:59], v[154:157], v[162:165], v[56:59]
	v_mfma_f32_16x16x32_bf16 v[52:55], v[146:149], v[170:173], v[52:55]
	v_mfma_f32_16x16x32_bf16 v[44:47], v[154:157], v[170:173], v[44:47]
	v_mfma_f32_16x16x32_bf16 v[36:39], v[146:149], v[178:181], v[36:39]
	v_mfma_f32_16x16x32_bf16 v[28:31], v[154:157], v[178:181], v[28:31]
	v_mfma_f32_16x16x32_bf16 v[20:23], v[146:149], v[196:199], v[20:23]
	v_mfma_f32_16x16x32_bf16 v[12:15], v[154:157], v[196:199], v[12:15]
	s_barrier
; #define PG8_STAGE(bufoff, gbase, voff) do { _Pragma("unroll") for (int _i = 0; _i < 2; ++_i) \
;         __builtin_amdgcn_global_load_lds((const unsigned*)((const char*)(gbase) + (voff)[_i]), (LAS unsigned*)(lds + (bufoff) + ldsw + _i * 8192), 16, 0, 0); } while (0)
; #define PG8_LDA(dst, b, h) do { _Pragma("unroll") for (int m = 0; m < 4; ++m) _Pragma("unroll") for (int k = 0; k < 2; ++k) dst[m][k] = *(const LAS bf16x8*)(lds + PG8_SA(b, h) + aoff + m * 2048 + k * 1024); } while (0)
; #define PG8_LDB(dst, b, h) do { _Pragma("unroll") for (int n = 0; n < 2; ++n) _Pragma("unroll") for (int k = 0; k < 2; ++k) dst[n][k] = *(const LAS bf16x8*)(lds + PG8_SB(b, h) + boff + n * 2048 + k * 1024); } while (0)
; #define PG8_MMA(ai, bj, At, Bt) do { __builtin_amdgcn_s_setprio(1); _Pragma("unroll") for (int m = 0; m < 4; ++m) _Pragma("unroll") for (int n = 0; n < 2; ++n) _Pragma("unroll") for (int k = 0; k < 2; ++k) \
;         acc[ai][bj][m][n] = __builtin_amdgcn_mfma_f32_16x16x32_bf16(Bt[n][k], At[m][k], acc[ai][bj][m][n], 0, 0, 0); __builtin_amdgcn_s_setprio(0); } while (0)
; #define PG8_WAIT_V(n) asm volatile("s_waitcnt vmcnt(" #n ")" ::: "memory")
; #define PG8_WAIT_L(n) asm volatile("s_waitcnt lgkmcnt(" #n ")" ::: "memory")
; #define PG8_BAR __builtin_amdgcn_s_barrier()
; #define PG8_SCHED __builtin_amdgcn_sched_barrier(0)
; template <class Epi>
; __device__ __forceinline__ void gemm_phase(LAS unsigned char* lds, const Gemm g, const StaticOrder& S, const Epi& E) {
;     ...
;             PG8_STAGE(PG8_SB(0, 1), b2 + hB, voffB);
;             PG8_WAIT_V(6); PG8_BAR; PG8_MMA(1, 1, At, B1); PG8_BAR;
;             PG8_LDB(B0, 1, 0); PG8_SCHED; PG8_LDA(At, 1, 0); PG8_STAGE(PG8_SA(0, 1), a2 + hA, voffA);
;             PG8_WAIT_L(8); PG8_BAR; PG8_WAIT_L(0); PG8_MMA(0, 0, At, B0); PG8_BAR; PG8_SCHED;
;             PG8_LDB(B1, 1, 1); PG8_STAGE(PG8_SB(1, 0), b3, voffB);
;             PG8_BAR; PG8_WAIT_L(0); PG8_MMA(0, 1, At, B1); PG8_BAR;
;             PG8_LDA(At, 1, 1); PG8_STAGE(PG8_SA(1, 0), a3, voffA);
;             PG8_BAR; PG8_WAIT_L(0); PG8_MMA(1, 0, At, B0); PG8_BAR; PG8_SCHED;
	s_add_u32 s10, s16, 0xb0000
	s_addc_u32 s11, s17, 0
	s_add_i32 s26, s27, s35
	s_mov_b32 m0, s26
	v_lshl_add_u64 v[134:135], s[10:11], 0, v[144:145]
	global_load_lds_dwordx4 v[134:135], off
	s_add_i32 m0, s26, 0x2000
	v_lshl_add_u64 v[134:135], s[10:11], 0, v[128:129]
	global_load_lds_dwordx4 v[134:135], off
	s_waitcnt vmcnt(6)
	s_barrier
	v_mfma_f32_16x16x32_bf16 v[48:51], v[200:203], v[158:161], v[48:51]
	v_mfma_f32_16x16x32_bf16 v[40:43], v[214:217], v[158:161], v[40:43]
	v_mfma_f32_16x16x32_bf16 v[32:35], v[200:203], v[166:169], v[32:35]
	v_mfma_f32_16x16x32_bf16 v[24:27], v[214:217], v[166:169], v[24:27]
	v_mfma_f32_16x16x32_bf16 v[16:19], v[200:203], v[174:177], v[16:19]
	v_mfma_f32_16x16x32_bf16 v[8:11], v[214:217], v[174:177], v[8:11]
	v_mfma_f32_16x16x32_bf16 v[4:7], v[200:203], v[182:185], v[4:7]
	v_mfma_f32_16x16x32_bf16 v[0:3], v[214:217], v[182:185], v[0:3]
	v_mfma_f32_16x16x32_bf16 v[48:51], v[204:207], v[162:165], v[48:51]
	v_mfma_f32_16x16x32_bf16 v[40:43], v[218:221], v[162:165], v[40:43]
	v_mfma_f32_16x16x32_bf16 v[32:35], v[204:207], v[170:173], v[32:35]
	v_mfma_f32_16x16x32_bf16 v[24:27], v[218:221], v[170:173], v[24:27]
	v_mfma_f32_16x16x32_bf16 v[16:19], v[204:207], v[178:181], v[16:19]
	v_mfma_f32_16x16x32_bf16 v[8:11], v[218:221], v[178:181], v[8:11]
	v_mfma_f32_16x16x32_bf16 v[4:7], v[204:207], v[196:199], v[4:7]
	v_mfma_f32_16x16x32_bf16 v[0:3], v[218:221], v[196:199], v[0:3]
	s_add_i32 s26, 0, 0x18000
	v_add_u32_e32 v154, s26, v139
	s_barrier
	ds_read_b128 v[134:137], v154
	ds_read_b128 v[146:149], v154 offset:1024
	ds_read_b128 v[150:153], v154 offset:2048
	ds_read_b128 v[154:157], v154 offset:3072
	s_add_u32 s10, s20, 0xb0000
	s_addc_u32 s11, s21, 0
	s_mov_b32 m0, s63
	v_lshl_add_u64 v[200:201], s[10:11], 0, v[144:145]
	ds_read_b128 v[158:161], v141 offset:32768
	ds_read_b128 v[162:165], v141 offset:33792
	ds_read_b128 v[166:169], v141 offset:34816
	ds_read_b128 v[170:173], v141 offset:35840
	ds_read_b128 v[174:177], v141 offset:36864
	ds_read_b128 v[178:181], v141 offset:37888
	ds_read_b128 v[182:185], v141 offset:38912
	ds_read_b128 v[196:199], v141 offset:39936
	global_load_lds_dwordx4 v[200:201], off
	s_mov_b32 m0, s64
	v_lshl_add_u64 v[200:201], s[10:11], 0, v[128:129]
	global_load_lds_dwordx4 v[200:201], off
	s_waitcnt lgkmcnt(8)
	s_barrier
	s_waitcnt lgkmcnt(0)
	v_mfma_f32_16x16x32_bf16 v[124:127], v[134:137], v[158:161], v[124:127]
	v_mfma_f32_16x16x32_bf16 v[120:123], v[150:153], v[158:161], v[120:123]
	v_mfma_f32_16x16x32_bf16 v[116:119], v[134:137], v[166:169], v[116:119]
	v_mfma_f32_16x16x32_bf16 v[108:111], v[150:153], v[166:169], v[108:111]
	v_mfma_f32_16x16x32_bf16 v[100:103], v[134:137], v[174:177], v[100:103]
	v_mfma_f32_16x16x32_bf16 v[92:95], v[150:153], v[174:177], v[92:95]
	v_mfma_f32_16x16x32_bf16 v[84:87], v[134:137], v[182:185], v[84:87]
	v_mfma_f32_16x16x32_bf16 v[76:79], v[150:153], v[182:185], v[76:79]
	v_mfma_f32_16x16x32_bf16 v[124:127], v[146:149], v[162:165], v[124:127]
	v_mfma_f32_16x16x32_bf16 v[120:123], v[154:157], v[162:165], v[120:123]
	v_mfma_f32_16x16x32_bf16 v[116:119], v[146:149], v[170:173], v[116:119]
	v_mfma_f32_16x16x32_bf16 v[108:111], v[154:157], v[170:173], v[108:111]
	v_mfma_f32_16x16x32_bf16 v[100:103], v[146:149], v[178:181], v[100:103]
	v_mfma_f32_16x16x32_bf16 v[92:95], v[154:157], v[178:181], v[92:95]
	v_mfma_f32_16x16x32_bf16 v[84:87], v[146:149], v[196:199], v[84:87]
	v_mfma_f32_16x16x32_bf16 v[76:79], v[154:157], v[196:199], v[76:79]
	s_barrier
	s_add_i32 s20, 0, 0x1c000
	s_add_i32 s10, s26, s35
	v_add_u32_e32 v190, s20, v139
	v_lshl_add_u64 v[142:143], v[142:143], 0, s[88:89]
	s_mov_b32 m0, s10
	ds_read_b128 v[200:203], v190
	ds_read_b128 v[204:207], v190 offset:1024
	ds_read_b128 v[214:217], v190 offset:2048
	ds_read_b128 v[218:221], v190 offset:3072
	global_load_lds_dwordx4 v[142:143], off
	s_add_i32 m0, s10, 0x2000
	v_lshl_add_u64 v[142:143], v[186:187], 0, s[88:89]
	global_load_lds_dwordx4 v[142:143], off
	s_barrier
	s_waitcnt lgkmcnt(0)
	v_mfma_f32_16x16x32_bf16 v[112:115], v[200:203], v[158:161], v[112:115]
	v_mfma_f32_16x16x32_bf16 v[104:107], v[214:217], v[158:161], v[104:107]
	v_mfma_f32_16x16x32_bf16 v[96:99], v[200:203], v[166:169], v[96:99]
	v_mfma_f32_16x16x32_bf16 v[88:91], v[214:217], v[166:169], v[88:91]
	v_mfma_f32_16x16x32_bf16 v[80:83], v[200:203], v[174:177], v[80:83]
	v_mfma_f32_16x16x32_bf16 v[72:75], v[214:217], v[174:177], v[72:75]
	v_mfma_f32_16x16x32_bf16 v[68:71], v[200:203], v[182:185], v[68:71]
	v_mfma_f32_16x16x32_bf16 v[64:67], v[214:217], v[182:185], v[64:67]
	v_mfma_f32_16x16x32_bf16 v[112:115], v[204:207], v[162:165], v[112:115]
	v_mfma_f32_16x16x32_bf16 v[104:107], v[218:221], v[162:165], v[104:107]
	v_mfma_f32_16x16x32_bf16 v[96:99], v[204:207], v[170:173], v[96:99]
	v_mfma_f32_16x16x32_bf16 v[88:91], v[218:221], v[170:173], v[88:91]
	v_mfma_f32_16x16x32_bf16 v[80:83], v[204:207], v[178:181], v[80:83]
	v_mfma_f32_16x16x32_bf16 v[72:75], v[218:221], v[178:181], v[72:75]
	v_mfma_f32_16x16x32_bf16 v[68:71], v[204:207], v[196:199], v[68:71]
	v_mfma_f32_16x16x32_bf16 v[64:67], v[218:221], v[196:199], v[64:67]
	s_mov_b32 m0, s65
	v_lshl_add_u64 v[142:143], v[188:189], 0, s[88:89]
	s_barrier
	ds_read_b128 v[158:161], v141 offset:49152
	ds_read_b128 v[162:165], v141 offset:50176
	ds_read_b128 v[166:169], v141 offset:51200
	ds_read_b128 v[170:173], v141 offset:52224
	ds_read_b128 v[174:177], v141 offset:53248
	ds_read_b128 v[178:181], v141 offset:54272
	ds_read_b128 v[182:185], v141 offset:55296
	ds_read_b128 v[196:199], v141 offset:56320
	global_load_lds_dwordx4 v[142:143], off
	s_mov_b32 m0, s66
	v_lshl_add_u64 v[142:143], v[192:193], 0, s[88:89]
	global_load_lds_dwordx4 v[142:143], off
	s_barrier
; #define PG8_STAGE(bufoff, gbase, voff) do { _Pragma("unroll") for (int _i = 0; _i < 2; ++_i) \
;         __builtin_amdgcn_global_load_lds((const unsigned*)((const char*)(gbase) + (voff)[_i]), (LAS unsigned*)(lds + (bufoff) + ldsw + _i * 8192), 16, 0, 0); } while (0)
; #define PG8_MMA(ai, bj, At, Bt) do { __builtin_amdgcn_s_setprio(1); _Pragma("unroll") for (int m = 0; m < 4; ++m) _Pragma("unroll") for (int n = 0; n < 2; ++n) _Pragma("unroll") for (int k = 0; k < 2; ++k) \
;         acc[ai][bj][m][n] = __builtin_amdgcn_mfma_f32_16x16x32_bf16(Bt[n][k], At[m][k], acc[ai][bj][m][n], 0, 0, 0); __builtin_amdgcn_s_setprio(0); } while (0)
; #define PG8_WAIT_V(n) asm volatile("s_waitcnt vmcnt(" #n ")" ::: "memory")
; #define PG8_WAIT_L(n) asm volatile("s_waitcnt lgkmcnt(" #n ")" ::: "memory")
; #define PG8_BAR __builtin_amdgcn_s_barrier()
; #define PG8_SCHED __builtin_amdgcn_sched_barrier(0)
; template <class Epi>
; __device__ __forceinline__ void gemm_phase(LAS unsigned char* lds, const Gemm g, const StaticOrder& S, const Epi& E) {
;     ...
;             PG8_BAR; PG8_WAIT_L(0); PG8_MMA(1, 0, At, B0); PG8_BAR; PG8_SCHED;
;             PG8_STAGE(PG8_SB(1, 1), b3 + hB, voffB);
;             PG8_WAIT_V(6); PG8_BAR; PG8_MMA(1, 1, At, B1); PG8_BAR;
;         }
	s_waitcnt lgkmcnt(0)
	v_mfma_f32_16x16x32_bf16 v[60:63], v[134:137], v[158:161], v[60:63]
	v_mfma_f32_16x16x32_bf16 v[56:59], v[150:153], v[158:161], v[56:59]
	v_mfma_f32_16x16x32_bf16 v[52:55], v[134:137], v[166:169], v[52:55]
	v_mfma_f32_16x16x32_bf16 v[44:47], v[150:153], v[166:169], v[44:47]
	v_mfma_f32_16x16x32_bf16 v[36:39], v[134:137], v[174:177], v[36:39]
	v_mfma_f32_16x16x32_bf16 v[28:31], v[150:153], v[174:177], v[28:31]
	v_mfma_f32_16x16x32_bf16 v[20:23], v[134:137], v[182:185], v[20:23]
	v_mfma_f32_16x16x32_bf16 v[12:15], v[150:153], v[182:185], v[12:15]
	v_mfma_f32_16x16x32_bf16 v[60:63], v[146:149], v[162:165], v[60:63]
	v_mfma_f32_16x16x32_bf16 v[56:59], v[154:157], v[162:165], v[56:59]
	v_mfma_f32_16x16x32_bf16 v[52:55], v[146:149], v[170:173], v[52:55]
	v_mfma_f32_16x16x32_bf16 v[44:47], v[154:157], v[170:173], v[44:47]
	v_mfma_f32_16x16x32_bf16 v[36:39], v[146:149], v[178:181], v[36:39]
	v_mfma_f32_16x16x32_bf16 v[28:31], v[154:157], v[178:181], v[28:31]
	v_mfma_f32_16x16x32_bf16 v[20:23], v[146:149], v[196:199], v[20:23]
	v_mfma_f32_16x16x32_bf16 v[12:15], v[154:157], v[196:199], v[12:15]
	s_barrier
	s_add_u32 s10, s16, 0xb0080
	s_addc_u32 s11, s17, 0
	s_add_i32 s16, s20, s35
	s_mov_b32 m0, s16
	v_lshl_add_u64 v[134:135], s[10:11], 0, v[144:145]
	global_load_lds_dwordx4 v[134:135], off
	s_add_i32 m0, s16, 0x2000
	v_lshl_add_u64 v[134:135], s[10:11], 0, v[128:129]
	global_load_lds_dwordx4 v[134:135], off
	s_waitcnt vmcnt(6)
	s_barrier
	v_mfma_f32_16x16x32_bf16 v[48:51], v[200:203], v[158:161], v[48:51]
	v_mfma_f32_16x16x32_bf16 v[40:43], v[214:217], v[158:161], v[40:43]
	v_mfma_f32_16x16x32_bf16 v[32:35], v[200:203], v[166:169], v[32:35]
	v_mfma_f32_16x16x32_bf16 v[24:27], v[214:217], v[166:169], v[24:27]
	v_mfma_f32_16x16x32_bf16 v[16:19], v[200:203], v[174:177], v[16:19]
	v_mfma_f32_16x16x32_bf16 v[8:11], v[214:217], v[174:177], v[8:11]
	v_mfma_f32_16x16x32_bf16 v[4:7], v[200:203], v[182:185], v[4:7]
	v_mfma_f32_16x16x32_bf16 v[0:3], v[214:217], v[182:185], v[0:3]
	v_mfma_f32_16x16x32_bf16 v[48:51], v[204:207], v[162:165], v[48:51]
	v_mfma_f32_16x16x32_bf16 v[40:43], v[218:221], v[162:165], v[40:43]
	v_mfma_f32_16x16x32_bf16 v[32:35], v[204:207], v[170:173], v[32:35]
	v_mfma_f32_16x16x32_bf16 v[24:27], v[218:221], v[170:173], v[24:27]
	v_mfma_f32_16x16x32_bf16 v[16:19], v[204:207], v[178:181], v[16:19]
	v_mfma_f32_16x16x32_bf16 v[8:11], v[218:221], v[178:181], v[8:11]
	v_mfma_f32_16x16x32_bf16 v[4:7], v[204:207], v[196:199], v[4:7]
	v_mfma_f32_16x16x32_bf16 v[0:3], v[218:221], v[196:199], v[0:3]
	s_add_i32 s72, s72, 2
	s_add_u32 s24, s24, 0x100
	s_addc_u32 s25, s25, 0
	s_cmp_gt_u32 s72, 41
	s_mov_b64 s[10:11], s[12:13]
	s_barrier
	s_cbranch_scc0 .LBB0_349
; __device__ __forceinline__ unsigned pk2(float lo, float hi) { unsigned r; asm("v_cvt_pk_bf16_f32 %0, %1, %2" : "=v"(r) : "v"(lo), "v"(hi)); return r; }
; #define PG8_WAIT_V(n) asm volatile("s_waitcnt vmcnt(" #n ")" ::: "memory")
; #define PG8_BAR __builtin_amdgcn_s_barrier()
; template <class Epi>
; __device__ __forceinline__ void gemm_phase(LAS unsigned char* lds, const Gemm g, const StaticOrder& S, const Epi& E) {
;     ...
;         E(acc, cur, wr, wc, fr, fq);
;         if (!has_next) break;
; #pragma unroll
;         for (int a = 0; a < 2; ++a)
; #pragma unroll
;             for (int b = 0; b < 2; ++b)
; #pragma unroll
;                 for (int m = 0; m < 4; ++m)
; #pragma unroll
;                     for (int n = 0; n < 2; ++n) acc[a][b][m][n] = (f32x4){0.f, 0.f, 0.f, 0.f};
;         cur = nxt; cA = nA; cB = nB; ++ui;
;     }
;     PG8_WAIT_V(0);
;     if (wr == 0) PG8_BAR;
;     __device__ __forceinline__ void operator()(const f32x4 (&acc)[2][2][4][2], const Unit& u, int wr, int wc, int fr, int fq) const {
;     ...
;         const int row_t = rmap == 1 ? odd_phys_row0(u.pm, grp) : (rmap == 2 ? odd_phys_row0(u.pm % (BG * TPB), u.pm / (BG * TPB)) : u.pm * BM);
;         int c = col_t + 64 * wc + 16 * fq;
;         if (mode == 2) c = (c >> 6) * 96 + (c & 63);
; #pragma unroll
;         for (int ai = 0; ai < 2; ++ai)
; #pragma unroll
;             for (int m = 0; m < 4; ++m) {
;                 const int row = row_t + ai * HALF + wr * 64 + m * 16 + fr;
;                 bf16_t* rp = O + (size_t)row * ldc + c;
; #pragma unroll
;                 for (int bj = 0; bj < 2; ++bj) {
;                     const f32x4 v0 = acc[ai][bj][m][0], v1 = acc[ai][bj][m][1];
;                     u32x4 o; o.x = pk2(v0[0], v0[1]); o.y = pk2(v0[2], v0[3]); o.z = pk2(v1[0], v1[1]); o.w = pk2(v1[2], v1[3]);
;                     *(u32x4*)(rp + 8 * bj) = o;
;                 }
;             }
	v_lshl_add_u32 v134, s71, 8, v138
	v_cvt_pk_bf16_f32 v68, v68, v69
	v_cvt_pk_bf16_f32 v69, v70, v71
	v_cvt_pk_bf16_f32 v70, v64, v65
	v_add_u32_e32 v64, 0x80, v134
	v_lshl_or_b32 v136, s15, 8, v140
	v_ashrrev_i32_e32 v135, 31, v134
	v_cvt_pk_bf16_f32 v112, v112, v113
	v_cvt_pk_bf16_f32 v113, v114, v115
	v_cvt_pk_bf16_f32 v114, v104, v105
	v_or_b32_e32 v104, 16, v134
	v_ashrrev_i32_e32 v65, 31, v64
	v_cvt_pk_bf16_f32 v48, v48, v49
	v_cvt_pk_bf16_f32 v49, v50, v51
	v_cvt_pk_bf16_f32 v50, v40, v41
	v_add_u32_e32 v40, 0x90, v134
	v_ashrrev_i32_e32 v137, 31, v136
	v_lshlrev_b64 v[142:143], 11, v[134:135]
	v_ashrrev_i32_e32 v105, 31, v104
	v_cvt_pk_bf16_f32 v96, v96, v97
	v_cvt_pk_bf16_f32 v97, v98, v99
	v_cvt_pk_bf16_f32 v98, v88, v89
	v_or_b32_e32 v88, 32, v134
	v_lshlrev_b64 v[64:65], 11, v[64:65]
	v_ashrrev_i32_e32 v41, 31, v40
	v_cvt_pk_bf16_f32 v32, v32, v33
	v_cvt_pk_bf16_f32 v33, v34, v35
	v_cvt_pk_bf16_f32 v34, v24, v25
	v_add_u32_e32 v24, 0xa0, v134
	v_lshl_add_u64 v[142:143], s[8:9], 0, v[142:143]
	v_lshlrev_b64 v[136:137], 1, v[136:137]
	v_lshlrev_b64 v[104:105], 11, v[104:105]
	v_ashrrev_i32_e32 v89, 31, v88
	v_cvt_pk_bf16_f32 v80, v80, v81
	v_cvt_pk_bf16_f32 v81, v82, v83
	v_cvt_pk_bf16_f32 v82, v72, v73
	v_or_b32_e32 v72, 48, v134
	v_lshl_add_u64 v[64:65], s[8:9], 0, v[64:65]
	v_lshlrev_b64 v[40:41], 11, v[40:41]
	v_ashrrev_i32_e32 v25, 31, v24
	v_cvt_pk_bf16_f32 v16, v16, v17
	v_cvt_pk_bf16_f32 v17, v18, v19
	v_cvt_pk_bf16_f32 v18, v8, v9
	v_add_u32_e32 v8, 0xb0, v134
	v_lshl_add_u64 v[142:143], v[142:143], 0, v[136:137]
	v_lshl_add_u64 v[104:105], s[8:9], 0, v[104:105]
	v_lshlrev_b64 v[88:89], 11, v[88:89]
	v_ashrrev_i32_e32 v73, 31, v72
	v_lshl_add_u64 v[64:65], v[64:65], 0, v[136:137]
	v_lshl_add_u64 v[40:41], s[8:9], 0, v[40:41]
	v_lshlrev_b64 v[24:25], 11, v[24:25]
	v_ashrrev_i32_e32 v9, 31, v8
	v_cvt_pk_bf16_f32 v115, v106, v107
	global_store_dwordx4 v[142:143], v[112:115], off offset:16
	v_lshl_add_u64 v[88:89], s[8:9], 0, v[88:89]
	v_lshlrev_b64 v[72:73], 11, v[72:73]
	v_lshl_add_u64 v[112:113], v[104:105], 0, v[136:137]
	v_cvt_pk_bf16_f32 v51, v42, v43
	global_store_dwordx4 v[64:65], v[48:51], off offset:16
	v_lshl_add_u64 v[24:25], s[8:9], 0, v[24:25]
	v_lshlrev_b64 v[8:9], 11, v[8:9]
	v_lshl_add_u64 v[48:49], v[40:41], 0, v[136:137]
	v_cvt_pk_bf16_f32 v99, v90, v91
	global_store_dwordx4 v[112:113], v[96:99], off offset:16
	v_lshl_add_u64 v[72:73], s[8:9], 0, v[72:73]
	v_cvt_pk_bf16_f32 v35, v26, v27
	global_store_dwordx4 v[48:49], v[32:35], off offset:16
	v_lshl_add_u64 v[96:97], v[88:89], 0, v[136:137]
	v_lshl_add_u64 v[8:9], s[8:9], 0, v[8:9]
	v_lshl_add_u64 v[32:33], v[24:25], 0, v[136:137]
	v_cvt_pk_bf16_f32 v83, v74, v75
	global_store_dwordx4 v[96:97], v[80:83], off offset:16
	v_cvt_pk_bf16_f32 v19, v10, v11
	global_store_dwordx4 v[32:33], v[16:19], off offset:16
	s_and_b64 vcc, exec, s[0:1]
	v_lshl_add_u64 v[80:81], v[72:73], 0, v[136:137]
	v_lshl_add_u64 v[16:17], v[8:9], 0, v[136:137]
	s_mov_b32 s15, s69
	s_mov_b32 s71, s70
	s_mov_b64 s[12:13], s[6:7]
	s_mov_b64 s[10:11], s[4:5]
	v_cvt_pk_bf16_f32 v124, v124, v125
	v_cvt_pk_bf16_f32 v125, v126, v127
	v_cvt_pk_bf16_f32 v126, v120, v121
	v_cvt_pk_bf16_f32 v127, v122, v123
	global_store_dwordx4 v[142:143], v[124:127], off
	v_cvt_pk_bf16_f32 v104, v116, v117
	v_cvt_pk_bf16_f32 v105, v118, v119
	v_cvt_pk_bf16_f32 v106, v108, v109
	v_cvt_pk_bf16_f32 v107, v110, v111
	global_store_dwordx4 v[112:113], v[104:107], off
	v_cvt_pk_bf16_f32 v88, v100, v101
	v_cvt_pk_bf16_f32 v89, v102, v103
	v_cvt_pk_bf16_f32 v90, v92, v93
	v_cvt_pk_bf16_f32 v91, v94, v95
	global_store_dwordx4 v[96:97], v[88:91], off
	v_cvt_pk_bf16_f32 v72, v84, v85
	v_cvt_pk_bf16_f32 v73, v86, v87
	v_cvt_pk_bf16_f32 v74, v76, v77
	v_cvt_pk_bf16_f32 v75, v78, v79
	global_store_dwordx4 v[80:81], v[72:75], off
	v_cvt_pk_bf16_f32 v71, v66, v67
	global_store_dwordx4 v[80:81], v[68:71], off offset:16
	v_cvt_pk_bf16_f32 v60, v60, v61
	v_cvt_pk_bf16_f32 v61, v62, v63
	v_cvt_pk_bf16_f32 v62, v56, v57
	v_cvt_pk_bf16_f32 v63, v58, v59
	global_store_dwordx4 v[64:65], v[60:63], off
	v_cvt_pk_bf16_f32 v40, v52, v53
	v_cvt_pk_bf16_f32 v41, v54, v55
	v_cvt_pk_bf16_f32 v42, v44, v45
	v_cvt_pk_bf16_f32 v43, v46, v47
	global_store_dwordx4 v[48:49], v[40:43], off
	v_cvt_pk_bf16_f32 v24, v36, v37
	v_cvt_pk_bf16_f32 v25, v38, v39
	v_cvt_pk_bf16_f32 v26, v28, v29
	v_cvt_pk_bf16_f32 v27, v30, v31
	global_store_dwordx4 v[32:33], v[24:27], off
	v_cvt_pk_bf16_f32 v8, v20, v21
	v_cvt_pk_bf16_f32 v9, v22, v23
	v_cvt_pk_bf16_f32 v10, v12, v13
	v_cvt_pk_bf16_f32 v11, v14, v15
	global_store_dwordx4 v[16:17], v[8:11], off
	v_cvt_pk_bf16_f32 v4, v4, v5
	v_cvt_pk_bf16_f32 v5, v6, v7
	v_cvt_pk_bf16_f32 v6, v0, v1
	v_cvt_pk_bf16_f32 v7, v2, v3
	global_store_dwordx4 v[16:17], v[4:7], off offset:16
	s_cbranch_vccz .LBB0_342
	s_waitcnt vmcnt(0)
	s_cmpk_gt_u32 s3, 0xff
	s_cbranch_scc1 .LBB0_353
	s_barrier

; #define PG8_STAGE(bufoff, gbase, voff) do { _Pragma("unroll") for (int _i = 0; _i < 2; ++_i) \
;         __builtin_amdgcn_global_load_lds((const unsigned*)((const char*)(gbase) + (voff)[_i]), (LAS unsigned*)(lds + (bufoff) + ldsw + _i * 8192), 16, 0, 0); } while (0)
; #define PG8_LDA(dst, b, h) do { _Pragma("unroll") for (int m = 0; m < 4; ++m) _Pragma("unroll") for (int k = 0; k < 2; ++k) dst[m][k] = *(const LAS bf16x8*)(lds + PG8_SA(b, h) + aoff + m * 2048 + k * 1024); } while (0)
; #define PG8_LDB(dst, b, h) do { _Pragma("unroll") for (int n = 0; n < 2; ++n) _Pragma("unroll") for (int k = 0; k < 2; ++k) dst[n][k] = *(const LAS bf16x8*)(lds + PG8_SB(b, h) + boff + n * 2048 + k * 1024); } while (0)
; #define PG8_MMA(ai, bj, At, Bt) do { __builtin_amdgcn_s_setprio(1); _Pragma("unroll") for (int m = 0; m < 4; ++m) _Pragma("unroll") for (int n = 0; n < 2; ++n) _Pragma("unroll") for (int k = 0; k < 2; ++k) \
;         acc[ai][bj][m][n] = __builtin_amdgcn_mfma_f32_16x16x32_bf16(Bt[n][k], At[m][k], acc[ai][bj][m][n], 0, 0, 0); __builtin_amdgcn_s_setprio(0); } while (0)
; #define PG8_WAIT_L(n) asm volatile("s_waitcnt lgkmcnt(" #n ")" ::: "memory")
; #define PG8_BAR __builtin_amdgcn_s_barrier()
; #define PG8_SCHED __builtin_amdgcn_sched_barrier(0)
; template <class Epi>
; __device__ __forceinline__ void gemm_phase(LAS unsigned char* lds, const Gemm g, const StaticOrder& S, const Epi& E) {
;     ...
;         for (int t = 0; t < nt; t += 2) {
;             const bool last = (t == nt - 2);
;             const char* a1 = cA + (size_t)(t + 1) * kstep;
;             const char* a2 = last ? nA : cA + (size_t)(t + 2) * kstep; const char* b2 = last ? nB : cB + (size_t)(t + 2) * kstep;
;             const char* a3 = a2 + kstep; const char* b3 = b2 + kstep;
;             PG8_LDB(B0, 0, 0); PG8_SCHED; PG8_LDA(At, 0, 0); PG8_STAGE(PG8_SA(1, 1), a1 + hA, voffA);
;             PG8_WAIT_L(8); PG8_BAR; PG8_WAIT_L(0); PG8_MMA(0, 0, At, B0); PG8_BAR; PG8_SCHED;
;             PG8_LDB(B1, 0, 1); PG8_STAGE(PG8_SB(0, 0), b2, voffB);
;             PG8_BAR; PG8_WAIT_L(0); PG8_MMA(0, 1, At, B1); PG8_BAR;
;             PG8_LDA(At, 0, 1); PG8_STAGE(PG8_SA(0, 0), a2, voffA);
;             PG8_BAR; PG8_WAIT_L(0); PG8_MMA(1, 0, At, B0); PG8_BAR; PG8_SCHED;
.LBB0_499:
	s_add_u32 s26, s4, 0xfffc0080
	s_addc_u32 s27, s5, -1
	s_add_i32 s28, 0, 0x10000
	v_add_u32_e32 v146, s28, v149
	ds_read_b128 v[136:139], v146
	ds_read_b128 v[140:143], v146 offset:1024
	ds_read_b128 v[158:161], v146 offset:2048
	ds_read_b128 v[162:165], v146 offset:3072
	s_cmp_eq_u32 s84, 12
	s_cselect_b32 s65, s21, s27
	s_cselect_b32 s64, s20, s26
	s_cselect_b32 s35, s15, s25
	s_cselect_b32 s34, s17, s24
	v_lshl_add_u64 v[146:147], s[4:5], 0, v[132:133]
	s_add_i32 m0, s66, 0xc000
	ds_read_b128 v[166:169], v154
	ds_read_b128 v[170:173], v154 offset:1024
	ds_read_b128 v[174:177], v154 offset:2048
	ds_read_b128 v[178:181], v154 offset:3072
	ds_read_b128 v[182:185], v154 offset:4096
	ds_read_b128 v[196:199], v154 offset:5120
	ds_read_b128 v[200:203], v154 offset:6144
	ds_read_b128 v[204:207], v154 offset:7168
	global_load_lds_dwordx4 v[146:147], off
	s_add_i32 m0, s66, 0xe000
	v_lshl_add_u64 v[146:147], s[4:5], 0, v[134:135]
	global_load_lds_dwordx4 v[146:147], off
	s_waitcnt lgkmcnt(8)
	s_barrier
	s_waitcnt lgkmcnt(0)
	v_mfma_f32_16x16x32_bf16 v[124:127], v[136:139], v[166:169], v[124:127]
	v_mfma_f32_16x16x32_bf16 v[120:123], v[158:161], v[166:169], v[120:123]
	v_mfma_f32_16x16x32_bf16 v[116:119], v[136:139], v[174:177], v[116:119]
	v_mfma_f32_16x16x32_bf16 v[108:111], v[158:161], v[174:177], v[108:111]
	v_mfma_f32_16x16x32_bf16 v[100:103], v[136:139], v[182:185], v[100:103]
	v_mfma_f32_16x16x32_bf16 v[92:95], v[158:161], v[182:185], v[92:95]
	v_mfma_f32_16x16x32_bf16 v[84:87], v[136:139], v[200:203], v[84:87]
	v_mfma_f32_16x16x32_bf16 v[76:79], v[158:161], v[200:203], v[76:79]
	v_mfma_f32_16x16x32_bf16 v[124:127], v[140:143], v[170:173], v[124:127]
	v_mfma_f32_16x16x32_bf16 v[120:123], v[162:165], v[170:173], v[120:123]
	v_mfma_f32_16x16x32_bf16 v[116:119], v[140:143], v[178:181], v[116:119]
	v_mfma_f32_16x16x32_bf16 v[108:111], v[162:165], v[178:181], v[108:111]
	v_mfma_f32_16x16x32_bf16 v[100:103], v[140:143], v[196:199], v[100:103]
	v_mfma_f32_16x16x32_bf16 v[92:95], v[162:165], v[196:199], v[92:95]
	v_mfma_f32_16x16x32_bf16 v[84:87], v[140:143], v[204:207], v[84:87]
	v_mfma_f32_16x16x32_bf16 v[76:79], v[162:165], v[204:207], v[76:79]
	s_barrier
	s_add_i32 s29, 0, 0x14000
	v_add_u32_e32 v146, s29, v149
	s_add_i32 s26, s28, s71
	ds_read_b128 v[216:219], v146
	ds_read_b128 v[220:223], v146 offset:1024
	ds_read_b128 v[224:227], v146 offset:2048
	ds_read_b128 v[228:231], v146 offset:3072
	v_lshl_add_u64 v[146:147], s[34:35], 0, v[128:129]
	s_mov_b32 m0, s26
	v_lshl_add_u64 v[186:187], s[34:35], 0, v[130:131]
	global_load_lds_dwordx4 v[146:147], off
	s_add_i32 m0, s26, 0x2000
	s_nop 0
	global_load_lds_dwordx4 v[186:187], off
	s_barrier
	s_waitcnt lgkmcnt(0)
	v_mfma_f32_16x16x32_bf16 v[112:115], v[216:219], v[166:169], v[112:115]
	v_mfma_f32_16x16x32_bf16 v[104:107], v[224:227], v[166:169], v[104:107]
	v_mfma_f32_16x16x32_bf16 v[96:99], v[216:219], v[174:177], v[96:99]
	v_mfma_f32_16x16x32_bf16 v[88:91], v[224:227], v[174:177], v[88:91]
	v_mfma_f32_16x16x32_bf16 v[80:83], v[216:219], v[182:185], v[80:83]
	v_mfma_f32_16x16x32_bf16 v[72:75], v[224:227], v[182:185], v[72:75]
	v_mfma_f32_16x16x32_bf16 v[68:71], v[216:219], v[200:203], v[68:71]
	v_mfma_f32_16x16x32_bf16 v[64:67], v[224:227], v[200:203], v[64:67]
	v_mfma_f32_16x16x32_bf16 v[112:115], v[220:223], v[170:173], v[112:115]
	v_mfma_f32_16x16x32_bf16 v[104:107], v[228:231], v[170:173], v[104:107]
	v_mfma_f32_16x16x32_bf16 v[96:99], v[220:223], v[178:181], v[96:99]
	v_mfma_f32_16x16x32_bf16 v[88:91], v[228:231], v[178:181], v[88:91]
	v_mfma_f32_16x16x32_bf16 v[80:83], v[220:223], v[196:199], v[80:83]
	v_mfma_f32_16x16x32_bf16 v[72:75], v[228:231], v[196:199], v[72:75]
	v_mfma_f32_16x16x32_bf16 v[68:71], v[220:223], v[204:207], v[68:71]
	v_mfma_f32_16x16x32_bf16 v[64:67], v[228:231], v[204:207], v[64:67]
	s_mov_b32 m0, s66
	v_lshl_add_u64 v[188:189], s[64:65], 0, v[128:129]
	s_barrier
	ds_read_b128 v[166:169], v154 offset:16384
	ds_read_b128 v[170:173], v154 offset:17408
	ds_read_b128 v[174:177], v154 offset:18432
	ds_read_b128 v[178:181], v154 offset:19456
	ds_read_b128 v[182:185], v154 offset:20480
	ds_read_b128 v[196:199], v154 offset:21504
	ds_read_b128 v[200:203], v154 offset:22528
	ds_read_b128 v[204:207], v154 offset:23552
	global_load_lds_dwordx4 v[188:189], off
	s_mov_b32 m0, s72
	v_lshl_add_u64 v[192:193], s[64:65], 0, v[130:131]
	global_load_lds_dwordx4 v[192:193], off
	s_barrier
	s_waitcnt lgkmcnt(0)
	v_mfma_f32_16x16x32_bf16 v[60:63], v[136:139], v[166:169], v[60:63]
	v_mfma_f32_16x16x32_bf16 v[56:59], v[158:161], v[166:169], v[56:59]
	v_mfma_f32_16x16x32_bf16 v[52:55], v[136:139], v[174:177], v[52:55]
	v_mfma_f32_16x16x32_bf16 v[44:47], v[158:161], v[174:177], v[44:47]
	v_mfma_f32_16x16x32_bf16 v[36:39], v[136:139], v[182:185], v[36:39]
	v_mfma_f32_16x16x32_bf16 v[28:31], v[158:161], v[182:185], v[28:31]
	v_mfma_f32_16x16x32_bf16 v[20:23], v[136:139], v[200:203], v[20:23]
	v_mfma_f32_16x16x32_bf16 v[12:15], v[158:161], v[200:203], v[12:15]
	v_mfma_f32_16x16x32_bf16 v[60:63], v[140:143], v[170:173], v[60:63]
	v_mfma_f32_16x16x32_bf16 v[56:59], v[162:165], v[170:173], v[56:59]
	v_mfma_f32_16x16x32_bf16 v[52:55], v[140:143], v[178:181], v[52:55]
	v_mfma_f32_16x16x32_bf16 v[44:47], v[162:165], v[178:181], v[44:47]
	v_mfma_f32_16x16x32_bf16 v[36:39], v[140:143], v[196:199], v[36:39]
	v_mfma_f32_16x16x32_bf16 v[28:31], v[162:165], v[196:199], v[28:31]
	v_mfma_f32_16x16x32_bf16 v[20:23], v[140:143], v[204:207], v[20:23]
	v_mfma_f32_16x16x32_bf16 v[12:15], v[162:165], v[204:207], v[12:15]
	s_barrier
; #define PG8_STAGE(bufoff, gbase, voff) do { _Pragma("unroll") for (int _i = 0; _i < 2; ++_i) \
;         __builtin_amdgcn_global_load_lds((const unsigned*)((const char*)(gbase) + (voff)[_i]), (LAS unsigned*)(lds + (bufoff) + ldsw + _i * 8192), 16, 0, 0); } while (0)
; #define PG8_LDA(dst, b, h) do { _Pragma("unroll") for (int m = 0; m < 4; ++m) _Pragma("unroll") for (int k = 0; k < 2; ++k) dst[m][k] = *(const LAS bf16x8*)(lds + PG8_SA(b, h) + aoff + m * 2048 + k * 1024); } while (0)
; #define PG8_LDB(dst, b, h) do { _Pragma("unroll") for (int n = 0; n < 2; ++n) _Pragma("unroll") for (int k = 0; k < 2; ++k) dst[n][k] = *(const LAS bf16x8*)(lds + PG8_SB(b, h) + boff + n * 2048 + k * 1024); } while (0)
; #define PG8_MMA(ai, bj, At, Bt) do { __builtin_amdgcn_s_setprio(1); _Pragma("unroll") for (int m = 0; m < 4; ++m) _Pragma("unroll") for (int n = 0; n < 2; ++n) _Pragma("unroll") for (int k = 0; k < 2; ++k) \
;         acc[ai][bj][m][n] = __builtin_amdgcn_mfma_f32_16x16x32_bf16(Bt[n][k], At[m][k], acc[ai][bj][m][n], 0, 0, 0); __builtin_amdgcn_s_setprio(0); } while (0)
; #define PG8_WAIT_V(n) asm volatile("s_waitcnt vmcnt(" #n ")" ::: "memory")
; #define PG8_WAIT_L(n) asm volatile("s_waitcnt lgkmcnt(" #n ")" ::: "memory")
; #define PG8_BAR __builtin_amdgcn_s_barrier()
; #define PG8_SCHED __builtin_amdgcn_sched_barrier(0)
; template <class Epi>
; __device__ __forceinline__ void gemm_phase(LAS unsigned char* lds, const Gemm g, const StaticOrder& S, const Epi& E) {
;     ...
;             PG8_STAGE(PG8_SB(0, 1), b2 + hB, voffB);
;             PG8_WAIT_V(6); PG8_BAR; PG8_MMA(1, 1, At, B1); PG8_BAR;
;             PG8_LDB(B0, 1, 0); PG8_SCHED; PG8_LDA(At, 1, 0); PG8_STAGE(PG8_SA(0, 1), a2 + hA, voffA);
;             PG8_WAIT_L(8); PG8_BAR; PG8_WAIT_L(0); PG8_MMA(0, 0, At, B0); PG8_BAR; PG8_SCHED;
;             PG8_LDB(B1, 1, 1); PG8_STAGE(PG8_SB(1, 0), b3, voffB);
;             PG8_BAR; PG8_WAIT_L(0); PG8_MMA(0, 1, At, B1); PG8_BAR;
;             PG8_LDA(At, 1, 1); PG8_STAGE(PG8_SA(1, 0), a3, voffA);
;             PG8_BAR; PG8_WAIT_L(0); PG8_MMA(1, 0, At, B0); PG8_BAR; PG8_SCHED;
	s_add_u32 s26, s34, 0x40000
	s_addc_u32 s27, s35, 0
	s_add_i32 s28, s29, s71
	s_mov_b32 m0, s28
	v_lshl_add_u64 v[136:137], s[26:27], 0, v[128:129]
	global_load_lds_dwordx4 v[136:137], off
	s_add_i32 m0, s28, 0x2000
	v_lshl_add_u64 v[136:137], s[26:27], 0, v[130:131]
	global_load_lds_dwordx4 v[136:137], off
	s_waitcnt vmcnt(6)
	s_barrier
	v_mfma_f32_16x16x32_bf16 v[48:51], v[216:219], v[166:169], v[48:51]
	v_mfma_f32_16x16x32_bf16 v[40:43], v[224:227], v[166:169], v[40:43]
	v_mfma_f32_16x16x32_bf16 v[32:35], v[216:219], v[174:177], v[32:35]
	v_mfma_f32_16x16x32_bf16 v[24:27], v[224:227], v[174:177], v[24:27]
	v_mfma_f32_16x16x32_bf16 v[16:19], v[216:219], v[182:185], v[16:19]
	v_mfma_f32_16x16x32_bf16 v[8:11], v[224:227], v[182:185], v[8:11]
	v_mfma_f32_16x16x32_bf16 v[4:7], v[216:219], v[200:203], v[4:7]
	v_mfma_f32_16x16x32_bf16 v[0:3], v[224:227], v[200:203], v[0:3]
	v_mfma_f32_16x16x32_bf16 v[48:51], v[220:223], v[170:173], v[48:51]
	v_mfma_f32_16x16x32_bf16 v[40:43], v[228:231], v[170:173], v[40:43]
	v_mfma_f32_16x16x32_bf16 v[32:35], v[220:223], v[178:181], v[32:35]
	v_mfma_f32_16x16x32_bf16 v[24:27], v[228:231], v[178:181], v[24:27]
	v_mfma_f32_16x16x32_bf16 v[16:19], v[220:223], v[196:199], v[16:19]
	v_mfma_f32_16x16x32_bf16 v[8:11], v[228:231], v[196:199], v[8:11]
	v_mfma_f32_16x16x32_bf16 v[4:7], v[220:223], v[204:207], v[4:7]
	v_mfma_f32_16x16x32_bf16 v[0:3], v[228:231], v[204:207], v[0:3]
	s_add_i32 s28, 0, 0x18000
	v_add_u32_e32 v157, s28, v149
	s_barrier
	ds_read_b128 v[136:139], v157
	ds_read_b128 v[140:143], v157 offset:1024
	ds_read_b128 v[158:161], v157 offset:2048
	ds_read_b128 v[162:165], v157 offset:3072
	s_add_u32 s26, s64, 0x40000
	s_addc_u32 s27, s65, 0
	s_mov_b32 m0, s76
	v_lshl_add_u64 v[216:217], s[26:27], 0, v[128:129]
	ds_read_b128 v[166:169], v154 offset:32768
	ds_read_b128 v[170:173], v154 offset:33792
	ds_read_b128 v[174:177], v154 offset:34816
	ds_read_b128 v[178:181], v154 offset:35840
	ds_read_b128 v[182:185], v154 offset:36864
	ds_read_b128 v[196:199], v154 offset:37888
	ds_read_b128 v[200:203], v154 offset:38912
	ds_read_b128 v[204:207], v154 offset:39936
	global_load_lds_dwordx4 v[216:217], off
	s_mov_b32 m0, s77
	v_lshl_add_u64 v[216:217], s[26:27], 0, v[130:131]
	global_load_lds_dwordx4 v[216:217], off
	s_waitcnt lgkmcnt(8)
	s_barrier
	s_waitcnt lgkmcnt(0)
	v_mfma_f32_16x16x32_bf16 v[124:127], v[136:139], v[166:169], v[124:127]
	v_mfma_f32_16x16x32_bf16 v[120:123], v[158:161], v[166:169], v[120:123]
	v_mfma_f32_16x16x32_bf16 v[116:119], v[136:139], v[174:177], v[116:119]
	v_mfma_f32_16x16x32_bf16 v[108:111], v[158:161], v[174:177], v[108:111]
	v_mfma_f32_16x16x32_bf16 v[100:103], v[136:139], v[182:185], v[100:103]
	v_mfma_f32_16x16x32_bf16 v[92:95], v[158:161], v[182:185], v[92:95]
	v_mfma_f32_16x16x32_bf16 v[84:87], v[136:139], v[200:203], v[84:87]
	v_mfma_f32_16x16x32_bf16 v[76:79], v[158:161], v[200:203], v[76:79]
	v_mfma_f32_16x16x32_bf16 v[124:127], v[140:143], v[170:173], v[124:127]
	v_mfma_f32_16x16x32_bf16 v[120:123], v[162:165], v[170:173], v[120:123]
	v_mfma_f32_16x16x32_bf16 v[116:119], v[140:143], v[178:181], v[116:119]
	v_mfma_f32_16x16x32_bf16 v[108:111], v[162:165], v[178:181], v[108:111]
	v_mfma_f32_16x16x32_bf16 v[100:103], v[140:143], v[196:199], v[100:103]
	v_mfma_f32_16x16x32_bf16 v[92:95], v[162:165], v[196:199], v[92:95]
	v_mfma_f32_16x16x32_bf16 v[84:87], v[140:143], v[204:207], v[84:87]
	v_mfma_f32_16x16x32_bf16 v[76:79], v[162:165], v[204:207], v[76:79]
	s_barrier
	s_add_i32 s29, 0, 0x1c000
	s_add_i32 s26, s28, s71
	v_add_u32_e32 v157, s29, v149
	v_lshl_add_u64 v[146:147], v[146:147], 0, s[88:89]
	s_mov_b32 m0, s26
	ds_read_b128 v[216:219], v157
	ds_read_b128 v[220:223], v157 offset:1024
	ds_read_b128 v[224:227], v157 offset:2048
	ds_read_b128 v[228:231], v157 offset:3072
	global_load_lds_dwordx4 v[146:147], off
	s_add_i32 m0, s26, 0x2000
	v_lshl_add_u64 v[146:147], v[186:187], 0, s[88:89]
	global_load_lds_dwordx4 v[146:147], off
	s_barrier
	s_waitcnt lgkmcnt(0)
	v_mfma_f32_16x16x32_bf16 v[112:115], v[216:219], v[166:169], v[112:115]
	v_mfma_f32_16x16x32_bf16 v[104:107], v[224:227], v[166:169], v[104:107]
	v_mfma_f32_16x16x32_bf16 v[96:99], v[216:219], v[174:177], v[96:99]
	v_mfma_f32_16x16x32_bf16 v[88:91], v[224:227], v[174:177], v[88:91]
	v_mfma_f32_16x16x32_bf16 v[80:83], v[216:219], v[182:185], v[80:83]
	v_mfma_f32_16x16x32_bf16 v[72:75], v[224:227], v[182:185], v[72:75]
	v_mfma_f32_16x16x32_bf16 v[68:71], v[216:219], v[200:203], v[68:71]
	v_mfma_f32_16x16x32_bf16 v[64:67], v[224:227], v[200:203], v[64:67]
	v_mfma_f32_16x16x32_bf16 v[112:115], v[220:223], v[170:173], v[112:115]
	v_mfma_f32_16x16x32_bf16 v[104:107], v[228:231], v[170:173], v[104:107]
	v_mfma_f32_16x16x32_bf16 v[96:99], v[220:223], v[178:181], v[96:99]
	v_mfma_f32_16x16x32_bf16 v[88:91], v[228:231], v[178:181], v[88:91]
	v_mfma_f32_16x16x32_bf16 v[80:83], v[220:223], v[196:199], v[80:83]
	v_mfma_f32_16x16x32_bf16 v[72:75], v[228:231], v[196:199], v[72:75]
	v_mfma_f32_16x16x32_bf16 v[68:71], v[220:223], v[204:207], v[68:71]
	v_mfma_f32_16x16x32_bf16 v[64:67], v[228:231], v[204:207], v[64:67]
	s_mov_b32 m0, s78
	v_lshl_add_u64 v[146:147], v[188:189], 0, s[88:89]
	s_barrier
	ds_read_b128 v[166:169], v154 offset:49152
	ds_read_b128 v[170:173], v154 offset:50176
	ds_read_b128 v[174:177], v154 offset:51200
	ds_read_b128 v[178:181], v154 offset:52224
	ds_read_b128 v[182:185], v154 offset:53248
	ds_read_b128 v[196:199], v154 offset:54272
	ds_read_b128 v[200:203], v154 offset:55296
	ds_read_b128 v[204:207], v154 offset:56320
	global_load_lds_dwordx4 v[146:147], off
	s_mov_b32 m0, s79
	v_lshl_add_u64 v[146:147], v[192:193], 0, s[88:89]
	global_load_lds_dwordx4 v[146:147], off
	s_barrier
; #define LAS __attribute__((address_space(3)))
; __device__ __forceinline__ unsigned pk2(float lo, float hi) { unsigned r; asm("v_cvt_pk_bf16_f32 %0, %1, %2" : "=v"(r) : "v"(lo), "v"(hi)); return r; }
; #define PG8_WAIT_V(n) asm volatile("s_waitcnt vmcnt(" #n ")" ::: "memory")
; #define PG8_WAIT_L(n) asm volatile("s_waitcnt lgkmcnt(" #n ")" ::: "memory")
; #define PG8_BAR __builtin_amdgcn_s_barrier()
; #define PG8_SCHED __builtin_amdgcn_sched_barrier(0)
; template <class Epi>
; __device__ __forceinline__ void gemm_phase(LAS unsigned char* lds, const Gemm g, const StaticOrder& S, const Epi& E) {
;     ...
;             PG8_BAR; PG8_WAIT_L(0); PG8_MMA(1, 0, At, B0); PG8_BAR; PG8_SCHED;
;             PG8_STAGE(PG8_SB(1, 1), b3 + hB, voffB);
;             PG8_WAIT_V(6); PG8_BAR; PG8_MMA(1, 1, At, B1); PG8_BAR;
;         }
;     __device__ __forceinline__ void operator()(const f32x4 (&acc)[2][2][4][2], const Unit& u, int wr, int wc, int fr, int fq) const {
;         const int col_t = u.pn * BM;
;         if (mode != 0 && col_t >= vt0) {
;             const int bl = u.pm / TPB, key0 = (u.pm - bl * TPB) * 256;
;             LAS bf16_t* sc = (LAS bf16_t*)(trs + (wr * 4 + wc) * 2304);
;             const int lane = fq * 16 + fr;
; #pragma unroll
;             for (int ai = 0; ai < 2; ++ai)
; #pragma unroll
;                 for (int bj = 0; bj < 2; ++bj)
; #pragma unroll
;                     for (int n = 0; n < 2; ++n) {
; #pragma unroll
;                         for (int m = 0; m < 4; ++m) {
;                             const f32x4 v = acc[ai][bj][m][n];
;                             const unsigned p0 = pk2(v[0], v[1]), p1 = pk2(v[2], v[3]);
;                             LAS bf16_t* w = sc + (4 * fq) * 72 + 16 * m + fr;
;                             w[0] = (bf16_t)(p0 & 0xffffu); w[72] = (bf16_t)(p0 >> 16); w[144] = (bf16_t)(p1 & 0xffffu); w[216] = (bf16_t)(p1 >> 16);
;                         }
; #pragma unroll
;                         for (int j = 0; j < 2; ++j) {
;                             const int ch = lane + 64 * j, fi = ch >> 3, seg = ch & 7;
;                             const u32x4 o = *(const LAS u32x4*)(sc + fi * 72 + 8 * seg);
;                             const int f = col_t - vt0 + 64 * wc + 16 * (fi >> 2) + 8 * bj + 4 * n + (fi & 3);
;                             *(u32x4*)(Vt + ((size_t)bl * vtnf + f) * KEYS + key0 + ai * HALF + wr * 64 + 8 * seg) = o;
	s_waitcnt lgkmcnt(0)
	v_mfma_f32_16x16x32_bf16 v[60:63], v[136:139], v[166:169], v[60:63]
	v_mfma_f32_16x16x32_bf16 v[56:59], v[158:161], v[166:169], v[56:59]
	v_mfma_f32_16x16x32_bf16 v[52:55], v[136:139], v[174:177], v[52:55]
	v_mfma_f32_16x16x32_bf16 v[44:47], v[158:161], v[174:177], v[44:47]
	v_mfma_f32_16x16x32_bf16 v[36:39], v[136:139], v[182:185], v[36:39]
	v_mfma_f32_16x16x32_bf16 v[28:31], v[158:161], v[182:185], v[28:31]
	v_mfma_f32_16x16x32_bf16 v[20:23], v[136:139], v[200:203], v[20:23]
	v_mfma_f32_16x16x32_bf16 v[12:15], v[158:161], v[200:203], v[12:15]
	v_mfma_f32_16x16x32_bf16 v[60:63], v[140:143], v[170:173], v[60:63]
	v_mfma_f32_16x16x32_bf16 v[56:59], v[162:165], v[170:173], v[56:59]
	v_mfma_f32_16x16x32_bf16 v[52:55], v[140:143], v[178:181], v[52:55]
	v_mfma_f32_16x16x32_bf16 v[44:47], v[162:165], v[178:181], v[44:47]
	v_mfma_f32_16x16x32_bf16 v[36:39], v[140:143], v[196:199], v[36:39]
	v_mfma_f32_16x16x32_bf16 v[28:31], v[162:165], v[196:199], v[28:31]
	v_mfma_f32_16x16x32_bf16 v[20:23], v[140:143], v[204:207], v[20:23]
	v_mfma_f32_16x16x32_bf16 v[12:15], v[162:165], v[204:207], v[12:15]
	s_barrier
	s_add_u32 s26, s34, 0x40080
	s_addc_u32 s27, s35, 0
	s_add_i32 s28, s29, s71
	s_mov_b32 m0, s28
	v_lshl_add_u64 v[136:137], s[26:27], 0, v[128:129]
	global_load_lds_dwordx4 v[136:137], off
	s_add_i32 m0, s28, 0x2000
	v_lshl_add_u64 v[136:137], s[26:27], 0, v[130:131]
	global_load_lds_dwordx4 v[136:137], off
	s_waitcnt vmcnt(6)
	s_barrier
	v_mfma_f32_16x16x32_bf16 v[48:51], v[216:219], v[166:169], v[48:51]
	v_mfma_f32_16x16x32_bf16 v[40:43], v[224:227], v[166:169], v[40:43]
	v_mfma_f32_16x16x32_bf16 v[32:35], v[216:219], v[174:177], v[32:35]
	v_mfma_f32_16x16x32_bf16 v[24:27], v[224:227], v[174:177], v[24:27]
	v_mfma_f32_16x16x32_bf16 v[16:19], v[216:219], v[182:185], v[16:19]
	v_mfma_f32_16x16x32_bf16 v[8:11], v[224:227], v[182:185], v[8:11]
	v_mfma_f32_16x16x32_bf16 v[4:7], v[216:219], v[200:203], v[4:7]
	v_mfma_f32_16x16x32_bf16 v[0:3], v[224:227], v[200:203], v[0:3]
	v_mfma_f32_16x16x32_bf16 v[48:51], v[220:223], v[170:173], v[48:51]
	v_mfma_f32_16x16x32_bf16 v[40:43], v[228:231], v[170:173], v[40:43]
	v_mfma_f32_16x16x32_bf16 v[32:35], v[220:223], v[178:181], v[32:35]
	v_mfma_f32_16x16x32_bf16 v[24:27], v[228:231], v[178:181], v[24:27]
	v_mfma_f32_16x16x32_bf16 v[16:19], v[220:223], v[196:199], v[16:19]
	v_mfma_f32_16x16x32_bf16 v[8:11], v[228:231], v[196:199], v[8:11]
	v_mfma_f32_16x16x32_bf16 v[4:7], v[220:223], v[204:207], v[4:7]
	v_mfma_f32_16x16x32_bf16 v[0:3], v[228:231], v[204:207], v[0:3]
	s_add_i32 s84, s84, 2
	s_add_u32 s4, s4, 0x100
	s_addc_u32 s5, s5, 0
	s_add_u32 s24, s24, 0x100
	s_addc_u32 s25, s25, 0
	s_cmp_gt_u32 s84, 13
	s_barrier
	s_cbranch_scc0 .LBB0_499
	s_lshl_b32 s15, s3, 8
	s_cmp_lt_i32 s3, 11
	s_mov_b64 s[4:5], -1
	s_cbranch_scc1 .LBB0_502
	s_mul_hi_i32 s3, s80, 0x3e0f83e1
	s_lshr_b32 s4, s3, 31
	s_ashr_i32 s3, s3, 3
	s_add_i32 s4, s3, s4
	v_cvt_pk_bf16_f32 v136, v124, v125
	s_mul_i32 s3, s4, 0xffffffdf
	v_cvt_pk_bf16_f32 v137, v126, v127
	ds_write_b16 v151, v136
	ds_write_b16_d16_hi v151, v136 offset:144
	ds_write_b16 v151, v137 offset:288
	ds_write_b16_d16_hi v151, v137 offset:432
	v_cvt_pk_bf16_f32 v136, v116, v117
	s_add_i32 s3, s3, s80
	v_cvt_pk_bf16_f32 v137, v118, v119
	ds_write_b16 v151, v136 offset:32
	ds_write_b16_d16_hi v151, v136 offset:176
	ds_write_b16 v151, v137 offset:320
	ds_write_b16_d16_hi v151, v137 offset:464
	v_cvt_pk_bf16_f32 v136, v100, v101
	s_lshl_b32 s24, s3, 8
	s_or_b32 s3, s15, s81
	v_cvt_pk_bf16_f32 v137, v102, v103
	ds_write_b16 v151, v136 offset:64
	ds_write_b16_d16_hi v151, v136 offset:208
	ds_write_b16 v151, v137 offset:352
	ds_write_b16_d16_hi v151, v137 offset:496
	v_cvt_pk_bf16_f32 v136, v84, v85
	s_ashr_i32 s5, s4, 31
	v_cvt_pk_bf16_f32 v137, v86, v87
	ds_write_b16 v151, v136 offset:96
	ds_write_b16_d16_hi v151, v136 offset:240
	ds_write_b16 v151, v137 offset:384
	ds_write_b16_d16_hi v151, v137 offset:528
	v_add_u32_e32 v136, s3, v152
	s_lshl_b64 s[4:5], s[4:5], 10
	v_ashrrev_i32_e32 v137, 31, v136
	v_lshl_add_u64 v[136:137], s[4:5], 0, v[136:137]
	v_mov_b64_e32 v[162:163], s[10:11]
	s_ashr_i32 s25, s24, 31
	ds_read_b128 v[138:141], v155
	v_mad_u64_u32 v[142:143], s[26:27], v136, s91, v[162:163]
	v_mad_i32_i24 v143, v137, s91, v143
	s_lshl_b64 s[34:35], s[24:25], 1
	v_lshl_add_u64 v[136:137], v[142:143], 0, s[34:35]
	v_lshl_add_u64 v[136:137], v[136:137], 0, s[12:13]
	v_lshl_add_u64 v[136:137], v[136:137], 0, v[144:145]
	s_waitcnt lgkmcnt(0)
	global_store_dwordx4 v[136:137], v[138:141], off
	ds_read_b128 v[140:143], v156
	s_or_b32 s17, s3, 4
	v_add_u32_e32 v138, s3, v153
	v_ashrrev_i32_e32 v139, 31, v138
	v_lshl_add_u64 v[138:139], s[4:5], 0, v[138:139]
	v_mad_u64_u32 v[146:147], s[24:25], v138, s91, v[162:163]
	v_mad_i32_i24 v147, v139, s91, v147
	v_lshl_add_u64 v[138:139], v[146:147], 0, s[34:35]
	v_lshl_add_u64 v[138:139], v[138:139], 0, s[12:13]
	v_lshl_add_u64 v[138:139], v[138:139], 0, v[144:145]
	s_waitcnt lgkmcnt(0)
; #define LAS __attribute__((address_space(3)))
; __device__ __forceinline__ unsigned pk2(float lo, float hi) { unsigned r; asm("v_cvt_pk_bf16_f32 %0, %1, %2" : "=v"(r) : "v"(lo), "v"(hi)); return r; }
;     __device__ __forceinline__ void operator()(const f32x4 (&acc)[2][2][4][2], const Unit& u, int wr, int wc, int fr, int fq) const {
;     ...
;             LAS bf16_t* sc = (LAS bf16_t*)(trs + (wr * 4 + wc) * 2304);
;             const int lane = fq * 16 + fr;
; #pragma unroll
;             for (int ai = 0; ai < 2; ++ai)
; #pragma unroll
;                 for (int bj = 0; bj < 2; ++bj)
; #pragma unroll
;                     for (int n = 0; n < 2; ++n) {
; #pragma unroll
;                         for (int m = 0; m < 4; ++m) {
;                             const f32x4 v = acc[ai][bj][m][n];
;                             const unsigned p0 = pk2(v[0], v[1]), p1 = pk2(v[2], v[3]);
;                             LAS bf16_t* w = sc + (4 * fq) * 72 + 16 * m + fr;
;                             w[0] = (bf16_t)(p0 & 0xffffu); w[72] = (bf16_t)(p0 >> 16); w[144] = (bf16_t)(p1 & 0xffffu); w[216] = (bf16_t)(p1 >> 16);
;                         }
; #pragma unroll
;                         for (int j = 0; j < 2; ++j) {
;                             const int ch = lane + 64 * j, fi = ch >> 3, seg = ch & 7;
;                             const u32x4 o = *(const LAS u32x4*)(sc + fi * 72 + 8 * seg);
;                             const int f = col_t - vt0 + 64 * wc + 16 * (fi >> 2) + 8 * bj + 4 * n + (fi & 3);
;                             *(u32x4*)(Vt + ((size_t)bl * vtnf + f) * KEYS + key0 + ai * HALF + wr * 64 + 8 * seg) = o;
;                         }
;                     }
	global_store_dwordx4 v[138:139], v[140:143], off
	v_cvt_pk_bf16_f32 v157, v104, v105
	s_nop 1
	v_cvt_pk_bf16_f32 v140, v120, v121
	v_cvt_pk_bf16_f32 v141, v122, v123
	ds_write_b16 v151, v140
	ds_write_b16_d16_hi v151, v140 offset:144
	ds_write_b16 v151, v141 offset:288
	ds_write_b16_d16_hi v151, v141 offset:432
	v_cvt_pk_bf16_f32 v140, v108, v109
	v_cvt_pk_bf16_f32 v141, v110, v111
	ds_write_b16 v151, v140 offset:32
	ds_write_b16_d16_hi v151, v140 offset:176
	ds_write_b16 v151, v141 offset:320
	ds_write_b16_d16_hi v151, v141 offset:464
	v_cvt_pk_bf16_f32 v140, v92, v93
	v_cvt_pk_bf16_f32 v141, v94, v95
	ds_write_b16 v151, v140 offset:64
	ds_write_b16_d16_hi v151, v140 offset:208
	ds_write_b16 v151, v141 offset:352
	ds_write_b16_d16_hi v151, v141 offset:496
	v_cvt_pk_bf16_f32 v140, v76, v77
	v_cvt_pk_bf16_f32 v141, v78, v79
	ds_write_b16 v151, v140 offset:96
	ds_write_b16_d16_hi v151, v140 offset:240
	ds_write_b16 v151, v141 offset:384
	ds_write_b16_d16_hi v151, v141 offset:528
	v_add_u32_e32 v140, s17, v152
	v_ashrrev_i32_e32 v141, 31, v140
	v_lshl_add_u64 v[140:141], s[4:5], 0, v[140:141]
	ds_read_b128 v[158:161], v155
	v_mad_u64_u32 v[142:143], s[24:25], v140, s91, v[162:163]
	v_mad_i32_i24 v143, v141, s91, v143
	v_lshl_add_u64 v[140:141], v[142:143], 0, s[34:35]
	v_add_u32_e32 v142, s17, v153
	v_lshl_add_u64 v[140:141], v[140:141], 0, s[12:13]
	v_ashrrev_i32_e32 v143, 31, v142
	v_lshl_add_u64 v[140:141], v[140:141], 0, v[144:145]
	v_lshl_add_u64 v[142:143], s[4:5], 0, v[142:143]
	s_waitcnt lgkmcnt(0)
	global_store_dwordx4 v[140:141], v[158:161], off
	ds_read_b128 v[158:161], v156
	v_mad_u64_u32 v[146:147], s[24:25], v142, s91, v[162:163]
	v_mad_i32_i24 v147, v143, s91, v147
	v_lshl_add_u64 v[142:143], v[146:147], 0, s[34:35]
	v_lshl_add_u64 v[142:143], v[142:143], 0, s[12:13]
	v_lshl_add_u64 v[142:143], v[142:143], 0, v[144:145]
	v_cvt_pk_bf16_f32 v146, v112, v113
	s_waitcnt lgkmcnt(0)
	global_store_dwordx4 v[142:143], v[158:161], off
	v_cvt_pk_bf16_f32 v147, v114, v115
	ds_write_b16 v151, v146
	ds_write_b16_d16_hi v151, v146 offset:144
	ds_write_b16 v151, v147 offset:288
	ds_write_b16_d16_hi v151, v147 offset:432
	v_cvt_pk_bf16_f32 v146, v96, v97
	v_cvt_pk_bf16_f32 v147, v98, v99
	ds_write_b16 v151, v146 offset:32
	ds_write_b16_d16_hi v151, v146 offset:176
	ds_write_b16 v151, v147 offset:320
	ds_write_b16_d16_hi v151, v147 offset:464
	v_cvt_pk_bf16_f32 v146, v80, v81
	s_or_b32 s17, s3, 8
	v_cvt_pk_bf16_f32 v147, v82, v83
	ds_write_b16 v151, v146 offset:64
	ds_write_b16_d16_hi v151, v146 offset:208
	ds_write_b16 v151, v147 offset:352
	ds_write_b16_d16_hi v151, v147 offset:496
	v_cvt_pk_bf16_f32 v146, v68, v69
	v_cvt_pk_bf16_f32 v147, v70, v71
	ds_write_b16 v151, v146 offset:96
	ds_write_b16_d16_hi v151, v146 offset:240
	ds_write_b16 v151, v147 offset:384
	ds_write_b16_d16_hi v151, v147 offset:528
	v_add_u32_e32 v146, s17, v152
	v_ashrrev_i32_e32 v147, 31, v146
	v_lshl_add_u64 v[146:147], s[4:5], 0, v[146:147]
	ds_read_b128 v[158:161], v155
	v_mad_u64_u32 v[164:165], s[24:25], v146, s91, v[162:163]
	v_mad_i32_i24 v165, v147, s91, v165
	v_lshl_add_u64 v[146:147], v[164:165], 0, s[34:35]
	v_add_u32_e32 v164, s17, v153
	v_lshl_add_u64 v[146:147], v[146:147], 0, s[12:13]
	v_ashrrev_i32_e32 v165, 31, v164
	v_lshl_add_u64 v[146:147], v[146:147], 0, v[144:145]
	v_lshl_add_u64 v[164:165], s[4:5], 0, v[164:165]
	s_waitcnt lgkmcnt(0)
	global_store_dwordx4 v[146:147], v[158:161], off
	ds_read_b128 v[158:161], v156
	v_mad_u64_u32 v[166:167], s[24:25], v164, s91, v[162:163]
	v_mad_i32_i24 v167, v165, s91, v167
	v_lshl_add_u64 v[164:165], v[166:167], 0, s[34:35]
	v_lshl_add_u64 v[164:165], v[164:165], 0, s[12:13]
	v_lshl_add_u64 v[164:165], v[164:165], 0, v[144:145]
	s_waitcnt lgkmcnt(0)
	global_store_dwordx4 v[164:165], v[158:161], off
	s_or_b32 s3, s3, 12
	v_add_u32_e32 v166, s3, v152
	v_cvt_pk_bf16_f32 v158, v106, v107
	ds_write_b16 v151, v157
	ds_write_b16_d16_hi v151, v157 offset:144
	ds_write_b16 v151, v158 offset:288
	ds_write_b16_d16_hi v151, v158 offset:432
	v_cvt_pk_bf16_f32 v157, v88, v89
	v_cvt_pk_bf16_f32 v158, v90, v91
	ds_write_b16 v151, v157 offset:32
	ds_write_b16_d16_hi v151, v157 offset:176
	ds_write_b16 v151, v158 offset:320
	ds_write_b16_d16_hi v151, v158 offset:464
	v_cvt_pk_bf16_f32 v157, v72, v73
	v_cvt_pk_bf16_f32 v158, v74, v75
	ds_write_b16 v151, v157 offset:64
	ds_write_b16_d16_hi v151, v157 offset:208
	ds_write_b16 v151, v158 offset:352
	ds_write_b16_d16_hi v151, v158 offset:496
	v_cvt_pk_bf16_f32 v157, v64, v65
	v_ashrrev_i32_e32 v167, 31, v166
	v_cvt_pk_bf16_f32 v158, v66, v67
	ds_write_b16 v151, v157 offset:96
	ds_write_b16_d16_hi v151, v157 offset:240
	ds_write_b16 v151, v158 offset:384
	ds_write_b16_d16_hi v151, v158 offset:528
	v_lshl_add_u64 v[166:167], s[4:5], 0, v[166:167]
	ds_read_b128 v[158:161], v155
	v_mad_u64_u32 v[168:169], s[24:25], v166, s91, v[162:163]
	v_mad_i32_i24 v169, v167, s91, v169
	v_lshl_add_u64 v[166:167], v[168:169], 0, s[34:35]
	v_add_u32_e32 v168, s3, v153
	v_lshl_add_u64 v[166:167], v[166:167], 0, s[12:13]
	v_ashrrev_i32_e32 v169, 31, v168
	v_lshl_add_u64 v[166:167], v[166:167], 0, v[144:145]
	v_lshl_add_u64 v[168:169], s[4:5], 0, v[168:169]
	s_waitcnt lgkmcnt(0)
; #define LAS __attribute__((address_space(3)))
; __device__ __forceinline__ unsigned pk2(float lo, float hi) { unsigned r; asm("v_cvt_pk_bf16_f32 %0, %1, %2" : "=v"(r) : "v"(lo), "v"(hi)); return r; }
;     __device__ __forceinline__ void operator()(const f32x4 (&acc)[2][2][4][2], const Unit& u, int wr, int wc, int fr, int fq) const {
;     ...
;             LAS bf16_t* sc = (LAS bf16_t*)(trs + (wr * 4 + wc) * 2304);
;             const int lane = fq * 16 + fr;
; #pragma unroll
;             for (int ai = 0; ai < 2; ++ai)
; #pragma unroll
;                 for (int bj = 0; bj < 2; ++bj)
; #pragma unroll
;                     for (int n = 0; n < 2; ++n) {
; #pragma unroll
;                         for (int m = 0; m < 4; ++m) {
;                             const f32x4 v = acc[ai][bj][m][n];
;                             const unsigned p0 = pk2(v[0], v[1]), p1 = pk2(v[2], v[3]);
;                             LAS bf16_t* w = sc + (4 * fq) * 72 + 16 * m + fr;
;                             w[0] = (bf16_t)(p0 & 0xffffu); w[72] = (bf16_t)(p0 >> 16); w[144] = (bf16_t)(p1 & 0xffffu); w[216] = (bf16_t)(p1 >> 16);
;                         }
; #pragma unroll
;                         for (int j = 0; j < 2; ++j) {
;                             const int ch = lane + 64 * j, fi = ch >> 3, seg = ch & 7;
;                             const u32x4 o = *(const LAS u32x4*)(sc + fi * 72 + 8 * seg);
;                             const int f = col_t - vt0 + 64 * wc + 16 * (fi >> 2) + 8 * bj + 4 * n + (fi & 3);
;                             *(u32x4*)(Vt + ((size_t)bl * vtnf + f) * KEYS + key0 + ai * HALF + wr * 64 + 8 * seg) = o;
;                         }
;                     }
	global_store_dwordx4 v[166:167], v[158:161], off
	ds_read_b128 v[158:161], v156
	v_mad_u64_u32 v[162:163], s[4:5], v168, s91, v[162:163]
	v_mad_i32_i24 v163, v169, s91, v163
	v_lshl_add_u64 v[162:163], v[162:163], 0, s[34:35]
	v_lshl_add_u64 v[162:163], v[162:163], 0, s[12:13]
	v_lshl_add_u64 v[162:163], v[162:163], 0, v[144:145]
	v_cvt_pk_bf16_f32 v157, v60, v61
	s_waitcnt lgkmcnt(0)
	global_store_dwordx4 v[162:163], v[158:161], off
	s_mov_b64 s[4:5], 0
	s_nop 0
	v_cvt_pk_bf16_f32 v158, v62, v63
	ds_write_b16 v151, v157
	ds_write_b16_d16_hi v151, v157 offset:144
	ds_write_b16 v151, v158 offset:288
	ds_write_b16_d16_hi v151, v158 offset:432
	v_cvt_pk_bf16_f32 v157, v52, v53
	v_cvt_pk_bf16_f32 v158, v54, v55
	ds_write_b16 v151, v157 offset:32
	ds_write_b16_d16_hi v151, v157 offset:176
	ds_write_b16 v151, v158 offset:320
	ds_write_b16_d16_hi v151, v158 offset:464
	v_cvt_pk_bf16_f32 v157, v36, v37
	v_cvt_pk_bf16_f32 v158, v38, v39
	ds_write_b16 v151, v157 offset:64
	ds_write_b16_d16_hi v151, v157 offset:208
	ds_write_b16 v151, v158 offset:352
	ds_write_b16_d16_hi v151, v158 offset:496
	v_cvt_pk_bf16_f32 v157, v20, v21
	v_cvt_pk_bf16_f32 v158, v22, v23
	ds_write_b16 v151, v157 offset:96
	ds_write_b16_d16_hi v151, v157 offset:240
	ds_write_b16 v151, v158 offset:384
	ds_write_b16_d16_hi v151, v158 offset:528
	ds_read_b128 v[158:161], v155
	s_waitcnt lgkmcnt(0)
	global_store_dwordx4 v[136:137], v[158:161], off offset:256
	ds_read_b128 v[158:161], v156
	v_cvt_pk_bf16_f32 v136, v56, v57
	v_cvt_pk_bf16_f32 v137, v58, v59
	s_waitcnt lgkmcnt(0)
	global_store_dwordx4 v[138:139], v[158:161], off offset:256
	ds_write_b16 v151, v136
	ds_write_b16_d16_hi v151, v136 offset:144
	ds_write_b16 v151, v137 offset:288
	ds_write_b16_d16_hi v151, v137 offset:432
	v_cvt_pk_bf16_f32 v136, v44, v45
	v_cvt_pk_bf16_f32 v137, v46, v47
	ds_write_b16 v151, v136 offset:32
	ds_write_b16_d16_hi v151, v136 offset:176
	ds_write_b16 v151, v137 offset:320
	ds_write_b16_d16_hi v151, v137 offset:464
	v_cvt_pk_bf16_f32 v136, v28, v29
	v_cvt_pk_bf16_f32 v137, v30, v31
	ds_write_b16 v151, v136 offset:64
	ds_write_b16_d16_hi v151, v136 offset:208
	ds_write_b16 v151, v137 offset:352
	ds_write_b16_d16_hi v151, v137 offset:496
	v_cvt_pk_bf16_f32 v136, v12, v13
	v_cvt_pk_bf16_f32 v137, v14, v15
	ds_write_b16 v151, v136 offset:96
	ds_write_b16_d16_hi v151, v136 offset:240
	ds_write_b16 v151, v137 offset:384
	ds_write_b16_d16_hi v151, v137 offset:528
	ds_read_b128 v[136:139], v155
	s_waitcnt lgkmcnt(0)
	global_store_dwordx4 v[140:141], v[136:139], off offset:256
	ds_read_b128 v[136:139], v156
	s_waitcnt lgkmcnt(0)
	global_store_dwordx4 v[142:143], v[136:139], off offset:256
	s_nop 1
	v_cvt_pk_bf16_f32 v136, v48, v49
	v_cvt_pk_bf16_f32 v137, v50, v51
	ds_write_b16 v151, v136
	ds_write_b16_d16_hi v151, v136 offset:144
	ds_write_b16 v151, v137 offset:288
	ds_write_b16_d16_hi v151, v137 offset:432
	v_cvt_pk_bf16_f32 v136, v32, v33
	v_cvt_pk_bf16_f32 v137, v34, v35
	ds_write_b16 v151, v136 offset:32
	ds_write_b16_d16_hi v151, v136 offset:176
	ds_write_b16 v151, v137 offset:320
	ds_write_b16_d16_hi v151, v137 offset:464
	v_cvt_pk_bf16_f32 v136, v16, v17
	v_cvt_pk_bf16_f32 v137, v18, v19
	ds_write_b16 v151, v136 offset:64
	ds_write_b16_d16_hi v151, v136 offset:208
	ds_write_b16 v151, v137 offset:352
	ds_write_b16_d16_hi v151, v137 offset:496
	v_cvt_pk_bf16_f32 v136, v4, v5
	v_cvt_pk_bf16_f32 v137, v6, v7
	ds_write_b16 v151, v136 offset:96
	ds_write_b16_d16_hi v151, v136 offset:240
	ds_write_b16 v151, v137 offset:384
	ds_write_b16_d16_hi v151, v137 offset:528
	ds_read_b128 v[136:139], v155
	s_waitcnt lgkmcnt(0)
	global_store_dwordx4 v[146:147], v[136:139], off offset:256
	ds_read_b128 v[136:139], v156
	s_waitcnt lgkmcnt(0)
	global_store_dwordx4 v[164:165], v[136:139], off offset:256
	s_nop 1
	v_cvt_pk_bf16_f32 v136, v40, v41
	v_cvt_pk_bf16_f32 v137, v42, v43
	ds_write_b16 v151, v136
	ds_write_b16_d16_hi v151, v136 offset:144
	ds_write_b16 v151, v137 offset:288
	ds_write_b16_d16_hi v151, v137 offset:432
	v_cvt_pk_bf16_f32 v136, v24, v25
	v_cvt_pk_bf16_f32 v137, v26, v27
	ds_write_b16 v151, v136 offset:32
	ds_write_b16_d16_hi v151, v136 offset:176
	ds_write_b16 v151, v137 offset:320
	ds_write_b16_d16_hi v151, v137 offset:464
	v_cvt_pk_bf16_f32 v136, v8, v9
	v_cvt_pk_bf16_f32 v137, v10, v11
	ds_write_b16 v151, v136 offset:64
	ds_write_b16_d16_hi v151, v136 offset:208
	ds_write_b16 v151, v137 offset:352
	ds_write_b16_d16_hi v151, v137 offset:496
	v_cvt_pk_bf16_f32 v136, v0, v1
	v_cvt_pk_bf16_f32 v137, v2, v3
	ds_write_b16 v151, v136 offset:96
	ds_write_b16_d16_hi v151, v136 offset:240
	ds_write_b16 v151, v137 offset:384
	ds_write_b16_d16_hi v151, v137 offset:528
	ds_read_b128 v[136:139], v155
	s_waitcnt lgkmcnt(0)
	global_store_dwordx4 v[166:167], v[136:139], off offset:256
	ds_read_b128 v[136:139], v156
	s_waitcnt lgkmcnt(0)
	global_store_dwordx4 v[162:163], v[136:139], off offset:256

; #define PG8_STAGE(bufoff, gbase, voff) do { _Pragma("unroll") for (int _i = 0; _i < 2; ++_i) \
;         __builtin_amdgcn_global_load_lds((const unsigned*)((const char*)(gbase) + (voff)[_i]), (LAS unsigned*)(lds + (bufoff) + ldsw + _i * 8192), 16, 0, 0); } while (0)
; #define PG8_LDA(dst, b, h) do { _Pragma("unroll") for (int m = 0; m < 4; ++m) _Pragma("unroll") for (int k = 0; k < 2; ++k) dst[m][k] = *(const LAS bf16x8*)(lds + PG8_SA(b, h) + aoff + m * 2048 + k * 1024); } while (0)
; #define PG8_LDB(dst, b, h) do { _Pragma("unroll") for (int n = 0; n < 2; ++n) _Pragma("unroll") for (int k = 0; k < 2; ++k) dst[n][k] = *(const LAS bf16x8*)(lds + PG8_SB(b, h) + boff + n * 2048 + k * 1024); } while (0)
; #define PG8_MMA(ai, bj, At, Bt) do { __builtin_amdgcn_s_setprio(1); _Pragma("unroll") for (int m = 0; m < 4; ++m) _Pragma("unroll") for (int n = 0; n < 2; ++n) _Pragma("unroll") for (int k = 0; k < 2; ++k) \
;         acc[ai][bj][m][n] = __builtin_amdgcn_mfma_f32_16x16x32_bf16(Bt[n][k], At[m][k], acc[ai][bj][m][n], 0, 0, 0); __builtin_amdgcn_s_setprio(0); } while (0)
; #define PG8_WAIT_L(n) asm volatile("s_waitcnt lgkmcnt(" #n ")" ::: "memory")
; #define PG8_BAR __builtin_amdgcn_s_barrier()
; #define PG8_SCHED __builtin_amdgcn_sched_barrier(0)
; template <class Epi>
; __device__ __forceinline__ void gemm_phase(LAS unsigned char* lds, const Gemm g, const StaticOrder& S, const Epi& E) {
;     ...
;         for (int t = 0; t < nt; t += 2) {
;             const bool last = (t == nt - 2);
;             const char* a1 = cA + (size_t)(t + 1) * kstep;
;             const char* a2 = last ? nA : cA + (size_t)(t + 2) * kstep; const char* b2 = last ? nB : cB + (size_t)(t + 2) * kstep;
;             const char* a3 = a2 + kstep; const char* b3 = b2 + kstep;
;             PG8_LDB(B0, 0, 0); PG8_SCHED; PG8_LDA(At, 0, 0); PG8_STAGE(PG8_SA(1, 1), a1 + hA, voffA);
;             PG8_WAIT_L(8); PG8_BAR; PG8_WAIT_L(0); PG8_MMA(0, 0, At, B0); PG8_BAR; PG8_SCHED;
;             PG8_LDB(B1, 0, 1); PG8_STAGE(PG8_SB(0, 0), b2, voffB);
;             PG8_BAR; PG8_WAIT_L(0); PG8_MMA(0, 1, At, B1); PG8_BAR;
;             PG8_LDA(At, 0, 1); PG8_STAGE(PG8_SA(0, 0), a2, voffA);
;             PG8_BAR; PG8_WAIT_L(0); PG8_MMA(1, 0, At, B0); PG8_BAR; PG8_SCHED;
.LBB0_655:
	s_add_u32 s12, s10, 0x100
	s_addc_u32 s13, s11, 0
	s_add_i32 s26, 0, 0x10000
	v_add_u32_e32 v156, s26, v143
	ds_read_b128 v[138:141], v156
	ds_read_b128 v[148:151], v156 offset:1024
	ds_read_b128 v[152:155], v156 offset:2048
	ds_read_b128 v[156:159], v156 offset:3072
	s_cmp_eq_u32 s78, 2
	s_cselect_b32 s21, s5, s13
	s_cselect_b32 s20, s4, s12
	s_cselect_b32 s17, s7, s25
	s_cselect_b32 s16, s6, s24
	v_lshl_add_u64 v[184:185], s[10:11], 0, v[134:135]
	s_add_i32 m0, s64, 0xc000
	ds_read_b128 v[160:163], v147
	ds_read_b128 v[164:167], v147 offset:1024
	ds_read_b128 v[168:171], v147 offset:2048
	ds_read_b128 v[172:175], v147 offset:3072
	ds_read_b128 v[176:179], v147 offset:4096
	ds_read_b128 v[180:183], v147 offset:5120
	ds_read_b128 v[196:199], v147 offset:6144
	ds_read_b128 v[200:203], v147 offset:7168
	global_load_lds_dwordx4 v[184:185], off
	s_add_i32 m0, s64, 0xe000
	v_lshl_add_u64 v[184:185], s[10:11], 0, v[136:137]
	global_load_lds_dwordx4 v[184:185], off
	s_waitcnt lgkmcnt(8)
	s_barrier
	s_waitcnt lgkmcnt(0)
	v_mfma_f32_16x16x32_bf16 v[124:127], v[138:141], v[160:163], v[124:127]
	v_mfma_f32_16x16x32_bf16 v[120:123], v[152:155], v[160:163], v[120:123]
	v_mfma_f32_16x16x32_bf16 v[116:119], v[138:141], v[168:171], v[116:119]
	v_mfma_f32_16x16x32_bf16 v[108:111], v[152:155], v[168:171], v[108:111]
	v_mfma_f32_16x16x32_bf16 v[100:103], v[138:141], v[176:179], v[100:103]
	v_mfma_f32_16x16x32_bf16 v[92:95], v[152:155], v[176:179], v[92:95]
	v_mfma_f32_16x16x32_bf16 v[84:87], v[138:141], v[196:199], v[84:87]
	v_mfma_f32_16x16x32_bf16 v[76:79], v[152:155], v[196:199], v[76:79]
	v_mfma_f32_16x16x32_bf16 v[124:127], v[148:151], v[164:167], v[124:127]
	v_mfma_f32_16x16x32_bf16 v[120:123], v[156:159], v[164:167], v[120:123]
	v_mfma_f32_16x16x32_bf16 v[116:119], v[148:151], v[172:175], v[116:119]
	v_mfma_f32_16x16x32_bf16 v[108:111], v[156:159], v[172:175], v[108:111]
	v_mfma_f32_16x16x32_bf16 v[100:103], v[148:151], v[180:183], v[100:103]
	v_mfma_f32_16x16x32_bf16 v[92:95], v[156:159], v[180:183], v[92:95]
	v_mfma_f32_16x16x32_bf16 v[84:87], v[148:151], v[200:203], v[84:87]
	v_mfma_f32_16x16x32_bf16 v[76:79], v[156:159], v[200:203], v[76:79]
	s_barrier
	s_add_i32 s27, 0, 0x14000
	v_add_u32_e32 v184, s27, v143
	s_add_i32 s10, s26, s63
	ds_read_b128 v[204:207], v184
	ds_read_b128 v[216:219], v184 offset:1024
	ds_read_b128 v[220:223], v184 offset:2048
	ds_read_b128 v[224:227], v184 offset:3072
	v_lshl_add_u64 v[184:185], s[16:17], 0, v[144:145]
	s_mov_b32 m0, s10
	v_lshl_add_u64 v[186:187], s[16:17], 0, v[132:133]
	global_load_lds_dwordx4 v[184:185], off
	s_add_i32 m0, s10, 0x2000
	s_nop 0
	global_load_lds_dwordx4 v[186:187], off
	s_barrier
	s_waitcnt lgkmcnt(0)
	v_mfma_f32_16x16x32_bf16 v[112:115], v[204:207], v[160:163], v[112:115]
	v_mfma_f32_16x16x32_bf16 v[104:107], v[220:223], v[160:163], v[104:107]
	v_mfma_f32_16x16x32_bf16 v[96:99], v[204:207], v[168:171], v[96:99]
	v_mfma_f32_16x16x32_bf16 v[88:91], v[220:223], v[168:171], v[88:91]
	v_mfma_f32_16x16x32_bf16 v[80:83], v[204:207], v[176:179], v[80:83]
	v_mfma_f32_16x16x32_bf16 v[72:75], v[220:223], v[176:179], v[72:75]
	v_mfma_f32_16x16x32_bf16 v[68:71], v[204:207], v[196:199], v[68:71]
	v_mfma_f32_16x16x32_bf16 v[64:67], v[220:223], v[196:199], v[64:67]
	v_mfma_f32_16x16x32_bf16 v[112:115], v[216:219], v[164:167], v[112:115]
	v_mfma_f32_16x16x32_bf16 v[104:107], v[224:227], v[164:167], v[104:107]
	v_mfma_f32_16x16x32_bf16 v[96:99], v[216:219], v[172:175], v[96:99]
	v_mfma_f32_16x16x32_bf16 v[88:91], v[224:227], v[172:175], v[88:91]
	v_mfma_f32_16x16x32_bf16 v[80:83], v[216:219], v[180:183], v[80:83]
	v_mfma_f32_16x16x32_bf16 v[72:75], v[224:227], v[180:183], v[72:75]
	v_mfma_f32_16x16x32_bf16 v[68:71], v[216:219], v[200:203], v[68:71]
	v_mfma_f32_16x16x32_bf16 v[64:67], v[224:227], v[200:203], v[64:67]
	s_mov_b32 m0, s64
	v_lshl_add_u64 v[188:189], s[20:21], 0, v[128:129]
	s_barrier
	ds_read_b128 v[160:163], v147 offset:16384
	ds_read_b128 v[164:167], v147 offset:17408
	ds_read_b128 v[168:171], v147 offset:18432
	ds_read_b128 v[172:175], v147 offset:19456
	ds_read_b128 v[176:179], v147 offset:20480
	ds_read_b128 v[180:183], v147 offset:21504
	ds_read_b128 v[196:199], v147 offset:22528
	ds_read_b128 v[200:203], v147 offset:23552
	global_load_lds_dwordx4 v[188:189], off
	s_mov_b32 m0, s65
	v_lshl_add_u64 v[192:193], s[20:21], 0, v[130:131]
	global_load_lds_dwordx4 v[192:193], off
	s_barrier
	s_waitcnt lgkmcnt(0)
	v_mfma_f32_16x16x32_bf16 v[60:63], v[138:141], v[160:163], v[60:63]
	v_mfma_f32_16x16x32_bf16 v[56:59], v[152:155], v[160:163], v[56:59]
	v_mfma_f32_16x16x32_bf16 v[52:55], v[138:141], v[168:171], v[52:55]
	v_mfma_f32_16x16x32_bf16 v[44:47], v[152:155], v[168:171], v[44:47]
	v_mfma_f32_16x16x32_bf16 v[36:39], v[138:141], v[176:179], v[36:39]
	v_mfma_f32_16x16x32_bf16 v[28:31], v[152:155], v[176:179], v[28:31]
	v_mfma_f32_16x16x32_bf16 v[20:23], v[138:141], v[196:199], v[20:23]
	v_mfma_f32_16x16x32_bf16 v[12:15], v[152:155], v[196:199], v[12:15]
	v_mfma_f32_16x16x32_bf16 v[60:63], v[148:151], v[164:167], v[60:63]
	v_mfma_f32_16x16x32_bf16 v[56:59], v[156:159], v[164:167], v[56:59]
	v_mfma_f32_16x16x32_bf16 v[52:55], v[148:151], v[172:175], v[52:55]
	v_mfma_f32_16x16x32_bf16 v[44:47], v[156:159], v[172:175], v[44:47]
	v_mfma_f32_16x16x32_bf16 v[36:39], v[148:151], v[180:183], v[36:39]
	v_mfma_f32_16x16x32_bf16 v[28:31], v[156:159], v[180:183], v[28:31]
	v_mfma_f32_16x16x32_bf16 v[20:23], v[148:151], v[200:203], v[20:23]
	v_mfma_f32_16x16x32_bf16 v[12:15], v[156:159], v[200:203], v[12:15]
	s_barrier
; #define PG8_STAGE(bufoff, gbase, voff) do { _Pragma("unroll") for (int _i = 0; _i < 2; ++_i) \
;         __builtin_amdgcn_global_load_lds((const unsigned*)((const char*)(gbase) + (voff)[_i]), (LAS unsigned*)(lds + (bufoff) + ldsw + _i * 8192), 16, 0, 0); } while (0)
; #define PG8_LDA(dst, b, h) do { _Pragma("unroll") for (int m = 0; m < 4; ++m) _Pragma("unroll") for (int k = 0; k < 2; ++k) dst[m][k] = *(const LAS bf16x8*)(lds + PG8_SA(b, h) + aoff + m * 2048 + k * 1024); } while (0)
; #define PG8_LDB(dst, b, h) do { _Pragma("unroll") for (int n = 0; n < 2; ++n) _Pragma("unroll") for (int k = 0; k < 2; ++k) dst[n][k] = *(const LAS bf16x8*)(lds + PG8_SB(b, h) + boff + n * 2048 + k * 1024); } while (0)
; #define PG8_MMA(ai, bj, At, Bt) do { __builtin_amdgcn_s_setprio(1); _Pragma("unroll") for (int m = 0; m < 4; ++m) _Pragma("unroll") for (int n = 0; n < 2; ++n) _Pragma("unroll") for (int k = 0; k < 2; ++k) \
;         acc[ai][bj][m][n] = __builtin_amdgcn_mfma_f32_16x16x32_bf16(Bt[n][k], At[m][k], acc[ai][bj][m][n], 0, 0, 0); __builtin_amdgcn_s_setprio(0); } while (0)
; #define PG8_WAIT_V(n) asm volatile("s_waitcnt vmcnt(" #n ")" ::: "memory")
; #define PG8_WAIT_L(n) asm volatile("s_waitcnt lgkmcnt(" #n ")" ::: "memory")
; #define PG8_BAR __builtin_amdgcn_s_barrier()
; #define PG8_SCHED __builtin_amdgcn_sched_barrier(0)
; template <class Epi>
; __device__ __forceinline__ void gemm_phase(LAS unsigned char* lds, const Gemm g, const StaticOrder& S, const Epi& E) {
;     ...
;             PG8_STAGE(PG8_SB(0, 1), b2 + hB, voffB);
;             PG8_WAIT_V(6); PG8_BAR; PG8_MMA(1, 1, At, B1); PG8_BAR;
;             PG8_LDB(B0, 1, 0); PG8_SCHED; PG8_LDA(At, 1, 0); PG8_STAGE(PG8_SA(0, 1), a2 + hA, voffA);
;             PG8_WAIT_L(8); PG8_BAR; PG8_WAIT_L(0); PG8_MMA(0, 0, At, B0); PG8_BAR; PG8_SCHED;
;             PG8_LDB(B1, 1, 1); PG8_STAGE(PG8_SB(1, 0), b3, voffB);
;             PG8_BAR; PG8_WAIT_L(0); PG8_MMA(0, 1, At, B1); PG8_BAR;
;             PG8_LDA(At, 1, 1); PG8_STAGE(PG8_SA(1, 0), a3, voffA);
;             PG8_BAR; PG8_WAIT_L(0); PG8_MMA(1, 0, At, B0); PG8_BAR; PG8_SCHED;
	s_add_u32 s10, s16, 0x18000
	s_addc_u32 s11, s17, 0
	s_add_i32 s26, s27, s63
	s_mov_b32 m0, s26
	v_lshl_add_u64 v[138:139], s[10:11], 0, v[144:145]
	global_load_lds_dwordx4 v[138:139], off
	s_add_i32 m0, s26, 0x2000
	v_lshl_add_u64 v[138:139], s[10:11], 0, v[132:133]
	global_load_lds_dwordx4 v[138:139], off
	s_waitcnt vmcnt(6)
	s_barrier
	v_mfma_f32_16x16x32_bf16 v[48:51], v[204:207], v[160:163], v[48:51]
	v_mfma_f32_16x16x32_bf16 v[40:43], v[220:223], v[160:163], v[40:43]
	v_mfma_f32_16x16x32_bf16 v[32:35], v[204:207], v[168:171], v[32:35]
	v_mfma_f32_16x16x32_bf16 v[24:27], v[220:223], v[168:171], v[24:27]
	v_mfma_f32_16x16x32_bf16 v[16:19], v[204:207], v[176:179], v[16:19]
	v_mfma_f32_16x16x32_bf16 v[8:11], v[220:223], v[176:179], v[8:11]
	v_mfma_f32_16x16x32_bf16 v[4:7], v[204:207], v[196:199], v[4:7]
	v_mfma_f32_16x16x32_bf16 v[0:3], v[220:223], v[196:199], v[0:3]
	v_mfma_f32_16x16x32_bf16 v[48:51], v[216:219], v[164:167], v[48:51]
	v_mfma_f32_16x16x32_bf16 v[40:43], v[224:227], v[164:167], v[40:43]
	v_mfma_f32_16x16x32_bf16 v[32:35], v[216:219], v[172:175], v[32:35]
	v_mfma_f32_16x16x32_bf16 v[24:27], v[224:227], v[172:175], v[24:27]
	v_mfma_f32_16x16x32_bf16 v[16:19], v[216:219], v[180:183], v[16:19]
	v_mfma_f32_16x16x32_bf16 v[8:11], v[224:227], v[180:183], v[8:11]
	v_mfma_f32_16x16x32_bf16 v[4:7], v[216:219], v[200:203], v[4:7]
	v_mfma_f32_16x16x32_bf16 v[0:3], v[224:227], v[200:203], v[0:3]
	s_add_i32 s26, 0, 0x18000
	v_add_u32_e32 v156, s26, v143
	s_barrier
	ds_read_b128 v[138:141], v156
	ds_read_b128 v[148:151], v156 offset:1024
	ds_read_b128 v[152:155], v156 offset:2048
	ds_read_b128 v[156:159], v156 offset:3072
	s_add_u32 s10, s20, 0xb0000
	s_addc_u32 s11, s21, 0
	s_mov_b32 m0, s66
	v_lshl_add_u64 v[204:205], s[10:11], 0, v[128:129]
	ds_read_b128 v[160:163], v147 offset:32768
	ds_read_b128 v[164:167], v147 offset:33792
	ds_read_b128 v[168:171], v147 offset:34816
	ds_read_b128 v[172:175], v147 offset:35840
	ds_read_b128 v[176:179], v147 offset:36864
	ds_read_b128 v[180:183], v147 offset:37888
	ds_read_b128 v[196:199], v147 offset:38912
	ds_read_b128 v[200:203], v147 offset:39936
	global_load_lds_dwordx4 v[204:205], off
	s_mov_b32 m0, s68
	v_lshl_add_u64 v[204:205], s[10:11], 0, v[130:131]
	global_load_lds_dwordx4 v[204:205], off
	s_waitcnt lgkmcnt(8)
	s_barrier
	s_waitcnt lgkmcnt(0)
	v_mfma_f32_16x16x32_bf16 v[124:127], v[138:141], v[160:163], v[124:127]
	v_mfma_f32_16x16x32_bf16 v[120:123], v[152:155], v[160:163], v[120:123]
	v_mfma_f32_16x16x32_bf16 v[116:119], v[138:141], v[168:171], v[116:119]
	v_mfma_f32_16x16x32_bf16 v[108:111], v[152:155], v[168:171], v[108:111]
	v_mfma_f32_16x16x32_bf16 v[100:103], v[138:141], v[176:179], v[100:103]
	v_mfma_f32_16x16x32_bf16 v[92:95], v[152:155], v[176:179], v[92:95]
	v_mfma_f32_16x16x32_bf16 v[84:87], v[138:141], v[196:199], v[84:87]
	v_mfma_f32_16x16x32_bf16 v[76:79], v[152:155], v[196:199], v[76:79]
	v_mfma_f32_16x16x32_bf16 v[124:127], v[148:151], v[164:167], v[124:127]
	v_mfma_f32_16x16x32_bf16 v[120:123], v[156:159], v[164:167], v[120:123]
	v_mfma_f32_16x16x32_bf16 v[116:119], v[148:151], v[172:175], v[116:119]
	v_mfma_f32_16x16x32_bf16 v[108:111], v[156:159], v[172:175], v[108:111]
	v_mfma_f32_16x16x32_bf16 v[100:103], v[148:151], v[180:183], v[100:103]
	v_mfma_f32_16x16x32_bf16 v[92:95], v[156:159], v[180:183], v[92:95]
	v_mfma_f32_16x16x32_bf16 v[84:87], v[148:151], v[200:203], v[84:87]
	v_mfma_f32_16x16x32_bf16 v[76:79], v[156:159], v[200:203], v[76:79]
	s_barrier
	s_add_i32 s20, 0, 0x1c000
	s_add_i32 s10, s26, s63
	v_add_u32_e32 v190, s20, v143
	v_lshl_add_u64 v[184:185], v[184:185], 0, s[88:89]
	s_mov_b32 m0, s10
	ds_read_b128 v[204:207], v190
	ds_read_b128 v[216:219], v190 offset:1024
	ds_read_b128 v[220:223], v190 offset:2048
	ds_read_b128 v[224:227], v190 offset:3072
	global_load_lds_dwordx4 v[184:185], off
	s_add_i32 m0, s10, 0x2000
	v_lshl_add_u64 v[184:185], v[186:187], 0, s[88:89]
	global_load_lds_dwordx4 v[184:185], off
	s_barrier
	s_waitcnt lgkmcnt(0)
	v_mfma_f32_16x16x32_bf16 v[112:115], v[204:207], v[160:163], v[112:115]
	v_mfma_f32_16x16x32_bf16 v[104:107], v[220:223], v[160:163], v[104:107]
	v_mfma_f32_16x16x32_bf16 v[96:99], v[204:207], v[168:171], v[96:99]
	v_mfma_f32_16x16x32_bf16 v[88:91], v[220:223], v[168:171], v[88:91]
	v_mfma_f32_16x16x32_bf16 v[80:83], v[204:207], v[176:179], v[80:83]
	v_mfma_f32_16x16x32_bf16 v[72:75], v[220:223], v[176:179], v[72:75]
	v_mfma_f32_16x16x32_bf16 v[68:71], v[204:207], v[196:199], v[68:71]
	v_mfma_f32_16x16x32_bf16 v[64:67], v[220:223], v[196:199], v[64:67]
	v_mfma_f32_16x16x32_bf16 v[112:115], v[216:219], v[164:167], v[112:115]
	v_mfma_f32_16x16x32_bf16 v[104:107], v[224:227], v[164:167], v[104:107]
	v_mfma_f32_16x16x32_bf16 v[96:99], v[216:219], v[172:175], v[96:99]
	v_mfma_f32_16x16x32_bf16 v[88:91], v[224:227], v[172:175], v[88:91]
	v_mfma_f32_16x16x32_bf16 v[80:83], v[216:219], v[180:183], v[80:83]
	v_mfma_f32_16x16x32_bf16 v[72:75], v[224:227], v[180:183], v[72:75]
	v_mfma_f32_16x16x32_bf16 v[68:71], v[216:219], v[200:203], v[68:71]
	v_mfma_f32_16x16x32_bf16 v[64:67], v[224:227], v[200:203], v[64:67]
	s_mov_b32 m0, s69
	v_lshl_add_u64 v[184:185], v[188:189], 0, s[88:89]
	s_barrier
	ds_read_b128 v[160:163], v147 offset:49152
	ds_read_b128 v[164:167], v147 offset:50176
	ds_read_b128 v[168:171], v147 offset:51200
	ds_read_b128 v[172:175], v147 offset:52224
	ds_read_b128 v[176:179], v147 offset:53248
	ds_read_b128 v[180:183], v147 offset:54272
	ds_read_b128 v[196:199], v147 offset:55296
	ds_read_b128 v[200:203], v147 offset:56320
	global_load_lds_dwordx4 v[184:185], off
	s_mov_b32 m0, s70
	v_lshl_add_u64 v[184:185], v[192:193], 0, s[88:89]
	global_load_lds_dwordx4 v[184:185], off
	s_barrier
; #define PG8_STAGE(bufoff, gbase, voff) do { _Pragma("unroll") for (int _i = 0; _i < 2; ++_i) \
;         __builtin_amdgcn_global_load_lds((const unsigned*)((const char*)(gbase) + (voff)[_i]), (LAS unsigned*)(lds + (bufoff) + ldsw + _i * 8192), 16, 0, 0); } while (0)
; #define PG8_MMA(ai, bj, At, Bt) do { __builtin_amdgcn_s_setprio(1); _Pragma("unroll") for (int m = 0; m < 4; ++m) _Pragma("unroll") for (int n = 0; n < 2; ++n) _Pragma("unroll") for (int k = 0; k < 2; ++k) \
;         acc[ai][bj][m][n] = __builtin_amdgcn_mfma_f32_16x16x32_bf16(Bt[n][k], At[m][k], acc[ai][bj][m][n], 0, 0, 0); __builtin_amdgcn_s_setprio(0); } while (0)
; #define PG8_WAIT_V(n) asm volatile("s_waitcnt vmcnt(" #n ")" ::: "memory")
; #define PG8_WAIT_L(n) asm volatile("s_waitcnt lgkmcnt(" #n ")" ::: "memory")
; #define PG8_BAR __builtin_amdgcn_s_barrier()
; #define PG8_SCHED __builtin_amdgcn_sched_barrier(0)
; template <class Epi>
; __device__ __forceinline__ void gemm_phase(LAS unsigned char* lds, const Gemm g, const StaticOrder& S, const Epi& E) {
;     ...
;             PG8_BAR; PG8_WAIT_L(0); PG8_MMA(1, 0, At, B0); PG8_BAR; PG8_SCHED;
;             PG8_STAGE(PG8_SB(1, 1), b3 + hB, voffB);
;             PG8_WAIT_V(6); PG8_BAR; PG8_MMA(1, 1, At, B1); PG8_BAR;
;         }
	s_waitcnt lgkmcnt(0)
	v_mfma_f32_16x16x32_bf16 v[60:63], v[138:141], v[160:163], v[60:63]
	v_mfma_f32_16x16x32_bf16 v[56:59], v[152:155], v[160:163], v[56:59]
	v_mfma_f32_16x16x32_bf16 v[52:55], v[138:141], v[168:171], v[52:55]
	v_mfma_f32_16x16x32_bf16 v[44:47], v[152:155], v[168:171], v[44:47]
	v_mfma_f32_16x16x32_bf16 v[36:39], v[138:141], v[176:179], v[36:39]
	v_mfma_f32_16x16x32_bf16 v[28:31], v[152:155], v[176:179], v[28:31]
	v_mfma_f32_16x16x32_bf16 v[20:23], v[138:141], v[196:199], v[20:23]
	v_mfma_f32_16x16x32_bf16 v[12:15], v[152:155], v[196:199], v[12:15]
	v_mfma_f32_16x16x32_bf16 v[60:63], v[148:151], v[164:167], v[60:63]
	v_mfma_f32_16x16x32_bf16 v[56:59], v[156:159], v[164:167], v[56:59]
	v_mfma_f32_16x16x32_bf16 v[52:55], v[148:151], v[172:175], v[52:55]
	v_mfma_f32_16x16x32_bf16 v[44:47], v[156:159], v[172:175], v[44:47]
	v_mfma_f32_16x16x32_bf16 v[36:39], v[148:151], v[180:183], v[36:39]
	v_mfma_f32_16x16x32_bf16 v[28:31], v[156:159], v[180:183], v[28:31]
	v_mfma_f32_16x16x32_bf16 v[20:23], v[148:151], v[200:203], v[20:23]
	v_mfma_f32_16x16x32_bf16 v[12:15], v[156:159], v[200:203], v[12:15]
	s_barrier
	s_add_u32 s10, s16, 0x18080
	s_addc_u32 s11, s17, 0
	s_add_i32 s16, s20, s63
	s_mov_b32 m0, s16
	v_lshl_add_u64 v[138:139], s[10:11], 0, v[144:145]
	global_load_lds_dwordx4 v[138:139], off
	s_add_i32 m0, s16, 0x2000
	v_lshl_add_u64 v[138:139], s[10:11], 0, v[132:133]
	global_load_lds_dwordx4 v[138:139], off
	s_waitcnt vmcnt(6)
	s_barrier
	v_mfma_f32_16x16x32_bf16 v[48:51], v[204:207], v[160:163], v[48:51]
	v_mfma_f32_16x16x32_bf16 v[40:43], v[220:223], v[160:163], v[40:43]
	v_mfma_f32_16x16x32_bf16 v[32:35], v[204:207], v[168:171], v[32:35]
	v_mfma_f32_16x16x32_bf16 v[24:27], v[220:223], v[168:171], v[24:27]
	v_mfma_f32_16x16x32_bf16 v[16:19], v[204:207], v[176:179], v[16:19]
	v_mfma_f32_16x16x32_bf16 v[8:11], v[220:223], v[176:179], v[8:11]
	v_mfma_f32_16x16x32_bf16 v[4:7], v[204:207], v[196:199], v[4:7]
	v_mfma_f32_16x16x32_bf16 v[0:3], v[220:223], v[196:199], v[0:3]
	v_mfma_f32_16x16x32_bf16 v[48:51], v[216:219], v[164:167], v[48:51]
	v_mfma_f32_16x16x32_bf16 v[40:43], v[224:227], v[164:167], v[40:43]
	v_mfma_f32_16x16x32_bf16 v[32:35], v[216:219], v[172:175], v[32:35]
	v_mfma_f32_16x16x32_bf16 v[24:27], v[224:227], v[172:175], v[24:27]
	v_mfma_f32_16x16x32_bf16 v[16:19], v[216:219], v[180:183], v[16:19]
	v_mfma_f32_16x16x32_bf16 v[8:11], v[224:227], v[180:183], v[8:11]
	v_mfma_f32_16x16x32_bf16 v[4:7], v[216:219], v[200:203], v[4:7]
	v_mfma_f32_16x16x32_bf16 v[0:3], v[224:227], v[200:203], v[0:3]
	s_add_i32 s78, s78, 2
	s_add_u32 s24, s24, 0x100
	s_addc_u32 s25, s25, 0
	s_cmp_gt_u32 s78, 3
	s_mov_b64 s[10:11], s[12:13]
	s_barrier
	s_cbranch_scc0 .LBB0_655
; __device__ __forceinline__ unsigned pk2(float lo, float hi) { unsigned r; asm("v_cvt_pk_bf16_f32 %0, %1, %2" : "=v"(r) : "v"(lo), "v"(hi)); return r; }
; #define PG8_WAIT_V(n) asm volatile("s_waitcnt vmcnt(" #n ")" ::: "memory")
; #define PG8_BAR __builtin_amdgcn_s_barrier()
; template <class Epi>
; __device__ __forceinline__ void gemm_phase(LAS unsigned char* lds, const Gemm g, const StaticOrder& S, const Epi& E) {
;     ...
;         E(acc, cur, wr, wc, fr, fq);
;         if (!has_next) break;
; #pragma unroll
;         for (int a = 0; a < 2; ++a)
; #pragma unroll
;             for (int b = 0; b < 2; ++b)
; #pragma unroll
;                 for (int m = 0; m < 4; ++m)
; #pragma unroll
;                     for (int n = 0; n < 2; ++n) acc[a][b][m][n] = (f32x4){0.f, 0.f, 0.f, 0.f};
;         cur = nxt; cA = nA; cB = nB; ++ui;
;     }
;     PG8_WAIT_V(0);
;     if (wr == 0) PG8_BAR;
;     __device__ __forceinline__ void operator()(const f32x4 (&acc)[2][2][4][2], const Unit& u, int wr, int wc, int fr, int fq) const {
;     ...
;         const int row_t = rmap == 1 ? odd_phys_row0(u.pm, grp) : (rmap == 2 ? odd_phys_row0(u.pm % (BG * TPB), u.pm / (BG * TPB)) : u.pm * BM);
;         int c = col_t + 64 * wc + 16 * fq;
;         if (mode == 2) c = (c >> 6) * 96 + (c & 63);
; #pragma unroll
;         for (int ai = 0; ai < 2; ++ai)
; #pragma unroll
;             for (int m = 0; m < 4; ++m) {
;                 const int row = row_t + ai * HALF + wr * 64 + m * 16 + fr;
;                 bf16_t* rp = O + (size_t)row * ldc + c;
; #pragma unroll
;                 for (int bj = 0; bj < 2; ++bj) {
;                     const f32x4 v0 = acc[ai][bj][m][0], v1 = acc[ai][bj][m][1];
;                     u32x4 o; o.x = pk2(v0[0], v0[1]); o.y = pk2(v0[2], v0[3]); o.z = pk2(v1[0], v1[1]); o.w = pk2(v1[2], v1[3]);
;                     *(u32x4*)(rp + 8 * bj) = o;
;                 }
;             }
	v_lshl_or_b32 v140, s15, 8, v146
	v_lshl_add_u32 v150, s77, 8, v142
	v_ashrrev_i32_e32 v141, 31, v140
	v_mov_b64_e32 v[138:139], s[8:9]
	v_cvt_pk_bf16_f32 v68, v68, v69
	v_cvt_pk_bf16_f32 v69, v70, v71
	v_cvt_pk_bf16_f32 v70, v64, v65
	v_add_u32_e32 v64, 0x80, v150
	v_mad_i64_i32 v[148:149], s[10:11], v150, s90, v[138:139]
	v_lshlrev_b64 v[140:141], 1, v[140:141]
	v_cvt_pk_bf16_f32 v112, v112, v113
	v_cvt_pk_bf16_f32 v113, v114, v115
	v_cvt_pk_bf16_f32 v114, v104, v105
	v_or_b32_e32 v104, 16, v150
	v_mad_i64_i32 v[64:65], s[10:11], v64, s90, v[138:139]
	v_cvt_pk_bf16_f32 v48, v48, v49
	v_cvt_pk_bf16_f32 v49, v50, v51
	v_cvt_pk_bf16_f32 v50, v40, v41
	v_add_u32_e32 v40, 0x90, v150
	v_lshl_add_u64 v[148:149], v[148:149], 0, v[140:141]
	v_mad_i64_i32 v[104:105], s[10:11], v104, s90, v[138:139]
	v_cvt_pk_bf16_f32 v96, v96, v97
	v_cvt_pk_bf16_f32 v97, v98, v99
	v_cvt_pk_bf16_f32 v98, v88, v89
	v_or_b32_e32 v88, 32, v150
	v_lshl_add_u64 v[64:65], v[64:65], 0, v[140:141]
	v_mad_i64_i32 v[40:41], s[10:11], v40, s90, v[138:139]
	v_cvt_pk_bf16_f32 v32, v32, v33
	v_cvt_pk_bf16_f32 v33, v34, v35
	v_cvt_pk_bf16_f32 v34, v24, v25
	v_add_u32_e32 v24, 0xa0, v150
	v_cvt_pk_bf16_f32 v115, v106, v107
	global_store_dwordx4 v[148:149], v[112:115], off offset:16
	v_mad_i64_i32 v[88:89], s[10:11], v88, s90, v[138:139]
	s_nop 0
	v_lshl_add_u64 v[112:113], v[104:105], 0, v[140:141]
	v_cvt_pk_bf16_f32 v80, v80, v81
	v_cvt_pk_bf16_f32 v81, v82, v83
	v_cvt_pk_bf16_f32 v82, v72, v73
	v_or_b32_e32 v72, 48, v150
	v_cvt_pk_bf16_f32 v51, v42, v43
	global_store_dwordx4 v[64:65], v[48:51], off offset:16
	v_mad_i64_i32 v[24:25], s[10:11], v24, s90, v[138:139]
	s_nop 0
	v_lshl_add_u64 v[48:49], v[40:41], 0, v[140:141]
	v_cvt_pk_bf16_f32 v16, v16, v17
	v_cvt_pk_bf16_f32 v17, v18, v19
	v_cvt_pk_bf16_f32 v18, v8, v9
	v_add_u32_e32 v8, 0xb0, v150
	v_cvt_pk_bf16_f32 v99, v90, v91
	global_store_dwordx4 v[112:113], v[96:99], off offset:16
	v_mad_i64_i32 v[72:73], s[10:11], v72, s90, v[138:139]
	s_nop 0
	v_lshl_add_u64 v[96:97], v[88:89], 0, v[140:141]
	v_cvt_pk_bf16_f32 v35, v26, v27
	global_store_dwordx4 v[48:49], v[32:35], off offset:16
	v_mad_i64_i32 v[8:9], s[10:11], v8, s90, v[138:139]
	s_nop 0
	v_lshl_add_u64 v[32:33], v[24:25], 0, v[140:141]
	v_cvt_pk_bf16_f32 v83, v74, v75
	global_store_dwordx4 v[96:97], v[80:83], off offset:16
	v_cvt_pk_bf16_f32 v19, v10, v11
	global_store_dwordx4 v[32:33], v[16:19], off offset:16
	s_and_b64 vcc, exec, s[0:1]
	v_lshl_add_u64 v[80:81], v[72:73], 0, v[140:141]
	v_lshl_add_u64 v[16:17], v[8:9], 0, v[140:141]
	s_mov_b32 s15, s72
	s_mov_b32 s77, s76
	s_mov_b64 s[12:13], s[6:7]
	s_mov_b64 s[10:11], s[4:5]
	v_cvt_pk_bf16_f32 v124, v124, v125
	v_cvt_pk_bf16_f32 v125, v126, v127
	v_cvt_pk_bf16_f32 v126, v120, v121
	v_cvt_pk_bf16_f32 v127, v122, v123
	global_store_dwordx4 v[148:149], v[124:127], off
	v_cvt_pk_bf16_f32 v104, v116, v117
	v_cvt_pk_bf16_f32 v105, v118, v119
	v_cvt_pk_bf16_f32 v106, v108, v109
	v_cvt_pk_bf16_f32 v107, v110, v111
	global_store_dwordx4 v[112:113], v[104:107], off
	v_cvt_pk_bf16_f32 v88, v100, v101
	v_cvt_pk_bf16_f32 v89, v102, v103
	v_cvt_pk_bf16_f32 v90, v92, v93
	v_cvt_pk_bf16_f32 v91, v94, v95
	global_store_dwordx4 v[96:97], v[88:91], off
	v_cvt_pk_bf16_f32 v72, v84, v85
	v_cvt_pk_bf16_f32 v73, v86, v87
	v_cvt_pk_bf16_f32 v74, v76, v77
	v_cvt_pk_bf16_f32 v75, v78, v79
	global_store_dwordx4 v[80:81], v[72:75], off
	v_cvt_pk_bf16_f32 v71, v66, v67
	global_store_dwordx4 v[80:81], v[68:71], off offset:16
	v_cvt_pk_bf16_f32 v60, v60, v61
	v_cvt_pk_bf16_f32 v61, v62, v63
	v_cvt_pk_bf16_f32 v62, v56, v57
	v_cvt_pk_bf16_f32 v63, v58, v59
	global_store_dwordx4 v[64:65], v[60:63], off
	v_cvt_pk_bf16_f32 v40, v52, v53
	v_cvt_pk_bf16_f32 v41, v54, v55
	v_cvt_pk_bf16_f32 v42, v44, v45
	v_cvt_pk_bf16_f32 v43, v46, v47
	global_store_dwordx4 v[48:49], v[40:43], off
	v_cvt_pk_bf16_f32 v24, v36, v37
	v_cvt_pk_bf16_f32 v25, v38, v39
	v_cvt_pk_bf16_f32 v26, v28, v29
	v_cvt_pk_bf16_f32 v27, v30, v31
	global_store_dwordx4 v[32:33], v[24:27], off
	v_cvt_pk_bf16_f32 v8, v20, v21
	v_cvt_pk_bf16_f32 v9, v22, v23
	v_cvt_pk_bf16_f32 v10, v12, v13
	v_cvt_pk_bf16_f32 v11, v14, v15
	global_store_dwordx4 v[16:17], v[8:11], off
	v_cvt_pk_bf16_f32 v4, v4, v5
	v_cvt_pk_bf16_f32 v5, v6, v7
	v_cvt_pk_bf16_f32 v6, v0, v1
	v_cvt_pk_bf16_f32 v7, v2, v3
	global_store_dwordx4 v[16:17], v[4:7], off offset:16
	s_cbranch_vccz .LBB0_644
	s_waitcnt vmcnt(0)
	s_cmpk_gt_u32 s14, 0xff
	s_cbranch_scc1 .LBB0_659
	s_barrier

; #define PG8_STAGE(bufoff, gbase, voff) do { _Pragma("unroll") for (int _i = 0; _i < 2; ++_i) \
;         __builtin_amdgcn_global_load_lds((const unsigned*)((const char*)(gbase) + (voff)[_i]), (LAS unsigned*)(lds + (bufoff) + ldsw + _i * 8192), 16, 0, 0); } while (0)
; #define PG8_LDA(dst, b, h) do { _Pragma("unroll") for (int m = 0; m < 4; ++m) _Pragma("unroll") for (int k = 0; k < 2; ++k) dst[m][k] = *(const LAS bf16x8*)(lds + PG8_SA(b, h) + aoff + m * 2048 + k * 1024); } while (0)
; #define PG8_LDB(dst, b, h) do { _Pragma("unroll") for (int n = 0; n < 2; ++n) _Pragma("unroll") for (int k = 0; k < 2; ++k) dst[n][k] = *(const LAS bf16x8*)(lds + PG8_SB(b, h) + boff + n * 2048 + k * 1024); } while (0)
; #define PG8_MMA(ai, bj, At, Bt) do { __builtin_amdgcn_s_setprio(1); _Pragma("unroll") for (int m = 0; m < 4; ++m) _Pragma("unroll") for (int n = 0; n < 2; ++n) _Pragma("unroll") for (int k = 0; k < 2; ++k) \
;         acc[ai][bj][m][n] = __builtin_amdgcn_mfma_f32_16x16x32_bf16(Bt[n][k], At[m][k], acc[ai][bj][m][n], 0, 0, 0); __builtin_amdgcn_s_setprio(0); } while (0)
; #define PG8_WAIT_L(n) asm volatile("s_waitcnt lgkmcnt(" #n ")" ::: "memory")
; #define PG8_BAR __builtin_amdgcn_s_barrier()
; #define PG8_SCHED __builtin_amdgcn_sched_barrier(0)
; template <class Epi>
; __device__ __forceinline__ void gemm_phase(LAS unsigned char* lds, const Gemm g, const StaticOrder& S, const Epi& E) {
;     ...
;         const char* nA = has_next ? g.arow(nxt.pm) : cA; const char* nB = has_next ? (const char*)g.Bt + (size_t)nxt.pn * tB : cB;
;         for (int t = 0; t < nt; t += 2) {
;             const bool last = (t == nt - 2);
;             const char* a1 = cA + (size_t)(t + 1) * kstep;
;             const char* a2 = last ? nA : cA + (size_t)(t + 2) * kstep; const char* b2 = last ? nB : cB + (size_t)(t + 2) * kstep;
;             const char* a3 = a2 + kstep; const char* b3 = b2 + kstep;
;             PG8_LDB(B0, 0, 0); PG8_SCHED; PG8_LDA(At, 0, 0); PG8_STAGE(PG8_SA(1, 1), a1 + hA, voffA);
;             PG8_WAIT_L(8); PG8_BAR; PG8_WAIT_L(0); PG8_MMA(0, 0, At, B0); PG8_BAR; PG8_SCHED;
;             PG8_LDB(B1, 0, 1); PG8_STAGE(PG8_SB(0, 0), b2, voffB);
;             PG8_BAR; PG8_WAIT_L(0); PG8_MMA(0, 1, At, B1); PG8_BAR;
;             PG8_LDA(At, 0, 1); PG8_STAGE(PG8_SA(0, 0), a2, voffA);
;             PG8_BAR; PG8_WAIT_L(0); PG8_MMA(1, 0, At, B0); PG8_BAR; PG8_SCHED;
.LBB0_670:
	s_add_u32 s28, s82, s25
	s_addc_u32 s29, s83, 0
	s_add_u32 s30, s28, 0x100
	s_addc_u32 s31, s29, 0
	s_and_b64 s[26:27], s[34:35], exec
	s_cselect_b32 s93, s17, s31
	s_cselect_b32 s92, s16, s30
	s_add_u32 s25, s64, s25
	s_addc_u32 s26, s65, 0
	s_add_u32 s25, s25, 0x100
	s_addc_u32 s30, s26, 0
	s_add_i32 s31, 0, 0x10000
	s_and_b64 s[26:27], s[34:35], exec
	s_cselect_b32 vcc_hi, s13, s30
	s_cselect_b32 vcc_lo, s24, s25
	s_add_u32 s76, s28, 0xb0080
	s_addc_u32 s77, s29, 0
	s_add_i32 s39, s31, s63
	s_add_i32 m0, s40, 0xc000
	s_add_i32 s68, s40, 0xe000
	s_add_i32 s29, 0, 0x14000
	s_add_i32 s37, s39, 0x2000
	s_add_u32 s86, vcc_lo, 0x10000
	v_add_u32_e32 v146, s31, v150
	s_addc_u32 s87, vcc_hi, 0
	s_add_i32 s30, s29, s63
	ds_read_b128 v[136:139], v146
	ds_read_b128 v[140:143], v146 offset:1024
	ds_read_b128 v[158:161], v146 offset:2048
	ds_read_b128 v[162:165], v146 offset:3072
	s_add_i32 s38, s30, 0x2000
	s_add_i32 s27, 0, 0x18000
	s_add_u32 s84, s92, 0xb0000
	s_addc_u32 s85, s93, 0
	s_add_i32 s25, s27, s63
	s_add_i32 s26, 0, 0x1c000
	s_add_i32 s28, s25, 0x2000
	s_add_u32 s34, vcc_lo, 0x10080
	s_addc_u32 s35, vcc_hi, 0
	s_add_i32 s31, s26, s63
	s_add_i32 s36, s31, 0x2000
	v_lshl_add_u64 v[146:147], s[76:77], 0, v[134:135]
	ds_read_b128 v[166:169], v154
	ds_read_b128 v[170:173], v154 offset:1024
	ds_read_b128 v[174:177], v154 offset:2048
	ds_read_b128 v[178:181], v154 offset:3072
	ds_read_b128 v[182:185], v154 offset:4096
	ds_read_b128 v[196:199], v154 offset:5120
	ds_read_b128 v[200:203], v154 offset:6144
	ds_read_b128 v[204:207], v154 offset:7168
	global_load_lds_dwordx4 v[146:147], off
	s_mov_b32 m0, s68
	v_lshl_add_u64 v[146:147], s[76:77], 0, v[130:131]
	global_load_lds_dwordx4 v[146:147], off
	s_waitcnt lgkmcnt(8)
	s_barrier
	s_waitcnt lgkmcnt(0)
	v_mfma_f32_16x16x32_bf16 v[124:127], v[136:139], v[166:169], v[124:127]
	v_mfma_f32_16x16x32_bf16 v[120:123], v[158:161], v[166:169], v[120:123]
	v_mfma_f32_16x16x32_bf16 v[116:119], v[136:139], v[174:177], v[116:119]
	v_mfma_f32_16x16x32_bf16 v[108:111], v[158:161], v[174:177], v[108:111]
	v_mfma_f32_16x16x32_bf16 v[100:103], v[136:139], v[182:185], v[100:103]
	v_mfma_f32_16x16x32_bf16 v[92:95], v[158:161], v[182:185], v[92:95]
	v_mfma_f32_16x16x32_bf16 v[84:87], v[136:139], v[200:203], v[84:87]
	v_mfma_f32_16x16x32_bf16 v[76:79], v[158:161], v[200:203], v[76:79]
	v_mfma_f32_16x16x32_bf16 v[124:127], v[140:143], v[170:173], v[124:127]
	v_mfma_f32_16x16x32_bf16 v[120:123], v[162:165], v[170:173], v[120:123]
	v_mfma_f32_16x16x32_bf16 v[116:119], v[140:143], v[178:181], v[116:119]
	v_mfma_f32_16x16x32_bf16 v[108:111], v[162:165], v[178:181], v[108:111]
	v_mfma_f32_16x16x32_bf16 v[100:103], v[140:143], v[196:199], v[100:103]
	v_mfma_f32_16x16x32_bf16 v[92:95], v[162:165], v[196:199], v[92:95]
	v_mfma_f32_16x16x32_bf16 v[84:87], v[140:143], v[204:207], v[84:87]
	v_mfma_f32_16x16x32_bf16 v[76:79], v[162:165], v[204:207], v[76:79]
	s_barrier
	v_add_u32_e32 v146, s29, v150
	s_mov_b32 m0, s39
	ds_read_b128 v[216:219], v146
	ds_read_b128 v[220:223], v146 offset:1024
	ds_read_b128 v[224:227], v146 offset:2048
	ds_read_b128 v[228:231], v146 offset:3072
	v_lshl_add_u64 v[146:147], vcc, 0, v[132:133]
	global_load_lds_dwordx4 v[146:147], off
	s_mov_b32 m0, s37
	v_lshl_add_u64 v[186:187], vcc, 0, v[128:129]
	global_load_lds_dwordx4 v[186:187], off
	s_barrier
	s_waitcnt lgkmcnt(0)
	v_mfma_f32_16x16x32_bf16 v[112:115], v[216:219], v[166:169], v[112:115]
	v_mfma_f32_16x16x32_bf16 v[104:107], v[224:227], v[166:169], v[104:107]
	v_mfma_f32_16x16x32_bf16 v[96:99], v[216:219], v[174:177], v[96:99]
	v_mfma_f32_16x16x32_bf16 v[88:91], v[224:227], v[174:177], v[88:91]
	v_mfma_f32_16x16x32_bf16 v[80:83], v[216:219], v[182:185], v[80:83]
	v_mfma_f32_16x16x32_bf16 v[72:75], v[224:227], v[182:185], v[72:75]
	v_mfma_f32_16x16x32_bf16 v[68:71], v[216:219], v[200:203], v[68:71]
	v_mfma_f32_16x16x32_bf16 v[64:67], v[224:227], v[200:203], v[64:67]
	v_mfma_f32_16x16x32_bf16 v[112:115], v[220:223], v[170:173], v[112:115]
	v_mfma_f32_16x16x32_bf16 v[104:107], v[228:231], v[170:173], v[104:107]
	v_mfma_f32_16x16x32_bf16 v[96:99], v[220:223], v[178:181], v[96:99]
	v_mfma_f32_16x16x32_bf16 v[88:91], v[228:231], v[178:181], v[88:91]
	v_mfma_f32_16x16x32_bf16 v[80:83], v[220:223], v[196:199], v[80:83]
	v_mfma_f32_16x16x32_bf16 v[72:75], v[228:231], v[196:199], v[72:75]
	v_mfma_f32_16x16x32_bf16 v[68:71], v[220:223], v[204:207], v[68:71]
	v_mfma_f32_16x16x32_bf16 v[64:67], v[228:231], v[204:207], v[64:67]
	s_mov_b32 m0, s40
	v_lshl_add_u64 v[188:189], s[92:93], 0, v[134:135]
	s_barrier
	ds_read_b128 v[166:169], v154 offset:16384
	ds_read_b128 v[170:173], v154 offset:17408
	ds_read_b128 v[174:177], v154 offset:18432
	ds_read_b128 v[178:181], v154 offset:19456
	ds_read_b128 v[182:185], v154 offset:20480
	ds_read_b128 v[196:199], v154 offset:21504
	ds_read_b128 v[200:203], v154 offset:22528
	ds_read_b128 v[204:207], v154 offset:23552
	global_load_lds_dwordx4 v[188:189], off
	s_mov_b32 m0, s69
	v_lshl_add_u64 v[192:193], s[92:93], 0, v[130:131]
	global_load_lds_dwordx4 v[192:193], off
	s_barrier
; #define PG8_STAGE(bufoff, gbase, voff) do { _Pragma("unroll") for (int _i = 0; _i < 2; ++_i) \
;         __builtin_amdgcn_global_load_lds((const unsigned*)((const char*)(gbase) + (voff)[_i]), (LAS unsigned*)(lds + (bufoff) + ldsw + _i * 8192), 16, 0, 0); } while (0)
; #define PG8_LDA(dst, b, h) do { _Pragma("unroll") for (int m = 0; m < 4; ++m) _Pragma("unroll") for (int k = 0; k < 2; ++k) dst[m][k] = *(const LAS bf16x8*)(lds + PG8_SA(b, h) + aoff + m * 2048 + k * 1024); } while (0)
; #define PG8_LDB(dst, b, h) do { _Pragma("unroll") for (int n = 0; n < 2; ++n) _Pragma("unroll") for (int k = 0; k < 2; ++k) dst[n][k] = *(const LAS bf16x8*)(lds + PG8_SB(b, h) + boff + n * 2048 + k * 1024); } while (0)
; #define PG8_MMA(ai, bj, At, Bt) do { __builtin_amdgcn_s_setprio(1); _Pragma("unroll") for (int m = 0; m < 4; ++m) _Pragma("unroll") for (int n = 0; n < 2; ++n) _Pragma("unroll") for (int k = 0; k < 2; ++k) \
;         acc[ai][bj][m][n] = __builtin_amdgcn_mfma_f32_16x16x32_bf16(Bt[n][k], At[m][k], acc[ai][bj][m][n], 0, 0, 0); __builtin_amdgcn_s_setprio(0); } while (0)
; #define PG8_WAIT_V(n) asm volatile("s_waitcnt vmcnt(" #n ")" ::: "memory")
; #define PG8_WAIT_L(n) asm volatile("s_waitcnt lgkmcnt(" #n ")" ::: "memory")
; #define PG8_BAR __builtin_amdgcn_s_barrier()
; #define PG8_SCHED __builtin_amdgcn_sched_barrier(0)
; template <class Epi>
; __device__ __forceinline__ void gemm_phase(LAS unsigned char* lds, const Gemm g, const StaticOrder& S, const Epi& E) {
;     ...
;             PG8_BAR; PG8_WAIT_L(0); PG8_MMA(1, 0, At, B0); PG8_BAR; PG8_SCHED;
;             PG8_STAGE(PG8_SB(0, 1), b2 + hB, voffB);
;             PG8_WAIT_V(6); PG8_BAR; PG8_MMA(1, 1, At, B1); PG8_BAR;
;             PG8_LDB(B0, 1, 0); PG8_SCHED; PG8_LDA(At, 1, 0); PG8_STAGE(PG8_SA(0, 1), a2 + hA, voffA);
;             PG8_WAIT_L(8); PG8_BAR; PG8_WAIT_L(0); PG8_MMA(0, 0, At, B0); PG8_BAR; PG8_SCHED;
;             PG8_LDB(B1, 1, 1); PG8_STAGE(PG8_SB(1, 0), b3, voffB);
;             PG8_BAR; PG8_WAIT_L(0); PG8_MMA(0, 1, At, B1); PG8_BAR;
;             PG8_LDA(At, 1, 1); PG8_STAGE(PG8_SA(1, 0), a3, voffA);
;             PG8_BAR; PG8_WAIT_L(0); PG8_MMA(1, 0, At, B0); PG8_BAR; PG8_SCHED;
	s_waitcnt lgkmcnt(0)
	v_mfma_f32_16x16x32_bf16 v[60:63], v[136:139], v[166:169], v[60:63]
	v_mfma_f32_16x16x32_bf16 v[56:59], v[158:161], v[166:169], v[56:59]
	v_mfma_f32_16x16x32_bf16 v[52:55], v[136:139], v[174:177], v[52:55]
	v_mfma_f32_16x16x32_bf16 v[44:47], v[158:161], v[174:177], v[44:47]
	v_mfma_f32_16x16x32_bf16 v[36:39], v[136:139], v[182:185], v[36:39]
	v_mfma_f32_16x16x32_bf16 v[28:31], v[158:161], v[182:185], v[28:31]
	v_mfma_f32_16x16x32_bf16 v[20:23], v[136:139], v[200:203], v[20:23]
	v_mfma_f32_16x16x32_bf16 v[12:15], v[158:161], v[200:203], v[12:15]
	v_mfma_f32_16x16x32_bf16 v[60:63], v[140:143], v[170:173], v[60:63]
	v_mfma_f32_16x16x32_bf16 v[56:59], v[162:165], v[170:173], v[56:59]
	v_mfma_f32_16x16x32_bf16 v[52:55], v[140:143], v[178:181], v[52:55]
	v_mfma_f32_16x16x32_bf16 v[44:47], v[162:165], v[178:181], v[44:47]
	v_mfma_f32_16x16x32_bf16 v[36:39], v[140:143], v[196:199], v[36:39]
	v_mfma_f32_16x16x32_bf16 v[28:31], v[162:165], v[196:199], v[28:31]
	v_mfma_f32_16x16x32_bf16 v[20:23], v[140:143], v[204:207], v[20:23]
	v_mfma_f32_16x16x32_bf16 v[12:15], v[162:165], v[204:207], v[12:15]
	s_barrier
	s_mov_b32 m0, s30
	v_lshl_add_u64 v[136:137], s[86:87], 0, v[132:133]
	global_load_lds_dwordx4 v[136:137], off
	s_mov_b32 m0, s38
	v_lshl_add_u64 v[136:137], s[86:87], 0, v[128:129]
	global_load_lds_dwordx4 v[136:137], off
	s_waitcnt vmcnt(6)
	s_barrier
	v_mfma_f32_16x16x32_bf16 v[48:51], v[216:219], v[166:169], v[48:51]
	v_mfma_f32_16x16x32_bf16 v[40:43], v[224:227], v[166:169], v[40:43]
	v_mfma_f32_16x16x32_bf16 v[32:35], v[216:219], v[174:177], v[32:35]
	v_mfma_f32_16x16x32_bf16 v[24:27], v[224:227], v[174:177], v[24:27]
	v_mfma_f32_16x16x32_bf16 v[16:19], v[216:219], v[182:185], v[16:19]
	v_mfma_f32_16x16x32_bf16 v[8:11], v[224:227], v[182:185], v[8:11]
	v_mfma_f32_16x16x32_bf16 v[4:7], v[216:219], v[200:203], v[4:7]
	v_mfma_f32_16x16x32_bf16 v[0:3], v[224:227], v[200:203], v[0:3]
	v_mfma_f32_16x16x32_bf16 v[48:51], v[220:223], v[170:173], v[48:51]
	v_mfma_f32_16x16x32_bf16 v[40:43], v[228:231], v[170:173], v[40:43]
	v_mfma_f32_16x16x32_bf16 v[32:35], v[220:223], v[178:181], v[32:35]
	v_mfma_f32_16x16x32_bf16 v[24:27], v[228:231], v[178:181], v[24:27]
	v_mfma_f32_16x16x32_bf16 v[16:19], v[220:223], v[196:199], v[16:19]
	v_mfma_f32_16x16x32_bf16 v[8:11], v[228:231], v[196:199], v[8:11]
	v_mfma_f32_16x16x32_bf16 v[4:7], v[220:223], v[204:207], v[4:7]
	v_mfma_f32_16x16x32_bf16 v[0:3], v[228:231], v[204:207], v[0:3]
	v_add_u32_e32 v157, s27, v150
	s_barrier
	ds_read_b128 v[136:139], v157
	ds_read_b128 v[140:143], v157 offset:1024
	ds_read_b128 v[158:161], v157 offset:2048
	ds_read_b128 v[162:165], v157 offset:3072
	s_mov_b32 m0, s70
	v_lshl_add_u64 v[216:217], s[84:85], 0, v[134:135]
	ds_read_b128 v[166:169], v154 offset:32768
	ds_read_b128 v[170:173], v154 offset:33792
	ds_read_b128 v[174:177], v154 offset:34816
	ds_read_b128 v[178:181], v154 offset:35840
	ds_read_b128 v[182:185], v154 offset:36864
	ds_read_b128 v[196:199], v154 offset:37888
	ds_read_b128 v[200:203], v154 offset:38912
	ds_read_b128 v[204:207], v154 offset:39936
	global_load_lds_dwordx4 v[216:217], off
	s_mov_b32 m0, s71
	v_lshl_add_u64 v[216:217], s[84:85], 0, v[130:131]
	global_load_lds_dwordx4 v[216:217], off
	s_waitcnt lgkmcnt(8)
	s_barrier
	s_waitcnt lgkmcnt(0)
	v_mfma_f32_16x16x32_bf16 v[124:127], v[136:139], v[166:169], v[124:127]
	v_mfma_f32_16x16x32_bf16 v[120:123], v[158:161], v[166:169], v[120:123]
	v_mfma_f32_16x16x32_bf16 v[116:119], v[136:139], v[174:177], v[116:119]
	v_mfma_f32_16x16x32_bf16 v[108:111], v[158:161], v[174:177], v[108:111]
	v_mfma_f32_16x16x32_bf16 v[100:103], v[136:139], v[182:185], v[100:103]
	v_mfma_f32_16x16x32_bf16 v[92:95], v[158:161], v[182:185], v[92:95]
	v_mfma_f32_16x16x32_bf16 v[84:87], v[136:139], v[200:203], v[84:87]
	v_mfma_f32_16x16x32_bf16 v[76:79], v[158:161], v[200:203], v[76:79]
	v_mfma_f32_16x16x32_bf16 v[124:127], v[140:143], v[170:173], v[124:127]
	v_mfma_f32_16x16x32_bf16 v[120:123], v[162:165], v[170:173], v[120:123]
	v_mfma_f32_16x16x32_bf16 v[116:119], v[140:143], v[178:181], v[116:119]
	v_mfma_f32_16x16x32_bf16 v[108:111], v[162:165], v[178:181], v[108:111]
	v_mfma_f32_16x16x32_bf16 v[100:103], v[140:143], v[196:199], v[100:103]
	v_mfma_f32_16x16x32_bf16 v[92:95], v[162:165], v[196:199], v[92:95]
	v_mfma_f32_16x16x32_bf16 v[84:87], v[140:143], v[204:207], v[84:87]
	v_mfma_f32_16x16x32_bf16 v[76:79], v[162:165], v[204:207], v[76:79]
	s_barrier
	s_mov_b32 m0, s25
	v_add_u32_e32 v157, s26, v150
	v_lshl_add_u64 v[146:147], v[146:147], 0, s[88:89]
	ds_read_b128 v[216:219], v157
	ds_read_b128 v[220:223], v157 offset:1024
	ds_read_b128 v[224:227], v157 offset:2048
	ds_read_b128 v[228:231], v157 offset:3072
	global_load_lds_dwordx4 v[146:147], off
	s_mov_b32 m0, s28
	v_lshl_add_u64 v[146:147], v[186:187], 0, s[88:89]
	global_load_lds_dwordx4 v[146:147], off
	s_barrier
	s_waitcnt lgkmcnt(0)
	v_mfma_f32_16x16x32_bf16 v[112:115], v[216:219], v[166:169], v[112:115]
	v_mfma_f32_16x16x32_bf16 v[104:107], v[224:227], v[166:169], v[104:107]
	v_mfma_f32_16x16x32_bf16 v[96:99], v[216:219], v[174:177], v[96:99]
	v_mfma_f32_16x16x32_bf16 v[88:91], v[224:227], v[174:177], v[88:91]
	v_mfma_f32_16x16x32_bf16 v[80:83], v[216:219], v[182:185], v[80:83]
	v_mfma_f32_16x16x32_bf16 v[72:75], v[224:227], v[182:185], v[72:75]
	v_mfma_f32_16x16x32_bf16 v[68:71], v[216:219], v[200:203], v[68:71]
	v_mfma_f32_16x16x32_bf16 v[64:67], v[224:227], v[200:203], v[64:67]
	v_mfma_f32_16x16x32_bf16 v[112:115], v[220:223], v[170:173], v[112:115]
	v_mfma_f32_16x16x32_bf16 v[104:107], v[228:231], v[170:173], v[104:107]
	v_mfma_f32_16x16x32_bf16 v[96:99], v[220:223], v[178:181], v[96:99]
	v_mfma_f32_16x16x32_bf16 v[88:91], v[228:231], v[178:181], v[88:91]
	v_mfma_f32_16x16x32_bf16 v[80:83], v[220:223], v[196:199], v[80:83]
	v_mfma_f32_16x16x32_bf16 v[72:75], v[228:231], v[196:199], v[72:75]
	v_mfma_f32_16x16x32_bf16 v[68:71], v[220:223], v[204:207], v[68:71]
	v_mfma_f32_16x16x32_bf16 v[64:67], v[228:231], v[204:207], v[64:67]
	s_mov_b32 m0, s72
	v_lshl_add_u64 v[146:147], v[188:189], 0, s[88:89]
	s_barrier
; #define LAS __attribute__((address_space(3)))
; __device__ __forceinline__ unsigned pk2(float lo, float hi) { unsigned r; asm("v_cvt_pk_bf16_f32 %0, %1, %2" : "=v"(r) : "v"(lo), "v"(hi)); return r; }
; #define PG8_WAIT_V(n) asm volatile("s_waitcnt vmcnt(" #n ")" ::: "memory")
; #define PG8_WAIT_L(n) asm volatile("s_waitcnt lgkmcnt(" #n ")" ::: "memory")
; #define PG8_BAR __builtin_amdgcn_s_barrier()
; #define PG8_SCHED __builtin_amdgcn_sched_barrier(0)
; template <class Epi>
; __device__ __forceinline__ void gemm_phase(LAS unsigned char* lds, const Gemm g, const StaticOrder& S, const Epi& E) {
;     ...
;             PG8_BAR; PG8_WAIT_L(0); PG8_MMA(1, 0, At, B0); PG8_BAR; PG8_SCHED;
;             PG8_STAGE(PG8_SB(1, 1), b3 + hB, voffB);
;             PG8_WAIT_V(6); PG8_BAR; PG8_MMA(1, 1, At, B1); PG8_BAR;
;         }
;     __device__ __forceinline__ void operator()(const f32x4 (&acc)[2][2][4][2], const Unit& u, int wr, int wc, int fr, int fq) const {
;         const int col_t = u.pn * BM;
;         if (mode != 0 && col_t >= vt0) {
;             const int bl = u.pm / TPB, key0 = (u.pm - bl * TPB) * 256;
;             LAS bf16_t* sc = (LAS bf16_t*)(trs + (wr * 4 + wc) * 2304);
;             const int lane = fq * 16 + fr;
; #pragma unroll
;             for (int ai = 0; ai < 2; ++ai)
; #pragma unroll
;                 for (int bj = 0; bj < 2; ++bj)
; #pragma unroll
;                     for (int n = 0; n < 2; ++n) {
; #pragma unroll
;                         for (int m = 0; m < 4; ++m) {
;                             const f32x4 v = acc[ai][bj][m][n];
;                             const unsigned p0 = pk2(v[0], v[1]), p1 = pk2(v[2], v[3]);
;                             LAS bf16_t* w = sc + (4 * fq) * 72 + 16 * m + fr;
;                             w[0] = (bf16_t)(p0 & 0xffffu); w[72] = (bf16_t)(p0 >> 16); w[144] = (bf16_t)(p1 & 0xffffu); w[216] = (bf16_t)(p1 >> 16);
;                         }
; #pragma unroll
;                         for (int j = 0; j < 2; ++j) {
;                             const int ch = lane + 64 * j, fi = ch >> 3, seg = ch & 7;
;                             const u32x4 o = *(const LAS u32x4*)(sc + fi * 72 + 8 * seg);
;                             const int f = col_t - vt0 + 64 * wc + 16 * (fi >> 2) + 8 * bj + 4 * n + (fi & 3);
;                             *(u32x4*)(Vt + ((size_t)bl * vtnf + f) * KEYS + key0 + ai * HALF + wr * 64 + 8 * seg) = o;
	ds_read_b128 v[166:169], v154 offset:49152
	ds_read_b128 v[170:173], v154 offset:50176
	ds_read_b128 v[174:177], v154 offset:51200
	ds_read_b128 v[178:181], v154 offset:52224
	ds_read_b128 v[182:185], v154 offset:53248
	ds_read_b128 v[196:199], v154 offset:54272
	ds_read_b128 v[200:203], v154 offset:55296
	ds_read_b128 v[204:207], v154 offset:56320
	global_load_lds_dwordx4 v[146:147], off
	s_mov_b32 m0, s78
	v_lshl_add_u64 v[146:147], v[192:193], 0, s[88:89]
	global_load_lds_dwordx4 v[146:147], off
	s_barrier
	s_waitcnt lgkmcnt(0)
	v_mfma_f32_16x16x32_bf16 v[60:63], v[136:139], v[166:169], v[60:63]
	v_mfma_f32_16x16x32_bf16 v[56:59], v[158:161], v[166:169], v[56:59]
	v_mfma_f32_16x16x32_bf16 v[52:55], v[136:139], v[174:177], v[52:55]
	v_mfma_f32_16x16x32_bf16 v[44:47], v[158:161], v[174:177], v[44:47]
	v_mfma_f32_16x16x32_bf16 v[36:39], v[136:139], v[182:185], v[36:39]
	v_mfma_f32_16x16x32_bf16 v[28:31], v[158:161], v[182:185], v[28:31]
	v_mfma_f32_16x16x32_bf16 v[20:23], v[136:139], v[200:203], v[20:23]
	v_mfma_f32_16x16x32_bf16 v[12:15], v[158:161], v[200:203], v[12:15]
	v_mfma_f32_16x16x32_bf16 v[60:63], v[140:143], v[170:173], v[60:63]
	v_mfma_f32_16x16x32_bf16 v[56:59], v[162:165], v[170:173], v[56:59]
	v_mfma_f32_16x16x32_bf16 v[52:55], v[140:143], v[178:181], v[52:55]
	v_mfma_f32_16x16x32_bf16 v[44:47], v[162:165], v[178:181], v[44:47]
	v_mfma_f32_16x16x32_bf16 v[36:39], v[140:143], v[196:199], v[36:39]
	v_mfma_f32_16x16x32_bf16 v[28:31], v[162:165], v[196:199], v[28:31]
	v_mfma_f32_16x16x32_bf16 v[20:23], v[140:143], v[204:207], v[20:23]
	v_mfma_f32_16x16x32_bf16 v[12:15], v[162:165], v[204:207], v[12:15]
	s_barrier
	s_mov_b32 m0, s31
	v_lshl_add_u64 v[136:137], s[34:35], 0, v[132:133]
	global_load_lds_dwordx4 v[136:137], off
	s_mov_b32 m0, s36
	v_lshl_add_u64 v[136:137], s[34:35], 0, v[128:129]
	global_load_lds_dwordx4 v[136:137], off
	s_waitcnt vmcnt(6)
	s_barrier
	v_mfma_f32_16x16x32_bf16 v[48:51], v[216:219], v[166:169], v[48:51]
	v_mfma_f32_16x16x32_bf16 v[40:43], v[224:227], v[166:169], v[40:43]
	v_mfma_f32_16x16x32_bf16 v[32:35], v[216:219], v[174:177], v[32:35]
	v_mfma_f32_16x16x32_bf16 v[24:27], v[224:227], v[174:177], v[24:27]
	v_mfma_f32_16x16x32_bf16 v[16:19], v[216:219], v[182:185], v[16:19]
	v_mfma_f32_16x16x32_bf16 v[8:11], v[224:227], v[182:185], v[8:11]
	v_mfma_f32_16x16x32_bf16 v[4:7], v[216:219], v[200:203], v[4:7]
	v_mfma_f32_16x16x32_bf16 v[0:3], v[224:227], v[200:203], v[0:3]
	v_mfma_f32_16x16x32_bf16 v[48:51], v[220:223], v[170:173], v[48:51]
	v_mfma_f32_16x16x32_bf16 v[40:43], v[228:231], v[170:173], v[40:43]
	v_mfma_f32_16x16x32_bf16 v[32:35], v[220:223], v[178:181], v[32:35]
	v_mfma_f32_16x16x32_bf16 v[24:27], v[228:231], v[178:181], v[24:27]
	v_mfma_f32_16x16x32_bf16 v[16:19], v[220:223], v[196:199], v[16:19]
	v_mfma_f32_16x16x32_bf16 v[8:11], v[228:231], v[196:199], v[8:11]
	v_mfma_f32_16x16x32_bf16 v[4:7], v[220:223], v[204:207], v[4:7]
	v_mfma_f32_16x16x32_bf16 v[0:3], v[228:231], v[204:207], v[0:3]
	s_movk_i32 s25, 0x100
	s_andn2_b64 vcc, exec, s[4:5]
	s_mov_b64 s[34:35], -1
	s_mov_b64 s[4:5], 0
	s_barrier
	s_cbranch_vccz .LBB0_670
	s_lshl_b32 s13, s15, 8
	s_cmp_lt_i32 s15, 2
	s_mov_b64 s[4:5], -1
	s_cbranch_scc1 .LBB0_673
	s_mul_hi_i32 s4, s81, 0x3e0f83e1
	s_lshr_b32 s5, s4, 31
	s_ashr_i32 s4, s4, 3
	v_cvt_pk_bf16_f32 v136, v124, v125
	s_add_i32 s4, s4, s5
	v_cvt_pk_bf16_f32 v137, v126, v127
	ds_write_b16 v151, v136
	ds_write_b16_d16_hi v151, v136 offset:144
	ds_write_b16 v151, v137 offset:288
	ds_write_b16_d16_hi v151, v137 offset:432
	v_cvt_pk_bf16_f32 v136, v116, v117
	s_mul_i32 s5, s4, 0xffffffdf
	v_cvt_pk_bf16_f32 v137, v118, v119
	ds_write_b16 v151, v136 offset:32
	ds_write_b16_d16_hi v151, v136 offset:176
	ds_write_b16 v151, v137 offset:320
	ds_write_b16_d16_hi v151, v137 offset:464
	v_cvt_pk_bf16_f32 v136, v100, v101
	s_add_i32 s5, s5, s81
	s_or_b32 s15, s13, s79
	v_cvt_pk_bf16_f32 v137, v102, v103
	ds_write_b16 v151, v136 offset:64
	ds_write_b16_d16_hi v151, v136 offset:208
	ds_write_b16 v151, v137 offset:352
	ds_write_b16_d16_hi v151, v137 offset:496
	v_cvt_pk_bf16_f32 v136, v84, v85
	s_lshl_b32 s24, s5, 8
	s_ashr_i32 s5, s4, 31
	v_cvt_pk_bf16_f32 v137, v86, v87
	ds_write_b16 v151, v136 offset:96
	ds_write_b16_d16_hi v151, v136 offset:240
	ds_write_b16 v151, v137 offset:384
	ds_write_b16_d16_hi v151, v137 offset:528
	v_add_u32_e32 v136, s15, v152
	s_lshl_b64 s[4:5], s[4:5], 9
	v_ashrrev_i32_e32 v137, 31, v136
	v_lshl_add_u64 v[136:137], s[4:5], 0, v[136:137]
	v_mov_b64_e32 v[162:163], s[8:9]
	s_ashr_i32 s25, s24, 31
	ds_read_b128 v[138:141], v155
	v_mad_u64_u32 v[142:143], s[26:27], v136, s91, v[162:163]
	v_mad_i32_i24 v143, v137, s91, v143
	s_lshl_b64 s[34:35], s[24:25], 1
	v_lshl_add_u64 v[136:137], v[142:143], 0, s[34:35]
	v_lshl_add_u64 v[136:137], v[136:137], 0, s[10:11]
	v_lshl_add_u64 v[136:137], v[136:137], 0, v[144:145]
	s_waitcnt lgkmcnt(0)
	global_store_dwordx4 v[136:137], v[138:141], off
	ds_read_b128 v[140:143], v156
	s_or_b32 s26, s15, 4
	v_add_u32_e32 v138, s15, v153
	v_ashrrev_i32_e32 v139, 31, v138
	v_lshl_add_u64 v[138:139], s[4:5], 0, v[138:139]
	v_mad_u64_u32 v[146:147], s[24:25], v138, s91, v[162:163]
	v_mad_i32_i24 v147, v139, s91, v147
	v_lshl_add_u64 v[138:139], v[146:147], 0, s[34:35]
	v_lshl_add_u64 v[138:139], v[138:139], 0, s[10:11]
	v_lshl_add_u64 v[138:139], v[138:139], 0, v[144:145]
	s_waitcnt lgkmcnt(0)
; #define LAS __attribute__((address_space(3)))
; __device__ __forceinline__ unsigned pk2(float lo, float hi) { unsigned r; asm("v_cvt_pk_bf16_f32 %0, %1, %2" : "=v"(r) : "v"(lo), "v"(hi)); return r; }
;     __device__ __forceinline__ void operator()(const f32x4 (&acc)[2][2][4][2], const Unit& u, int wr, int wc, int fr, int fq) const {
;     ...
;             LAS bf16_t* sc = (LAS bf16_t*)(trs + (wr * 4 + wc) * 2304);
;             const int lane = fq * 16 + fr;
; #pragma unroll
;             for (int ai = 0; ai < 2; ++ai)
; #pragma unroll
;                 for (int bj = 0; bj < 2; ++bj)
; #pragma unroll
;                     for (int n = 0; n < 2; ++n) {
; #pragma unroll
;                         for (int m = 0; m < 4; ++m) {
;                             const f32x4 v = acc[ai][bj][m][n];
;                             const unsigned p0 = pk2(v[0], v[1]), p1 = pk2(v[2], v[3]);
;                             LAS bf16_t* w = sc + (4 * fq) * 72 + 16 * m + fr;
;                             w[0] = (bf16_t)(p0 & 0xffffu); w[72] = (bf16_t)(p0 >> 16); w[144] = (bf16_t)(p1 & 0xffffu); w[216] = (bf16_t)(p1 >> 16);
;                         }
; #pragma unroll
;                         for (int j = 0; j < 2; ++j) {
;                             const int ch = lane + 64 * j, fi = ch >> 3, seg = ch & 7;
;                             const u32x4 o = *(const LAS u32x4*)(sc + fi * 72 + 8 * seg);
;                             const int f = col_t - vt0 + 64 * wc + 16 * (fi >> 2) + 8 * bj + 4 * n + (fi & 3);
;                             *(u32x4*)(Vt + ((size_t)bl * vtnf + f) * KEYS + key0 + ai * HALF + wr * 64 + 8 * seg) = o;
;                         }
;                     }
	global_store_dwordx4 v[138:139], v[140:143], off
	v_cvt_pk_bf16_f32 v157, v104, v105
	s_nop 1
	v_cvt_pk_bf16_f32 v140, v120, v121
	v_cvt_pk_bf16_f32 v141, v122, v123
	ds_write_b16 v151, v140
	ds_write_b16_d16_hi v151, v140 offset:144
	ds_write_b16 v151, v141 offset:288
	ds_write_b16_d16_hi v151, v141 offset:432
	v_cvt_pk_bf16_f32 v140, v108, v109
	v_cvt_pk_bf16_f32 v141, v110, v111
	ds_write_b16 v151, v140 offset:32
	ds_write_b16_d16_hi v151, v140 offset:176
	ds_write_b16 v151, v141 offset:320
	ds_write_b16_d16_hi v151, v141 offset:464
	v_cvt_pk_bf16_f32 v140, v92, v93
	v_cvt_pk_bf16_f32 v141, v94, v95
	ds_write_b16 v151, v140 offset:64
	ds_write_b16_d16_hi v151, v140 offset:208
	ds_write_b16 v151, v141 offset:352
	ds_write_b16_d16_hi v151, v141 offset:496
	v_cvt_pk_bf16_f32 v140, v76, v77
	v_cvt_pk_bf16_f32 v141, v78, v79
	ds_write_b16 v151, v140 offset:96
	ds_write_b16_d16_hi v151, v140 offset:240
	ds_write_b16 v151, v141 offset:384
	ds_write_b16_d16_hi v151, v141 offset:528
	v_add_u32_e32 v140, s26, v152
	v_ashrrev_i32_e32 v141, 31, v140
	v_lshl_add_u64 v[140:141], s[4:5], 0, v[140:141]
	ds_read_b128 v[158:161], v155
	v_mad_u64_u32 v[142:143], s[24:25], v140, s91, v[162:163]
	v_mad_i32_i24 v143, v141, s91, v143
	v_lshl_add_u64 v[140:141], v[142:143], 0, s[34:35]
	v_add_u32_e32 v142, s26, v153
	v_lshl_add_u64 v[140:141], v[140:141], 0, s[10:11]
	v_ashrrev_i32_e32 v143, 31, v142
	v_lshl_add_u64 v[140:141], v[140:141], 0, v[144:145]
	v_lshl_add_u64 v[142:143], s[4:5], 0, v[142:143]
	s_waitcnt lgkmcnt(0)
	global_store_dwordx4 v[140:141], v[158:161], off
	ds_read_b128 v[158:161], v156
	v_mad_u64_u32 v[146:147], s[24:25], v142, s91, v[162:163]
	v_mad_i32_i24 v147, v143, s91, v147
	v_lshl_add_u64 v[142:143], v[146:147], 0, s[34:35]
	v_lshl_add_u64 v[142:143], v[142:143], 0, s[10:11]
	v_lshl_add_u64 v[142:143], v[142:143], 0, v[144:145]
	v_cvt_pk_bf16_f32 v146, v112, v113
	s_waitcnt lgkmcnt(0)
	global_store_dwordx4 v[142:143], v[158:161], off
	v_cvt_pk_bf16_f32 v147, v114, v115
	ds_write_b16 v151, v146
	ds_write_b16_d16_hi v151, v146 offset:144
	ds_write_b16 v151, v147 offset:288
	ds_write_b16_d16_hi v151, v147 offset:432
	v_cvt_pk_bf16_f32 v146, v96, v97
	v_cvt_pk_bf16_f32 v147, v98, v99
	ds_write_b16 v151, v146 offset:32
	ds_write_b16_d16_hi v151, v146 offset:176
	ds_write_b16 v151, v147 offset:320
	ds_write_b16_d16_hi v151, v147 offset:464
	v_cvt_pk_bf16_f32 v146, v80, v81
	s_or_b32 s26, s15, 8
	v_cvt_pk_bf16_f32 v147, v82, v83
	ds_write_b16 v151, v146 offset:64
	ds_write_b16_d16_hi v151, v146 offset:208
	ds_write_b16 v151, v147 offset:352
	ds_write_b16_d16_hi v151, v147 offset:496
	v_cvt_pk_bf16_f32 v146, v68, v69
	v_cvt_pk_bf16_f32 v147, v70, v71
	ds_write_b16 v151, v146 offset:96
	ds_write_b16_d16_hi v151, v146 offset:240
	ds_write_b16 v151, v147 offset:384
	ds_write_b16_d16_hi v151, v147 offset:528
	v_add_u32_e32 v146, s26, v152
	v_ashrrev_i32_e32 v147, 31, v146
	v_lshl_add_u64 v[146:147], s[4:5], 0, v[146:147]
	ds_read_b128 v[158:161], v155
	v_mad_u64_u32 v[164:165], s[24:25], v146, s91, v[162:163]
	v_mad_i32_i24 v165, v147, s91, v165
	v_lshl_add_u64 v[146:147], v[164:165], 0, s[34:35]
	v_add_u32_e32 v164, s26, v153
	v_lshl_add_u64 v[146:147], v[146:147], 0, s[10:11]
	v_ashrrev_i32_e32 v165, 31, v164
	v_lshl_add_u64 v[146:147], v[146:147], 0, v[144:145]
	v_lshl_add_u64 v[164:165], s[4:5], 0, v[164:165]
	s_waitcnt lgkmcnt(0)
	global_store_dwordx4 v[146:147], v[158:161], off
	ds_read_b128 v[158:161], v156
	v_mad_u64_u32 v[166:167], s[24:25], v164, s91, v[162:163]
	v_mad_i32_i24 v167, v165, s91, v167
	v_lshl_add_u64 v[164:165], v[166:167], 0, s[34:35]
	v_lshl_add_u64 v[164:165], v[164:165], 0, s[10:11]
	v_lshl_add_u64 v[164:165], v[164:165], 0, v[144:145]
	s_waitcnt lgkmcnt(0)
	global_store_dwordx4 v[164:165], v[158:161], off
	s_or_b32 s15, s15, 12
	v_add_u32_e32 v166, s15, v152
	v_cvt_pk_bf16_f32 v158, v106, v107
	ds_write_b16 v151, v157
	ds_write_b16_d16_hi v151, v157 offset:144
	ds_write_b16 v151, v158 offset:288
	ds_write_b16_d16_hi v151, v158 offset:432
	v_cvt_pk_bf16_f32 v157, v88, v89
	v_cvt_pk_bf16_f32 v158, v90, v91
	ds_write_b16 v151, v157 offset:32
	ds_write_b16_d16_hi v151, v157 offset:176
	ds_write_b16 v151, v158 offset:320
	ds_write_b16_d16_hi v151, v158 offset:464
	v_cvt_pk_bf16_f32 v157, v72, v73
	v_cvt_pk_bf16_f32 v158, v74, v75
	ds_write_b16 v151, v157 offset:64
	ds_write_b16_d16_hi v151, v157 offset:208
	ds_write_b16 v151, v158 offset:352
	ds_write_b16_d16_hi v151, v158 offset:496
	v_cvt_pk_bf16_f32 v157, v64, v65
	v_ashrrev_i32_e32 v167, 31, v166
	v_cvt_pk_bf16_f32 v158, v66, v67
	ds_write_b16 v151, v157 offset:96
	ds_write_b16_d16_hi v151, v157 offset:240
	ds_write_b16 v151, v158 offset:384
	ds_write_b16_d16_hi v151, v158 offset:528
	v_lshl_add_u64 v[166:167], s[4:5], 0, v[166:167]
	ds_read_b128 v[158:161], v155
	v_mad_u64_u32 v[168:169], s[24:25], v166, s91, v[162:163]
	v_mad_i32_i24 v169, v167, s91, v169
	v_lshl_add_u64 v[166:167], v[168:169], 0, s[34:35]
	v_add_u32_e32 v168, s15, v153
	v_lshl_add_u64 v[166:167], v[166:167], 0, s[10:11]
	v_ashrrev_i32_e32 v169, 31, v168
	v_lshl_add_u64 v[166:167], v[166:167], 0, v[144:145]
	v_lshl_add_u64 v[168:169], s[4:5], 0, v[168:169]
	s_waitcnt lgkmcnt(0)
; #define LAS __attribute__((address_space(3)))
; __device__ __forceinline__ unsigned pk2(float lo, float hi) { unsigned r; asm("v_cvt_pk_bf16_f32 %0, %1, %2" : "=v"(r) : "v"(lo), "v"(hi)); return r; }
;     __device__ __forceinline__ void operator()(const f32x4 (&acc)[2][2][4][2], const Unit& u, int wr, int wc, int fr, int fq) const {
;     ...
;             LAS bf16_t* sc = (LAS bf16_t*)(trs + (wr * 4 + wc) * 2304);
;             const int lane = fq * 16 + fr;
; #pragma unroll
;             for (int ai = 0; ai < 2; ++ai)
; #pragma unroll
;                 for (int bj = 0; bj < 2; ++bj)
; #pragma unroll
;                     for (int n = 0; n < 2; ++n) {
; #pragma unroll
;                         for (int m = 0; m < 4; ++m) {
;                             const f32x4 v = acc[ai][bj][m][n];
;                             const unsigned p0 = pk2(v[0], v[1]), p1 = pk2(v[2], v[3]);
;                             LAS bf16_t* w = sc + (4 * fq) * 72 + 16 * m + fr;
;                             w[0] = (bf16_t)(p0 & 0xffffu); w[72] = (bf16_t)(p0 >> 16); w[144] = (bf16_t)(p1 & 0xffffu); w[216] = (bf16_t)(p1 >> 16);
;                         }
; #pragma unroll
;                         for (int j = 0; j < 2; ++j) {
;                             const int ch = lane + 64 * j, fi = ch >> 3, seg = ch & 7;
;                             const u32x4 o = *(const LAS u32x4*)(sc + fi * 72 + 8 * seg);
;                             const int f = col_t - vt0 + 64 * wc + 16 * (fi >> 2) + 8 * bj + 4 * n + (fi & 3);
;                             *(u32x4*)(Vt + ((size_t)bl * vtnf + f) * KEYS + key0 + ai * HALF + wr * 64 + 8 * seg) = o;
;                         }
;                     }
	global_store_dwordx4 v[166:167], v[158:161], off
	ds_read_b128 v[158:161], v156
	v_mad_u64_u32 v[162:163], s[4:5], v168, s91, v[162:163]
	v_mad_i32_i24 v163, v169, s91, v163
	v_lshl_add_u64 v[162:163], v[162:163], 0, s[34:35]
	v_lshl_add_u64 v[162:163], v[162:163], 0, s[10:11]
	v_lshl_add_u64 v[162:163], v[162:163], 0, v[144:145]
	v_cvt_pk_bf16_f32 v157, v60, v61
	s_waitcnt lgkmcnt(0)
	global_store_dwordx4 v[162:163], v[158:161], off
	s_mov_b64 s[4:5], 0
	s_nop 0
	v_cvt_pk_bf16_f32 v158, v62, v63
	ds_write_b16 v151, v157
	ds_write_b16_d16_hi v151, v157 offset:144
	ds_write_b16 v151, v158 offset:288
	ds_write_b16_d16_hi v151, v158 offset:432
	v_cvt_pk_bf16_f32 v157, v52, v53
	v_cvt_pk_bf16_f32 v158, v54, v55
	ds_write_b16 v151, v157 offset:32
	ds_write_b16_d16_hi v151, v157 offset:176
	ds_write_b16 v151, v158 offset:320
	ds_write_b16_d16_hi v151, v158 offset:464
	v_cvt_pk_bf16_f32 v157, v36, v37
	v_cvt_pk_bf16_f32 v158, v38, v39
	ds_write_b16 v151, v157 offset:64
	ds_write_b16_d16_hi v151, v157 offset:208
	ds_write_b16 v151, v158 offset:352
	ds_write_b16_d16_hi v151, v158 offset:496
	v_cvt_pk_bf16_f32 v157, v20, v21
	v_cvt_pk_bf16_f32 v158, v22, v23
	ds_write_b16 v151, v157 offset:96
	ds_write_b16_d16_hi v151, v157 offset:240
	ds_write_b16 v151, v158 offset:384
	ds_write_b16_d16_hi v151, v158 offset:528
	ds_read_b128 v[158:161], v155
	s_waitcnt lgkmcnt(0)
	global_store_dwordx4 v[136:137], v[158:161], off offset:256
	ds_read_b128 v[158:161], v156
	v_cvt_pk_bf16_f32 v136, v56, v57
	v_cvt_pk_bf16_f32 v137, v58, v59
	s_waitcnt lgkmcnt(0)
	global_store_dwordx4 v[138:139], v[158:161], off offset:256
	ds_write_b16 v151, v136
	ds_write_b16_d16_hi v151, v136 offset:144
	ds_write_b16 v151, v137 offset:288
	ds_write_b16_d16_hi v151, v137 offset:432
	v_cvt_pk_bf16_f32 v136, v44, v45
	v_cvt_pk_bf16_f32 v137, v46, v47
	ds_write_b16 v151, v136 offset:32
	ds_write_b16_d16_hi v151, v136 offset:176
	ds_write_b16 v151, v137 offset:320
	ds_write_b16_d16_hi v151, v137 offset:464
	v_cvt_pk_bf16_f32 v136, v28, v29
	v_cvt_pk_bf16_f32 v137, v30, v31
	ds_write_b16 v151, v136 offset:64
	ds_write_b16_d16_hi v151, v136 offset:208
	ds_write_b16 v151, v137 offset:352
	ds_write_b16_d16_hi v151, v137 offset:496
	v_cvt_pk_bf16_f32 v136, v12, v13
	v_cvt_pk_bf16_f32 v137, v14, v15
	ds_write_b16 v151, v136 offset:96
	ds_write_b16_d16_hi v151, v136 offset:240
	ds_write_b16 v151, v137 offset:384
	ds_write_b16_d16_hi v151, v137 offset:528
	ds_read_b128 v[136:139], v155
	s_waitcnt lgkmcnt(0)
	global_store_dwordx4 v[140:141], v[136:139], off offset:256
	ds_read_b128 v[136:139], v156
	s_waitcnt lgkmcnt(0)
	global_store_dwordx4 v[142:143], v[136:139], off offset:256
	s_nop 1
	v_cvt_pk_bf16_f32 v136, v48, v49
	v_cvt_pk_bf16_f32 v137, v50, v51
	ds_write_b16 v151, v136
	ds_write_b16_d16_hi v151, v136 offset:144
	ds_write_b16 v151, v137 offset:288
	ds_write_b16_d16_hi v151, v137 offset:432
	v_cvt_pk_bf16_f32 v136, v32, v33
	v_cvt_pk_bf16_f32 v137, v34, v35
	ds_write_b16 v151, v136 offset:32
	ds_write_b16_d16_hi v151, v136 offset:176
	ds_write_b16 v151, v137 offset:320
	ds_write_b16_d16_hi v151, v137 offset:464
	v_cvt_pk_bf16_f32 v136, v16, v17
	v_cvt_pk_bf16_f32 v137, v18, v19
	ds_write_b16 v151, v136 offset:64
	ds_write_b16_d16_hi v151, v136 offset:208
	ds_write_b16 v151, v137 offset:352
	ds_write_b16_d16_hi v151, v137 offset:496
	v_cvt_pk_bf16_f32 v136, v4, v5
	v_cvt_pk_bf16_f32 v137, v6, v7
	ds_write_b16 v151, v136 offset:96
	ds_write_b16_d16_hi v151, v136 offset:240
	ds_write_b16 v151, v137 offset:384
	ds_write_b16_d16_hi v151, v137 offset:528
	ds_read_b128 v[136:139], v155
	s_waitcnt lgkmcnt(0)
	global_store_dwordx4 v[146:147], v[136:139], off offset:256
	ds_read_b128 v[136:139], v156
	s_waitcnt lgkmcnt(0)
	global_store_dwordx4 v[164:165], v[136:139], off offset:256
	s_nop 1
	v_cvt_pk_bf16_f32 v136, v40, v41
	v_cvt_pk_bf16_f32 v137, v42, v43
	ds_write_b16 v151, v136
	ds_write_b16_d16_hi v151, v136 offset:144
	ds_write_b16 v151, v137 offset:288
	ds_write_b16_d16_hi v151, v137 offset:432
	v_cvt_pk_bf16_f32 v136, v24, v25
	v_cvt_pk_bf16_f32 v137, v26, v27
	ds_write_b16 v151, v136 offset:32
	ds_write_b16_d16_hi v151, v136 offset:176
	ds_write_b16 v151, v137 offset:320
	ds_write_b16_d16_hi v151, v137 offset:464
	v_cvt_pk_bf16_f32 v136, v8, v9
	v_cvt_pk_bf16_f32 v137, v10, v11
	ds_write_b16 v151, v136 offset:64
	ds_write_b16_d16_hi v151, v136 offset:208
	ds_write_b16 v151, v137 offset:352
	ds_write_b16_d16_hi v151, v137 offset:496
	v_cvt_pk_bf16_f32 v136, v0, v1
	v_cvt_pk_bf16_f32 v137, v2, v3
	ds_write_b16 v151, v136 offset:96
	ds_write_b16_d16_hi v151, v136 offset:240
	ds_write_b16 v151, v137 offset:384
	ds_write_b16_d16_hi v151, v137 offset:528
	ds_read_b128 v[136:139], v155
	s_waitcnt lgkmcnt(0)
	global_store_dwordx4 v[166:167], v[136:139], off offset:256
	ds_read_b128 v[136:139], v156
	s_waitcnt lgkmcnt(0)
	global_store_dwordx4 v[162:163], v[136:139], off offset:256

; #define PG8_STAGE(bufoff, gbase, voff) do { _Pragma("unroll") for (int _i = 0; _i < 2; ++_i) \
;         __builtin_amdgcn_global_load_lds((const unsigned*)((const char*)(gbase) + (voff)[_i]), (LAS unsigned*)(lds + (bufoff) + ldsw + _i * 8192), 16, 0, 0); } while (0)
; #define PG8_LDA(dst, b, h) do { _Pragma("unroll") for (int m = 0; m < 4; ++m) _Pragma("unroll") for (int k = 0; k < 2; ++k) dst[m][k] = *(const LAS bf16x8*)(lds + PG8_SA(b, h) + aoff + m * 2048 + k * 1024); } while (0)
; #define PG8_LDB(dst, b, h) do { _Pragma("unroll") for (int n = 0; n < 2; ++n) _Pragma("unroll") for (int k = 0; k < 2; ++k) dst[n][k] = *(const LAS bf16x8*)(lds + PG8_SB(b, h) + boff + n * 2048 + k * 1024); } while (0)
; #define PG8_MMA(ai, bj, At, Bt) do { __builtin_amdgcn_s_setprio(1); _Pragma("unroll") for (int m = 0; m < 4; ++m) _Pragma("unroll") for (int n = 0; n < 2; ++n) _Pragma("unroll") for (int k = 0; k < 2; ++k) \
;         acc[ai][bj][m][n] = __builtin_amdgcn_mfma_f32_16x16x32_bf16(Bt[n][k], At[m][k], acc[ai][bj][m][n], 0, 0, 0); __builtin_amdgcn_s_setprio(0); } while (0)
; #define PG8_WAIT_L(n) asm volatile("s_waitcnt lgkmcnt(" #n ")" ::: "memory")
; #define PG8_BAR __builtin_amdgcn_s_barrier()
; #define PG8_SCHED __builtin_amdgcn_sched_barrier(0)
; template <class Epi>
; __device__ __forceinline__ void gemm_phase(LAS unsigned char* lds, const Gemm g, const StaticOrder& S, const Epi& E) {
;     ...
;         for (int t = 0; t < nt; t += 2) {
;             const bool last = (t == nt - 2);
;             const char* a1 = cA + (size_t)(t + 1) * kstep;
;             const char* a2 = last ? nA : cA + (size_t)(t + 2) * kstep; const char* b2 = last ? nB : cB + (size_t)(t + 2) * kstep;
;             const char* a3 = a2 + kstep; const char* b3 = b2 + kstep;
;             PG8_LDB(B0, 0, 0); PG8_SCHED; PG8_LDA(At, 0, 0); PG8_STAGE(PG8_SA(1, 1), a1 + hA, voffA);
;             PG8_WAIT_L(8); PG8_BAR; PG8_WAIT_L(0); PG8_MMA(0, 0, At, B0); PG8_BAR; PG8_SCHED;
;             PG8_LDB(B1, 0, 1); PG8_STAGE(PG8_SB(0, 0), b2, voffB);
;             PG8_BAR; PG8_WAIT_L(0); PG8_MMA(0, 1, At, B1); PG8_BAR;
;             PG8_LDA(At, 0, 1); PG8_STAGE(PG8_SA(0, 0), a2, voffA);
;             PG8_BAR; PG8_WAIT_L(0); PG8_MMA(1, 0, At, B0); PG8_BAR; PG8_SCHED;
.LBB0_985:
	s_add_u32 s12, s10, 0x100
	s_addc_u32 s13, s11, 0
	s_add_i32 s26, 0, 0x10000
	v_add_u32_e32 v142, s26, v139
	ds_read_b128 v[134:137], v142
	ds_read_b128 v[146:149], v142 offset:1024
	ds_read_b128 v[150:153], v142 offset:2048
	ds_read_b128 v[154:157], v142 offset:3072
	s_cmp_eq_u32 s72, 20
	s_cselect_b32 s21, s5, s13
	s_cselect_b32 s20, s4, s12
	s_cselect_b32 s17, s7, s25
	s_cselect_b32 s16, s6, s24
	v_lshl_add_u64 v[142:143], s[10:11], 0, v[130:131]
	s_add_i32 m0, s61, 0xc000
	ds_read_b128 v[158:161], v141
	ds_read_b128 v[162:165], v141 offset:1024
	ds_read_b128 v[166:169], v141 offset:2048
	ds_read_b128 v[170:173], v141 offset:3072
	ds_read_b128 v[174:177], v141 offset:4096
	ds_read_b128 v[178:181], v141 offset:5120
	ds_read_b128 v[182:185], v141 offset:6144
	ds_read_b128 v[186:189], v141 offset:7168
	global_load_lds_dwordx4 v[142:143], off
	s_add_i32 m0, s61, 0xe000
	v_lshl_add_u64 v[142:143], s[10:11], 0, v[132:133]
	global_load_lds_dwordx4 v[142:143], off
	s_waitcnt lgkmcnt(8)
	s_barrier
	s_waitcnt lgkmcnt(0)
	v_mfma_f32_16x16x32_bf16 v[124:127], v[134:137], v[158:161], v[124:127]
	v_mfma_f32_16x16x32_bf16 v[120:123], v[150:153], v[158:161], v[120:123]
	v_mfma_f32_16x16x32_bf16 v[116:119], v[134:137], v[166:169], v[116:119]
	v_mfma_f32_16x16x32_bf16 v[108:111], v[150:153], v[166:169], v[108:111]
	v_mfma_f32_16x16x32_bf16 v[100:103], v[134:137], v[174:177], v[100:103]
	v_mfma_f32_16x16x32_bf16 v[92:95], v[150:153], v[174:177], v[92:95]
	v_mfma_f32_16x16x32_bf16 v[84:87], v[134:137], v[182:185], v[84:87]
	v_mfma_f32_16x16x32_bf16 v[76:79], v[150:153], v[182:185], v[76:79]
	v_mfma_f32_16x16x32_bf16 v[124:127], v[146:149], v[162:165], v[124:127]
	v_mfma_f32_16x16x32_bf16 v[120:123], v[154:157], v[162:165], v[120:123]
	v_mfma_f32_16x16x32_bf16 v[116:119], v[146:149], v[170:173], v[116:119]
	v_mfma_f32_16x16x32_bf16 v[108:111], v[154:157], v[170:173], v[108:111]
	v_mfma_f32_16x16x32_bf16 v[100:103], v[146:149], v[178:181], v[100:103]
	v_mfma_f32_16x16x32_bf16 v[92:95], v[154:157], v[178:181], v[92:95]
	v_mfma_f32_16x16x32_bf16 v[84:87], v[146:149], v[186:189], v[84:87]
	v_mfma_f32_16x16x32_bf16 v[76:79], v[154:157], v[186:189], v[76:79]
	s_barrier
	s_add_i32 s27, 0, 0x14000
	v_add_u32_e32 v142, s27, v139
	s_add_i32 s10, s26, s35
	ds_read_b128 v[196:199], v142
	ds_read_b128 v[200:203], v142 offset:1024
	ds_read_b128 v[204:207], v142 offset:2048
	ds_read_b128 v[214:217], v142 offset:3072
	v_lshl_add_u64 v[142:143], s[16:17], 0, v[144:145]
	s_mov_b32 m0, s10
	v_lshl_add_u64 v[192:193], s[16:17], 0, v[128:129]
	global_load_lds_dwordx4 v[142:143], off
	s_add_i32 m0, s10, 0x2000
	s_nop 0
	global_load_lds_dwordx4 v[192:193], off
	s_barrier
	s_waitcnt lgkmcnt(0)
	v_mfma_f32_16x16x32_bf16 v[112:115], v[196:199], v[158:161], v[112:115]
	v_mfma_f32_16x16x32_bf16 v[104:107], v[204:207], v[158:161], v[104:107]
	v_mfma_f32_16x16x32_bf16 v[96:99], v[196:199], v[166:169], v[96:99]
	v_mfma_f32_16x16x32_bf16 v[88:91], v[204:207], v[166:169], v[88:91]
	v_mfma_f32_16x16x32_bf16 v[80:83], v[196:199], v[174:177], v[80:83]
	v_mfma_f32_16x16x32_bf16 v[72:75], v[204:207], v[174:177], v[72:75]
	v_mfma_f32_16x16x32_bf16 v[68:71], v[196:199], v[182:185], v[68:71]
	v_mfma_f32_16x16x32_bf16 v[64:67], v[204:207], v[182:185], v[64:67]
	v_mfma_f32_16x16x32_bf16 v[112:115], v[200:203], v[162:165], v[112:115]
	v_mfma_f32_16x16x32_bf16 v[104:107], v[214:217], v[162:165], v[104:107]
	v_mfma_f32_16x16x32_bf16 v[96:99], v[200:203], v[170:173], v[96:99]
	v_mfma_f32_16x16x32_bf16 v[88:91], v[214:217], v[170:173], v[88:91]
	v_mfma_f32_16x16x32_bf16 v[80:83], v[200:203], v[178:181], v[80:83]
	v_mfma_f32_16x16x32_bf16 v[72:75], v[214:217], v[178:181], v[72:75]
	v_mfma_f32_16x16x32_bf16 v[68:71], v[200:203], v[186:189], v[68:71]
	v_mfma_f32_16x16x32_bf16 v[64:67], v[214:217], v[186:189], v[64:67]
	s_mov_b32 m0, s61
	v_lshl_add_u64 v[218:219], s[20:21], 0, v[144:145]
	s_barrier
	ds_read_b128 v[158:161], v141 offset:16384
	ds_read_b128 v[162:165], v141 offset:17408
	ds_read_b128 v[166:169], v141 offset:18432
	ds_read_b128 v[170:173], v141 offset:19456
	ds_read_b128 v[174:177], v141 offset:20480
	ds_read_b128 v[178:181], v141 offset:21504
	ds_read_b128 v[182:185], v141 offset:22528
	ds_read_b128 v[186:189], v141 offset:23552
	global_load_lds_dwordx4 v[218:219], off
	s_mov_b32 m0, s62
	v_lshl_add_u64 v[220:221], s[20:21], 0, v[128:129]
	global_load_lds_dwordx4 v[220:221], off
	s_barrier
	s_waitcnt lgkmcnt(0)
	v_mfma_f32_16x16x32_bf16 v[60:63], v[134:137], v[158:161], v[60:63]
	v_mfma_f32_16x16x32_bf16 v[56:59], v[150:153], v[158:161], v[56:59]
	v_mfma_f32_16x16x32_bf16 v[52:55], v[134:137], v[166:169], v[52:55]
	v_mfma_f32_16x16x32_bf16 v[44:47], v[150:153], v[166:169], v[44:47]
	v_mfma_f32_16x16x32_bf16 v[36:39], v[134:137], v[174:177], v[36:39]
	v_mfma_f32_16x16x32_bf16 v[28:31], v[150:153], v[174:177], v[28:31]
	v_mfma_f32_16x16x32_bf16 v[20:23], v[134:137], v[182:185], v[20:23]
	v_mfma_f32_16x16x32_bf16 v[12:15], v[150:153], v[182:185], v[12:15]
	v_mfma_f32_16x16x32_bf16 v[60:63], v[146:149], v[162:165], v[60:63]
	v_mfma_f32_16x16x32_bf16 v[56:59], v[154:157], v[162:165], v[56:59]
	v_mfma_f32_16x16x32_bf16 v[52:55], v[146:149], v[170:173], v[52:55]
	v_mfma_f32_16x16x32_bf16 v[44:47], v[154:157], v[170:173], v[44:47]
	v_mfma_f32_16x16x32_bf16 v[36:39], v[146:149], v[178:181], v[36:39]
	v_mfma_f32_16x16x32_bf16 v[28:31], v[154:157], v[178:181], v[28:31]
	v_mfma_f32_16x16x32_bf16 v[20:23], v[146:149], v[186:189], v[20:23]
	v_mfma_f32_16x16x32_bf16 v[12:15], v[154:157], v[186:189], v[12:15]
	s_barrier
; #define PG8_STAGE(bufoff, gbase, voff) do { _Pragma("unroll") for (int _i = 0; _i < 2; ++_i) \
;         __builtin_amdgcn_global_load_lds((const unsigned*)((const char*)(gbase) + (voff)[_i]), (LAS unsigned*)(lds + (bufoff) + ldsw + _i * 8192), 16, 0, 0); } while (0)
; #define PG8_LDA(dst, b, h) do { _Pragma("unroll") for (int m = 0; m < 4; ++m) _Pragma("unroll") for (int k = 0; k < 2; ++k) dst[m][k] = *(const LAS bf16x8*)(lds + PG8_SA(b, h) + aoff + m * 2048 + k * 1024); } while (0)
; #define PG8_LDB(dst, b, h) do { _Pragma("unroll") for (int n = 0; n < 2; ++n) _Pragma("unroll") for (int k = 0; k < 2; ++k) dst[n][k] = *(const LAS bf16x8*)(lds + PG8_SB(b, h) + boff + n * 2048 + k * 1024); } while (0)
; #define PG8_MMA(ai, bj, At, Bt) do { __builtin_amdgcn_s_setprio(1); _Pragma("unroll") for (int m = 0; m < 4; ++m) _Pragma("unroll") for (int n = 0; n < 2; ++n) _Pragma("unroll") for (int k = 0; k < 2; ++k) \
;         acc[ai][bj][m][n] = __builtin_amdgcn_mfma_f32_16x16x32_bf16(Bt[n][k], At[m][k], acc[ai][bj][m][n], 0, 0, 0); __builtin_amdgcn_s_setprio(0); } while (0)
; #define PG8_WAIT_V(n) asm volatile("s_waitcnt vmcnt(" #n ")" ::: "memory")
; #define PG8_WAIT_L(n) asm volatile("s_waitcnt lgkmcnt(" #n ")" ::: "memory")
; #define PG8_BAR __builtin_amdgcn_s_barrier()
; #define PG8_SCHED __builtin_amdgcn_sched_barrier(0)
; template <class Epi>
; __device__ __forceinline__ void gemm_phase(LAS unsigned char* lds, const Gemm g, const StaticOrder& S, const Epi& E) {
;     ...
;             PG8_STAGE(PG8_SB(0, 1), b2 + hB, voffB);
;             PG8_WAIT_V(6); PG8_BAR; PG8_MMA(1, 1, At, B1); PG8_BAR;
;             PG8_LDB(B0, 1, 0); PG8_SCHED; PG8_LDA(At, 1, 0); PG8_STAGE(PG8_SA(0, 1), a2 + hA, voffA);
;             PG8_WAIT_L(8); PG8_BAR; PG8_WAIT_L(0); PG8_MMA(0, 0, At, B0); PG8_BAR; PG8_SCHED;
;             PG8_LDB(B1, 1, 1); PG8_STAGE(PG8_SB(1, 0), b3, voffB);
;             PG8_BAR; PG8_WAIT_L(0); PG8_MMA(0, 1, At, B1); PG8_BAR;
	s_add_u32 s10, s16, 0x60000
	s_addc_u32 s11, s17, 0
	s_add_i32 s26, s27, s35
	s_mov_b32 m0, s26
	v_lshl_add_u64 v[134:135], s[10:11], 0, v[144:145]
	global_load_lds_dwordx4 v[134:135], off
	s_add_i32 m0, s26, 0x2000
	v_lshl_add_u64 v[134:135], s[10:11], 0, v[128:129]
	global_load_lds_dwordx4 v[134:135], off
	s_waitcnt vmcnt(6)
	s_barrier
	v_mfma_f32_16x16x32_bf16 v[48:51], v[196:199], v[158:161], v[48:51]
	v_mfma_f32_16x16x32_bf16 v[40:43], v[204:207], v[158:161], v[40:43]
	v_mfma_f32_16x16x32_bf16 v[32:35], v[196:199], v[166:169], v[32:35]
	v_mfma_f32_16x16x32_bf16 v[24:27], v[204:207], v[166:169], v[24:27]
	v_mfma_f32_16x16x32_bf16 v[16:19], v[196:199], v[174:177], v[16:19]
	v_mfma_f32_16x16x32_bf16 v[8:11], v[204:207], v[174:177], v[8:11]
	v_mfma_f32_16x16x32_bf16 v[4:7], v[196:199], v[182:185], v[4:7]
	v_mfma_f32_16x16x32_bf16 v[0:3], v[204:207], v[182:185], v[0:3]
	v_mfma_f32_16x16x32_bf16 v[48:51], v[200:203], v[162:165], v[48:51]
	v_mfma_f32_16x16x32_bf16 v[40:43], v[214:217], v[162:165], v[40:43]
	v_mfma_f32_16x16x32_bf16 v[32:35], v[200:203], v[170:173], v[32:35]
	v_mfma_f32_16x16x32_bf16 v[24:27], v[214:217], v[170:173], v[24:27]
	v_mfma_f32_16x16x32_bf16 v[16:19], v[200:203], v[178:181], v[16:19]
	v_mfma_f32_16x16x32_bf16 v[8:11], v[214:217], v[178:181], v[8:11]
	v_mfma_f32_16x16x32_bf16 v[4:7], v[200:203], v[186:189], v[4:7]
	v_mfma_f32_16x16x32_bf16 v[0:3], v[214:217], v[186:189], v[0:3]
	s_add_i32 s26, 0, 0x18000
	v_add_u32_e32 v154, s26, v139
	s_barrier
	ds_read_b128 v[134:137], v154
	ds_read_b128 v[146:149], v154 offset:1024
	ds_read_b128 v[150:153], v154 offset:2048
	ds_read_b128 v[154:157], v154 offset:3072
	s_add_u32 s10, s20, 0x60000
	s_addc_u32 s11, s21, 0
	s_mov_b32 m0, s63
	v_lshl_add_u64 v[196:197], s[10:11], 0, v[144:145]
	ds_read_b128 v[158:161], v141 offset:32768
	ds_read_b128 v[162:165], v141 offset:33792
	ds_read_b128 v[166:169], v141 offset:34816
	ds_read_b128 v[170:173], v141 offset:35840
	ds_read_b128 v[174:177], v141 offset:36864
	ds_read_b128 v[178:181], v141 offset:37888
	ds_read_b128 v[182:185], v141 offset:38912
	ds_read_b128 v[186:189], v141 offset:39936
	global_load_lds_dwordx4 v[196:197], off
	s_mov_b32 m0, s64
	v_lshl_add_u64 v[196:197], s[10:11], 0, v[128:129]
	global_load_lds_dwordx4 v[196:197], off
	s_waitcnt lgkmcnt(8)
	s_barrier
	s_waitcnt lgkmcnt(0)
	v_mfma_f32_16x16x32_bf16 v[124:127], v[134:137], v[158:161], v[124:127]
	v_mfma_f32_16x16x32_bf16 v[120:123], v[150:153], v[158:161], v[120:123]
	v_mfma_f32_16x16x32_bf16 v[116:119], v[134:137], v[166:169], v[116:119]
	v_mfma_f32_16x16x32_bf16 v[108:111], v[150:153], v[166:169], v[108:111]
	v_mfma_f32_16x16x32_bf16 v[100:103], v[134:137], v[174:177], v[100:103]
	v_mfma_f32_16x16x32_bf16 v[92:95], v[150:153], v[174:177], v[92:95]
	v_mfma_f32_16x16x32_bf16 v[84:87], v[134:137], v[182:185], v[84:87]
	v_mfma_f32_16x16x32_bf16 v[76:79], v[150:153], v[182:185], v[76:79]
	v_mfma_f32_16x16x32_bf16 v[124:127], v[146:149], v[162:165], v[124:127]
	v_mfma_f32_16x16x32_bf16 v[120:123], v[154:157], v[162:165], v[120:123]
	v_mfma_f32_16x16x32_bf16 v[116:119], v[146:149], v[170:173], v[116:119]
	v_mfma_f32_16x16x32_bf16 v[108:111], v[154:157], v[170:173], v[108:111]
	v_mfma_f32_16x16x32_bf16 v[100:103], v[146:149], v[178:181], v[100:103]
	v_mfma_f32_16x16x32_bf16 v[92:95], v[154:157], v[178:181], v[92:95]
	v_mfma_f32_16x16x32_bf16 v[84:87], v[146:149], v[186:189], v[84:87]
	v_mfma_f32_16x16x32_bf16 v[76:79], v[154:157], v[186:189], v[76:79]
	s_barrier
	s_add_i32 s20, 0, 0x1c000
	s_add_i32 s10, s26, s35
	v_add_u32_e32 v190, s20, v139
	v_lshl_add_u64 v[142:143], v[142:143], 0, s[88:89]
	s_mov_b32 m0, s10
	ds_read_b128 v[196:199], v190
	ds_read_b128 v[200:203], v190 offset:1024
	ds_read_b128 v[204:207], v190 offset:2048
	ds_read_b128 v[214:217], v190 offset:3072
	global_load_lds_dwordx4 v[142:143], off
	s_add_i32 m0, s10, 0x2000
	v_lshl_add_u64 v[142:143], v[192:193], 0, s[88:89]
	global_load_lds_dwordx4 v[142:143], off
	s_barrier
; #define PG8_STAGE(bufoff, gbase, voff) do { _Pragma("unroll") for (int _i = 0; _i < 2; ++_i) \
;         __builtin_amdgcn_global_load_lds((const unsigned*)((const char*)(gbase) + (voff)[_i]), (LAS unsigned*)(lds + (bufoff) + ldsw + _i * 8192), 16, 0, 0); } while (0)
; #define PG8_LDA(dst, b, h) do { _Pragma("unroll") for (int m = 0; m < 4; ++m) _Pragma("unroll") for (int k = 0; k < 2; ++k) dst[m][k] = *(const LAS bf16x8*)(lds + PG8_SA(b, h) + aoff + m * 2048 + k * 1024); } while (0)
; #define PG8_MMA(ai, bj, At, Bt) do { __builtin_amdgcn_s_setprio(1); _Pragma("unroll") for (int m = 0; m < 4; ++m) _Pragma("unroll") for (int n = 0; n < 2; ++n) _Pragma("unroll") for (int k = 0; k < 2; ++k) \
;         acc[ai][bj][m][n] = __builtin_amdgcn_mfma_f32_16x16x32_bf16(Bt[n][k], At[m][k], acc[ai][bj][m][n], 0, 0, 0); __builtin_amdgcn_s_setprio(0); } while (0)
; #define PG8_WAIT_V(n) asm volatile("s_waitcnt vmcnt(" #n ")" ::: "memory")
; #define PG8_WAIT_L(n) asm volatile("s_waitcnt lgkmcnt(" #n ")" ::: "memory")
; #define PG8_BAR __builtin_amdgcn_s_barrier()
; #define PG8_SCHED __builtin_amdgcn_sched_barrier(0)
; template <class Epi>
; __device__ __forceinline__ void gemm_phase(LAS unsigned char* lds, const Gemm g, const StaticOrder& S, const Epi& E) {
;     ...
;             PG8_BAR; PG8_WAIT_L(0); PG8_MMA(0, 1, At, B1); PG8_BAR;
;             PG8_LDA(At, 1, 1); PG8_STAGE(PG8_SA(1, 0), a3, voffA);
;             PG8_BAR; PG8_WAIT_L(0); PG8_MMA(1, 0, At, B0); PG8_BAR; PG8_SCHED;
;             PG8_STAGE(PG8_SB(1, 1), b3 + hB, voffB);
;             PG8_WAIT_V(6); PG8_BAR; PG8_MMA(1, 1, At, B1); PG8_BAR;
	s_waitcnt lgkmcnt(0)
	v_mfma_f32_16x16x32_bf16 v[112:115], v[196:199], v[158:161], v[112:115]
	v_mfma_f32_16x16x32_bf16 v[104:107], v[204:207], v[158:161], v[104:107]
	v_mfma_f32_16x16x32_bf16 v[96:99], v[196:199], v[166:169], v[96:99]
	v_mfma_f32_16x16x32_bf16 v[88:91], v[204:207], v[166:169], v[88:91]
	v_mfma_f32_16x16x32_bf16 v[80:83], v[196:199], v[174:177], v[80:83]
	v_mfma_f32_16x16x32_bf16 v[72:75], v[204:207], v[174:177], v[72:75]
	v_mfma_f32_16x16x32_bf16 v[68:71], v[196:199], v[182:185], v[68:71]
	v_mfma_f32_16x16x32_bf16 v[64:67], v[204:207], v[182:185], v[64:67]
	v_mfma_f32_16x16x32_bf16 v[112:115], v[200:203], v[162:165], v[112:115]
	v_mfma_f32_16x16x32_bf16 v[104:107], v[214:217], v[162:165], v[104:107]
	v_mfma_f32_16x16x32_bf16 v[96:99], v[200:203], v[170:173], v[96:99]
	v_mfma_f32_16x16x32_bf16 v[88:91], v[214:217], v[170:173], v[88:91]
	v_mfma_f32_16x16x32_bf16 v[80:83], v[200:203], v[178:181], v[80:83]
	v_mfma_f32_16x16x32_bf16 v[72:75], v[214:217], v[178:181], v[72:75]
	v_mfma_f32_16x16x32_bf16 v[68:71], v[200:203], v[186:189], v[68:71]
	v_mfma_f32_16x16x32_bf16 v[64:67], v[214:217], v[186:189], v[64:67]
	s_mov_b32 m0, s65
	v_lshl_add_u64 v[142:143], v[218:219], 0, s[88:89]
	s_barrier
	ds_read_b128 v[158:161], v141 offset:49152
	ds_read_b128 v[162:165], v141 offset:50176
	ds_read_b128 v[166:169], v141 offset:51200
	ds_read_b128 v[170:173], v141 offset:52224
	ds_read_b128 v[174:177], v141 offset:53248
	ds_read_b128 v[178:181], v141 offset:54272
	ds_read_b128 v[182:185], v141 offset:55296
	ds_read_b128 v[186:189], v141 offset:56320
	global_load_lds_dwordx4 v[142:143], off
	s_mov_b32 m0, s66
	v_lshl_add_u64 v[142:143], v[220:221], 0, s[88:89]
	global_load_lds_dwordx4 v[142:143], off
	s_barrier
	s_waitcnt lgkmcnt(0)
	v_mfma_f32_16x16x32_bf16 v[60:63], v[134:137], v[158:161], v[60:63]
	v_mfma_f32_16x16x32_bf16 v[56:59], v[150:153], v[158:161], v[56:59]
	v_mfma_f32_16x16x32_bf16 v[52:55], v[134:137], v[166:169], v[52:55]
	v_mfma_f32_16x16x32_bf16 v[44:47], v[150:153], v[166:169], v[44:47]
	v_mfma_f32_16x16x32_bf16 v[36:39], v[134:137], v[174:177], v[36:39]
	v_mfma_f32_16x16x32_bf16 v[28:31], v[150:153], v[174:177], v[28:31]
	v_mfma_f32_16x16x32_bf16 v[20:23], v[134:137], v[182:185], v[20:23]
	v_mfma_f32_16x16x32_bf16 v[12:15], v[150:153], v[182:185], v[12:15]
	v_mfma_f32_16x16x32_bf16 v[60:63], v[146:149], v[162:165], v[60:63]
	v_mfma_f32_16x16x32_bf16 v[56:59], v[154:157], v[162:165], v[56:59]
	v_mfma_f32_16x16x32_bf16 v[52:55], v[146:149], v[170:173], v[52:55]
	v_mfma_f32_16x16x32_bf16 v[44:47], v[154:157], v[170:173], v[44:47]
	v_mfma_f32_16x16x32_bf16 v[36:39], v[146:149], v[178:181], v[36:39]
	v_mfma_f32_16x16x32_bf16 v[28:31], v[154:157], v[178:181], v[28:31]
	v_mfma_f32_16x16x32_bf16 v[20:23], v[146:149], v[186:189], v[20:23]
	v_mfma_f32_16x16x32_bf16 v[12:15], v[154:157], v[186:189], v[12:15]
	s_barrier
	s_add_u32 s10, s16, 0x60080
	s_addc_u32 s11, s17, 0
	s_add_i32 s16, s20, s35
	s_mov_b32 m0, s16
	v_lshl_add_u64 v[134:135], s[10:11], 0, v[144:145]
	global_load_lds_dwordx4 v[134:135], off
	s_add_i32 m0, s16, 0x2000
	v_lshl_add_u64 v[134:135], s[10:11], 0, v[128:129]
	global_load_lds_dwordx4 v[134:135], off
	s_waitcnt vmcnt(6)
	s_barrier
	v_mfma_f32_16x16x32_bf16 v[48:51], v[196:199], v[158:161], v[48:51]
	v_mfma_f32_16x16x32_bf16 v[40:43], v[204:207], v[158:161], v[40:43]
	v_mfma_f32_16x16x32_bf16 v[32:35], v[196:199], v[166:169], v[32:35]
	v_mfma_f32_16x16x32_bf16 v[24:27], v[204:207], v[166:169], v[24:27]
	v_mfma_f32_16x16x32_bf16 v[16:19], v[196:199], v[174:177], v[16:19]
	v_mfma_f32_16x16x32_bf16 v[8:11], v[204:207], v[174:177], v[8:11]
	v_mfma_f32_16x16x32_bf16 v[4:7], v[196:199], v[182:185], v[4:7]
	v_mfma_f32_16x16x32_bf16 v[0:3], v[204:207], v[182:185], v[0:3]
	v_mfma_f32_16x16x32_bf16 v[48:51], v[200:203], v[162:165], v[48:51]
	v_mfma_f32_16x16x32_bf16 v[40:43], v[214:217], v[162:165], v[40:43]
	v_mfma_f32_16x16x32_bf16 v[32:35], v[200:203], v[170:173], v[32:35]
	v_mfma_f32_16x16x32_bf16 v[24:27], v[214:217], v[170:173], v[24:27]
	v_mfma_f32_16x16x32_bf16 v[16:19], v[200:203], v[178:181], v[16:19]
	v_mfma_f32_16x16x32_bf16 v[8:11], v[214:217], v[178:181], v[8:11]
	v_mfma_f32_16x16x32_bf16 v[4:7], v[200:203], v[186:189], v[4:7]
	v_mfma_f32_16x16x32_bf16 v[0:3], v[214:217], v[186:189], v[0:3]
	s_add_i32 s72, s72, 2
	s_add_u32 s24, s24, 0x100
	s_addc_u32 s25, s25, 0
	s_cmp_gt_u32 s72, 21
	s_mov_b64 s[10:11], s[12:13]
	s_barrier
	s_cbranch_scc0 .LBB0_985
	s_mul_hi_i32 s10, s71, 0x3e0f83e1
	s_lshr_b32 s11, s10, 31
	s_ashr_i32 s10, s10, 5
	s_add_i32 s11, s10, s11
	s_mul_i32 s10, s11, 0x84
	s_sub_i32 s10, s71, s10
	s_mul_i32 s12, s10, 0x7c2
	s_lshr_b32 s13, s12, 31
	s_lshr_b32 s12, s12, 16
	s_add_i32 s12, s12, s13
	s_sext_i32_i16 s12, s12
	s_mul_i32 s13, s12, 0xffffffdf
	s_lshl_b32 s11, s11, 2
	s_add_i32 s10, s13, s10
	s_add_i32 s12, s11, s12
	s_cmp_lg_u32 s10, 0
	s_cbranch_scc0 .LBB0_988
	s_lshl_b32 s11, s12, 13
	s_lshl_b32 s10, s10, 8
	s_add_i32 s10, s11, s10
	s_add_i32 s13, s10, 0xffffff00
	s_cbranch_execnz .LBB0_977
	s_branch .LBB0_976

; #define PG8_STAGE(bufoff, gbase, voff) do { _Pragma("unroll") for (int _i = 0; _i < 2; ++_i) \
;         __builtin_amdgcn_global_load_lds((const unsigned*)((const char*)(gbase) + (voff)[_i]), (LAS unsigned*)(lds + (bufoff) + ldsw + _i * 8192), 16, 0, 0); } while (0)
; #define PG8_LDA(dst, b, h) do { _Pragma("unroll") for (int m = 0; m < 4; ++m) _Pragma("unroll") for (int k = 0; k < 2; ++k) dst[m][k] = *(const LAS bf16x8*)(lds + PG8_SA(b, h) + aoff + m * 2048 + k * 1024); } while (0)
; #define PG8_LDB(dst, b, h) do { _Pragma("unroll") for (int n = 0; n < 2; ++n) _Pragma("unroll") for (int k = 0; k < 2; ++k) dst[n][k] = *(const LAS bf16x8*)(lds + PG8_SB(b, h) + boff + n * 2048 + k * 1024); } while (0)
; #define PG8_MMA(ai, bj, At, Bt) do { __builtin_amdgcn_s_setprio(1); _Pragma("unroll") for (int m = 0; m < 4; ++m) _Pragma("unroll") for (int n = 0; n < 2; ++n) _Pragma("unroll") for (int k = 0; k < 2; ++k) \
;         acc[ai][bj][m][n] = __builtin_amdgcn_mfma_f32_16x16x32_bf16(Bt[n][k], At[m][k], acc[ai][bj][m][n], 0, 0, 0); __builtin_amdgcn_s_setprio(0); } while (0)
; #define PG8_WAIT_L(n) asm volatile("s_waitcnt lgkmcnt(" #n ")" ::: "memory")
; #define PG8_BAR __builtin_amdgcn_s_barrier()
; #define PG8_SCHED __builtin_amdgcn_sched_barrier(0)
; template <class Epi>
; __device__ __forceinline__ void gemm_phase(LAS unsigned char* lds, const Gemm g, const StaticOrder& S, const Epi& E) {
;     ...
;             const bool last = (t == nt - 2);
;             const char* a1 = cA + (size_t)(t + 1) * kstep;
;             const char* a2 = last ? nA : cA + (size_t)(t + 2) * kstep; const char* b2 = last ? nB : cB + (size_t)(t + 2) * kstep;
;             const char* a3 = a2 + kstep; const char* b3 = b2 + kstep;
;             PG8_LDB(B0, 0, 0); PG8_SCHED; PG8_LDA(At, 0, 0); PG8_STAGE(PG8_SA(1, 1), a1 + hA, voffA);
;             PG8_WAIT_L(8); PG8_BAR; PG8_WAIT_L(0); PG8_MMA(0, 0, At, B0); PG8_BAR; PG8_SCHED;
;             PG8_LDB(B1, 0, 1); PG8_STAGE(PG8_SB(0, 0), b2, voffB);
;             PG8_BAR; PG8_WAIT_L(0); PG8_MMA(0, 1, At, B1); PG8_BAR;
;             PG8_LDA(At, 0, 1); PG8_STAGE(PG8_SA(0, 0), a2, voffA);
;             PG8_BAR; PG8_WAIT_L(0); PG8_MMA(1, 0, At, B0); PG8_BAR; PG8_SCHED;
.LBB0_1013:
	s_add_u32 s12, s10, 0x100
	s_addc_u32 s13, s11, 0
	s_add_i32 s26, 0, 0x10000
	v_add_u32_e32 v142, s26, v139
	ds_read_b128 v[134:137], v142
	ds_read_b128 v[146:149], v142 offset:1024
	ds_read_b128 v[150:153], v142 offset:2048
	ds_read_b128 v[154:157], v142 offset:3072
	s_cmp_eq_u32 s72, 20
	s_cselect_b32 s21, s5, s13
	s_cselect_b32 s20, s4, s12
	s_cselect_b32 s17, s7, s25
	s_cselect_b32 s16, s6, s24
	v_lshl_add_u64 v[142:143], s[10:11], 0, v[130:131]
	s_add_i32 m0, s61, 0xc000
	ds_read_b128 v[158:161], v141
	ds_read_b128 v[162:165], v141 offset:1024
	ds_read_b128 v[166:169], v141 offset:2048
	ds_read_b128 v[170:173], v141 offset:3072
	ds_read_b128 v[174:177], v141 offset:4096
	ds_read_b128 v[178:181], v141 offset:5120
	ds_read_b128 v[182:185], v141 offset:6144
	ds_read_b128 v[186:189], v141 offset:7168
	global_load_lds_dwordx4 v[142:143], off
	s_add_i32 m0, s61, 0xe000
	v_lshl_add_u64 v[142:143], s[10:11], 0, v[132:133]
	global_load_lds_dwordx4 v[142:143], off
	s_waitcnt lgkmcnt(8)
	s_barrier
	s_waitcnt lgkmcnt(0)
	v_mfma_f32_16x16x32_bf16 v[124:127], v[134:137], v[158:161], v[124:127]
	v_mfma_f32_16x16x32_bf16 v[120:123], v[150:153], v[158:161], v[120:123]
	v_mfma_f32_16x16x32_bf16 v[116:119], v[134:137], v[166:169], v[116:119]
	v_mfma_f32_16x16x32_bf16 v[108:111], v[150:153], v[166:169], v[108:111]
	v_mfma_f32_16x16x32_bf16 v[100:103], v[134:137], v[174:177], v[100:103]
	v_mfma_f32_16x16x32_bf16 v[92:95], v[150:153], v[174:177], v[92:95]
	v_mfma_f32_16x16x32_bf16 v[84:87], v[134:137], v[182:185], v[84:87]
	v_mfma_f32_16x16x32_bf16 v[76:79], v[150:153], v[182:185], v[76:79]
	v_mfma_f32_16x16x32_bf16 v[124:127], v[146:149], v[162:165], v[124:127]
	v_mfma_f32_16x16x32_bf16 v[120:123], v[154:157], v[162:165], v[120:123]
	v_mfma_f32_16x16x32_bf16 v[116:119], v[146:149], v[170:173], v[116:119]
	v_mfma_f32_16x16x32_bf16 v[108:111], v[154:157], v[170:173], v[108:111]
	v_mfma_f32_16x16x32_bf16 v[100:103], v[146:149], v[178:181], v[100:103]
	v_mfma_f32_16x16x32_bf16 v[92:95], v[154:157], v[178:181], v[92:95]
	v_mfma_f32_16x16x32_bf16 v[84:87], v[146:149], v[186:189], v[84:87]
	v_mfma_f32_16x16x32_bf16 v[76:79], v[154:157], v[186:189], v[76:79]
	s_barrier
	s_add_i32 s27, 0, 0x14000
	v_add_u32_e32 v142, s27, v139
	s_add_i32 s10, s26, s60
	ds_read_b128 v[196:199], v142
	ds_read_b128 v[200:203], v142 offset:1024
	ds_read_b128 v[204:207], v142 offset:2048
	ds_read_b128 v[214:217], v142 offset:3072
	v_lshl_add_u64 v[142:143], s[16:17], 0, v[144:145]
	s_mov_b32 m0, s10
	v_lshl_add_u64 v[192:193], s[16:17], 0, v[128:129]
	global_load_lds_dwordx4 v[142:143], off
	s_add_i32 m0, s10, 0x2000
	s_nop 0
	global_load_lds_dwordx4 v[192:193], off
	s_barrier
	s_waitcnt lgkmcnt(0)
	v_mfma_f32_16x16x32_bf16 v[112:115], v[196:199], v[158:161], v[112:115]
	v_mfma_f32_16x16x32_bf16 v[104:107], v[204:207], v[158:161], v[104:107]
	v_mfma_f32_16x16x32_bf16 v[96:99], v[196:199], v[166:169], v[96:99]
	v_mfma_f32_16x16x32_bf16 v[88:91], v[204:207], v[166:169], v[88:91]
	v_mfma_f32_16x16x32_bf16 v[80:83], v[196:199], v[174:177], v[80:83]
	v_mfma_f32_16x16x32_bf16 v[72:75], v[204:207], v[174:177], v[72:75]
	v_mfma_f32_16x16x32_bf16 v[68:71], v[196:199], v[182:185], v[68:71]
	v_mfma_f32_16x16x32_bf16 v[64:67], v[204:207], v[182:185], v[64:67]
	v_mfma_f32_16x16x32_bf16 v[112:115], v[200:203], v[162:165], v[112:115]
	v_mfma_f32_16x16x32_bf16 v[104:107], v[214:217], v[162:165], v[104:107]
	v_mfma_f32_16x16x32_bf16 v[96:99], v[200:203], v[170:173], v[96:99]
	v_mfma_f32_16x16x32_bf16 v[88:91], v[214:217], v[170:173], v[88:91]
	v_mfma_f32_16x16x32_bf16 v[80:83], v[200:203], v[178:181], v[80:83]
	v_mfma_f32_16x16x32_bf16 v[72:75], v[214:217], v[178:181], v[72:75]
	v_mfma_f32_16x16x32_bf16 v[68:71], v[200:203], v[186:189], v[68:71]
	v_mfma_f32_16x16x32_bf16 v[64:67], v[214:217], v[186:189], v[64:67]
	s_mov_b32 m0, s61
	v_lshl_add_u64 v[218:219], s[20:21], 0, v[144:145]
	s_barrier
	ds_read_b128 v[158:161], v141 offset:16384
	ds_read_b128 v[162:165], v141 offset:17408
	ds_read_b128 v[166:169], v141 offset:18432
	ds_read_b128 v[170:173], v141 offset:19456
	ds_read_b128 v[174:177], v141 offset:20480
	ds_read_b128 v[178:181], v141 offset:21504
	ds_read_b128 v[182:185], v141 offset:22528
	ds_read_b128 v[186:189], v141 offset:23552
	global_load_lds_dwordx4 v[218:219], off
	s_mov_b32 m0, s62
	v_lshl_add_u64 v[220:221], s[20:21], 0, v[128:129]
	global_load_lds_dwordx4 v[220:221], off
	s_barrier
	s_waitcnt lgkmcnt(0)
	v_mfma_f32_16x16x32_bf16 v[60:63], v[134:137], v[158:161], v[60:63]
	v_mfma_f32_16x16x32_bf16 v[56:59], v[150:153], v[158:161], v[56:59]
	v_mfma_f32_16x16x32_bf16 v[52:55], v[134:137], v[166:169], v[52:55]
	v_mfma_f32_16x16x32_bf16 v[44:47], v[150:153], v[166:169], v[44:47]
	v_mfma_f32_16x16x32_bf16 v[36:39], v[134:137], v[174:177], v[36:39]
	v_mfma_f32_16x16x32_bf16 v[28:31], v[150:153], v[174:177], v[28:31]
	v_mfma_f32_16x16x32_bf16 v[20:23], v[134:137], v[182:185], v[20:23]
	v_mfma_f32_16x16x32_bf16 v[12:15], v[150:153], v[182:185], v[12:15]
	v_mfma_f32_16x16x32_bf16 v[60:63], v[146:149], v[162:165], v[60:63]
	v_mfma_f32_16x16x32_bf16 v[56:59], v[154:157], v[162:165], v[56:59]
	v_mfma_f32_16x16x32_bf16 v[52:55], v[146:149], v[170:173], v[52:55]
	v_mfma_f32_16x16x32_bf16 v[44:47], v[154:157], v[170:173], v[44:47]
	v_mfma_f32_16x16x32_bf16 v[36:39], v[146:149], v[178:181], v[36:39]
	v_mfma_f32_16x16x32_bf16 v[28:31], v[154:157], v[178:181], v[28:31]
	v_mfma_f32_16x16x32_bf16 v[20:23], v[146:149], v[186:189], v[20:23]
	v_mfma_f32_16x16x32_bf16 v[12:15], v[154:157], v[186:189], v[12:15]
	s_barrier
; #define PG8_STAGE(bufoff, gbase, voff) do { _Pragma("unroll") for (int _i = 0; _i < 2; ++_i) \
;         __builtin_amdgcn_global_load_lds((const unsigned*)((const char*)(gbase) + (voff)[_i]), (LAS unsigned*)(lds + (bufoff) + ldsw + _i * 8192), 16, 0, 0); } while (0)
; #define PG8_LDA(dst, b, h) do { _Pragma("unroll") for (int m = 0; m < 4; ++m) _Pragma("unroll") for (int k = 0; k < 2; ++k) dst[m][k] = *(const LAS bf16x8*)(lds + PG8_SA(b, h) + aoff + m * 2048 + k * 1024); } while (0)
; #define PG8_LDB(dst, b, h) do { _Pragma("unroll") for (int n = 0; n < 2; ++n) _Pragma("unroll") for (int k = 0; k < 2; ++k) dst[n][k] = *(const LAS bf16x8*)(lds + PG8_SB(b, h) + boff + n * 2048 + k * 1024); } while (0)
; #define PG8_MMA(ai, bj, At, Bt) do { __builtin_amdgcn_s_setprio(1); _Pragma("unroll") for (int m = 0; m < 4; ++m) _Pragma("unroll") for (int n = 0; n < 2; ++n) _Pragma("unroll") for (int k = 0; k < 2; ++k) \
;         acc[ai][bj][m][n] = __builtin_amdgcn_mfma_f32_16x16x32_bf16(Bt[n][k], At[m][k], acc[ai][bj][m][n], 0, 0, 0); __builtin_amdgcn_s_setprio(0); } while (0)
; #define PG8_WAIT_V(n) asm volatile("s_waitcnt vmcnt(" #n ")" ::: "memory")
; #define PG8_WAIT_L(n) asm volatile("s_waitcnt lgkmcnt(" #n ")" ::: "memory")
; #define PG8_BAR __builtin_amdgcn_s_barrier()
; #define PG8_SCHED __builtin_amdgcn_sched_barrier(0)
; template <class Epi>
; __device__ __forceinline__ void gemm_phase(LAS unsigned char* lds, const Gemm g, const StaticOrder& S, const Epi& E) {
;     ...
;             PG8_STAGE(PG8_SB(0, 1), b2 + hB, voffB);
;             PG8_WAIT_V(6); PG8_BAR; PG8_MMA(1, 1, At, B1); PG8_BAR;
;             PG8_LDB(B0, 1, 0); PG8_SCHED; PG8_LDA(At, 1, 0); PG8_STAGE(PG8_SA(0, 1), a2 + hA, voffA);
;             PG8_WAIT_L(8); PG8_BAR; PG8_WAIT_L(0); PG8_MMA(0, 0, At, B0); PG8_BAR; PG8_SCHED;
;             PG8_LDB(B1, 1, 1); PG8_STAGE(PG8_SB(1, 0), b3, voffB);
;             PG8_BAR; PG8_WAIT_L(0); PG8_MMA(0, 1, At, B1); PG8_BAR;
;             PG8_LDA(At, 1, 1); PG8_STAGE(PG8_SA(1, 0), a3, voffA);
	s_add_u32 s10, s16, 0x60000
	s_addc_u32 s11, s17, 0
	s_add_i32 s26, s27, s60
	s_mov_b32 m0, s26
	v_lshl_add_u64 v[134:135], s[10:11], 0, v[144:145]
	global_load_lds_dwordx4 v[134:135], off
	s_add_i32 m0, s26, 0x2000
	v_lshl_add_u64 v[134:135], s[10:11], 0, v[128:129]
	global_load_lds_dwordx4 v[134:135], off
	s_waitcnt vmcnt(6)
	s_barrier
	v_mfma_f32_16x16x32_bf16 v[48:51], v[196:199], v[158:161], v[48:51]
	v_mfma_f32_16x16x32_bf16 v[40:43], v[204:207], v[158:161], v[40:43]
	v_mfma_f32_16x16x32_bf16 v[32:35], v[196:199], v[166:169], v[32:35]
	v_mfma_f32_16x16x32_bf16 v[24:27], v[204:207], v[166:169], v[24:27]
	v_mfma_f32_16x16x32_bf16 v[16:19], v[196:199], v[174:177], v[16:19]
	v_mfma_f32_16x16x32_bf16 v[8:11], v[204:207], v[174:177], v[8:11]
	v_mfma_f32_16x16x32_bf16 v[4:7], v[196:199], v[182:185], v[4:7]
	v_mfma_f32_16x16x32_bf16 v[0:3], v[204:207], v[182:185], v[0:3]
	v_mfma_f32_16x16x32_bf16 v[48:51], v[200:203], v[162:165], v[48:51]
	v_mfma_f32_16x16x32_bf16 v[40:43], v[214:217], v[162:165], v[40:43]
	v_mfma_f32_16x16x32_bf16 v[32:35], v[200:203], v[170:173], v[32:35]
	v_mfma_f32_16x16x32_bf16 v[24:27], v[214:217], v[170:173], v[24:27]
	v_mfma_f32_16x16x32_bf16 v[16:19], v[200:203], v[178:181], v[16:19]
	v_mfma_f32_16x16x32_bf16 v[8:11], v[214:217], v[178:181], v[8:11]
	v_mfma_f32_16x16x32_bf16 v[4:7], v[200:203], v[186:189], v[4:7]
	v_mfma_f32_16x16x32_bf16 v[0:3], v[214:217], v[186:189], v[0:3]
	s_add_i32 s26, 0, 0x18000
	v_add_u32_e32 v154, s26, v139
	s_barrier
	ds_read_b128 v[134:137], v154
	ds_read_b128 v[146:149], v154 offset:1024
	ds_read_b128 v[150:153], v154 offset:2048
	ds_read_b128 v[154:157], v154 offset:3072
	s_add_u32 s10, s20, 0x60000
	s_addc_u32 s11, s21, 0
	s_mov_b32 m0, s63
	v_lshl_add_u64 v[196:197], s[10:11], 0, v[144:145]
	ds_read_b128 v[158:161], v141 offset:32768
	ds_read_b128 v[162:165], v141 offset:33792
	ds_read_b128 v[166:169], v141 offset:34816
	ds_read_b128 v[170:173], v141 offset:35840
	ds_read_b128 v[174:177], v141 offset:36864
	ds_read_b128 v[178:181], v141 offset:37888
	ds_read_b128 v[182:185], v141 offset:38912
	ds_read_b128 v[186:189], v141 offset:39936
	global_load_lds_dwordx4 v[196:197], off
	s_mov_b32 m0, s64
	v_lshl_add_u64 v[196:197], s[10:11], 0, v[128:129]
	global_load_lds_dwordx4 v[196:197], off
	s_waitcnt lgkmcnt(8)
	s_barrier
	s_waitcnt lgkmcnt(0)
	v_mfma_f32_16x16x32_bf16 v[124:127], v[134:137], v[158:161], v[124:127]
	v_mfma_f32_16x16x32_bf16 v[120:123], v[150:153], v[158:161], v[120:123]
	v_mfma_f32_16x16x32_bf16 v[116:119], v[134:137], v[166:169], v[116:119]
	v_mfma_f32_16x16x32_bf16 v[108:111], v[150:153], v[166:169], v[108:111]
	v_mfma_f32_16x16x32_bf16 v[100:103], v[134:137], v[174:177], v[100:103]
	v_mfma_f32_16x16x32_bf16 v[92:95], v[150:153], v[174:177], v[92:95]
	v_mfma_f32_16x16x32_bf16 v[84:87], v[134:137], v[182:185], v[84:87]
	v_mfma_f32_16x16x32_bf16 v[76:79], v[150:153], v[182:185], v[76:79]
	v_mfma_f32_16x16x32_bf16 v[124:127], v[146:149], v[162:165], v[124:127]
	v_mfma_f32_16x16x32_bf16 v[120:123], v[154:157], v[162:165], v[120:123]
	v_mfma_f32_16x16x32_bf16 v[116:119], v[146:149], v[170:173], v[116:119]
	v_mfma_f32_16x16x32_bf16 v[108:111], v[154:157], v[170:173], v[108:111]
	v_mfma_f32_16x16x32_bf16 v[100:103], v[146:149], v[178:181], v[100:103]
	v_mfma_f32_16x16x32_bf16 v[92:95], v[154:157], v[178:181], v[92:95]
	v_mfma_f32_16x16x32_bf16 v[84:87], v[146:149], v[186:189], v[84:87]
	v_mfma_f32_16x16x32_bf16 v[76:79], v[154:157], v[186:189], v[76:79]
	s_barrier
	s_add_i32 s20, 0, 0x1c000
	s_add_i32 s10, s26, s60
	v_add_u32_e32 v190, s20, v139
	v_lshl_add_u64 v[142:143], v[142:143], 0, s[88:89]
	s_mov_b32 m0, s10
	ds_read_b128 v[196:199], v190
	ds_read_b128 v[200:203], v190 offset:1024
	ds_read_b128 v[204:207], v190 offset:2048
	ds_read_b128 v[214:217], v190 offset:3072
	global_load_lds_dwordx4 v[142:143], off
	s_add_i32 m0, s10, 0x2000
	v_lshl_add_u64 v[142:143], v[192:193], 0, s[88:89]
	global_load_lds_dwordx4 v[142:143], off
	s_barrier
	s_waitcnt lgkmcnt(0)
	v_mfma_f32_16x16x32_bf16 v[112:115], v[196:199], v[158:161], v[112:115]
	v_mfma_f32_16x16x32_bf16 v[104:107], v[204:207], v[158:161], v[104:107]
	v_mfma_f32_16x16x32_bf16 v[96:99], v[196:199], v[166:169], v[96:99]
	v_mfma_f32_16x16x32_bf16 v[88:91], v[204:207], v[166:169], v[88:91]
	v_mfma_f32_16x16x32_bf16 v[80:83], v[196:199], v[174:177], v[80:83]
	v_mfma_f32_16x16x32_bf16 v[72:75], v[204:207], v[174:177], v[72:75]
	v_mfma_f32_16x16x32_bf16 v[68:71], v[196:199], v[182:185], v[68:71]
	v_mfma_f32_16x16x32_bf16 v[64:67], v[204:207], v[182:185], v[64:67]
	v_mfma_f32_16x16x32_bf16 v[112:115], v[200:203], v[162:165], v[112:115]
	v_mfma_f32_16x16x32_bf16 v[104:107], v[214:217], v[162:165], v[104:107]
	v_mfma_f32_16x16x32_bf16 v[96:99], v[200:203], v[170:173], v[96:99]
	v_mfma_f32_16x16x32_bf16 v[88:91], v[214:217], v[170:173], v[88:91]
	v_mfma_f32_16x16x32_bf16 v[80:83], v[200:203], v[178:181], v[80:83]
	v_mfma_f32_16x16x32_bf16 v[72:75], v[214:217], v[178:181], v[72:75]
	v_mfma_f32_16x16x32_bf16 v[68:71], v[200:203], v[186:189], v[68:71]
	v_mfma_f32_16x16x32_bf16 v[64:67], v[214:217], v[186:189], v[64:67]
	s_mov_b32 m0, s65
	v_lshl_add_u64 v[142:143], v[218:219], 0, s[88:89]
	s_barrier
	ds_read_b128 v[158:161], v141 offset:49152
	ds_read_b128 v[162:165], v141 offset:50176
	ds_read_b128 v[166:169], v141 offset:51200
	ds_read_b128 v[170:173], v141 offset:52224
	ds_read_b128 v[174:177], v141 offset:53248
	ds_read_b128 v[178:181], v141 offset:54272
	ds_read_b128 v[182:185], v141 offset:55296
	ds_read_b128 v[186:189], v141 offset:56320
	global_load_lds_dwordx4 v[142:143], off
	s_mov_b32 m0, s66
	v_lshl_add_u64 v[142:143], v[220:221], 0, s[88:89]
	global_load_lds_dwordx4 v[142:143], off
	s_barrier
; #define PG8_STAGE(bufoff, gbase, voff) do { _Pragma("unroll") for (int _i = 0; _i < 2; ++_i) \
;         __builtin_amdgcn_global_load_lds((const unsigned*)((const char*)(gbase) + (voff)[_i]), (LAS unsigned*)(lds + (bufoff) + ldsw + _i * 8192), 16, 0, 0); } while (0)
; #define PG8_MMA(ai, bj, At, Bt) do { __builtin_amdgcn_s_setprio(1); _Pragma("unroll") for (int m = 0; m < 4; ++m) _Pragma("unroll") for (int n = 0; n < 2; ++n) _Pragma("unroll") for (int k = 0; k < 2; ++k) \
;         acc[ai][bj][m][n] = __builtin_amdgcn_mfma_f32_16x16x32_bf16(Bt[n][k], At[m][k], acc[ai][bj][m][n], 0, 0, 0); __builtin_amdgcn_s_setprio(0); } while (0)
; #define PG8_WAIT_V(n) asm volatile("s_waitcnt vmcnt(" #n ")" ::: "memory")
; #define PG8_WAIT_L(n) asm volatile("s_waitcnt lgkmcnt(" #n ")" ::: "memory")
; #define PG8_BAR __builtin_amdgcn_s_barrier()
; #define PG8_SCHED __builtin_amdgcn_sched_barrier(0)
; template <class Epi>
; __device__ __forceinline__ void gemm_phase(LAS unsigned char* lds, const Gemm g, const StaticOrder& S, const Epi& E) {
;     ...
;             PG8_BAR; PG8_WAIT_L(0); PG8_MMA(1, 0, At, B0); PG8_BAR; PG8_SCHED;
;             PG8_STAGE(PG8_SB(1, 1), b3 + hB, voffB);
;             PG8_WAIT_V(6); PG8_BAR; PG8_MMA(1, 1, At, B1); PG8_BAR;
	s_waitcnt lgkmcnt(0)
	v_mfma_f32_16x16x32_bf16 v[60:63], v[134:137], v[158:161], v[60:63]
	v_mfma_f32_16x16x32_bf16 v[56:59], v[150:153], v[158:161], v[56:59]
	v_mfma_f32_16x16x32_bf16 v[52:55], v[134:137], v[166:169], v[52:55]
	v_mfma_f32_16x16x32_bf16 v[44:47], v[150:153], v[166:169], v[44:47]
	v_mfma_f32_16x16x32_bf16 v[36:39], v[134:137], v[174:177], v[36:39]
	v_mfma_f32_16x16x32_bf16 v[28:31], v[150:153], v[174:177], v[28:31]
	v_mfma_f32_16x16x32_bf16 v[20:23], v[134:137], v[182:185], v[20:23]
	v_mfma_f32_16x16x32_bf16 v[12:15], v[150:153], v[182:185], v[12:15]
	v_mfma_f32_16x16x32_bf16 v[60:63], v[146:149], v[162:165], v[60:63]
	v_mfma_f32_16x16x32_bf16 v[56:59], v[154:157], v[162:165], v[56:59]
	v_mfma_f32_16x16x32_bf16 v[52:55], v[146:149], v[170:173], v[52:55]
	v_mfma_f32_16x16x32_bf16 v[44:47], v[154:157], v[170:173], v[44:47]
	v_mfma_f32_16x16x32_bf16 v[36:39], v[146:149], v[178:181], v[36:39]
	v_mfma_f32_16x16x32_bf16 v[28:31], v[154:157], v[178:181], v[28:31]
	v_mfma_f32_16x16x32_bf16 v[20:23], v[146:149], v[186:189], v[20:23]
	v_mfma_f32_16x16x32_bf16 v[12:15], v[154:157], v[186:189], v[12:15]
	s_barrier
	s_add_u32 s10, s16, 0x60080
	s_addc_u32 s11, s17, 0
	s_add_i32 s16, s20, s60
	s_mov_b32 m0, s16
	v_lshl_add_u64 v[134:135], s[10:11], 0, v[144:145]
	global_load_lds_dwordx4 v[134:135], off
	s_add_i32 m0, s16, 0x2000
	v_lshl_add_u64 v[134:135], s[10:11], 0, v[128:129]
	global_load_lds_dwordx4 v[134:135], off
	s_waitcnt vmcnt(6)
	s_barrier
	v_mfma_f32_16x16x32_bf16 v[48:51], v[196:199], v[158:161], v[48:51]
	v_mfma_f32_16x16x32_bf16 v[40:43], v[204:207], v[158:161], v[40:43]
	v_mfma_f32_16x16x32_bf16 v[32:35], v[196:199], v[166:169], v[32:35]
	v_mfma_f32_16x16x32_bf16 v[24:27], v[204:207], v[166:169], v[24:27]
	v_mfma_f32_16x16x32_bf16 v[16:19], v[196:199], v[174:177], v[16:19]
	v_mfma_f32_16x16x32_bf16 v[8:11], v[204:207], v[174:177], v[8:11]
	v_mfma_f32_16x16x32_bf16 v[4:7], v[196:199], v[182:185], v[4:7]
	v_mfma_f32_16x16x32_bf16 v[0:3], v[204:207], v[182:185], v[0:3]
	v_mfma_f32_16x16x32_bf16 v[48:51], v[200:203], v[162:165], v[48:51]
	v_mfma_f32_16x16x32_bf16 v[40:43], v[214:217], v[162:165], v[40:43]
	v_mfma_f32_16x16x32_bf16 v[32:35], v[200:203], v[170:173], v[32:35]
	v_mfma_f32_16x16x32_bf16 v[24:27], v[214:217], v[170:173], v[24:27]
	v_mfma_f32_16x16x32_bf16 v[16:19], v[200:203], v[178:181], v[16:19]
	v_mfma_f32_16x16x32_bf16 v[8:11], v[214:217], v[178:181], v[8:11]
	v_mfma_f32_16x16x32_bf16 v[4:7], v[200:203], v[186:189], v[4:7]
	v_mfma_f32_16x16x32_bf16 v[0:3], v[214:217], v[186:189], v[0:3]
	s_add_i32 s72, s72, 2
	s_add_u32 s24, s24, 0x100
	s_addc_u32 s25, s25, 0
	s_cmp_gt_u32 s72, 21
	s_mov_b64 s[10:11], s[12:13]
	s_barrier
	s_cbranch_scc0 .LBB0_1013
; __device__ __forceinline__ unsigned pk2(float lo, float hi) { unsigned r; asm("v_cvt_pk_bf16_f32 %0, %1, %2" : "=v"(r) : "v"(lo), "v"(hi)); return r; }
;     __device__ __forceinline__ void operator()(const f32x4 (&acc)[2][2][4][2], const Unit& u, int wr, int wc, int fr, int fq) const {
;     ...
;         const int row_t = rmap == 1 ? odd_phys_row0(u.pm, grp) : (rmap == 2 ? odd_phys_row0(u.pm % (BG * TPB), u.pm / (BG * TPB)) : u.pm * BM);
;         int c = col_t + 64 * wc + 16 * fq;
;         if (mode == 2) c = (c >> 6) * 96 + (c & 63);
; #pragma unroll
;         for (int ai = 0; ai < 2; ++ai)
; #pragma unroll
;             for (int m = 0; m < 4; ++m) {
;                 const int row = row_t + ai * HALF + wr * 64 + m * 16 + fr;
;                 bf16_t* rp = O + (size_t)row * ldc + c;
; #pragma unroll
;                 for (int bj = 0; bj < 2; ++bj) {
;                     const f32x4 v0 = acc[ai][bj][m][0], v1 = acc[ai][bj][m][1];
;                     u32x4 o; o.x = pk2(v0[0], v0[1]); o.y = pk2(v0[2], v0[3]); o.z = pk2(v1[0], v1[1]); o.w = pk2(v1[2], v1[3]);
;                     *(u32x4*)(rp + 8 * bj) = o;
;                 }
;             }
	v_lshl_add_u32 v134, s71, 8, v138
	v_cvt_pk_bf16_f32 v68, v68, v69
	v_cvt_pk_bf16_f32 v69, v70, v71
	v_cvt_pk_bf16_f32 v70, v64, v65
	v_add_u32_e32 v64, 0x80, v134
	v_lshl_or_b32 v136, s15, 8, v140
	v_ashrrev_i32_e32 v135, 31, v134
	v_cvt_pk_bf16_f32 v112, v112, v113
	v_cvt_pk_bf16_f32 v113, v114, v115
	v_cvt_pk_bf16_f32 v114, v104, v105
	v_or_b32_e32 v104, 16, v134
	v_ashrrev_i32_e32 v65, 31, v64
	v_cvt_pk_bf16_f32 v48, v48, v49
	v_cvt_pk_bf16_f32 v49, v50, v51
	v_cvt_pk_bf16_f32 v50, v40, v41
	v_add_u32_e32 v40, 0x90, v134
	v_ashrrev_i32_e32 v137, 31, v136
	v_lshlrev_b64 v[142:143], 11, v[134:135]
	v_ashrrev_i32_e32 v105, 31, v104
	v_cvt_pk_bf16_f32 v96, v96, v97
	v_cvt_pk_bf16_f32 v97, v98, v99
	v_cvt_pk_bf16_f32 v98, v88, v89
	v_or_b32_e32 v88, 32, v134
	v_lshlrev_b64 v[64:65], 11, v[64:65]
	v_ashrrev_i32_e32 v41, 31, v40
	v_cvt_pk_bf16_f32 v32, v32, v33
	v_cvt_pk_bf16_f32 v33, v34, v35
	v_cvt_pk_bf16_f32 v34, v24, v25
	v_add_u32_e32 v24, 0xa0, v134
	v_lshl_add_u64 v[142:143], s[8:9], 0, v[142:143]
	v_lshlrev_b64 v[136:137], 1, v[136:137]
	v_lshlrev_b64 v[104:105], 11, v[104:105]
	v_ashrrev_i32_e32 v89, 31, v88
	v_cvt_pk_bf16_f32 v80, v80, v81
	v_cvt_pk_bf16_f32 v81, v82, v83
	v_cvt_pk_bf16_f32 v82, v72, v73
	v_or_b32_e32 v72, 48, v134
	v_lshl_add_u64 v[64:65], s[8:9], 0, v[64:65]
	v_lshlrev_b64 v[40:41], 11, v[40:41]
	v_ashrrev_i32_e32 v25, 31, v24
	v_cvt_pk_bf16_f32 v16, v16, v17
	v_cvt_pk_bf16_f32 v17, v18, v19
	v_cvt_pk_bf16_f32 v18, v8, v9
	v_add_u32_e32 v8, 0xb0, v134
	v_lshl_add_u64 v[142:143], v[142:143], 0, v[136:137]
	v_lshl_add_u64 v[104:105], s[8:9], 0, v[104:105]
	v_lshlrev_b64 v[88:89], 11, v[88:89]
	v_ashrrev_i32_e32 v73, 31, v72
	v_lshl_add_u64 v[64:65], v[64:65], 0, v[136:137]
	v_lshl_add_u64 v[40:41], s[8:9], 0, v[40:41]
	v_lshlrev_b64 v[24:25], 11, v[24:25]
	v_ashrrev_i32_e32 v9, 31, v8
	v_cvt_pk_bf16_f32 v115, v106, v107
	global_store_dwordx4 v[142:143], v[112:115], off offset:16
	v_lshl_add_u64 v[88:89], s[8:9], 0, v[88:89]
	v_lshlrev_b64 v[72:73], 11, v[72:73]
	v_lshl_add_u64 v[112:113], v[104:105], 0, v[136:137]
	v_cvt_pk_bf16_f32 v51, v42, v43
	global_store_dwordx4 v[64:65], v[48:51], off offset:16
	v_lshl_add_u64 v[24:25], s[8:9], 0, v[24:25]
	v_lshlrev_b64 v[8:9], 11, v[8:9]
	v_lshl_add_u64 v[48:49], v[40:41], 0, v[136:137]
	v_cvt_pk_bf16_f32 v99, v90, v91
	global_store_dwordx4 v[112:113], v[96:99], off offset:16
	v_lshl_add_u64 v[72:73], s[8:9], 0, v[72:73]
	v_cvt_pk_bf16_f32 v35, v26, v27
	global_store_dwordx4 v[48:49], v[32:35], off offset:16
	v_lshl_add_u64 v[96:97], v[88:89], 0, v[136:137]
	v_lshl_add_u64 v[8:9], s[8:9], 0, v[8:9]
	v_lshl_add_u64 v[32:33], v[24:25], 0, v[136:137]
	v_cvt_pk_bf16_f32 v83, v74, v75
	global_store_dwordx4 v[96:97], v[80:83], off offset:16
	v_cvt_pk_bf16_f32 v19, v10, v11
	global_store_dwordx4 v[32:33], v[16:19], off offset:16
	s_and_b64 vcc, exec, s[0:1]
	v_lshl_add_u64 v[80:81], v[72:73], 0, v[136:137]
	v_lshl_add_u64 v[16:17], v[8:9], 0, v[136:137]
	s_mov_b32 s15, s69
	s_mov_b32 s71, s70
	s_mov_b64 s[12:13], s[6:7]
	s_mov_b64 s[10:11], s[4:5]
	v_cvt_pk_bf16_f32 v124, v124, v125
	v_cvt_pk_bf16_f32 v125, v126, v127
	v_cvt_pk_bf16_f32 v126, v120, v121
	v_cvt_pk_bf16_f32 v127, v122, v123
	global_store_dwordx4 v[142:143], v[124:127], off
	v_cvt_pk_bf16_f32 v104, v116, v117
	v_cvt_pk_bf16_f32 v105, v118, v119
	v_cvt_pk_bf16_f32 v106, v108, v109
	v_cvt_pk_bf16_f32 v107, v110, v111
	global_store_dwordx4 v[112:113], v[104:107], off
	v_cvt_pk_bf16_f32 v88, v100, v101
	v_cvt_pk_bf16_f32 v89, v102, v103
	v_cvt_pk_bf16_f32 v90, v92, v93
	v_cvt_pk_bf16_f32 v91, v94, v95
	global_store_dwordx4 v[96:97], v[88:91], off
	v_cvt_pk_bf16_f32 v72, v84, v85
	v_cvt_pk_bf16_f32 v73, v86, v87
	v_cvt_pk_bf16_f32 v74, v76, v77
	v_cvt_pk_bf16_f32 v75, v78, v79
	global_store_dwordx4 v[80:81], v[72:75], off
	v_cvt_pk_bf16_f32 v71, v66, v67
	global_store_dwordx4 v[80:81], v[68:71], off offset:16
	v_cvt_pk_bf16_f32 v60, v60, v61
	v_cvt_pk_bf16_f32 v61, v62, v63
	v_cvt_pk_bf16_f32 v62, v56, v57
	v_cvt_pk_bf16_f32 v63, v58, v59
	global_store_dwordx4 v[64:65], v[60:63], off
	v_cvt_pk_bf16_f32 v40, v52, v53
	v_cvt_pk_bf16_f32 v41, v54, v55
	v_cvt_pk_bf16_f32 v42, v44, v45
	v_cvt_pk_bf16_f32 v43, v46, v47
	global_store_dwordx4 v[48:49], v[40:43], off
	v_cvt_pk_bf16_f32 v24, v36, v37
	v_cvt_pk_bf16_f32 v25, v38, v39
	v_cvt_pk_bf16_f32 v26, v28, v29
	v_cvt_pk_bf16_f32 v27, v30, v31
	global_store_dwordx4 v[32:33], v[24:27], off
	v_cvt_pk_bf16_f32 v8, v20, v21
	v_cvt_pk_bf16_f32 v9, v22, v23
	v_cvt_pk_bf16_f32 v10, v12, v13
	v_cvt_pk_bf16_f32 v11, v14, v15
	global_store_dwordx4 v[16:17], v[8:11], off
	v_cvt_pk_bf16_f32 v4, v4, v5
	v_cvt_pk_bf16_f32 v5, v6, v7
	v_cvt_pk_bf16_f32 v6, v0, v1
	v_cvt_pk_bf16_f32 v7, v2, v3
	global_store_dwordx4 v[16:17], v[4:7], off offset:16
	s_cbranch_vccz .LBB0_1002
	s_waitcnt vmcnt(0)
	s_cmpk_gt_u32 s34, 0xff
	s_cbranch_scc1 .LBB0_1017
	s_barrier

; #define PG8_STAGE(bufoff, gbase, voff) do { _Pragma("unroll") for (int _i = 0; _i < 2; ++_i) \
;         __builtin_amdgcn_global_load_lds((const unsigned*)((const char*)(gbase) + (voff)[_i]), (LAS unsigned*)(lds + (bufoff) + ldsw + _i * 8192), 16, 0, 0); } while (0)
; #define PG8_LDA(dst, b, h) do { _Pragma("unroll") for (int m = 0; m < 4; ++m) _Pragma("unroll") for (int k = 0; k < 2; ++k) dst[m][k] = *(const LAS bf16x8*)(lds + PG8_SA(b, h) + aoff + m * 2048 + k * 1024); } while (0)
; #define PG8_LDB(dst, b, h) do { _Pragma("unroll") for (int n = 0; n < 2; ++n) _Pragma("unroll") for (int k = 0; k < 2; ++k) dst[n][k] = *(const LAS bf16x8*)(lds + PG8_SB(b, h) + boff + n * 2048 + k * 1024); } while (0)
; #define PG8_MMA(ai, bj, At, Bt) do { __builtin_amdgcn_s_setprio(1); _Pragma("unroll") for (int m = 0; m < 4; ++m) _Pragma("unroll") for (int n = 0; n < 2; ++n) _Pragma("unroll") for (int k = 0; k < 2; ++k) \
;         acc[ai][bj][m][n] = __builtin_amdgcn_mfma_f32_16x16x32_bf16(Bt[n][k], At[m][k], acc[ai][bj][m][n], 0, 0, 0); __builtin_amdgcn_s_setprio(0); } while (0)
; #define PG8_WAIT_L(n) asm volatile("s_waitcnt lgkmcnt(" #n ")" ::: "memory")
; #define PG8_BAR __builtin_amdgcn_s_barrier()
; #define PG8_SCHED __builtin_amdgcn_sched_barrier(0)
; template <class Epi>
; __device__ __forceinline__ void gemm_phase(LAS unsigned char* lds, const Gemm g, const StaticOrder& S, const Epi& E) {
;     ...
;             const bool last = (t == nt - 2);
;             const char* a1 = cA + (size_t)(t + 1) * kstep;
;             const char* a2 = last ? nA : cA + (size_t)(t + 2) * kstep; const char* b2 = last ? nB : cB + (size_t)(t + 2) * kstep;
;             const char* a3 = a2 + kstep; const char* b3 = b2 + kstep;
;             PG8_LDB(B0, 0, 0); PG8_SCHED; PG8_LDA(At, 0, 0); PG8_STAGE(PG8_SA(1, 1), a1 + hA, voffA);
;             PG8_WAIT_L(8); PG8_BAR; PG8_WAIT_L(0); PG8_MMA(0, 0, At, B0); PG8_BAR; PG8_SCHED;
;             PG8_LDB(B1, 0, 1); PG8_STAGE(PG8_SB(0, 0), b2, voffB);
;             PG8_BAR; PG8_WAIT_L(0); PG8_MMA(0, 1, At, B1); PG8_BAR;
;             PG8_LDA(At, 0, 1); PG8_STAGE(PG8_SA(0, 0), a2, voffA);
;             PG8_BAR; PG8_WAIT_L(0); PG8_MMA(1, 0, At, B0); PG8_BAR; PG8_SCHED;
.LBB0_1079:
	s_add_u32 s16, s12, 0xfffc0080
	s_addc_u32 s17, s13, -1
	s_add_i32 s26, 0, 0x10000
	v_add_u32_e32 v142, s26, v139
	ds_read_b128 v[134:137], v142
	ds_read_b128 v[146:149], v142 offset:1024
	ds_read_b128 v[150:153], v142 offset:2048
	ds_read_b128 v[154:157], v142 offset:3072
	s_cmp_eq_u32 s77, 12
	s_cselect_b32 s21, s71, s17
	s_cselect_b32 s20, s72, s16
	s_cselect_b32 s17, s7, s76
	s_cselect_b32 s16, s24, s25
	v_lshl_add_u64 v[142:143], s[12:13], 0, v[130:131]
	s_add_i32 m0, s61, 0xc000
	ds_read_b128 v[158:161], v141
	ds_read_b128 v[162:165], v141 offset:1024
	ds_read_b128 v[166:169], v141 offset:2048
	ds_read_b128 v[170:173], v141 offset:3072
	ds_read_b128 v[174:177], v141 offset:4096
	ds_read_b128 v[178:181], v141 offset:5120
	ds_read_b128 v[182:185], v141 offset:6144
	ds_read_b128 v[196:199], v141 offset:7168
	global_load_lds_dwordx4 v[142:143], off
	s_add_i32 m0, s61, 0xe000
	v_lshl_add_u64 v[142:143], s[12:13], 0, v[132:133]
	global_load_lds_dwordx4 v[142:143], off
	s_waitcnt lgkmcnt(8)
	s_barrier
	s_waitcnt lgkmcnt(0)
	v_mfma_f32_16x16x32_bf16 v[124:127], v[134:137], v[158:161], v[124:127]
	v_mfma_f32_16x16x32_bf16 v[120:123], v[150:153], v[158:161], v[120:123]
	v_mfma_f32_16x16x32_bf16 v[116:119], v[134:137], v[166:169], v[116:119]
	v_mfma_f32_16x16x32_bf16 v[108:111], v[150:153], v[166:169], v[108:111]
	v_mfma_f32_16x16x32_bf16 v[100:103], v[134:137], v[174:177], v[100:103]
	v_mfma_f32_16x16x32_bf16 v[92:95], v[150:153], v[174:177], v[92:95]
	v_mfma_f32_16x16x32_bf16 v[84:87], v[134:137], v[182:185], v[84:87]
	v_mfma_f32_16x16x32_bf16 v[76:79], v[150:153], v[182:185], v[76:79]
	v_mfma_f32_16x16x32_bf16 v[124:127], v[146:149], v[162:165], v[124:127]
	v_mfma_f32_16x16x32_bf16 v[120:123], v[154:157], v[162:165], v[120:123]
	v_mfma_f32_16x16x32_bf16 v[116:119], v[146:149], v[170:173], v[116:119]
	v_mfma_f32_16x16x32_bf16 v[108:111], v[154:157], v[170:173], v[108:111]
	v_mfma_f32_16x16x32_bf16 v[100:103], v[146:149], v[178:181], v[100:103]
	v_mfma_f32_16x16x32_bf16 v[92:95], v[154:157], v[178:181], v[92:95]
	v_mfma_f32_16x16x32_bf16 v[84:87], v[146:149], v[196:199], v[84:87]
	v_mfma_f32_16x16x32_bf16 v[76:79], v[154:157], v[196:199], v[76:79]
	s_barrier
	s_add_i32 s28, 0, 0x14000
	v_add_u32_e32 v142, s28, v139
	s_add_i32 s26, s26, s35
	ds_read_b128 v[200:203], v142
	ds_read_b128 v[204:207], v142 offset:1024
	ds_read_b128 v[214:217], v142 offset:2048
	ds_read_b128 v[218:221], v142 offset:3072
	v_lshl_add_u64 v[142:143], s[16:17], 0, v[144:145]
	s_mov_b32 m0, s26
	v_lshl_add_u64 v[186:187], s[16:17], 0, v[128:129]
	global_load_lds_dwordx4 v[142:143], off
	s_add_i32 m0, s26, 0x2000
	s_nop 0
	global_load_lds_dwordx4 v[186:187], off
	s_barrier
	s_waitcnt lgkmcnt(0)
	v_mfma_f32_16x16x32_bf16 v[112:115], v[200:203], v[158:161], v[112:115]
	v_mfma_f32_16x16x32_bf16 v[104:107], v[214:217], v[158:161], v[104:107]
	v_mfma_f32_16x16x32_bf16 v[96:99], v[200:203], v[166:169], v[96:99]
	v_mfma_f32_16x16x32_bf16 v[88:91], v[214:217], v[166:169], v[88:91]
	v_mfma_f32_16x16x32_bf16 v[80:83], v[200:203], v[174:177], v[80:83]
	v_mfma_f32_16x16x32_bf16 v[72:75], v[214:217], v[174:177], v[72:75]
	v_mfma_f32_16x16x32_bf16 v[68:71], v[200:203], v[182:185], v[68:71]
	v_mfma_f32_16x16x32_bf16 v[64:67], v[214:217], v[182:185], v[64:67]
	v_mfma_f32_16x16x32_bf16 v[112:115], v[204:207], v[162:165], v[112:115]
	v_mfma_f32_16x16x32_bf16 v[104:107], v[218:221], v[162:165], v[104:107]
	v_mfma_f32_16x16x32_bf16 v[96:99], v[204:207], v[170:173], v[96:99]
	v_mfma_f32_16x16x32_bf16 v[88:91], v[218:221], v[170:173], v[88:91]
	v_mfma_f32_16x16x32_bf16 v[80:83], v[204:207], v[178:181], v[80:83]
	v_mfma_f32_16x16x32_bf16 v[72:75], v[218:221], v[178:181], v[72:75]
	v_mfma_f32_16x16x32_bf16 v[68:71], v[204:207], v[196:199], v[68:71]
	v_mfma_f32_16x16x32_bf16 v[64:67], v[218:221], v[196:199], v[64:67]
	s_mov_b32 m0, s61
	v_lshl_add_u64 v[188:189], s[20:21], 0, v[144:145]
	s_barrier
	ds_read_b128 v[158:161], v141 offset:16384
	ds_read_b128 v[162:165], v141 offset:17408
	ds_read_b128 v[166:169], v141 offset:18432
	ds_read_b128 v[170:173], v141 offset:19456
	ds_read_b128 v[174:177], v141 offset:20480
	ds_read_b128 v[178:181], v141 offset:21504
	ds_read_b128 v[182:185], v141 offset:22528
	ds_read_b128 v[196:199], v141 offset:23552
	global_load_lds_dwordx4 v[188:189], off
	s_mov_b32 m0, s62
	v_lshl_add_u64 v[192:193], s[20:21], 0, v[128:129]
	global_load_lds_dwordx4 v[192:193], off
	s_barrier
	s_waitcnt lgkmcnt(0)
	v_mfma_f32_16x16x32_bf16 v[60:63], v[134:137], v[158:161], v[60:63]
	v_mfma_f32_16x16x32_bf16 v[56:59], v[150:153], v[158:161], v[56:59]
	v_mfma_f32_16x16x32_bf16 v[52:55], v[134:137], v[166:169], v[52:55]
	v_mfma_f32_16x16x32_bf16 v[44:47], v[150:153], v[166:169], v[44:47]
	v_mfma_f32_16x16x32_bf16 v[36:39], v[134:137], v[174:177], v[36:39]
	v_mfma_f32_16x16x32_bf16 v[28:31], v[150:153], v[174:177], v[28:31]
	v_mfma_f32_16x16x32_bf16 v[20:23], v[134:137], v[182:185], v[20:23]
	v_mfma_f32_16x16x32_bf16 v[12:15], v[150:153], v[182:185], v[12:15]
	v_mfma_f32_16x16x32_bf16 v[60:63], v[146:149], v[162:165], v[60:63]
	v_mfma_f32_16x16x32_bf16 v[56:59], v[154:157], v[162:165], v[56:59]
	v_mfma_f32_16x16x32_bf16 v[52:55], v[146:149], v[170:173], v[52:55]
	v_mfma_f32_16x16x32_bf16 v[44:47], v[154:157], v[170:173], v[44:47]
	v_mfma_f32_16x16x32_bf16 v[36:39], v[146:149], v[178:181], v[36:39]
	v_mfma_f32_16x16x32_bf16 v[28:31], v[154:157], v[178:181], v[28:31]
	v_mfma_f32_16x16x32_bf16 v[20:23], v[146:149], v[196:199], v[20:23]
	v_mfma_f32_16x16x32_bf16 v[12:15], v[154:157], v[196:199], v[12:15]
	s_barrier
; #define PG8_STAGE(bufoff, gbase, voff) do { _Pragma("unroll") for (int _i = 0; _i < 2; ++_i) \
;         __builtin_amdgcn_global_load_lds((const unsigned*)((const char*)(gbase) + (voff)[_i]), (LAS unsigned*)(lds + (bufoff) + ldsw + _i * 8192), 16, 0, 0); } while (0)
; #define PG8_LDA(dst, b, h) do { _Pragma("unroll") for (int m = 0; m < 4; ++m) _Pragma("unroll") for (int k = 0; k < 2; ++k) dst[m][k] = *(const LAS bf16x8*)(lds + PG8_SA(b, h) + aoff + m * 2048 + k * 1024); } while (0)
; #define PG8_LDB(dst, b, h) do { _Pragma("unroll") for (int n = 0; n < 2; ++n) _Pragma("unroll") for (int k = 0; k < 2; ++k) dst[n][k] = *(const LAS bf16x8*)(lds + PG8_SB(b, h) + boff + n * 2048 + k * 1024); } while (0)
; #define PG8_MMA(ai, bj, At, Bt) do { __builtin_amdgcn_s_setprio(1); _Pragma("unroll") for (int m = 0; m < 4; ++m) _Pragma("unroll") for (int n = 0; n < 2; ++n) _Pragma("unroll") for (int k = 0; k < 2; ++k) \
;         acc[ai][bj][m][n] = __builtin_amdgcn_mfma_f32_16x16x32_bf16(Bt[n][k], At[m][k], acc[ai][bj][m][n], 0, 0, 0); __builtin_amdgcn_s_setprio(0); } while (0)
; #define PG8_WAIT_V(n) asm volatile("s_waitcnt vmcnt(" #n ")" ::: "memory")
; #define PG8_WAIT_L(n) asm volatile("s_waitcnt lgkmcnt(" #n ")" ::: "memory")
; #define PG8_BAR __builtin_amdgcn_s_barrier()
; #define PG8_SCHED __builtin_amdgcn_sched_barrier(0)
; template <class Epi>
; __device__ __forceinline__ void gemm_phase(LAS unsigned char* lds, const Gemm g, const StaticOrder& S, const Epi& E) {
;     ...
;             PG8_STAGE(PG8_SB(0, 1), b2 + hB, voffB);
;             PG8_WAIT_V(6); PG8_BAR; PG8_MMA(1, 1, At, B1); PG8_BAR;
;             PG8_LDB(B0, 1, 0); PG8_SCHED; PG8_LDA(At, 1, 0); PG8_STAGE(PG8_SA(0, 1), a2 + hA, voffA);
;             PG8_WAIT_L(8); PG8_BAR; PG8_WAIT_L(0); PG8_MMA(0, 0, At, B0); PG8_BAR; PG8_SCHED;
;             PG8_LDB(B1, 1, 1); PG8_STAGE(PG8_SB(1, 0), b3, voffB);
;             PG8_BAR; PG8_WAIT_L(0); PG8_MMA(0, 1, At, B1); PG8_BAR;
;             PG8_LDA(At, 1, 1); PG8_STAGE(PG8_SA(1, 0), a3, voffA);
	s_add_u32 s26, s16, 0x40000
	s_addc_u32 s27, s17, 0
	s_add_i32 s28, s28, s35
	s_mov_b32 m0, s28
	v_lshl_add_u64 v[134:135], s[26:27], 0, v[144:145]
	global_load_lds_dwordx4 v[134:135], off
	s_add_i32 m0, s28, 0x2000
	v_lshl_add_u64 v[134:135], s[26:27], 0, v[128:129]
	global_load_lds_dwordx4 v[134:135], off
	s_waitcnt vmcnt(6)
	s_barrier
	v_mfma_f32_16x16x32_bf16 v[48:51], v[200:203], v[158:161], v[48:51]
	v_mfma_f32_16x16x32_bf16 v[40:43], v[214:217], v[158:161], v[40:43]
	v_mfma_f32_16x16x32_bf16 v[32:35], v[200:203], v[166:169], v[32:35]
	v_mfma_f32_16x16x32_bf16 v[24:27], v[214:217], v[166:169], v[24:27]
	v_mfma_f32_16x16x32_bf16 v[16:19], v[200:203], v[174:177], v[16:19]
	v_mfma_f32_16x16x32_bf16 v[8:11], v[214:217], v[174:177], v[8:11]
	v_mfma_f32_16x16x32_bf16 v[4:7], v[200:203], v[182:185], v[4:7]
	v_mfma_f32_16x16x32_bf16 v[0:3], v[214:217], v[182:185], v[0:3]
	v_mfma_f32_16x16x32_bf16 v[48:51], v[204:207], v[162:165], v[48:51]
	v_mfma_f32_16x16x32_bf16 v[40:43], v[218:221], v[162:165], v[40:43]
	v_mfma_f32_16x16x32_bf16 v[32:35], v[204:207], v[170:173], v[32:35]
	v_mfma_f32_16x16x32_bf16 v[24:27], v[218:221], v[170:173], v[24:27]
	v_mfma_f32_16x16x32_bf16 v[16:19], v[204:207], v[178:181], v[16:19]
	v_mfma_f32_16x16x32_bf16 v[8:11], v[218:221], v[178:181], v[8:11]
	v_mfma_f32_16x16x32_bf16 v[4:7], v[204:207], v[196:199], v[4:7]
	v_mfma_f32_16x16x32_bf16 v[0:3], v[218:221], v[196:199], v[0:3]
	s_add_i32 s26, 0, 0x18000
	v_add_u32_e32 v154, s26, v139
	s_barrier
	ds_read_b128 v[134:137], v154
	ds_read_b128 v[146:149], v154 offset:1024
	ds_read_b128 v[150:153], v154 offset:2048
	ds_read_b128 v[154:157], v154 offset:3072
	s_add_u32 s20, s20, 0x40000
	s_addc_u32 s21, s21, 0
	s_mov_b32 m0, s63
	v_lshl_add_u64 v[200:201], s[20:21], 0, v[144:145]
	ds_read_b128 v[158:161], v141 offset:32768
	ds_read_b128 v[162:165], v141 offset:33792
	ds_read_b128 v[166:169], v141 offset:34816
	ds_read_b128 v[170:173], v141 offset:35840
	ds_read_b128 v[174:177], v141 offset:36864
	ds_read_b128 v[178:181], v141 offset:37888
	ds_read_b128 v[182:185], v141 offset:38912
	ds_read_b128 v[196:199], v141 offset:39936
	global_load_lds_dwordx4 v[200:201], off
	s_mov_b32 m0, s64
	v_lshl_add_u64 v[200:201], s[20:21], 0, v[128:129]
	global_load_lds_dwordx4 v[200:201], off
	s_waitcnt lgkmcnt(8)
	s_barrier
	s_waitcnt lgkmcnt(0)
	v_mfma_f32_16x16x32_bf16 v[124:127], v[134:137], v[158:161], v[124:127]
	v_mfma_f32_16x16x32_bf16 v[120:123], v[150:153], v[158:161], v[120:123]
	v_mfma_f32_16x16x32_bf16 v[116:119], v[134:137], v[166:169], v[116:119]
	v_mfma_f32_16x16x32_bf16 v[108:111], v[150:153], v[166:169], v[108:111]
	v_mfma_f32_16x16x32_bf16 v[100:103], v[134:137], v[174:177], v[100:103]
	v_mfma_f32_16x16x32_bf16 v[92:95], v[150:153], v[174:177], v[92:95]
	v_mfma_f32_16x16x32_bf16 v[84:87], v[134:137], v[182:185], v[84:87]
	v_mfma_f32_16x16x32_bf16 v[76:79], v[150:153], v[182:185], v[76:79]
	v_mfma_f32_16x16x32_bf16 v[124:127], v[146:149], v[162:165], v[124:127]
	v_mfma_f32_16x16x32_bf16 v[120:123], v[154:157], v[162:165], v[120:123]
	v_mfma_f32_16x16x32_bf16 v[116:119], v[146:149], v[170:173], v[116:119]
	v_mfma_f32_16x16x32_bf16 v[108:111], v[154:157], v[170:173], v[108:111]
	v_mfma_f32_16x16x32_bf16 v[100:103], v[146:149], v[178:181], v[100:103]
	v_mfma_f32_16x16x32_bf16 v[92:95], v[154:157], v[178:181], v[92:95]
	v_mfma_f32_16x16x32_bf16 v[84:87], v[146:149], v[196:199], v[84:87]
	v_mfma_f32_16x16x32_bf16 v[76:79], v[154:157], v[196:199], v[76:79]
	s_barrier
	s_add_i32 s20, 0, 0x1c000
	s_add_i32 s21, s26, s35
	v_add_u32_e32 v190, s20, v139
	v_lshl_add_u64 v[142:143], v[142:143], 0, s[88:89]
	s_mov_b32 m0, s21
	ds_read_b128 v[200:203], v190
	ds_read_b128 v[204:207], v190 offset:1024
	ds_read_b128 v[214:217], v190 offset:2048
	ds_read_b128 v[218:221], v190 offset:3072
	global_load_lds_dwordx4 v[142:143], off
	s_add_i32 m0, s21, 0x2000
	v_lshl_add_u64 v[142:143], v[186:187], 0, s[88:89]
	global_load_lds_dwordx4 v[142:143], off
	s_barrier
	s_waitcnt lgkmcnt(0)
	v_mfma_f32_16x16x32_bf16 v[112:115], v[200:203], v[158:161], v[112:115]
	v_mfma_f32_16x16x32_bf16 v[104:107], v[214:217], v[158:161], v[104:107]
	v_mfma_f32_16x16x32_bf16 v[96:99], v[200:203], v[166:169], v[96:99]
	v_mfma_f32_16x16x32_bf16 v[88:91], v[214:217], v[166:169], v[88:91]
	v_mfma_f32_16x16x32_bf16 v[80:83], v[200:203], v[174:177], v[80:83]
	v_mfma_f32_16x16x32_bf16 v[72:75], v[214:217], v[174:177], v[72:75]
	v_mfma_f32_16x16x32_bf16 v[68:71], v[200:203], v[182:185], v[68:71]
	v_mfma_f32_16x16x32_bf16 v[64:67], v[214:217], v[182:185], v[64:67]
	v_mfma_f32_16x16x32_bf16 v[112:115], v[204:207], v[162:165], v[112:115]
	v_mfma_f32_16x16x32_bf16 v[104:107], v[218:221], v[162:165], v[104:107]
	v_mfma_f32_16x16x32_bf16 v[96:99], v[204:207], v[170:173], v[96:99]
	v_mfma_f32_16x16x32_bf16 v[88:91], v[218:221], v[170:173], v[88:91]
	v_mfma_f32_16x16x32_bf16 v[80:83], v[204:207], v[178:181], v[80:83]
	v_mfma_f32_16x16x32_bf16 v[72:75], v[218:221], v[178:181], v[72:75]
	v_mfma_f32_16x16x32_bf16 v[68:71], v[204:207], v[196:199], v[68:71]
	v_mfma_f32_16x16x32_bf16 v[64:67], v[218:221], v[196:199], v[64:67]
	s_mov_b32 m0, s65
	v_lshl_add_u64 v[142:143], v[188:189], 0, s[88:89]
	s_barrier
	ds_read_b128 v[158:161], v141 offset:49152
	ds_read_b128 v[162:165], v141 offset:50176
	ds_read_b128 v[166:169], v141 offset:51200
	ds_read_b128 v[170:173], v141 offset:52224
	ds_read_b128 v[174:177], v141 offset:53248
	ds_read_b128 v[178:181], v141 offset:54272
	ds_read_b128 v[182:185], v141 offset:55296
	ds_read_b128 v[196:199], v141 offset:56320
	global_load_lds_dwordx4 v[142:143], off
	s_mov_b32 m0, s66
	v_lshl_add_u64 v[142:143], v[192:193], 0, s[88:89]
	global_load_lds_dwordx4 v[142:143], off
	s_barrier
; #define PG8_STAGE(bufoff, gbase, voff) do { _Pragma("unroll") for (int _i = 0; _i < 2; ++_i) \
;         __builtin_amdgcn_global_load_lds((const unsigned*)((const char*)(gbase) + (voff)[_i]), (LAS unsigned*)(lds + (bufoff) + ldsw + _i * 8192), 16, 0, 0); } while (0)
; #define PG8_MMA(ai, bj, At, Bt) do { __builtin_amdgcn_s_setprio(1); _Pragma("unroll") for (int m = 0; m < 4; ++m) _Pragma("unroll") for (int n = 0; n < 2; ++n) _Pragma("unroll") for (int k = 0; k < 2; ++k) \
;         acc[ai][bj][m][n] = __builtin_amdgcn_mfma_f32_16x16x32_bf16(Bt[n][k], At[m][k], acc[ai][bj][m][n], 0, 0, 0); __builtin_amdgcn_s_setprio(0); } while (0)
; #define PG8_WAIT_V(n) asm volatile("s_waitcnt vmcnt(" #n ")" ::: "memory")
; #define PG8_WAIT_L(n) asm volatile("s_waitcnt lgkmcnt(" #n ")" ::: "memory")
; #define PG8_BAR __builtin_amdgcn_s_barrier()
; #define PG8_SCHED __builtin_amdgcn_sched_barrier(0)
; template <class Epi>
; __device__ __forceinline__ void gemm_phase(LAS unsigned char* lds, const Gemm g, const StaticOrder& S, const Epi& E) {
;     ...
;             PG8_BAR; PG8_WAIT_L(0); PG8_MMA(1, 0, At, B0); PG8_BAR; PG8_SCHED;
;             PG8_STAGE(PG8_SB(1, 1), b3 + hB, voffB);
;             PG8_WAIT_V(6); PG8_BAR; PG8_MMA(1, 1, At, B1); PG8_BAR;
	s_waitcnt lgkmcnt(0)
	v_mfma_f32_16x16x32_bf16 v[60:63], v[134:137], v[158:161], v[60:63]
	v_mfma_f32_16x16x32_bf16 v[56:59], v[150:153], v[158:161], v[56:59]
	v_mfma_f32_16x16x32_bf16 v[52:55], v[134:137], v[166:169], v[52:55]
	v_mfma_f32_16x16x32_bf16 v[44:47], v[150:153], v[166:169], v[44:47]
	v_mfma_f32_16x16x32_bf16 v[36:39], v[134:137], v[174:177], v[36:39]
	v_mfma_f32_16x16x32_bf16 v[28:31], v[150:153], v[174:177], v[28:31]
	v_mfma_f32_16x16x32_bf16 v[20:23], v[134:137], v[182:185], v[20:23]
	v_mfma_f32_16x16x32_bf16 v[12:15], v[150:153], v[182:185], v[12:15]
	v_mfma_f32_16x16x32_bf16 v[60:63], v[146:149], v[162:165], v[60:63]
	v_mfma_f32_16x16x32_bf16 v[56:59], v[154:157], v[162:165], v[56:59]
	v_mfma_f32_16x16x32_bf16 v[52:55], v[146:149], v[170:173], v[52:55]
	v_mfma_f32_16x16x32_bf16 v[44:47], v[154:157], v[170:173], v[44:47]
	v_mfma_f32_16x16x32_bf16 v[36:39], v[146:149], v[178:181], v[36:39]
	v_mfma_f32_16x16x32_bf16 v[28:31], v[154:157], v[178:181], v[28:31]
	v_mfma_f32_16x16x32_bf16 v[20:23], v[146:149], v[196:199], v[20:23]
	v_mfma_f32_16x16x32_bf16 v[12:15], v[154:157], v[196:199], v[12:15]
	s_barrier
	s_add_u32 s16, s16, 0x40080
	s_addc_u32 s17, s17, 0
	s_add_i32 s20, s20, s35
	s_mov_b32 m0, s20
	v_lshl_add_u64 v[134:135], s[16:17], 0, v[144:145]
	global_load_lds_dwordx4 v[134:135], off
	s_add_i32 m0, s20, 0x2000
	v_lshl_add_u64 v[134:135], s[16:17], 0, v[128:129]
	global_load_lds_dwordx4 v[134:135], off
	s_waitcnt vmcnt(6)
	s_barrier
	v_mfma_f32_16x16x32_bf16 v[48:51], v[200:203], v[158:161], v[48:51]
	v_mfma_f32_16x16x32_bf16 v[40:43], v[214:217], v[158:161], v[40:43]
	v_mfma_f32_16x16x32_bf16 v[32:35], v[200:203], v[166:169], v[32:35]
	v_mfma_f32_16x16x32_bf16 v[24:27], v[214:217], v[166:169], v[24:27]
	v_mfma_f32_16x16x32_bf16 v[16:19], v[200:203], v[174:177], v[16:19]
	v_mfma_f32_16x16x32_bf16 v[8:11], v[214:217], v[174:177], v[8:11]
	v_mfma_f32_16x16x32_bf16 v[4:7], v[200:203], v[182:185], v[4:7]
	v_mfma_f32_16x16x32_bf16 v[0:3], v[214:217], v[182:185], v[0:3]
	v_mfma_f32_16x16x32_bf16 v[48:51], v[204:207], v[162:165], v[48:51]
	v_mfma_f32_16x16x32_bf16 v[40:43], v[218:221], v[162:165], v[40:43]
	v_mfma_f32_16x16x32_bf16 v[32:35], v[204:207], v[170:173], v[32:35]
	v_mfma_f32_16x16x32_bf16 v[24:27], v[218:221], v[170:173], v[24:27]
	v_mfma_f32_16x16x32_bf16 v[16:19], v[204:207], v[178:181], v[16:19]
	v_mfma_f32_16x16x32_bf16 v[8:11], v[218:221], v[178:181], v[8:11]
	v_mfma_f32_16x16x32_bf16 v[4:7], v[204:207], v[196:199], v[4:7]
	v_mfma_f32_16x16x32_bf16 v[0:3], v[218:221], v[196:199], v[0:3]
	s_add_i32 s77, s77, 2
	s_add_u32 s12, s12, 0x100
	s_addc_u32 s13, s13, 0
	s_add_u32 s25, s25, 0x100
	s_addc_u32 s76, s76, 0
	s_cmp_gt_u32 s77, 13
	s_barrier
	s_cbranch_scc0 .LBB0_1079
; __device__ __forceinline__ unsigned pk2(float lo, float hi) { unsigned r; asm("v_cvt_pk_bf16_f32 %0, %1, %2" : "=v"(r) : "v"(lo), "v"(hi)); return r; }
;     __device__ __forceinline__ void operator()(const f32x4 (&acc)[2][2][4][2], const Unit& u, int wr, int wc, int fr, int fq) const {
;     ...
;         const int row_t = rmap == 1 ? odd_phys_row0(u.pm, grp) : (rmap == 2 ? odd_phys_row0(u.pm % (BG * TPB), u.pm / (BG * TPB)) : u.pm * BM);
;         int c = col_t + 64 * wc + 16 * fq;
;         if (mode == 2) c = (c >> 6) * 96 + (c & 63);
; #pragma unroll
;         for (int ai = 0; ai < 2; ++ai)
; #pragma unroll
;             for (int m = 0; m < 4; ++m) {
;                 const int row = row_t + ai * HALF + wr * 64 + m * 16 + fr;
;                 bf16_t* rp = O + (size_t)row * ldc + c;
; #pragma unroll
;                 for (int bj = 0; bj < 2; ++bj) {
;                     const f32x4 v0 = acc[ai][bj][m][0], v1 = acc[ai][bj][m][1];
;                     u32x4 o; o.x = pk2(v0[0], v0[1]); o.y = pk2(v0[2], v0[3]); o.z = pk2(v1[0], v1[1]); o.w = pk2(v1[2], v1[3]);
;                     *(u32x4*)(rp + 8 * bj) = o;
;                 }
;             }
	v_lshl_or_b32 v136, s15, 8, v140
	v_lshl_add_u32 v146, s70, 8, v138
	v_ashrrev_i32_e32 v137, 31, v136
	v_mov_b64_e32 v[134:135], s[4:5]
	s_movk_i32 s7, 0x1400
	v_cvt_pk_bf16_f32 v68, v68, v69
	v_cvt_pk_bf16_f32 v69, v70, v71
	v_cvt_pk_bf16_f32 v70, v64, v65
	v_add_u32_e32 v64, 0x80, v146
	v_mad_i64_i32 v[142:143], s[12:13], v146, s7, v[134:135]
	v_lshlrev_b64 v[136:137], 1, v[136:137]
	v_cvt_pk_bf16_f32 v112, v112, v113
	v_cvt_pk_bf16_f32 v113, v114, v115
	v_cvt_pk_bf16_f32 v114, v104, v105
	v_or_b32_e32 v104, 16, v146
	v_mad_i64_i32 v[64:65], s[12:13], v64, s7, v[134:135]
	v_cvt_pk_bf16_f32 v48, v48, v49
	v_cvt_pk_bf16_f32 v49, v50, v51
	v_cvt_pk_bf16_f32 v50, v40, v41
	v_add_u32_e32 v40, 0x90, v146
	v_lshl_add_u64 v[142:143], v[142:143], 0, v[136:137]
	v_mad_i64_i32 v[104:105], s[12:13], v104, s7, v[134:135]
	v_cvt_pk_bf16_f32 v96, v96, v97
	v_cvt_pk_bf16_f32 v97, v98, v99
	v_cvt_pk_bf16_f32 v98, v88, v89
	v_or_b32_e32 v88, 32, v146
	v_lshl_add_u64 v[64:65], v[64:65], 0, v[136:137]
	v_mad_i64_i32 v[40:41], s[12:13], v40, s7, v[134:135]
	v_cvt_pk_bf16_f32 v32, v32, v33
	v_cvt_pk_bf16_f32 v33, v34, v35
	v_cvt_pk_bf16_f32 v34, v24, v25
	v_add_u32_e32 v24, 0xa0, v146
	v_cvt_pk_bf16_f32 v115, v106, v107
	global_store_dwordx4 v[142:143], v[112:115], off offset:16
	v_mad_i64_i32 v[88:89], s[12:13], v88, s7, v[134:135]
	s_nop 0
	v_lshl_add_u64 v[112:113], v[104:105], 0, v[136:137]
	v_cvt_pk_bf16_f32 v80, v80, v81
	v_cvt_pk_bf16_f32 v81, v82, v83
	v_cvt_pk_bf16_f32 v82, v72, v73
	v_or_b32_e32 v72, 48, v146
	v_cvt_pk_bf16_f32 v51, v42, v43
	global_store_dwordx4 v[64:65], v[48:51], off offset:16
	v_mad_i64_i32 v[24:25], s[12:13], v24, s7, v[134:135]
	s_nop 0
	v_lshl_add_u64 v[48:49], v[40:41], 0, v[136:137]
	v_cvt_pk_bf16_f32 v16, v16, v17
	v_cvt_pk_bf16_f32 v17, v18, v19
	v_cvt_pk_bf16_f32 v18, v8, v9
	v_add_u32_e32 v8, 0xb0, v146
	v_cvt_pk_bf16_f32 v99, v90, v91
	global_store_dwordx4 v[112:113], v[96:99], off offset:16
	v_mad_i64_i32 v[72:73], s[12:13], v72, s7, v[134:135]
	s_nop 0
	v_lshl_add_u64 v[96:97], v[88:89], 0, v[136:137]
	v_cvt_pk_bf16_f32 v35, v26, v27
	global_store_dwordx4 v[48:49], v[32:35], off offset:16
	v_mad_i64_i32 v[8:9], s[12:13], v8, s7, v[134:135]
	s_nop 0
	v_lshl_add_u64 v[32:33], v[24:25], 0, v[136:137]
	v_cvt_pk_bf16_f32 v83, v74, v75
	global_store_dwordx4 v[96:97], v[80:83], off offset:16
	v_cvt_pk_bf16_f32 v19, v10, v11
	global_store_dwordx4 v[32:33], v[16:19], off offset:16
	s_and_b64 vcc, exec, s[0:1]
	v_lshl_add_u64 v[80:81], v[72:73], 0, v[136:137]
	v_lshl_add_u64 v[16:17], v[8:9], 0, v[136:137]
	s_mov_b32 s15, s6
	s_mov_b32 s70, s69
	s_mov_b64 s[16:17], s[10:11]
	s_mov_b64 s[12:13], s[8:9]
	v_cvt_pk_bf16_f32 v124, v124, v125
	v_cvt_pk_bf16_f32 v125, v126, v127
	v_cvt_pk_bf16_f32 v126, v120, v121
	v_cvt_pk_bf16_f32 v127, v122, v123
	global_store_dwordx4 v[142:143], v[124:127], off
	v_cvt_pk_bf16_f32 v104, v116, v117
	v_cvt_pk_bf16_f32 v105, v118, v119
	v_cvt_pk_bf16_f32 v106, v108, v109
	v_cvt_pk_bf16_f32 v107, v110, v111
	global_store_dwordx4 v[112:113], v[104:107], off
	v_cvt_pk_bf16_f32 v88, v100, v101
	v_cvt_pk_bf16_f32 v89, v102, v103
	v_cvt_pk_bf16_f32 v90, v92, v93
	v_cvt_pk_bf16_f32 v91, v94, v95
	global_store_dwordx4 v[96:97], v[88:91], off
	v_cvt_pk_bf16_f32 v72, v84, v85
	v_cvt_pk_bf16_f32 v73, v86, v87
	v_cvt_pk_bf16_f32 v74, v76, v77
	v_cvt_pk_bf16_f32 v75, v78, v79
	global_store_dwordx4 v[80:81], v[72:75], off
	v_cvt_pk_bf16_f32 v71, v66, v67
	global_store_dwordx4 v[80:81], v[68:71], off offset:16
	v_cvt_pk_bf16_f32 v60, v60, v61
	v_cvt_pk_bf16_f32 v61, v62, v63
	v_cvt_pk_bf16_f32 v62, v56, v57
	v_cvt_pk_bf16_f32 v63, v58, v59
	global_store_dwordx4 v[64:65], v[60:63], off
	v_cvt_pk_bf16_f32 v40, v52, v53
	v_cvt_pk_bf16_f32 v41, v54, v55
	v_cvt_pk_bf16_f32 v42, v44, v45
	v_cvt_pk_bf16_f32 v43, v46, v47
	global_store_dwordx4 v[48:49], v[40:43], off
	v_cvt_pk_bf16_f32 v24, v36, v37
	v_cvt_pk_bf16_f32 v25, v38, v39
	v_cvt_pk_bf16_f32 v26, v28, v29
	v_cvt_pk_bf16_f32 v27, v30, v31
	global_store_dwordx4 v[32:33], v[24:27], off
	v_cvt_pk_bf16_f32 v8, v20, v21
	v_cvt_pk_bf16_f32 v9, v22, v23
	v_cvt_pk_bf16_f32 v10, v12, v13
	v_cvt_pk_bf16_f32 v11, v14, v15
	global_store_dwordx4 v[16:17], v[8:11], off
	v_cvt_pk_bf16_f32 v4, v4, v5
	v_cvt_pk_bf16_f32 v5, v6, v7
	v_cvt_pk_bf16_f32 v6, v0, v1
	v_cvt_pk_bf16_f32 v7, v2, v3
	global_store_dwordx4 v[16:17], v[4:7], off offset:16
	s_cbranch_vccz .LBB0_1076
	s_waitcnt vmcnt(0)
	s_cmpk_gt_u32 s3, 0xff
	s_cbranch_scc1 .LBB0_1083
	s_barrier

; #define PG8_STAGE(bufoff, gbase, voff) do { _Pragma("unroll") for (int _i = 0; _i < 2; ++_i) \
;         __builtin_amdgcn_global_load_lds((const unsigned*)((const char*)(gbase) + (voff)[_i]), (LAS unsigned*)(lds + (bufoff) + ldsw + _i * 8192), 16, 0, 0); } while (0)
; #define PG8_LDA(dst, b, h) do { _Pragma("unroll") for (int m = 0; m < 4; ++m) _Pragma("unroll") for (int k = 0; k < 2; ++k) dst[m][k] = *(const LAS bf16x8*)(lds + PG8_SA(b, h) + aoff + m * 2048 + k * 1024); } while (0)
; #define PG8_LDB(dst, b, h) do { _Pragma("unroll") for (int n = 0; n < 2; ++n) _Pragma("unroll") for (int k = 0; k < 2; ++k) dst[n][k] = *(const LAS bf16x8*)(lds + PG8_SB(b, h) + boff + n * 2048 + k * 1024); } while (0)
; #define PG8_MMA(ai, bj, At, Bt) do { __builtin_amdgcn_s_setprio(1); _Pragma("unroll") for (int m = 0; m < 4; ++m) _Pragma("unroll") for (int n = 0; n < 2; ++n) _Pragma("unroll") for (int k = 0; k < 2; ++k) \
;         acc[ai][bj][m][n] = __builtin_amdgcn_mfma_f32_16x16x32_bf16(Bt[n][k], At[m][k], acc[ai][bj][m][n], 0, 0, 0); __builtin_amdgcn_s_setprio(0); } while (0)
; #define PG8_WAIT_L(n) asm volatile("s_waitcnt lgkmcnt(" #n ")" ::: "memory")
; #define PG8_BAR __builtin_amdgcn_s_barrier()
; #define PG8_SCHED __builtin_amdgcn_sched_barrier(0)
; template <class Epi>
; __device__ __forceinline__ void gemm_phase(LAS unsigned char* lds, const Gemm g, const StaticOrder& S, const Epi& E) {
;     ...
;             const bool last = (t == nt - 2);
;             const char* a1 = cA + (size_t)(t + 1) * kstep;
;             const char* a2 = last ? nA : cA + (size_t)(t + 2) * kstep; const char* b2 = last ? nB : cB + (size_t)(t + 2) * kstep;
;             const char* a3 = a2 + kstep; const char* b3 = b2 + kstep;
;             PG8_LDB(B0, 0, 0); PG8_SCHED; PG8_LDA(At, 0, 0); PG8_STAGE(PG8_SA(1, 1), a1 + hA, voffA);
;             PG8_WAIT_L(8); PG8_BAR; PG8_WAIT_L(0); PG8_MMA(0, 0, At, B0); PG8_BAR; PG8_SCHED;
;             PG8_LDB(B1, 0, 1); PG8_STAGE(PG8_SB(0, 0), b2, voffB);
;             PG8_BAR; PG8_WAIT_L(0); PG8_MMA(0, 1, At, B1); PG8_BAR;
;             PG8_LDA(At, 0, 1); PG8_STAGE(PG8_SA(0, 0), a2, voffA);
;             PG8_BAR; PG8_WAIT_L(0); PG8_MMA(1, 0, At, B0); PG8_BAR; PG8_SCHED;
.LBB0_1270:
	s_add_u32 s16, s12, 0xfffc0080
	s_addc_u32 s17, s13, -1
	s_add_i32 s26, 0, 0x10000
	v_add_u32_e32 v142, s26, v139
	ds_read_b128 v[134:137], v142
	ds_read_b128 v[146:149], v142 offset:1024
	ds_read_b128 v[150:153], v142 offset:2048
	ds_read_b128 v[154:157], v142 offset:3072
	s_cmp_eq_u32 s77, 12
	s_cselect_b32 s21, s71, s17
	s_cselect_b32 s20, s72, s16
	s_cselect_b32 s17, s7, s76
	s_cselect_b32 s16, s24, s25
	v_lshl_add_u64 v[142:143], s[12:13], 0, v[130:131]
	s_add_i32 m0, s61, 0xc000
	ds_read_b128 v[158:161], v141
	ds_read_b128 v[162:165], v141 offset:1024
	ds_read_b128 v[166:169], v141 offset:2048
	ds_read_b128 v[170:173], v141 offset:3072
	ds_read_b128 v[174:177], v141 offset:4096
	ds_read_b128 v[178:181], v141 offset:5120
	ds_read_b128 v[182:185], v141 offset:6144
	ds_read_b128 v[196:199], v141 offset:7168
	global_load_lds_dwordx4 v[142:143], off
	s_add_i32 m0, s61, 0xe000
	v_lshl_add_u64 v[142:143], s[12:13], 0, v[132:133]
	global_load_lds_dwordx4 v[142:143], off
	s_waitcnt lgkmcnt(8)
	s_barrier
	s_waitcnt lgkmcnt(0)
	v_mfma_f32_16x16x32_bf16 v[124:127], v[134:137], v[158:161], v[124:127]
	v_mfma_f32_16x16x32_bf16 v[120:123], v[150:153], v[158:161], v[120:123]
	v_mfma_f32_16x16x32_bf16 v[116:119], v[134:137], v[166:169], v[116:119]
	v_mfma_f32_16x16x32_bf16 v[108:111], v[150:153], v[166:169], v[108:111]
	v_mfma_f32_16x16x32_bf16 v[100:103], v[134:137], v[174:177], v[100:103]
	v_mfma_f32_16x16x32_bf16 v[92:95], v[150:153], v[174:177], v[92:95]
	v_mfma_f32_16x16x32_bf16 v[84:87], v[134:137], v[182:185], v[84:87]
	v_mfma_f32_16x16x32_bf16 v[76:79], v[150:153], v[182:185], v[76:79]
	v_mfma_f32_16x16x32_bf16 v[124:127], v[146:149], v[162:165], v[124:127]
	v_mfma_f32_16x16x32_bf16 v[120:123], v[154:157], v[162:165], v[120:123]
	v_mfma_f32_16x16x32_bf16 v[116:119], v[146:149], v[170:173], v[116:119]
	v_mfma_f32_16x16x32_bf16 v[108:111], v[154:157], v[170:173], v[108:111]
	v_mfma_f32_16x16x32_bf16 v[100:103], v[146:149], v[178:181], v[100:103]
	v_mfma_f32_16x16x32_bf16 v[92:95], v[154:157], v[178:181], v[92:95]
	v_mfma_f32_16x16x32_bf16 v[84:87], v[146:149], v[196:199], v[84:87]
	v_mfma_f32_16x16x32_bf16 v[76:79], v[154:157], v[196:199], v[76:79]
	s_barrier
	s_add_i32 s28, 0, 0x14000
	v_add_u32_e32 v142, s28, v139
	s_add_i32 s26, s26, s35
	ds_read_b128 v[200:203], v142
	ds_read_b128 v[204:207], v142 offset:1024
	ds_read_b128 v[214:217], v142 offset:2048
	ds_read_b128 v[218:221], v142 offset:3072
	v_lshl_add_u64 v[142:143], s[16:17], 0, v[144:145]
	s_mov_b32 m0, s26
	v_lshl_add_u64 v[186:187], s[16:17], 0, v[128:129]
	global_load_lds_dwordx4 v[142:143], off
	s_add_i32 m0, s26, 0x2000
	s_nop 0
	global_load_lds_dwordx4 v[186:187], off
	s_barrier
	s_waitcnt lgkmcnt(0)
	v_mfma_f32_16x16x32_bf16 v[112:115], v[200:203], v[158:161], v[112:115]
	v_mfma_f32_16x16x32_bf16 v[104:107], v[214:217], v[158:161], v[104:107]
	v_mfma_f32_16x16x32_bf16 v[96:99], v[200:203], v[166:169], v[96:99]
	v_mfma_f32_16x16x32_bf16 v[88:91], v[214:217], v[166:169], v[88:91]
	v_mfma_f32_16x16x32_bf16 v[80:83], v[200:203], v[174:177], v[80:83]
	v_mfma_f32_16x16x32_bf16 v[72:75], v[214:217], v[174:177], v[72:75]
	v_mfma_f32_16x16x32_bf16 v[68:71], v[200:203], v[182:185], v[68:71]
	v_mfma_f32_16x16x32_bf16 v[64:67], v[214:217], v[182:185], v[64:67]
	v_mfma_f32_16x16x32_bf16 v[112:115], v[204:207], v[162:165], v[112:115]
	v_mfma_f32_16x16x32_bf16 v[104:107], v[218:221], v[162:165], v[104:107]
	v_mfma_f32_16x16x32_bf16 v[96:99], v[204:207], v[170:173], v[96:99]
	v_mfma_f32_16x16x32_bf16 v[88:91], v[218:221], v[170:173], v[88:91]
	v_mfma_f32_16x16x32_bf16 v[80:83], v[204:207], v[178:181], v[80:83]
	v_mfma_f32_16x16x32_bf16 v[72:75], v[218:221], v[178:181], v[72:75]
	v_mfma_f32_16x16x32_bf16 v[68:71], v[204:207], v[196:199], v[68:71]
	v_mfma_f32_16x16x32_bf16 v[64:67], v[218:221], v[196:199], v[64:67]
	s_mov_b32 m0, s61
	v_lshl_add_u64 v[188:189], s[20:21], 0, v[144:145]
	s_barrier
	ds_read_b128 v[158:161], v141 offset:16384
	ds_read_b128 v[162:165], v141 offset:17408
	ds_read_b128 v[166:169], v141 offset:18432
	ds_read_b128 v[170:173], v141 offset:19456
	ds_read_b128 v[174:177], v141 offset:20480
	ds_read_b128 v[178:181], v141 offset:21504
	ds_read_b128 v[182:185], v141 offset:22528
	ds_read_b128 v[196:199], v141 offset:23552
	global_load_lds_dwordx4 v[188:189], off
	s_mov_b32 m0, s62
	v_lshl_add_u64 v[192:193], s[20:21], 0, v[128:129]
	global_load_lds_dwordx4 v[192:193], off
	s_barrier
	s_waitcnt lgkmcnt(0)
	v_mfma_f32_16x16x32_bf16 v[60:63], v[134:137], v[158:161], v[60:63]
	v_mfma_f32_16x16x32_bf16 v[56:59], v[150:153], v[158:161], v[56:59]
	v_mfma_f32_16x16x32_bf16 v[52:55], v[134:137], v[166:169], v[52:55]
	v_mfma_f32_16x16x32_bf16 v[44:47], v[150:153], v[166:169], v[44:47]
	v_mfma_f32_16x16x32_bf16 v[36:39], v[134:137], v[174:177], v[36:39]
	v_mfma_f32_16x16x32_bf16 v[28:31], v[150:153], v[174:177], v[28:31]
	v_mfma_f32_16x16x32_bf16 v[20:23], v[134:137], v[182:185], v[20:23]
	v_mfma_f32_16x16x32_bf16 v[12:15], v[150:153], v[182:185], v[12:15]
	v_mfma_f32_16x16x32_bf16 v[60:63], v[146:149], v[162:165], v[60:63]
	v_mfma_f32_16x16x32_bf16 v[56:59], v[154:157], v[162:165], v[56:59]
	v_mfma_f32_16x16x32_bf16 v[52:55], v[146:149], v[170:173], v[52:55]
	v_mfma_f32_16x16x32_bf16 v[44:47], v[154:157], v[170:173], v[44:47]
	v_mfma_f32_16x16x32_bf16 v[36:39], v[146:149], v[178:181], v[36:39]
	v_mfma_f32_16x16x32_bf16 v[28:31], v[154:157], v[178:181], v[28:31]
	v_mfma_f32_16x16x32_bf16 v[20:23], v[146:149], v[196:199], v[20:23]
	v_mfma_f32_16x16x32_bf16 v[12:15], v[154:157], v[196:199], v[12:15]
	s_barrier
; #define PG8_STAGE(bufoff, gbase, voff) do { _Pragma("unroll") for (int _i = 0; _i < 2; ++_i) \
;         __builtin_amdgcn_global_load_lds((const unsigned*)((const char*)(gbase) + (voff)[_i]), (LAS unsigned*)(lds + (bufoff) + ldsw + _i * 8192), 16, 0, 0); } while (0)
; #define PG8_LDA(dst, b, h) do { _Pragma("unroll") for (int m = 0; m < 4; ++m) _Pragma("unroll") for (int k = 0; k < 2; ++k) dst[m][k] = *(const LAS bf16x8*)(lds + PG8_SA(b, h) + aoff + m * 2048 + k * 1024); } while (0)
; #define PG8_LDB(dst, b, h) do { _Pragma("unroll") for (int n = 0; n < 2; ++n) _Pragma("unroll") for (int k = 0; k < 2; ++k) dst[n][k] = *(const LAS bf16x8*)(lds + PG8_SB(b, h) + boff + n * 2048 + k * 1024); } while (0)
; #define PG8_MMA(ai, bj, At, Bt) do { __builtin_amdgcn_s_setprio(1); _Pragma("unroll") for (int m = 0; m < 4; ++m) _Pragma("unroll") for (int n = 0; n < 2; ++n) _Pragma("unroll") for (int k = 0; k < 2; ++k) \
;         acc[ai][bj][m][n] = __builtin_amdgcn_mfma_f32_16x16x32_bf16(Bt[n][k], At[m][k], acc[ai][bj][m][n], 0, 0, 0); __builtin_amdgcn_s_setprio(0); } while (0)
; #define PG8_WAIT_V(n) asm volatile("s_waitcnt vmcnt(" #n ")" ::: "memory")
; #define PG8_WAIT_L(n) asm volatile("s_waitcnt lgkmcnt(" #n ")" ::: "memory")
; #define PG8_BAR __builtin_amdgcn_s_barrier()
; #define PG8_SCHED __builtin_amdgcn_sched_barrier(0)
; template <class Epi>
; __device__ __forceinline__ void gemm_phase(LAS unsigned char* lds, const Gemm g, const StaticOrder& S, const Epi& E) {
;     ...
;             PG8_STAGE(PG8_SB(0, 1), b2 + hB, voffB);
;             PG8_WAIT_V(6); PG8_BAR; PG8_MMA(1, 1, At, B1); PG8_BAR;
;             PG8_LDB(B0, 1, 0); PG8_SCHED; PG8_LDA(At, 1, 0); PG8_STAGE(PG8_SA(0, 1), a2 + hA, voffA);
;             PG8_WAIT_L(8); PG8_BAR; PG8_WAIT_L(0); PG8_MMA(0, 0, At, B0); PG8_BAR; PG8_SCHED;
;             PG8_LDB(B1, 1, 1); PG8_STAGE(PG8_SB(1, 0), b3, voffB);
;             PG8_BAR; PG8_WAIT_L(0); PG8_MMA(0, 1, At, B1); PG8_BAR;
;             PG8_LDA(At, 1, 1); PG8_STAGE(PG8_SA(1, 0), a3, voffA);
	s_add_u32 s26, s16, 0x40000
	s_addc_u32 s27, s17, 0
	s_add_i32 s28, s28, s35
	s_mov_b32 m0, s28
	v_lshl_add_u64 v[134:135], s[26:27], 0, v[144:145]
	global_load_lds_dwordx4 v[134:135], off
	s_add_i32 m0, s28, 0x2000
	v_lshl_add_u64 v[134:135], s[26:27], 0, v[128:129]
	global_load_lds_dwordx4 v[134:135], off
	s_waitcnt vmcnt(6)
	s_barrier
	v_mfma_f32_16x16x32_bf16 v[48:51], v[200:203], v[158:161], v[48:51]
	v_mfma_f32_16x16x32_bf16 v[40:43], v[214:217], v[158:161], v[40:43]
	v_mfma_f32_16x16x32_bf16 v[32:35], v[200:203], v[166:169], v[32:35]
	v_mfma_f32_16x16x32_bf16 v[24:27], v[214:217], v[166:169], v[24:27]
	v_mfma_f32_16x16x32_bf16 v[16:19], v[200:203], v[174:177], v[16:19]
	v_mfma_f32_16x16x32_bf16 v[8:11], v[214:217], v[174:177], v[8:11]
	v_mfma_f32_16x16x32_bf16 v[4:7], v[200:203], v[182:185], v[4:7]
	v_mfma_f32_16x16x32_bf16 v[0:3], v[214:217], v[182:185], v[0:3]
	v_mfma_f32_16x16x32_bf16 v[48:51], v[204:207], v[162:165], v[48:51]
	v_mfma_f32_16x16x32_bf16 v[40:43], v[218:221], v[162:165], v[40:43]
	v_mfma_f32_16x16x32_bf16 v[32:35], v[204:207], v[170:173], v[32:35]
	v_mfma_f32_16x16x32_bf16 v[24:27], v[218:221], v[170:173], v[24:27]
	v_mfma_f32_16x16x32_bf16 v[16:19], v[204:207], v[178:181], v[16:19]
	v_mfma_f32_16x16x32_bf16 v[8:11], v[218:221], v[178:181], v[8:11]
	v_mfma_f32_16x16x32_bf16 v[4:7], v[204:207], v[196:199], v[4:7]
	v_mfma_f32_16x16x32_bf16 v[0:3], v[218:221], v[196:199], v[0:3]
	s_add_i32 s26, 0, 0x18000
	v_add_u32_e32 v154, s26, v139
	s_barrier
	ds_read_b128 v[134:137], v154
	ds_read_b128 v[146:149], v154 offset:1024
	ds_read_b128 v[150:153], v154 offset:2048
	ds_read_b128 v[154:157], v154 offset:3072
	s_add_u32 s20, s20, 0x40000
	s_addc_u32 s21, s21, 0
	s_mov_b32 m0, s63
	v_lshl_add_u64 v[200:201], s[20:21], 0, v[144:145]
	ds_read_b128 v[158:161], v141 offset:32768
	ds_read_b128 v[162:165], v141 offset:33792
	ds_read_b128 v[166:169], v141 offset:34816
	ds_read_b128 v[170:173], v141 offset:35840
	ds_read_b128 v[174:177], v141 offset:36864
	ds_read_b128 v[178:181], v141 offset:37888
	ds_read_b128 v[182:185], v141 offset:38912
	ds_read_b128 v[196:199], v141 offset:39936
	global_load_lds_dwordx4 v[200:201], off
	s_mov_b32 m0, s64
	v_lshl_add_u64 v[200:201], s[20:21], 0, v[128:129]
	global_load_lds_dwordx4 v[200:201], off
	s_waitcnt lgkmcnt(8)
	s_barrier
	s_waitcnt lgkmcnt(0)
	v_mfma_f32_16x16x32_bf16 v[124:127], v[134:137], v[158:161], v[124:127]
	v_mfma_f32_16x16x32_bf16 v[120:123], v[150:153], v[158:161], v[120:123]
	v_mfma_f32_16x16x32_bf16 v[116:119], v[134:137], v[166:169], v[116:119]
	v_mfma_f32_16x16x32_bf16 v[108:111], v[150:153], v[166:169], v[108:111]
	v_mfma_f32_16x16x32_bf16 v[100:103], v[134:137], v[174:177], v[100:103]
	v_mfma_f32_16x16x32_bf16 v[92:95], v[150:153], v[174:177], v[92:95]
	v_mfma_f32_16x16x32_bf16 v[84:87], v[134:137], v[182:185], v[84:87]
	v_mfma_f32_16x16x32_bf16 v[76:79], v[150:153], v[182:185], v[76:79]
	v_mfma_f32_16x16x32_bf16 v[124:127], v[146:149], v[162:165], v[124:127]
	v_mfma_f32_16x16x32_bf16 v[120:123], v[154:157], v[162:165], v[120:123]
	v_mfma_f32_16x16x32_bf16 v[116:119], v[146:149], v[170:173], v[116:119]
	v_mfma_f32_16x16x32_bf16 v[108:111], v[154:157], v[170:173], v[108:111]
	v_mfma_f32_16x16x32_bf16 v[100:103], v[146:149], v[178:181], v[100:103]
	v_mfma_f32_16x16x32_bf16 v[92:95], v[154:157], v[178:181], v[92:95]
	v_mfma_f32_16x16x32_bf16 v[84:87], v[146:149], v[196:199], v[84:87]
	v_mfma_f32_16x16x32_bf16 v[76:79], v[154:157], v[196:199], v[76:79]
	s_barrier
	s_add_i32 s20, 0, 0x1c000
	s_add_i32 s21, s26, s35
	v_add_u32_e32 v190, s20, v139
	v_lshl_add_u64 v[142:143], v[142:143], 0, s[88:89]
	s_mov_b32 m0, s21
	ds_read_b128 v[200:203], v190
	ds_read_b128 v[204:207], v190 offset:1024
	ds_read_b128 v[214:217], v190 offset:2048
	ds_read_b128 v[218:221], v190 offset:3072
	global_load_lds_dwordx4 v[142:143], off
	s_add_i32 m0, s21, 0x2000
	v_lshl_add_u64 v[142:143], v[186:187], 0, s[88:89]
	global_load_lds_dwordx4 v[142:143], off
	s_barrier
	s_waitcnt lgkmcnt(0)
	v_mfma_f32_16x16x32_bf16 v[112:115], v[200:203], v[158:161], v[112:115]
	v_mfma_f32_16x16x32_bf16 v[104:107], v[214:217], v[158:161], v[104:107]
	v_mfma_f32_16x16x32_bf16 v[96:99], v[200:203], v[166:169], v[96:99]
	v_mfma_f32_16x16x32_bf16 v[88:91], v[214:217], v[166:169], v[88:91]
	v_mfma_f32_16x16x32_bf16 v[80:83], v[200:203], v[174:177], v[80:83]
	v_mfma_f32_16x16x32_bf16 v[72:75], v[214:217], v[174:177], v[72:75]
	v_mfma_f32_16x16x32_bf16 v[68:71], v[200:203], v[182:185], v[68:71]
	v_mfma_f32_16x16x32_bf16 v[64:67], v[214:217], v[182:185], v[64:67]
	v_mfma_f32_16x16x32_bf16 v[112:115], v[204:207], v[162:165], v[112:115]
	v_mfma_f32_16x16x32_bf16 v[104:107], v[218:221], v[162:165], v[104:107]
	v_mfma_f32_16x16x32_bf16 v[96:99], v[204:207], v[170:173], v[96:99]
	v_mfma_f32_16x16x32_bf16 v[88:91], v[218:221], v[170:173], v[88:91]
	v_mfma_f32_16x16x32_bf16 v[80:83], v[204:207], v[178:181], v[80:83]
	v_mfma_f32_16x16x32_bf16 v[72:75], v[218:221], v[178:181], v[72:75]
	v_mfma_f32_16x16x32_bf16 v[68:71], v[204:207], v[196:199], v[68:71]
	v_mfma_f32_16x16x32_bf16 v[64:67], v[218:221], v[196:199], v[64:67]
	s_mov_b32 m0, s65
	v_lshl_add_u64 v[142:143], v[188:189], 0, s[88:89]
	s_barrier
	ds_read_b128 v[158:161], v141 offset:49152
	ds_read_b128 v[162:165], v141 offset:50176
	ds_read_b128 v[166:169], v141 offset:51200
	ds_read_b128 v[170:173], v141 offset:52224
	ds_read_b128 v[174:177], v141 offset:53248
	ds_read_b128 v[178:181], v141 offset:54272
	ds_read_b128 v[182:185], v141 offset:55296
	ds_read_b128 v[196:199], v141 offset:56320
	global_load_lds_dwordx4 v[142:143], off
	s_mov_b32 m0, s66
	v_lshl_add_u64 v[142:143], v[192:193], 0, s[88:89]
	global_load_lds_dwordx4 v[142:143], off
	s_barrier
; #define PG8_STAGE(bufoff, gbase, voff) do { _Pragma("unroll") for (int _i = 0; _i < 2; ++_i) \
;         __builtin_amdgcn_global_load_lds((const unsigned*)((const char*)(gbase) + (voff)[_i]), (LAS unsigned*)(lds + (bufoff) + ldsw + _i * 8192), 16, 0, 0); } while (0)
; #define PG8_MMA(ai, bj, At, Bt) do { __builtin_amdgcn_s_setprio(1); _Pragma("unroll") for (int m = 0; m < 4; ++m) _Pragma("unroll") for (int n = 0; n < 2; ++n) _Pragma("unroll") for (int k = 0; k < 2; ++k) \
;         acc[ai][bj][m][n] = __builtin_amdgcn_mfma_f32_16x16x32_bf16(Bt[n][k], At[m][k], acc[ai][bj][m][n], 0, 0, 0); __builtin_amdgcn_s_setprio(0); } while (0)
; #define PG8_WAIT_V(n) asm volatile("s_waitcnt vmcnt(" #n ")" ::: "memory")
; #define PG8_WAIT_L(n) asm volatile("s_waitcnt lgkmcnt(" #n ")" ::: "memory")
; #define PG8_BAR __builtin_amdgcn_s_barrier()
; #define PG8_SCHED __builtin_amdgcn_sched_barrier(0)
; template <class Epi>
; __device__ __forceinline__ void gemm_phase(LAS unsigned char* lds, const Gemm g, const StaticOrder& S, const Epi& E) {
;     ...
;             PG8_BAR; PG8_WAIT_L(0); PG8_MMA(1, 0, At, B0); PG8_BAR; PG8_SCHED;
;             PG8_STAGE(PG8_SB(1, 1), b3 + hB, voffB);
;             PG8_WAIT_V(6); PG8_BAR; PG8_MMA(1, 1, At, B1); PG8_BAR;
	s_waitcnt lgkmcnt(0)
	v_mfma_f32_16x16x32_bf16 v[60:63], v[134:137], v[158:161], v[60:63]
	v_mfma_f32_16x16x32_bf16 v[56:59], v[150:153], v[158:161], v[56:59]
	v_mfma_f32_16x16x32_bf16 v[52:55], v[134:137], v[166:169], v[52:55]
	v_mfma_f32_16x16x32_bf16 v[44:47], v[150:153], v[166:169], v[44:47]
	v_mfma_f32_16x16x32_bf16 v[36:39], v[134:137], v[174:177], v[36:39]
	v_mfma_f32_16x16x32_bf16 v[28:31], v[150:153], v[174:177], v[28:31]
	v_mfma_f32_16x16x32_bf16 v[20:23], v[134:137], v[182:185], v[20:23]
	v_mfma_f32_16x16x32_bf16 v[12:15], v[150:153], v[182:185], v[12:15]
	v_mfma_f32_16x16x32_bf16 v[60:63], v[146:149], v[162:165], v[60:63]
	v_mfma_f32_16x16x32_bf16 v[56:59], v[154:157], v[162:165], v[56:59]
	v_mfma_f32_16x16x32_bf16 v[52:55], v[146:149], v[170:173], v[52:55]
	v_mfma_f32_16x16x32_bf16 v[44:47], v[154:157], v[170:173], v[44:47]
	v_mfma_f32_16x16x32_bf16 v[36:39], v[146:149], v[178:181], v[36:39]
	v_mfma_f32_16x16x32_bf16 v[28:31], v[154:157], v[178:181], v[28:31]
	v_mfma_f32_16x16x32_bf16 v[20:23], v[146:149], v[196:199], v[20:23]
	v_mfma_f32_16x16x32_bf16 v[12:15], v[154:157], v[196:199], v[12:15]
	s_barrier
	s_add_u32 s16, s16, 0x40080
	s_addc_u32 s17, s17, 0
	s_add_i32 s20, s20, s35
	s_mov_b32 m0, s20
	v_lshl_add_u64 v[134:135], s[16:17], 0, v[144:145]
	global_load_lds_dwordx4 v[134:135], off
	s_add_i32 m0, s20, 0x2000
	v_lshl_add_u64 v[134:135], s[16:17], 0, v[128:129]
	global_load_lds_dwordx4 v[134:135], off
	s_waitcnt vmcnt(6)
	s_barrier
	v_mfma_f32_16x16x32_bf16 v[48:51], v[200:203], v[158:161], v[48:51]
	v_mfma_f32_16x16x32_bf16 v[40:43], v[214:217], v[158:161], v[40:43]
	v_mfma_f32_16x16x32_bf16 v[32:35], v[200:203], v[166:169], v[32:35]
	v_mfma_f32_16x16x32_bf16 v[24:27], v[214:217], v[166:169], v[24:27]
	v_mfma_f32_16x16x32_bf16 v[16:19], v[200:203], v[174:177], v[16:19]
	v_mfma_f32_16x16x32_bf16 v[8:11], v[214:217], v[174:177], v[8:11]
	v_mfma_f32_16x16x32_bf16 v[4:7], v[200:203], v[182:185], v[4:7]
	v_mfma_f32_16x16x32_bf16 v[0:3], v[214:217], v[182:185], v[0:3]
	v_mfma_f32_16x16x32_bf16 v[48:51], v[204:207], v[162:165], v[48:51]
	v_mfma_f32_16x16x32_bf16 v[40:43], v[218:221], v[162:165], v[40:43]
	v_mfma_f32_16x16x32_bf16 v[32:35], v[204:207], v[170:173], v[32:35]
	v_mfma_f32_16x16x32_bf16 v[24:27], v[218:221], v[170:173], v[24:27]
	v_mfma_f32_16x16x32_bf16 v[16:19], v[204:207], v[178:181], v[16:19]
	v_mfma_f32_16x16x32_bf16 v[8:11], v[218:221], v[178:181], v[8:11]
	v_mfma_f32_16x16x32_bf16 v[4:7], v[204:207], v[196:199], v[4:7]
	v_mfma_f32_16x16x32_bf16 v[0:3], v[218:221], v[196:199], v[0:3]
	s_add_i32 s77, s77, 2
	s_add_u32 s12, s12, 0x100
	s_addc_u32 s13, s13, 0
	s_add_u32 s25, s25, 0x100
	s_addc_u32 s76, s76, 0
	s_cmp_gt_u32 s77, 13
	s_barrier
	s_cbranch_scc0 .LBB0_1270
; __device__ __forceinline__ unsigned pk2(float lo, float hi) { unsigned r; asm("v_cvt_pk_bf16_f32 %0, %1, %2" : "=v"(r) : "v"(lo), "v"(hi)); return r; }
;     __device__ __forceinline__ void operator()(const f32x4 (&acc)[2][2][4][2], const Unit& u, int wr, int wc, int fr, int fq) const {
;     ...
;         const int row_t = rmap == 1 ? odd_phys_row0(u.pm, grp) : (rmap == 2 ? odd_phys_row0(u.pm % (BG * TPB), u.pm / (BG * TPB)) : u.pm * BM);
;         int c = col_t + 64 * wc + 16 * fq;
;         if (mode == 2) c = (c >> 6) * 96 + (c & 63);
; #pragma unroll
;         for (int ai = 0; ai < 2; ++ai)
; #pragma unroll
;             for (int m = 0; m < 4; ++m) {
;                 const int row = row_t + ai * HALF + wr * 64 + m * 16 + fr;
;                 bf16_t* rp = O + (size_t)row * ldc + c;
; #pragma unroll
;                 for (int bj = 0; bj < 2; ++bj) {
;                     const f32x4 v0 = acc[ai][bj][m][0], v1 = acc[ai][bj][m][1];
;                     u32x4 o; o.x = pk2(v0[0], v0[1]); o.y = pk2(v0[2], v0[3]); o.z = pk2(v1[0], v1[1]); o.w = pk2(v1[2], v1[3]);
;                     *(u32x4*)(rp + 8 * bj) = o;
;                 }
;             }
	v_lshl_add_u32 v134, s70, 8, v138
	v_cvt_pk_bf16_f32 v68, v68, v69
	v_cvt_pk_bf16_f32 v69, v70, v71
	v_cvt_pk_bf16_f32 v70, v64, v65
	v_add_u32_e32 v64, 0x80, v134
	v_lshl_or_b32 v136, s15, 8, v140
	v_ashrrev_i32_e32 v135, 31, v134
	v_cvt_pk_bf16_f32 v112, v112, v113
	v_cvt_pk_bf16_f32 v113, v114, v115
	v_cvt_pk_bf16_f32 v114, v104, v105
	v_or_b32_e32 v104, 16, v134
	v_ashrrev_i32_e32 v65, 31, v64
	v_cvt_pk_bf16_f32 v48, v48, v49
	v_cvt_pk_bf16_f32 v49, v50, v51
	v_cvt_pk_bf16_f32 v50, v40, v41
	v_add_u32_e32 v40, 0x90, v134
	v_ashrrev_i32_e32 v137, 31, v136
	v_lshlrev_b64 v[142:143], 11, v[134:135]
	v_ashrrev_i32_e32 v105, 31, v104
	v_cvt_pk_bf16_f32 v96, v96, v97
	v_cvt_pk_bf16_f32 v97, v98, v99
	v_cvt_pk_bf16_f32 v98, v88, v89
	v_or_b32_e32 v88, 32, v134
	v_lshlrev_b64 v[64:65], 11, v[64:65]
	v_ashrrev_i32_e32 v41, 31, v40
	v_cvt_pk_bf16_f32 v32, v32, v33
	v_cvt_pk_bf16_f32 v33, v34, v35
	v_cvt_pk_bf16_f32 v34, v24, v25
	v_add_u32_e32 v24, 0xa0, v134
	v_lshl_add_u64 v[142:143], s[4:5], 0, v[142:143]
	v_lshlrev_b64 v[136:137], 1, v[136:137]
	v_lshlrev_b64 v[104:105], 11, v[104:105]
	v_ashrrev_i32_e32 v89, 31, v88
	v_cvt_pk_bf16_f32 v80, v80, v81
	v_cvt_pk_bf16_f32 v81, v82, v83
	v_cvt_pk_bf16_f32 v82, v72, v73
	v_or_b32_e32 v72, 48, v134
	v_lshl_add_u64 v[64:65], s[4:5], 0, v[64:65]
	v_lshlrev_b64 v[40:41], 11, v[40:41]
	v_ashrrev_i32_e32 v25, 31, v24
	v_cvt_pk_bf16_f32 v16, v16, v17
	v_cvt_pk_bf16_f32 v17, v18, v19
	v_cvt_pk_bf16_f32 v18, v8, v9
	v_add_u32_e32 v8, 0xb0, v134
	v_lshl_add_u64 v[142:143], v[142:143], 0, v[136:137]
	v_lshl_add_u64 v[104:105], s[4:5], 0, v[104:105]
	v_lshlrev_b64 v[88:89], 11, v[88:89]
	v_ashrrev_i32_e32 v73, 31, v72
	v_lshl_add_u64 v[64:65], v[64:65], 0, v[136:137]
	v_lshl_add_u64 v[40:41], s[4:5], 0, v[40:41]
	v_lshlrev_b64 v[24:25], 11, v[24:25]
	v_ashrrev_i32_e32 v9, 31, v8
	v_cvt_pk_bf16_f32 v115, v106, v107
	global_store_dwordx4 v[142:143], v[112:115], off offset:16
	v_lshl_add_u64 v[88:89], s[4:5], 0, v[88:89]
	v_lshlrev_b64 v[72:73], 11, v[72:73]
	v_lshl_add_u64 v[112:113], v[104:105], 0, v[136:137]
	v_cvt_pk_bf16_f32 v51, v42, v43
	global_store_dwordx4 v[64:65], v[48:51], off offset:16
	v_lshl_add_u64 v[24:25], s[4:5], 0, v[24:25]
	v_lshlrev_b64 v[8:9], 11, v[8:9]
	v_lshl_add_u64 v[48:49], v[40:41], 0, v[136:137]
	v_cvt_pk_bf16_f32 v99, v90, v91
	global_store_dwordx4 v[112:113], v[96:99], off offset:16
	v_lshl_add_u64 v[72:73], s[4:5], 0, v[72:73]
	v_cvt_pk_bf16_f32 v35, v26, v27
	global_store_dwordx4 v[48:49], v[32:35], off offset:16
	v_lshl_add_u64 v[96:97], v[88:89], 0, v[136:137]
	v_lshl_add_u64 v[8:9], s[4:5], 0, v[8:9]
	v_lshl_add_u64 v[32:33], v[24:25], 0, v[136:137]
	v_cvt_pk_bf16_f32 v83, v74, v75
	global_store_dwordx4 v[96:97], v[80:83], off offset:16
	v_cvt_pk_bf16_f32 v19, v10, v11
	global_store_dwordx4 v[32:33], v[16:19], off offset:16
	s_and_b64 vcc, exec, s[0:1]
	v_lshl_add_u64 v[80:81], v[72:73], 0, v[136:137]
	v_lshl_add_u64 v[16:17], v[8:9], 0, v[136:137]
	s_mov_b32 s15, s6
	s_mov_b32 s70, s69
	s_mov_b64 s[16:17], s[10:11]
	s_mov_b64 s[12:13], s[8:9]
	v_cvt_pk_bf16_f32 v124, v124, v125
	v_cvt_pk_bf16_f32 v125, v126, v127
	v_cvt_pk_bf16_f32 v126, v120, v121
	v_cvt_pk_bf16_f32 v127, v122, v123
	global_store_dwordx4 v[142:143], v[124:127], off
	v_cvt_pk_bf16_f32 v104, v116, v117
	v_cvt_pk_bf16_f32 v105, v118, v119
	v_cvt_pk_bf16_f32 v106, v108, v109
	v_cvt_pk_bf16_f32 v107, v110, v111
	global_store_dwordx4 v[112:113], v[104:107], off
	v_cvt_pk_bf16_f32 v88, v100, v101
	v_cvt_pk_bf16_f32 v89, v102, v103
	v_cvt_pk_bf16_f32 v90, v92, v93
	v_cvt_pk_bf16_f32 v91, v94, v95
	global_store_dwordx4 v[96:97], v[88:91], off
	v_cvt_pk_bf16_f32 v72, v84, v85
	v_cvt_pk_bf16_f32 v73, v86, v87
	v_cvt_pk_bf16_f32 v74, v76, v77
	v_cvt_pk_bf16_f32 v75, v78, v79
	global_store_dwordx4 v[80:81], v[72:75], off
	v_cvt_pk_bf16_f32 v71, v66, v67
	global_store_dwordx4 v[80:81], v[68:71], off offset:16
	v_cvt_pk_bf16_f32 v60, v60, v61
	v_cvt_pk_bf16_f32 v61, v62, v63
	v_cvt_pk_bf16_f32 v62, v56, v57
	v_cvt_pk_bf16_f32 v63, v58, v59
	global_store_dwordx4 v[64:65], v[60:63], off
	v_cvt_pk_bf16_f32 v40, v52, v53
	v_cvt_pk_bf16_f32 v41, v54, v55
	v_cvt_pk_bf16_f32 v42, v44, v45
	v_cvt_pk_bf16_f32 v43, v46, v47
	global_store_dwordx4 v[48:49], v[40:43], off
	v_cvt_pk_bf16_f32 v24, v36, v37
	v_cvt_pk_bf16_f32 v25, v38, v39
	v_cvt_pk_bf16_f32 v26, v28, v29
	v_cvt_pk_bf16_f32 v27, v30, v31
	global_store_dwordx4 v[32:33], v[24:27], off
	v_cvt_pk_bf16_f32 v8, v20, v21
	v_cvt_pk_bf16_f32 v9, v22, v23
	v_cvt_pk_bf16_f32 v10, v12, v13
	v_cvt_pk_bf16_f32 v11, v14, v15
	global_store_dwordx4 v[16:17], v[8:11], off
	v_cvt_pk_bf16_f32 v4, v4, v5
	v_cvt_pk_bf16_f32 v5, v6, v7
	v_cvt_pk_bf16_f32 v6, v0, v1
	v_cvt_pk_bf16_f32 v7, v2, v3
	global_store_dwordx4 v[16:17], v[4:7], off offset:16
	s_cbranch_vccz .LBB0_1267
	s_waitcnt vmcnt(0)
	s_cmpk_gt_u32 s3, 0xff
	s_cbranch_scc1 .LBB0_1274
	s_barrier

; #define PG8_STAGE(bufoff, gbase, voff) do { _Pragma("unroll") for (int _i = 0; _i < 2; ++_i) \
;         __builtin_amdgcn_global_load_lds((const unsigned*)((const char*)(gbase) + (voff)[_i]), (LAS unsigned*)(lds + (bufoff) + ldsw + _i * 8192), 16, 0, 0); } while (0)
; #define PG8_LDA(dst, b, h) do { _Pragma("unroll") for (int m = 0; m < 4; ++m) _Pragma("unroll") for (int k = 0; k < 2; ++k) dst[m][k] = *(const LAS bf16x8*)(lds + PG8_SA(b, h) + aoff + m * 2048 + k * 1024); } while (0)
; #define PG8_LDB(dst, b, h) do { _Pragma("unroll") for (int n = 0; n < 2; ++n) _Pragma("unroll") for (int k = 0; k < 2; ++k) dst[n][k] = *(const LAS bf16x8*)(lds + PG8_SB(b, h) + boff + n * 2048 + k * 1024); } while (0)
; #define PG8_MMA(ai, bj, At, Bt) do { __builtin_amdgcn_s_setprio(1); _Pragma("unroll") for (int m = 0; m < 4; ++m) _Pragma("unroll") for (int n = 0; n < 2; ++n) _Pragma("unroll") for (int k = 0; k < 2; ++k) \
;         acc[ai][bj][m][n] = __builtin_amdgcn_mfma_f32_16x16x32_bf16(Bt[n][k], At[m][k], acc[ai][bj][m][n], 0, 0, 0); __builtin_amdgcn_s_setprio(0); } while (0)
; #define PG8_WAIT_L(n) asm volatile("s_waitcnt lgkmcnt(" #n ")" ::: "memory")
; #define PG8_BAR __builtin_amdgcn_s_barrier()
; #define PG8_SCHED __builtin_amdgcn_sched_barrier(0)
; template <class Epi>
; __device__ __forceinline__ void gemm_phase(LAS unsigned char* lds, const Gemm g, const StaticOrder& S, const Epi& E) {
;     ...
;             const bool last = (t == nt - 2);
;             const char* a1 = cA + (size_t)(t + 1) * kstep;
;             const char* a2 = last ? nA : cA + (size_t)(t + 2) * kstep; const char* b2 = last ? nB : cB + (size_t)(t + 2) * kstep;
;             const char* a3 = a2 + kstep; const char* b3 = b2 + kstep;
;             PG8_LDB(B0, 0, 0); PG8_SCHED; PG8_LDA(At, 0, 0); PG8_STAGE(PG8_SA(1, 1), a1 + hA, voffA);
;             PG8_WAIT_L(8); PG8_BAR; PG8_WAIT_L(0); PG8_MMA(0, 0, At, B0); PG8_BAR; PG8_SCHED;
;             PG8_LDB(B1, 0, 1); PG8_STAGE(PG8_SB(0, 0), b2, voffB);
;             PG8_BAR; PG8_WAIT_L(0); PG8_MMA(0, 1, At, B1); PG8_BAR;
;             PG8_LDA(At, 0, 1); PG8_STAGE(PG8_SA(0, 0), a2, voffA);
;             PG8_BAR; PG8_WAIT_L(0); PG8_MMA(1, 0, At, B0); PG8_BAR; PG8_SCHED;
.LBB0_1394:
	s_add_u32 s20, s16, 0xfffc0080
	s_addc_u32 s21, s17, -1
	s_add_i32 s26, 0, 0x10000
	v_add_u32_e32 v139, s26, v137
	ds_read_b128 v[140:143], v139
	ds_read_b128 v[146:149], v139 offset:1024
	ds_read_b128 v[150:153], v139 offset:2048
	ds_read_b128 v[154:157], v139 offset:3072
	s_cmp_eq_u32 s85, 12
	s_cselect_b32 s35, s82, s21
	s_cselect_b32 s34, s83, s20
	s_cselect_b32 s21, s9, s84
	s_cselect_b32 s20, s24, s25
	v_lshl_add_u64 v[192:193], s[16:17], 0, v[132:133]
	s_add_i32 m0, s70, 0xc000
	ds_read_b128 v[158:161], v138
	ds_read_b128 v[162:165], v138 offset:1024
	ds_read_b128 v[166:169], v138 offset:2048
	ds_read_b128 v[170:173], v138 offset:3072
	ds_read_b128 v[174:177], v138 offset:4096
	ds_read_b128 v[178:181], v138 offset:5120
	ds_read_b128 v[182:185], v138 offset:6144
	ds_read_b128 v[186:189], v138 offset:7168
	global_load_lds_dwordx4 v[192:193], off
	s_add_i32 m0, s70, 0xe000
	v_lshl_add_u64 v[192:193], s[16:17], 0, v[134:135]
	global_load_lds_dwordx4 v[192:193], off
	s_waitcnt lgkmcnt(8)
	s_barrier
	s_waitcnt lgkmcnt(0)
	v_mfma_f32_16x16x32_bf16 v[120:123], v[140:143], v[158:161], v[120:123]
	v_mfma_f32_16x16x32_bf16 v[124:127], v[150:153], v[158:161], v[124:127]
	v_mfma_f32_16x16x32_bf16 v[104:107], v[140:143], v[166:169], v[104:107]
	v_mfma_f32_16x16x32_bf16 v[108:111], v[150:153], v[166:169], v[108:111]
	v_mfma_f32_16x16x32_bf16 v[88:91], v[140:143], v[174:177], v[88:91]
	v_mfma_f32_16x16x32_bf16 v[92:95], v[150:153], v[174:177], v[92:95]
	v_mfma_f32_16x16x32_bf16 v[72:75], v[140:143], v[182:185], v[72:75]
	v_mfma_f32_16x16x32_bf16 v[76:79], v[150:153], v[182:185], v[76:79]
	v_mfma_f32_16x16x32_bf16 v[120:123], v[146:149], v[162:165], v[120:123]
	v_mfma_f32_16x16x32_bf16 v[124:127], v[154:157], v[162:165], v[124:127]
	v_mfma_f32_16x16x32_bf16 v[104:107], v[146:149], v[170:173], v[104:107]
	v_mfma_f32_16x16x32_bf16 v[108:111], v[154:157], v[170:173], v[108:111]
	v_mfma_f32_16x16x32_bf16 v[88:91], v[146:149], v[178:181], v[88:91]
	v_mfma_f32_16x16x32_bf16 v[92:95], v[154:157], v[178:181], v[92:95]
	v_mfma_f32_16x16x32_bf16 v[72:75], v[146:149], v[186:189], v[72:75]
	v_mfma_f32_16x16x32_bf16 v[76:79], v[154:157], v[186:189], v[76:79]
	s_barrier
	s_add_i32 s28, 0, 0x14000
	s_add_i32 s26, s26, s64
	v_add_u32_e32 v139, s28, v137
	v_lshl_add_u64 v[192:193], s[20:21], 0, v[130:131]
	s_mov_b32 m0, s26
	ds_read_b128 v[196:199], v139
	ds_read_b128 v[200:203], v139 offset:1024
	ds_read_b128 v[204:207], v139 offset:2048
	ds_read_b128 v[214:217], v139 offset:3072
	global_load_lds_dwordx4 v[192:193], off
	s_add_i32 m0, s26, 0x2000
	v_lshl_add_u64 v[218:219], s[20:21], 0, v[128:129]
	global_load_lds_dwordx4 v[218:219], off
	s_barrier
	s_waitcnt lgkmcnt(0)
	v_mfma_f32_16x16x32_bf16 v[112:115], v[196:199], v[158:161], v[112:115]
	v_mfma_f32_16x16x32_bf16 v[116:119], v[204:207], v[158:161], v[116:119]
	v_mfma_f32_16x16x32_bf16 v[96:99], v[196:199], v[166:169], v[96:99]
	v_mfma_f32_16x16x32_bf16 v[100:103], v[204:207], v[166:169], v[100:103]
	v_mfma_f32_16x16x32_bf16 v[80:83], v[196:199], v[174:177], v[80:83]
	v_mfma_f32_16x16x32_bf16 v[84:87], v[204:207], v[174:177], v[84:87]
	v_mfma_f32_16x16x32_bf16 v[64:67], v[196:199], v[182:185], v[64:67]
	v_mfma_f32_16x16x32_bf16 v[68:71], v[204:207], v[182:185], v[68:71]
	v_mfma_f32_16x16x32_bf16 v[112:115], v[200:203], v[162:165], v[112:115]
	v_mfma_f32_16x16x32_bf16 v[116:119], v[214:217], v[162:165], v[116:119]
	v_mfma_f32_16x16x32_bf16 v[96:99], v[200:203], v[170:173], v[96:99]
	v_mfma_f32_16x16x32_bf16 v[100:103], v[214:217], v[170:173], v[100:103]
	v_mfma_f32_16x16x32_bf16 v[80:83], v[200:203], v[178:181], v[80:83]
	v_mfma_f32_16x16x32_bf16 v[84:87], v[214:217], v[178:181], v[84:87]
	v_mfma_f32_16x16x32_bf16 v[64:67], v[200:203], v[186:189], v[64:67]
	v_mfma_f32_16x16x32_bf16 v[68:71], v[214:217], v[186:189], v[68:71]
	s_mov_b32 m0, s70
	v_lshl_add_u64 v[220:221], s[34:35], 0, v[130:131]
	s_barrier
	ds_read_b128 v[158:161], v138 offset:16384
	ds_read_b128 v[162:165], v138 offset:17408
	ds_read_b128 v[166:169], v138 offset:18432
	ds_read_b128 v[170:173], v138 offset:19456
	ds_read_b128 v[174:177], v138 offset:20480
	ds_read_b128 v[178:181], v138 offset:21504
	ds_read_b128 v[182:185], v138 offset:22528
	ds_read_b128 v[186:189], v138 offset:23552
	global_load_lds_dwordx4 v[220:221], off
	s_mov_b32 m0, s71
	v_lshl_add_u64 v[222:223], s[34:35], 0, v[128:129]
	global_load_lds_dwordx4 v[222:223], off
	s_barrier
	s_waitcnt lgkmcnt(0)
	v_mfma_f32_16x16x32_bf16 v[56:59], v[140:143], v[158:161], v[56:59]
	v_mfma_f32_16x16x32_bf16 v[60:63], v[150:153], v[158:161], v[60:63]
	v_mfma_f32_16x16x32_bf16 v[40:43], v[140:143], v[166:169], v[40:43]
	v_mfma_f32_16x16x32_bf16 v[44:47], v[150:153], v[166:169], v[44:47]
	v_mfma_f32_16x16x32_bf16 v[24:27], v[140:143], v[174:177], v[24:27]
	v_mfma_f32_16x16x32_bf16 v[28:31], v[150:153], v[174:177], v[28:31]
	v_mfma_f32_16x16x32_bf16 v[8:11], v[140:143], v[182:185], v[8:11]
	v_mfma_f32_16x16x32_bf16 v[12:15], v[150:153], v[182:185], v[12:15]
	v_mfma_f32_16x16x32_bf16 v[56:59], v[146:149], v[162:165], v[56:59]
	v_mfma_f32_16x16x32_bf16 v[60:63], v[154:157], v[162:165], v[60:63]
	v_mfma_f32_16x16x32_bf16 v[40:43], v[146:149], v[170:173], v[40:43]
	v_mfma_f32_16x16x32_bf16 v[44:47], v[154:157], v[170:173], v[44:47]
	v_mfma_f32_16x16x32_bf16 v[24:27], v[146:149], v[178:181], v[24:27]
	v_mfma_f32_16x16x32_bf16 v[28:31], v[154:157], v[178:181], v[28:31]
	v_mfma_f32_16x16x32_bf16 v[8:11], v[146:149], v[186:189], v[8:11]
	v_mfma_f32_16x16x32_bf16 v[12:15], v[154:157], v[186:189], v[12:15]
	s_barrier
; #define PG8_STAGE(bufoff, gbase, voff) do { _Pragma("unroll") for (int _i = 0; _i < 2; ++_i) \
;         __builtin_amdgcn_global_load_lds((const unsigned*)((const char*)(gbase) + (voff)[_i]), (LAS unsigned*)(lds + (bufoff) + ldsw + _i * 8192), 16, 0, 0); } while (0)
; #define PG8_LDA(dst, b, h) do { _Pragma("unroll") for (int m = 0; m < 4; ++m) _Pragma("unroll") for (int k = 0; k < 2; ++k) dst[m][k] = *(const LAS bf16x8*)(lds + PG8_SA(b, h) + aoff + m * 2048 + k * 1024); } while (0)
; #define PG8_LDB(dst, b, h) do { _Pragma("unroll") for (int n = 0; n < 2; ++n) _Pragma("unroll") for (int k = 0; k < 2; ++k) dst[n][k] = *(const LAS bf16x8*)(lds + PG8_SB(b, h) + boff + n * 2048 + k * 1024); } while (0)
; #define PG8_MMA(ai, bj, At, Bt) do { __builtin_amdgcn_s_setprio(1); _Pragma("unroll") for (int m = 0; m < 4; ++m) _Pragma("unroll") for (int n = 0; n < 2; ++n) _Pragma("unroll") for (int k = 0; k < 2; ++k) \
;         acc[ai][bj][m][n] = __builtin_amdgcn_mfma_f32_16x16x32_bf16(Bt[n][k], At[m][k], acc[ai][bj][m][n], 0, 0, 0); __builtin_amdgcn_s_setprio(0); } while (0)
; #define PG8_WAIT_V(n) asm volatile("s_waitcnt vmcnt(" #n ")" ::: "memory")
; #define PG8_WAIT_L(n) asm volatile("s_waitcnt lgkmcnt(" #n ")" ::: "memory")
; #define PG8_BAR __builtin_amdgcn_s_barrier()
; #define PG8_SCHED __builtin_amdgcn_sched_barrier(0)
; template <class Epi>
; __device__ __forceinline__ void gemm_phase(LAS unsigned char* lds, const Gemm g, const StaticOrder& S, const Epi& E) {
;     ...
;             PG8_STAGE(PG8_SB(0, 1), b2 + hB, voffB);
;             PG8_WAIT_V(6); PG8_BAR; PG8_MMA(1, 1, At, B1); PG8_BAR;
;             PG8_LDB(B0, 1, 0); PG8_SCHED; PG8_LDA(At, 1, 0); PG8_STAGE(PG8_SA(0, 1), a2 + hA, voffA);
;             PG8_WAIT_L(8); PG8_BAR; PG8_WAIT_L(0); PG8_MMA(0, 0, At, B0); PG8_BAR; PG8_SCHED;
;             PG8_LDB(B1, 1, 1); PG8_STAGE(PG8_SB(1, 0), b3, voffB);
;             PG8_BAR; PG8_WAIT_L(0); PG8_MMA(0, 1, At, B1); PG8_BAR;
;             PG8_LDA(At, 1, 1); PG8_STAGE(PG8_SA(1, 0), a3, voffA);
	s_add_u32 s26, s20, 0x40000
	s_addc_u32 s27, s21, 0
	s_add_i32 s28, s28, s64
	s_mov_b32 m0, s28
	v_lshl_add_u64 v[140:141], s[26:27], 0, v[130:131]
	global_load_lds_dwordx4 v[140:141], off
	s_add_i32 m0, s28, 0x2000
	v_lshl_add_u64 v[140:141], s[26:27], 0, v[128:129]
	global_load_lds_dwordx4 v[140:141], off
	s_waitcnt vmcnt(6)
	s_barrier
	v_mfma_f32_16x16x32_bf16 v[48:51], v[196:199], v[158:161], v[48:51]
	v_mfma_f32_16x16x32_bf16 v[52:55], v[204:207], v[158:161], v[52:55]
	v_mfma_f32_16x16x32_bf16 v[32:35], v[196:199], v[166:169], v[32:35]
	v_mfma_f32_16x16x32_bf16 v[36:39], v[204:207], v[166:169], v[36:39]
	v_mfma_f32_16x16x32_bf16 v[16:19], v[196:199], v[174:177], v[16:19]
	v_mfma_f32_16x16x32_bf16 v[20:23], v[204:207], v[174:177], v[20:23]
	v_mfma_f32_16x16x32_bf16 v[0:3], v[196:199], v[182:185], v[0:3]
	v_mfma_f32_16x16x32_bf16 v[4:7], v[204:207], v[182:185], v[4:7]
	v_mfma_f32_16x16x32_bf16 v[48:51], v[200:203], v[162:165], v[48:51]
	v_mfma_f32_16x16x32_bf16 v[52:55], v[214:217], v[162:165], v[52:55]
	v_mfma_f32_16x16x32_bf16 v[32:35], v[200:203], v[170:173], v[32:35]
	v_mfma_f32_16x16x32_bf16 v[36:39], v[214:217], v[170:173], v[36:39]
	v_mfma_f32_16x16x32_bf16 v[16:19], v[200:203], v[178:181], v[16:19]
	v_mfma_f32_16x16x32_bf16 v[20:23], v[214:217], v[178:181], v[20:23]
	v_mfma_f32_16x16x32_bf16 v[0:3], v[200:203], v[186:189], v[0:3]
	v_mfma_f32_16x16x32_bf16 v[4:7], v[214:217], v[186:189], v[4:7]
	s_add_i32 s28, 0, 0x18000
	v_add_u32_e32 v139, s28, v137
	s_barrier
	ds_read_b128 v[140:143], v139
	ds_read_b128 v[146:149], v139 offset:1024
	ds_read_b128 v[150:153], v139 offset:2048
	ds_read_b128 v[154:157], v139 offset:3072
	s_add_u32 s26, s34, 0x40000
	s_addc_u32 s27, s35, 0
	s_mov_b32 m0, s72
	v_lshl_add_u64 v[196:197], s[26:27], 0, v[130:131]
	ds_read_b128 v[158:161], v138 offset:32768
	ds_read_b128 v[162:165], v138 offset:33792
	ds_read_b128 v[166:169], v138 offset:34816
	ds_read_b128 v[170:173], v138 offset:35840
	ds_read_b128 v[174:177], v138 offset:36864
	ds_read_b128 v[178:181], v138 offset:37888
	ds_read_b128 v[182:185], v138 offset:38912
	ds_read_b128 v[186:189], v138 offset:39936
	global_load_lds_dwordx4 v[196:197], off
	s_mov_b32 m0, s76
	v_lshl_add_u64 v[196:197], s[26:27], 0, v[128:129]
	global_load_lds_dwordx4 v[196:197], off
	s_waitcnt lgkmcnt(8)
	s_barrier
	s_waitcnt lgkmcnt(0)
	v_mfma_f32_16x16x32_bf16 v[120:123], v[140:143], v[158:161], v[120:123]
	v_mfma_f32_16x16x32_bf16 v[124:127], v[150:153], v[158:161], v[124:127]
	v_mfma_f32_16x16x32_bf16 v[104:107], v[140:143], v[166:169], v[104:107]
	v_mfma_f32_16x16x32_bf16 v[108:111], v[150:153], v[166:169], v[108:111]
	v_mfma_f32_16x16x32_bf16 v[88:91], v[140:143], v[174:177], v[88:91]
	v_mfma_f32_16x16x32_bf16 v[92:95], v[150:153], v[174:177], v[92:95]
	v_mfma_f32_16x16x32_bf16 v[72:75], v[140:143], v[182:185], v[72:75]
	v_mfma_f32_16x16x32_bf16 v[76:79], v[150:153], v[182:185], v[76:79]
	v_mfma_f32_16x16x32_bf16 v[120:123], v[146:149], v[162:165], v[120:123]
	v_mfma_f32_16x16x32_bf16 v[124:127], v[154:157], v[162:165], v[124:127]
	v_mfma_f32_16x16x32_bf16 v[104:107], v[146:149], v[170:173], v[104:107]
	v_mfma_f32_16x16x32_bf16 v[108:111], v[154:157], v[170:173], v[108:111]
	v_mfma_f32_16x16x32_bf16 v[88:91], v[146:149], v[178:181], v[88:91]
	v_mfma_f32_16x16x32_bf16 v[92:95], v[154:157], v[178:181], v[92:95]
	v_mfma_f32_16x16x32_bf16 v[72:75], v[146:149], v[186:189], v[72:75]
	v_mfma_f32_16x16x32_bf16 v[76:79], v[154:157], v[186:189], v[76:79]
	s_barrier
	s_add_i32 s26, 0, 0x1c000
	s_add_i32 s27, s28, s64
	v_add_u32_e32 v139, s26, v137
	v_lshl_add_u64 v[192:193], v[192:193], 0, s[88:89]
	s_mov_b32 m0, s27
	ds_read_b128 v[196:199], v139
	ds_read_b128 v[200:203], v139 offset:1024
	ds_read_b128 v[204:207], v139 offset:2048
	ds_read_b128 v[214:217], v139 offset:3072
	global_load_lds_dwordx4 v[192:193], off
	s_add_i32 m0, s27, 0x2000
	v_lshl_add_u64 v[192:193], v[218:219], 0, s[88:89]
	global_load_lds_dwordx4 v[192:193], off
	s_barrier
	s_waitcnt lgkmcnt(0)
	v_mfma_f32_16x16x32_bf16 v[112:115], v[196:199], v[158:161], v[112:115]
	v_mfma_f32_16x16x32_bf16 v[116:119], v[204:207], v[158:161], v[116:119]
	v_mfma_f32_16x16x32_bf16 v[96:99], v[196:199], v[166:169], v[96:99]
	v_mfma_f32_16x16x32_bf16 v[100:103], v[204:207], v[166:169], v[100:103]
	v_mfma_f32_16x16x32_bf16 v[80:83], v[196:199], v[174:177], v[80:83]
	v_mfma_f32_16x16x32_bf16 v[84:87], v[204:207], v[174:177], v[84:87]
	v_mfma_f32_16x16x32_bf16 v[64:67], v[196:199], v[182:185], v[64:67]
	v_mfma_f32_16x16x32_bf16 v[68:71], v[204:207], v[182:185], v[68:71]
	v_mfma_f32_16x16x32_bf16 v[112:115], v[200:203], v[162:165], v[112:115]
	v_mfma_f32_16x16x32_bf16 v[116:119], v[214:217], v[162:165], v[116:119]
	v_mfma_f32_16x16x32_bf16 v[96:99], v[200:203], v[170:173], v[96:99]
	v_mfma_f32_16x16x32_bf16 v[100:103], v[214:217], v[170:173], v[100:103]
	v_mfma_f32_16x16x32_bf16 v[80:83], v[200:203], v[178:181], v[80:83]
	v_mfma_f32_16x16x32_bf16 v[84:87], v[214:217], v[178:181], v[84:87]
	v_mfma_f32_16x16x32_bf16 v[64:67], v[200:203], v[186:189], v[64:67]
	v_mfma_f32_16x16x32_bf16 v[68:71], v[214:217], v[186:189], v[68:71]
	s_mov_b32 m0, s77
	v_lshl_add_u64 v[192:193], v[220:221], 0, s[88:89]
	s_barrier
	ds_read_b128 v[158:161], v138 offset:49152
	ds_read_b128 v[162:165], v138 offset:50176
	ds_read_b128 v[166:169], v138 offset:51200
	ds_read_b128 v[170:173], v138 offset:52224
	ds_read_b128 v[174:177], v138 offset:53248
	ds_read_b128 v[178:181], v138 offset:54272
	ds_read_b128 v[182:185], v138 offset:55296
	ds_read_b128 v[186:189], v138 offset:56320
	global_load_lds_dwordx4 v[192:193], off
	s_mov_b32 m0, s78
	v_lshl_add_u64 v[192:193], v[222:223], 0, s[88:89]
	global_load_lds_dwordx4 v[192:193], off
	s_barrier
; __device__ __forceinline__ unsigned pk2(float lo, float hi) { unsigned r; asm("v_cvt_pk_bf16_f32 %0, %1, %2" : "=v"(r) : "v"(lo), "v"(hi)); return r; }
; #define PG8_STAGE(bufoff, gbase, voff) do { _Pragma("unroll") for (int _i = 0; _i < 2; ++_i) \
;         __builtin_amdgcn_global_load_lds((const unsigned*)((const char*)(gbase) + (voff)[_i]), (LAS unsigned*)(lds + (bufoff) + ldsw + _i * 8192), 16, 0, 0); } while (0)
; #define PG8_MMA(ai, bj, At, Bt) do { __builtin_amdgcn_s_setprio(1); _Pragma("unroll") for (int m = 0; m < 4; ++m) _Pragma("unroll") for (int n = 0; n < 2; ++n) _Pragma("unroll") for (int k = 0; k < 2; ++k) \
;         acc[ai][bj][m][n] = __builtin_amdgcn_mfma_f32_16x16x32_bf16(Bt[n][k], At[m][k], acc[ai][bj][m][n], 0, 0, 0); __builtin_amdgcn_s_setprio(0); } while (0)
; #define PG8_WAIT_V(n) asm volatile("s_waitcnt vmcnt(" #n ")" ::: "memory")
; #define PG8_WAIT_L(n) asm volatile("s_waitcnt lgkmcnt(" #n ")" ::: "memory")
; #define PG8_BAR __builtin_amdgcn_s_barrier()
; #define PG8_SCHED __builtin_amdgcn_sched_barrier(0)
; template <class Epi>
; __device__ __forceinline__ void gemm_phase(LAS unsigned char* lds, const Gemm g, const StaticOrder& S, const Epi& E) {
;     ...
;             PG8_BAR; PG8_WAIT_L(0); PG8_MMA(1, 0, At, B0); PG8_BAR; PG8_SCHED;
;             PG8_STAGE(PG8_SB(1, 1), b3 + hB, voffB);
;             PG8_WAIT_V(6); PG8_BAR; PG8_MMA(1, 1, At, B1); PG8_BAR;
;     static __device__ __forceinline__ float sg(float g, float u) { return (g * u) * __builtin_amdgcn_rcpf(1.f + __builtin_amdgcn_exp2f(-g)); }
;     __device__ __forceinline__ void operator()(const f32x4 (&acc)[2][2][4][2], const Unit& u, int wr, int wc, int fr, int fq) const {
; #pragma unroll
;         for (int ai = 0; ai < 2; ++ai)
; #pragma unroll
;             for (int m = 0; m < 4; ++m) {
;                 const int row = u.pm * BM + ai * HALF + wr * 64 + m * 16 + fr;
;                 const f32x4 g0 = acc[ai][0][m][0], u0 = acc[ai][0][m][1], g1 = acc[ai][1][m][0], u1 = acc[ai][1][m][1];
;                 u32x4 o; o.x = pk2(sg(g0[0], u0[0]), sg(g0[1], u0[1])); o.y = pk2(sg(g0[2], u0[2]), sg(g0[3], u0[3]));
;                 o.z = pk2(sg(g1[0], u1[0]), sg(g1[1], u1[1])); o.w = pk2(sg(g1[2], u1[2]), sg(g1[3], u1[3]));
;                 *(u32x4*)(O + (size_t)row * DFF + u.pn * 128 + wc * 32 + fq * 8) = o;
	s_waitcnt lgkmcnt(0)
	v_mfma_f32_16x16x32_bf16 v[56:59], v[140:143], v[158:161], v[56:59]
	v_mfma_f32_16x16x32_bf16 v[60:63], v[150:153], v[158:161], v[60:63]
	v_mfma_f32_16x16x32_bf16 v[40:43], v[140:143], v[166:169], v[40:43]
	v_mfma_f32_16x16x32_bf16 v[44:47], v[150:153], v[166:169], v[44:47]
	v_mfma_f32_16x16x32_bf16 v[24:27], v[140:143], v[174:177], v[24:27]
	v_mfma_f32_16x16x32_bf16 v[28:31], v[150:153], v[174:177], v[28:31]
	v_mfma_f32_16x16x32_bf16 v[8:11], v[140:143], v[182:185], v[8:11]
	v_mfma_f32_16x16x32_bf16 v[12:15], v[150:153], v[182:185], v[12:15]
	v_mfma_f32_16x16x32_bf16 v[56:59], v[146:149], v[162:165], v[56:59]
	v_mfma_f32_16x16x32_bf16 v[60:63], v[154:157], v[162:165], v[60:63]
	v_mfma_f32_16x16x32_bf16 v[40:43], v[146:149], v[170:173], v[40:43]
	v_mfma_f32_16x16x32_bf16 v[44:47], v[154:157], v[170:173], v[44:47]
	v_mfma_f32_16x16x32_bf16 v[24:27], v[146:149], v[178:181], v[24:27]
	v_mfma_f32_16x16x32_bf16 v[28:31], v[154:157], v[178:181], v[28:31]
	v_mfma_f32_16x16x32_bf16 v[8:11], v[146:149], v[186:189], v[8:11]
	v_mfma_f32_16x16x32_bf16 v[12:15], v[154:157], v[186:189], v[12:15]
	s_barrier
	s_add_u32 s20, s20, 0x40080
	s_addc_u32 s21, s21, 0
	s_add_i32 s26, s26, s64
	s_mov_b32 m0, s26
	v_lshl_add_u64 v[140:141], s[20:21], 0, v[130:131]
	global_load_lds_dwordx4 v[140:141], off
	s_add_i32 m0, s26, 0x2000
	v_lshl_add_u64 v[140:141], s[20:21], 0, v[128:129]
	global_load_lds_dwordx4 v[140:141], off
	s_waitcnt vmcnt(6)
	s_barrier
	v_mfma_f32_16x16x32_bf16 v[48:51], v[196:199], v[158:161], v[48:51]
	v_mfma_f32_16x16x32_bf16 v[52:55], v[204:207], v[158:161], v[52:55]
	v_mfma_f32_16x16x32_bf16 v[32:35], v[196:199], v[166:169], v[32:35]
	v_mfma_f32_16x16x32_bf16 v[36:39], v[204:207], v[166:169], v[36:39]
	v_mfma_f32_16x16x32_bf16 v[16:19], v[196:199], v[174:177], v[16:19]
	v_mfma_f32_16x16x32_bf16 v[20:23], v[204:207], v[174:177], v[20:23]
	v_mfma_f32_16x16x32_bf16 v[0:3], v[196:199], v[182:185], v[0:3]
	v_mfma_f32_16x16x32_bf16 v[4:7], v[204:207], v[182:185], v[4:7]
	v_mfma_f32_16x16x32_bf16 v[48:51], v[200:203], v[162:165], v[48:51]
	v_mfma_f32_16x16x32_bf16 v[52:55], v[214:217], v[162:165], v[52:55]
	v_mfma_f32_16x16x32_bf16 v[32:35], v[200:203], v[170:173], v[32:35]
	v_mfma_f32_16x16x32_bf16 v[36:39], v[214:217], v[170:173], v[36:39]
	v_mfma_f32_16x16x32_bf16 v[16:19], v[200:203], v[178:181], v[16:19]
	v_mfma_f32_16x16x32_bf16 v[20:23], v[214:217], v[178:181], v[20:23]
	v_mfma_f32_16x16x32_bf16 v[0:3], v[200:203], v[186:189], v[0:3]
	v_mfma_f32_16x16x32_bf16 v[4:7], v[214:217], v[186:189], v[4:7]
	s_add_i32 s85, s85, 2
	s_add_u32 s16, s16, 0x100
	s_addc_u32 s17, s17, 0
	s_add_u32 s25, s25, 0x100
	s_addc_u32 s84, s84, 0
	s_cmp_gt_u32 s85, 13
	s_barrier
	s_cbranch_scc0 .LBB0_1394
	v_mul_f32_e32 v124, v120, v124
	v_exp_f32_e64 v120, -v120
	v_mul_f32_e32 v108, v104, v108
	v_exp_f32_e64 v104, -v104
	v_mul_f32_e32 v92, v88, v92
	v_add_f32_e32 v120, 1.0, v120
	v_rcp_f32_e32 v120, v120
	v_add_f32_e32 v104, 1.0, v104
	v_rcp_f32_e32 v104, v104
	v_exp_f32_e64 v88, -v88
	v_mul_f32_e32 v120, v124, v120
	v_mul_f32_e32 v124, v121, v125
	v_exp_f32_e64 v121, -v121
	v_mul_f32_e32 v104, v108, v104
	v_mul_f32_e32 v108, v105, v109
	v_exp_f32_e64 v105, -v105
	v_add_f32_e32 v121, 1.0, v121
	v_rcp_f32_e32 v121, v121
	v_add_f32_e32 v88, 1.0, v88
	v_rcp_f32_e32 v88, v88
	v_mul_f32_e32 v76, v72, v76
	v_exp_f32_e64 v72, -v72
	v_mul_f32_e32 v121, v124, v121
	v_cvt_pk_bf16_f32 v120, v120, v121
	v_mul_f32_e32 v121, v122, v126
	v_exp_f32_e64 v122, -v122
	v_mul_f32_e32 v116, v112, v116
	v_exp_f32_e64 v112, -v112
	v_add_f32_e32 v105, 1.0, v105
	v_rcp_f32_e32 v105, v105
	v_mul_f32_e32 v88, v92, v88
	v_mul_f32_e32 v92, v89, v93
	v_exp_f32_e64 v89, -v89
	v_add_f32_e32 v72, 1.0, v72
	v_rcp_f32_e32 v72, v72
	v_mul_f32_e32 v60, v56, v60
	v_exp_f32_e64 v56, -v56
	v_add_f32_e32 v122, 1.0, v122
	v_add_f32_e32 v112, 1.0, v112
	v_rcp_f32_e32 v122, v122
	v_rcp_f32_e32 v112, v112
	v_mul_f32_e32 v105, v108, v105
	v_add_f32_e32 v89, 1.0, v89
	v_cvt_pk_bf16_f32 v104, v104, v105
	v_mul_f32_e32 v105, v106, v110
	v_exp_f32_e64 v106, -v106
	v_mul_f32_e32 v100, v96, v100
	v_exp_f32_e64 v96, -v96
	v_rcp_f32_e32 v89, v89
	v_mul_f32_e32 v72, v76, v72
	v_mul_f32_e32 v76, v73, v77
	v_exp_f32_e64 v73, -v73
	v_add_f32_e32 v56, 1.0, v56
	v_rcp_f32_e32 v56, v56
	v_mul_f32_e32 v44, v40, v44
	v_exp_f32_e64 v40, -v40
	v_mul_f32_e32 v121, v121, v122
	v_mul_f32_e32 v122, v123, v127
	v_exp_f32_e64 v123, -v123
	v_mul_f32_e32 v112, v116, v112
	v_mul_f32_e32 v116, v113, v117
	v_exp_f32_e64 v113, -v113
	v_add_f32_e32 v106, 1.0, v106
	v_add_f32_e32 v96, 1.0, v96
	v_mul_f32_e32 v89, v92, v89
	v_add_f32_e32 v73, 1.0, v73
	v_rcp_f32_e32 v106, v106
	v_rcp_f32_e32 v96, v96
	v_cvt_pk_bf16_f32 v88, v88, v89
	v_mul_f32_e32 v89, v90, v94
	v_exp_f32_e64 v90, -v90
	v_mul_f32_e32 v84, v80, v84
	v_exp_f32_e64 v80, -v80
	v_rcp_f32_e32 v73, v73
	v_mul_f32_e32 v56, v60, v56
	v_mul_f32_e32 v60, v57, v61
	v_exp_f32_e64 v57, -v57
	v_add_f32_e32 v40, 1.0, v40
	v_rcp_f32_e32 v40, v40
	v_mul_f32_e32 v28, v24, v28
	v_exp_f32_e64 v24, -v24
	v_add_f32_e32 v123, 1.0, v123
	v_add_f32_e32 v113, 1.0, v113
	v_rcp_f32_e32 v123, v123
	v_rcp_f32_e32 v113, v113
	v_mul_f32_e32 v105, v105, v106
	v_mul_f32_e32 v106, v107, v111
	v_exp_f32_e64 v107, -v107
	v_mul_f32_e32 v96, v100, v96
	v_mul_f32_e32 v100, v97, v101
	v_exp_f32_e64 v97, -v97
	v_add_f32_e32 v90, 1.0, v90
	v_add_f32_e32 v80, 1.0, v80
	v_mul_f32_e32 v73, v76, v73
	v_add_f32_e32 v57, 1.0, v57
	v_rcp_f32_e32 v90, v90
	v_rcp_f32_e32 v80, v80
	v_cvt_pk_bf16_f32 v72, v72, v73
	v_mul_f32_e32 v73, v74, v78
	v_exp_f32_e64 v74, -v74
	v_mul_f32_e32 v68, v64, v68
; __device__ __forceinline__ unsigned pk2(float lo, float hi) { unsigned r; asm("v_cvt_pk_bf16_f32 %0, %1, %2" : "=v"(r) : "v"(lo), "v"(hi)); return r; }
;     static __device__ __forceinline__ float sg(float g, float u) { return (g * u) * __builtin_amdgcn_rcpf(1.f + __builtin_amdgcn_exp2f(-g)); }
;     __device__ __forceinline__ void operator()(const f32x4 (&acc)[2][2][4][2], const Unit& u, int wr, int wc, int fr, int fq) const {
; #pragma unroll
;         for (int ai = 0; ai < 2; ++ai)
; #pragma unroll
;             for (int m = 0; m < 4; ++m) {
;                 const int row = u.pm * BM + ai * HALF + wr * 64 + m * 16 + fr;
;                 const f32x4 g0 = acc[ai][0][m][0], u0 = acc[ai][0][m][1], g1 = acc[ai][1][m][0], u1 = acc[ai][1][m][1];
;                 u32x4 o; o.x = pk2(sg(g0[0], u0[0]), sg(g0[1], u0[1])); o.y = pk2(sg(g0[2], u0[2]), sg(g0[3], u0[3]));
;                 o.z = pk2(sg(g1[0], u1[0]), sg(g1[1], u1[1])); o.w = pk2(sg(g1[2], u1[2]), sg(g1[3], u1[3]));
;                 *(u32x4*)(O + (size_t)row * DFF + u.pn * 128 + wc * 32 + fq * 8) = o;
	v_exp_f32_e64 v64, -v64
	v_rcp_f32_e32 v57, v57
	v_mul_f32_e32 v40, v44, v40
	v_mul_f32_e32 v44, v41, v45
	v_exp_f32_e64 v41, -v41
	v_add_f32_e32 v24, 1.0, v24
	v_rcp_f32_e32 v24, v24
	v_mul_f32_e32 v12, v8, v12
	v_exp_f32_e64 v8, -v8
	v_mul_f32_e32 v122, v122, v123
	v_mul_f32_e32 v113, v116, v113
	v_cvt_pk_bf16_f32 v121, v121, v122
	v_cvt_pk_bf16_f32 v122, v112, v113
	v_exp_f32_e64 v113, -v114
	v_add_f32_e32 v107, 1.0, v107
	v_add_f32_e32 v97, 1.0, v97
	v_mul_f32_e32 v112, v114, v118
	v_exp_f32_e64 v114, -v115
	v_rcp_f32_e32 v107, v107
	v_rcp_f32_e32 v97, v97
	v_mul_f32_e32 v89, v89, v90
	v_mul_f32_e32 v90, v91, v95
	v_exp_f32_e64 v91, -v91
	v_mul_f32_e32 v80, v84, v80
	v_mul_f32_e32 v84, v81, v85
	v_exp_f32_e64 v81, -v81
	v_add_f32_e32 v74, 1.0, v74
	v_add_f32_e32 v64, 1.0, v64
	v_mul_f32_e32 v57, v60, v57
	v_add_f32_e32 v41, 1.0, v41
	v_rcp_f32_e32 v74, v74
	v_rcp_f32_e32 v64, v64
	v_cvt_pk_bf16_f32 v56, v56, v57
	v_mul_f32_e32 v57, v58, v62
	v_exp_f32_e64 v58, -v58
	v_mul_f32_e32 v52, v48, v52
	v_exp_f32_e64 v48, -v48
	v_rcp_f32_e32 v41, v41
	v_mul_f32_e32 v24, v28, v24
	v_mul_f32_e32 v28, v25, v29
	v_exp_f32_e64 v25, -v25
	v_add_f32_e32 v8, 1.0, v8
	v_rcp_f32_e32 v8, v8
	v_add_f32_e32 v113, 1.0, v113
	v_rcp_f32_e32 v113, v113
	v_add_f32_e32 v114, 1.0, v114
	v_mul_f32_e32 v106, v106, v107
	v_mul_f32_e32 v97, v100, v97
	v_add_f32_e32 v91, 1.0, v91
	v_add_f32_e32 v81, 1.0, v81
	v_rcp_f32_e32 v114, v114
	v_cvt_pk_bf16_f32 v105, v105, v106
	v_cvt_pk_bf16_f32 v106, v96, v97
	v_exp_f32_e64 v97, -v98
	v_rcp_f32_e32 v91, v91
	v_rcp_f32_e32 v81, v81
	v_mul_f32_e32 v73, v73, v74
	v_mul_f32_e32 v74, v75, v79
	v_exp_f32_e64 v75, -v75
	v_mul_f32_e32 v64, v68, v64
	v_mul_f32_e32 v68, v65, v69
	v_exp_f32_e64 v65, -v65
	v_add_f32_e32 v58, 1.0, v58
	v_add_f32_e32 v48, 1.0, v48
	v_mul_f32_e32 v41, v44, v41
	v_add_f32_e32 v25, 1.0, v25
	v_mul_f32_e32 v96, v98, v102
	v_exp_f32_e64 v98, -v99
	v_rcp_f32_e32 v58, v58
	v_rcp_f32_e32 v48, v48
	v_cvt_pk_bf16_f32 v40, v40, v41
	v_mul_f32_e32 v41, v42, v46
	v_exp_f32_e64 v42, -v42
	v_mul_f32_e32 v36, v32, v36
	v_exp_f32_e64 v32, -v32
	v_rcp_f32_e32 v25, v25
	v_mul_f32_e32 v8, v12, v8
	v_mul_f32_e32 v12, v9, v13
	v_exp_f32_e64 v9, -v9
	v_mul_f32_e32 v112, v112, v113
	v_mul_f32_e32 v113, v115, v119
	s_lshl_b32 s16, s15, 7
	v_mul_f32_e32 v113, v113, v114
	v_add_f32_e32 v97, 1.0, v97
	v_mul_f32_e32 v90, v90, v91
	v_mul_f32_e32 v81, v84, v81
	v_add_f32_e32 v75, 1.0, v75
	v_add_f32_e32 v65, 1.0, v65
	v_lshl_add_u32 v139, s81, 8, v136
	s_ashr_i32 s17, s16, 31
	v_cvt_pk_bf16_f32 v123, v112, v113
	v_mov_b64_e32 v[112:113], s[6:7]
	v_rcp_f32_e32 v97, v97
	v_add_f32_e32 v98, 1.0, v98
	v_cvt_pk_bf16_f32 v89, v89, v90
	v_cvt_pk_bf16_f32 v90, v80, v81
	v_exp_f32_e64 v81, -v82
	v_rcp_f32_e32 v75, v75
	v_rcp_f32_e32 v65, v65
	v_mul_f32_e32 v57, v57, v58
	v_mul_f32_e32 v58, v59, v63
	v_exp_f32_e64 v59, -v59
	v_mul_f32_e32 v48, v52, v48
	v_mul_f32_e32 v52, v49, v53
	v_exp_f32_e64 v49, -v49
	v_add_f32_e32 v42, 1.0, v42
	v_add_f32_e32 v32, 1.0, v32
	v_mul_f32_e32 v25, v28, v25
	v_add_f32_e32 v9, 1.0, v9
	v_mad_i64_i32 v[114:115], s[20:21], v139, s33, v[112:113]
	s_lshl_b64 s[16:17], s[16:17], 1
	v_rcp_f32_e32 v98, v98
	v_mul_f32_e32 v80, v82, v86
	v_exp_f32_e64 v82, -v83
	v_rcp_f32_e32 v42, v42
	v_rcp_f32_e32 v32, v32
	v_cvt_pk_bf16_f32 v24, v24, v25
	v_mul_f32_e32 v25, v26, v30
	v_exp_f32_e64 v26, -v26
	v_mul_f32_e32 v20, v16, v20
	v_exp_f32_e64 v16, -v16
	v_rcp_f32_e32 v9, v9
	v_lshl_add_u64 v[114:115], v[114:115], 0, s[16:17]
	v_lshl_add_u64 v[114:115], v[114:115], 0, s[66:67]
	v_lshl_add_u64 v[114:115], v[114:115], 0, v[144:145]
	v_mul_f32_e32 v96, v96, v97
	v_mul_f32_e32 v97, v99, v103
	v_add_f32_e32 v81, 1.0, v81
	v_mul_f32_e32 v74, v74, v75
	v_mul_f32_e32 v65, v68, v65
	v_add_f32_e32 v59, 1.0, v59
	v_add_f32_e32 v49, 1.0, v49
	global_store_dwordx4 v[114:115], v[120:123], off
	v_or_b32_e32 v114, 16, v139
	v_mul_f32_e32 v97, v97, v98
	v_rcp_f32_e32 v81, v81
	v_add_f32_e32 v82, 1.0, v82
	v_cvt_pk_bf16_f32 v73, v73, v74
	v_cvt_pk_bf16_f32 v74, v64, v65
	v_exp_f32_e64 v65, -v66
	v_rcp_f32_e32 v59, v59
	v_rcp_f32_e32 v49, v49
	v_mul_f32_e32 v41, v41, v42
	v_mul_f32_e32 v42, v43, v47
	v_exp_f32_e64 v43, -v43
	v_mul_f32_e32 v32, v36, v32
	v_mul_f32_e32 v36, v33, v37
	v_exp_f32_e64 v33, -v33
	v_add_f32_e32 v26, 1.0, v26
	v_add_f32_e32 v16, 1.0, v16
	v_mul_f32_e32 v9, v12, v9
	v_cvt_pk_bf16_f32 v107, v96, v97
	v_mad_i64_i32 v[96:97], s[20:21], v114, s33, v[112:113]
	v_rcp_f32_e32 v82, v82
	v_mul_f32_e32 v64, v66, v70
	v_exp_f32_e64 v66, -v67
	v_rcp_f32_e32 v26, v26
	v_rcp_f32_e32 v16, v16
	v_cvt_pk_bf16_f32 v8, v8, v9
	v_mul_f32_e32 v9, v10, v14
	v_exp_f32_e64 v10, -v10
	v_mul_f32_e32 v4, v0, v4
	v_exp_f32_e64 v0, -v0
	v_lshl_add_u64 v[96:97], v[96:97], 0, s[16:17]
; __device__ __forceinline__ unsigned pk2(float lo, float hi) { unsigned r; asm("v_cvt_pk_bf16_f32 %0, %1, %2" : "=v"(r) : "v"(lo), "v"(hi)); return r; }
;     static __device__ __forceinline__ float sg(float g, float u) { return (g * u) * __builtin_amdgcn_rcpf(1.f + __builtin_amdgcn_exp2f(-g)); }
;     __device__ __forceinline__ void operator()(const f32x4 (&acc)[2][2][4][2], const Unit& u, int wr, int wc, int fr, int fq) const {
; #pragma unroll
;         for (int ai = 0; ai < 2; ++ai)
; #pragma unroll
;             for (int m = 0; m < 4; ++m) {
;                 const int row = u.pm * BM + ai * HALF + wr * 64 + m * 16 + fr;
;                 const f32x4 g0 = acc[ai][0][m][0], u0 = acc[ai][0][m][1], g1 = acc[ai][1][m][0], u1 = acc[ai][1][m][1];
;                 u32x4 o; o.x = pk2(sg(g0[0], u0[0]), sg(g0[1], u0[1])); o.y = pk2(sg(g0[2], u0[2]), sg(g0[3], u0[3]));
;                 o.z = pk2(sg(g1[0], u1[0]), sg(g1[1], u1[1])); o.w = pk2(sg(g1[2], u1[2]), sg(g1[3], u1[3]));
;                 *(u32x4*)(O + (size_t)row * DFF + u.pn * 128 + wc * 32 + fq * 8) = o;
	v_lshl_add_u64 v[96:97], v[96:97], 0, s[66:67]
	v_lshl_add_u64 v[96:97], v[96:97], 0, v[144:145]
	v_mul_f32_e32 v80, v80, v81
	v_mul_f32_e32 v81, v83, v87
	v_add_f32_e32 v65, 1.0, v65
	v_mul_f32_e32 v58, v58, v59
	v_mul_f32_e32 v49, v52, v49
	v_add_f32_e32 v43, 1.0, v43
	v_add_f32_e32 v33, 1.0, v33
	global_store_dwordx4 v[96:97], v[104:107], off
	v_or_b32_e32 v96, 32, v139
	v_mul_f32_e32 v81, v81, v82
	v_rcp_f32_e32 v65, v65
	v_add_f32_e32 v66, 1.0, v66
	v_cvt_pk_bf16_f32 v57, v57, v58
	v_cvt_pk_bf16_f32 v58, v48, v49
	v_exp_f32_e64 v49, -v50
	v_rcp_f32_e32 v43, v43
	v_rcp_f32_e32 v33, v33
	v_mul_f32_e32 v25, v25, v26
	v_mul_f32_e32 v26, v27, v31
	v_exp_f32_e64 v27, -v27
	v_mul_f32_e32 v16, v20, v16
	v_mul_f32_e32 v20, v17, v21
	v_exp_f32_e64 v17, -v17
	v_add_f32_e32 v10, 1.0, v10
	v_add_f32_e32 v0, 1.0, v0
	v_cvt_pk_bf16_f32 v91, v80, v81
	v_mad_i64_i32 v[80:81], s[20:21], v96, s33, v[112:113]
	v_rcp_f32_e32 v66, v66
	v_mul_f32_e32 v48, v50, v54
	v_exp_f32_e64 v50, -v51
	v_rcp_f32_e32 v10, v10
	v_rcp_f32_e32 v0, v0
	v_lshl_add_u64 v[80:81], v[80:81], 0, s[16:17]
	v_lshl_add_u64 v[80:81], v[80:81], 0, s[66:67]
	v_lshl_add_u64 v[80:81], v[80:81], 0, v[144:145]
	v_mul_f32_e32 v64, v64, v65
	v_mul_f32_e32 v65, v67, v71
	v_add_f32_e32 v49, 1.0, v49
	v_mul_f32_e32 v42, v42, v43
	v_mul_f32_e32 v33, v36, v33
	v_add_f32_e32 v27, 1.0, v27
	v_add_f32_e32 v17, 1.0, v17
	global_store_dwordx4 v[80:81], v[88:91], off
	v_or_b32_e32 v80, 48, v139
	v_mul_f32_e32 v65, v65, v66
	v_rcp_f32_e32 v49, v49
	v_add_f32_e32 v50, 1.0, v50
	v_cvt_pk_bf16_f32 v41, v41, v42
	v_cvt_pk_bf16_f32 v42, v32, v33
	v_exp_f32_e64 v33, -v34
	v_rcp_f32_e32 v27, v27
	v_rcp_f32_e32 v17, v17
	v_mul_f32_e32 v9, v9, v10
	v_mul_f32_e32 v10, v11, v15
	v_exp_f32_e64 v11, -v11
	v_mul_f32_e32 v0, v4, v0
	v_mul_f32_e32 v4, v1, v5
	v_exp_f32_e64 v1, -v1
	v_cvt_pk_bf16_f32 v75, v64, v65
	v_mad_i64_i32 v[64:65], s[20:21], v80, s33, v[112:113]
	v_rcp_f32_e32 v50, v50
	v_mul_f32_e32 v32, v34, v38
	v_exp_f32_e64 v34, -v35
	v_lshl_add_u64 v[64:65], v[64:65], 0, s[16:17]
	v_lshl_add_u64 v[64:65], v[64:65], 0, s[66:67]
	v_lshl_add_u64 v[64:65], v[64:65], 0, v[144:145]
	v_mul_f32_e32 v48, v48, v49
	v_mul_f32_e32 v49, v51, v55
	v_add_f32_e32 v33, 1.0, v33
	v_mul_f32_e32 v26, v26, v27
	v_mul_f32_e32 v17, v20, v17
	v_add_f32_e32 v11, 1.0, v11
	v_add_f32_e32 v1, 1.0, v1
	global_store_dwordx4 v[64:65], v[72:75], off
	v_add_u32_e32 v64, 0x80, v139
	v_mul_f32_e32 v49, v49, v50
	v_rcp_f32_e32 v33, v33
	v_add_f32_e32 v34, 1.0, v34
	v_cvt_pk_bf16_f32 v25, v25, v26
	v_cvt_pk_bf16_f32 v26, v16, v17
	v_exp_f32_e64 v17, -v18
	v_rcp_f32_e32 v11, v11
	v_rcp_f32_e32 v1, v1
	v_cvt_pk_bf16_f32 v59, v48, v49
	v_mad_i64_i32 v[48:49], s[20:21], v64, s33, v[112:113]
	v_rcp_f32_e32 v34, v34
	v_mul_f32_e32 v16, v18, v22
	v_exp_f32_e64 v18, -v19
	v_lshl_add_u64 v[48:49], v[48:49], 0, s[16:17]
	v_lshl_add_u64 v[48:49], v[48:49], 0, s[66:67]
	v_lshl_add_u64 v[48:49], v[48:49], 0, v[144:145]
	v_mul_f32_e32 v32, v32, v33
	v_mul_f32_e32 v33, v35, v39
	v_add_f32_e32 v17, 1.0, v17
	v_mul_f32_e32 v10, v10, v11
	v_mul_f32_e32 v1, v4, v1
	global_store_dwordx4 v[48:49], v[56:59], off
	v_add_u32_e32 v48, 0x90, v139
	v_mul_f32_e32 v33, v33, v34
	v_rcp_f32_e32 v17, v17
	v_add_f32_e32 v18, 1.0, v18
	v_cvt_pk_bf16_f32 v9, v9, v10
	v_cvt_pk_bf16_f32 v10, v0, v1
	v_exp_f32_e64 v1, -v2
	v_cvt_pk_bf16_f32 v43, v32, v33
	v_mad_i64_i32 v[32:33], s[20:21], v48, s33, v[112:113]
	v_rcp_f32_e32 v18, v18
	v_mul_f32_e32 v0, v2, v6
	v_exp_f32_e64 v2, -v3
	v_lshl_add_u64 v[32:33], v[32:33], 0, s[16:17]
	v_lshl_add_u64 v[32:33], v[32:33], 0, s[66:67]
	v_lshl_add_u64 v[32:33], v[32:33], 0, v[144:145]
	v_mul_f32_e32 v16, v16, v17
	v_mul_f32_e32 v17, v19, v23
	v_add_f32_e32 v1, 1.0, v1
	global_store_dwordx4 v[32:33], v[40:43], off
	v_add_u32_e32 v32, 0xa0, v139
	v_mul_f32_e32 v17, v17, v18
	v_rcp_f32_e32 v1, v1
	v_add_f32_e32 v2, 1.0, v2
	v_cvt_pk_bf16_f32 v27, v16, v17
	v_mad_i64_i32 v[16:17], s[20:21], v32, s33, v[112:113]
	v_rcp_f32_e32 v2, v2
	v_lshl_add_u64 v[16:17], v[16:17], 0, s[16:17]
	v_lshl_add_u64 v[16:17], v[16:17], 0, s[66:67]
	v_lshl_add_u64 v[16:17], v[16:17], 0, v[144:145]
	v_mul_f32_e32 v0, v0, v1
	v_mul_f32_e32 v1, v3, v7
	global_store_dwordx4 v[16:17], v[24:27], off
	v_add_u32_e32 v16, 0xb0, v139
	v_mul_f32_e32 v1, v1, v2
	v_cvt_pk_bf16_f32 v11, v0, v1
	v_mad_i64_i32 v[0:1], s[20:21], v16, s33, v[112:113]
	v_lshl_add_u64 v[0:1], v[0:1], 0, s[16:17]
	v_lshl_add_u64 v[0:1], v[0:1], 0, s[66:67]
	v_lshl_add_u64 v[0:1], v[0:1], 0, v[144:145]
	s_and_b64 vcc, exec, s[0:1]
	s_mov_b32 s15, s8
	s_mov_b32 s81, s80
	s_mov_b64 s[20:21], s[12:13]
	s_mov_b64 s[16:17], s[10:11]
	global_store_dwordx4 v[0:1], v[8:11], off
	s_cbranch_vccz .LBB0_1391
	s_waitcnt vmcnt(0)
	s_cmpk_gt_u32 s23, 0xff
	s_cbranch_scc1 .LBB0_1398
	s_barrier

; #define PG8_STAGE(bufoff, gbase, voff) do { _Pragma("unroll") for (int _i = 0; _i < 2; ++_i) \
;         __builtin_amdgcn_global_load_lds((const unsigned*)((const char*)(gbase) + (voff)[_i]), (LAS unsigned*)(lds + (bufoff) + ldsw + _i * 8192), 16, 0, 0); } while (0)
; #define PG8_LDA(dst, b, h) do { _Pragma("unroll") for (int m = 0; m < 4; ++m) _Pragma("unroll") for (int k = 0; k < 2; ++k) dst[m][k] = *(const LAS bf16x8*)(lds + PG8_SA(b, h) + aoff + m * 2048 + k * 1024); } while (0)
; #define PG8_LDB(dst, b, h) do { _Pragma("unroll") for (int n = 0; n < 2; ++n) _Pragma("unroll") for (int k = 0; k < 2; ++k) dst[n][k] = *(const LAS bf16x8*)(lds + PG8_SB(b, h) + boff + n * 2048 + k * 1024); } while (0)
; #define PG8_MMA(ai, bj, At, Bt) do { __builtin_amdgcn_s_setprio(1); _Pragma("unroll") for (int m = 0; m < 4; ++m) _Pragma("unroll") for (int n = 0; n < 2; ++n) _Pragma("unroll") for (int k = 0; k < 2; ++k) \
;         acc[ai][bj][m][n] = __builtin_amdgcn_mfma_f32_16x16x32_bf16(Bt[n][k], At[m][k], acc[ai][bj][m][n], 0, 0, 0); __builtin_amdgcn_s_setprio(0); } while (0)
; #define PG8_WAIT_L(n) asm volatile("s_waitcnt lgkmcnt(" #n ")" ::: "memory")
; #define PG8_BAR __builtin_amdgcn_s_barrier()
; #define PG8_SCHED __builtin_amdgcn_sched_barrier(0)
; template <class Epi>
; __device__ __forceinline__ void gemm_phase(LAS unsigned char* lds, const Gemm g, const StaticOrder& S, const Epi& E) {
;     ...
;             const bool last = (t == nt - 2);
;             const char* a1 = cA + (size_t)(t + 1) * kstep;
;             const char* a2 = last ? nA : cA + (size_t)(t + 2) * kstep; const char* b2 = last ? nB : cB + (size_t)(t + 2) * kstep;
;             const char* a3 = a2 + kstep; const char* b3 = b2 + kstep;
;             PG8_LDB(B0, 0, 0); PG8_SCHED; PG8_LDA(At, 0, 0); PG8_STAGE(PG8_SA(1, 1), a1 + hA, voffA);
;             PG8_WAIT_L(8); PG8_BAR; PG8_WAIT_L(0); PG8_MMA(0, 0, At, B0); PG8_BAR; PG8_SCHED;
;             PG8_LDB(B1, 0, 1); PG8_STAGE(PG8_SB(0, 0), b2, voffB);
;             PG8_BAR; PG8_WAIT_L(0); PG8_MMA(0, 1, At, B1); PG8_BAR;
;             PG8_LDA(At, 0, 1); PG8_STAGE(PG8_SA(0, 0), a2, voffA);
;             PG8_BAR; PG8_WAIT_L(0); PG8_MMA(1, 0, At, B0); PG8_BAR; PG8_SCHED;
.LBB0_1462:
	s_add_u32 s12, s10, 0x100
	s_addc_u32 s13, s11, 0
	s_add_i32 s26, 0, 0x10000
	v_add_u32_e32 v142, s26, v139
	ds_read_b128 v[134:137], v142
	ds_read_b128 v[146:149], v142 offset:1024
	ds_read_b128 v[150:153], v142 offset:2048
	ds_read_b128 v[154:157], v142 offset:3072
	s_cmp_eq_u32 s78, 40
	s_cselect_b32 s21, s5, s13
	s_cselect_b32 s20, s4, s12
	s_cselect_b32 s17, s7, s25
	s_cselect_b32 s16, s6, s24
	v_lshl_add_u64 v[142:143], s[10:11], 0, v[130:131]
	s_add_i32 m0, s63, 0xc000
	ds_read_b128 v[158:161], v141
	ds_read_b128 v[162:165], v141 offset:1024
	ds_read_b128 v[166:169], v141 offset:2048
	ds_read_b128 v[170:173], v141 offset:3072
	ds_read_b128 v[174:177], v141 offset:4096
	ds_read_b128 v[178:181], v141 offset:5120
	ds_read_b128 v[182:185], v141 offset:6144
	ds_read_b128 v[186:189], v141 offset:7168
	global_load_lds_dwordx4 v[142:143], off
	s_add_i32 m0, s63, 0xe000
	v_lshl_add_u64 v[142:143], s[10:11], 0, v[132:133]
	global_load_lds_dwordx4 v[142:143], off
	s_waitcnt lgkmcnt(8)
	s_barrier
	s_waitcnt lgkmcnt(0)
	v_mfma_f32_16x16x32_bf16 v[124:127], v[134:137], v[158:161], v[124:127]
	v_mfma_f32_16x16x32_bf16 v[120:123], v[150:153], v[158:161], v[120:123]
	v_mfma_f32_16x16x32_bf16 v[116:119], v[134:137], v[166:169], v[116:119]
	v_mfma_f32_16x16x32_bf16 v[108:111], v[150:153], v[166:169], v[108:111]
	v_mfma_f32_16x16x32_bf16 v[100:103], v[134:137], v[174:177], v[100:103]
	v_mfma_f32_16x16x32_bf16 v[92:95], v[150:153], v[174:177], v[92:95]
	v_mfma_f32_16x16x32_bf16 v[84:87], v[134:137], v[182:185], v[84:87]
	v_mfma_f32_16x16x32_bf16 v[76:79], v[150:153], v[182:185], v[76:79]
	v_mfma_f32_16x16x32_bf16 v[124:127], v[146:149], v[162:165], v[124:127]
	v_mfma_f32_16x16x32_bf16 v[120:123], v[154:157], v[162:165], v[120:123]
	v_mfma_f32_16x16x32_bf16 v[116:119], v[146:149], v[170:173], v[116:119]
	v_mfma_f32_16x16x32_bf16 v[108:111], v[154:157], v[170:173], v[108:111]
	v_mfma_f32_16x16x32_bf16 v[100:103], v[146:149], v[178:181], v[100:103]
	v_mfma_f32_16x16x32_bf16 v[92:95], v[154:157], v[178:181], v[92:95]
	v_mfma_f32_16x16x32_bf16 v[84:87], v[146:149], v[186:189], v[84:87]
	v_mfma_f32_16x16x32_bf16 v[76:79], v[154:157], v[186:189], v[76:79]
	s_barrier
	s_add_i32 s27, 0, 0x14000
	v_add_u32_e32 v142, s27, v139
	s_add_i32 s10, s26, s61
	ds_read_b128 v[196:199], v142
	ds_read_b128 v[200:203], v142 offset:1024
	ds_read_b128 v[204:207], v142 offset:2048
	ds_read_b128 v[214:217], v142 offset:3072
	v_lshl_add_u64 v[142:143], s[16:17], 0, v[144:145]
	s_mov_b32 m0, s10
	v_lshl_add_u64 v[192:193], s[16:17], 0, v[128:129]
	global_load_lds_dwordx4 v[142:143], off
	s_add_i32 m0, s10, 0x2000
	s_nop 0
	global_load_lds_dwordx4 v[192:193], off
	s_barrier
	s_waitcnt lgkmcnt(0)
	v_mfma_f32_16x16x32_bf16 v[112:115], v[196:199], v[158:161], v[112:115]
	v_mfma_f32_16x16x32_bf16 v[104:107], v[204:207], v[158:161], v[104:107]
	v_mfma_f32_16x16x32_bf16 v[96:99], v[196:199], v[166:169], v[96:99]
	v_mfma_f32_16x16x32_bf16 v[88:91], v[204:207], v[166:169], v[88:91]
	v_mfma_f32_16x16x32_bf16 v[80:83], v[196:199], v[174:177], v[80:83]
	v_mfma_f32_16x16x32_bf16 v[72:75], v[204:207], v[174:177], v[72:75]
	v_mfma_f32_16x16x32_bf16 v[68:71], v[196:199], v[182:185], v[68:71]
	v_mfma_f32_16x16x32_bf16 v[64:67], v[204:207], v[182:185], v[64:67]
	v_mfma_f32_16x16x32_bf16 v[112:115], v[200:203], v[162:165], v[112:115]
	v_mfma_f32_16x16x32_bf16 v[104:107], v[214:217], v[162:165], v[104:107]
	v_mfma_f32_16x16x32_bf16 v[96:99], v[200:203], v[170:173], v[96:99]
	v_mfma_f32_16x16x32_bf16 v[88:91], v[214:217], v[170:173], v[88:91]
	v_mfma_f32_16x16x32_bf16 v[80:83], v[200:203], v[178:181], v[80:83]
	v_mfma_f32_16x16x32_bf16 v[72:75], v[214:217], v[178:181], v[72:75]
	v_mfma_f32_16x16x32_bf16 v[68:71], v[200:203], v[186:189], v[68:71]
	v_mfma_f32_16x16x32_bf16 v[64:67], v[214:217], v[186:189], v[64:67]
	s_mov_b32 m0, s63
	v_lshl_add_u64 v[218:219], s[20:21], 0, v[144:145]
	s_barrier
	ds_read_b128 v[158:161], v141 offset:16384
	ds_read_b128 v[162:165], v141 offset:17408
	ds_read_b128 v[166:169], v141 offset:18432
	ds_read_b128 v[170:173], v141 offset:19456
	ds_read_b128 v[174:177], v141 offset:20480
	ds_read_b128 v[178:181], v141 offset:21504
	ds_read_b128 v[182:185], v141 offset:22528
	ds_read_b128 v[186:189], v141 offset:23552
	global_load_lds_dwordx4 v[218:219], off
	s_mov_b32 m0, s64
	v_lshl_add_u64 v[220:221], s[20:21], 0, v[128:129]
	global_load_lds_dwordx4 v[220:221], off
	s_barrier
	s_waitcnt lgkmcnt(0)
	v_mfma_f32_16x16x32_bf16 v[60:63], v[134:137], v[158:161], v[60:63]
	v_mfma_f32_16x16x32_bf16 v[56:59], v[150:153], v[158:161], v[56:59]
	v_mfma_f32_16x16x32_bf16 v[52:55], v[134:137], v[166:169], v[52:55]
	v_mfma_f32_16x16x32_bf16 v[44:47], v[150:153], v[166:169], v[44:47]
	v_mfma_f32_16x16x32_bf16 v[36:39], v[134:137], v[174:177], v[36:39]
	v_mfma_f32_16x16x32_bf16 v[28:31], v[150:153], v[174:177], v[28:31]
	v_mfma_f32_16x16x32_bf16 v[20:23], v[134:137], v[182:185], v[20:23]
	v_mfma_f32_16x16x32_bf16 v[12:15], v[150:153], v[182:185], v[12:15]
	v_mfma_f32_16x16x32_bf16 v[60:63], v[146:149], v[162:165], v[60:63]
	v_mfma_f32_16x16x32_bf16 v[56:59], v[154:157], v[162:165], v[56:59]
	v_mfma_f32_16x16x32_bf16 v[52:55], v[146:149], v[170:173], v[52:55]
	v_mfma_f32_16x16x32_bf16 v[44:47], v[154:157], v[170:173], v[44:47]
	v_mfma_f32_16x16x32_bf16 v[36:39], v[146:149], v[178:181], v[36:39]
	v_mfma_f32_16x16x32_bf16 v[28:31], v[154:157], v[178:181], v[28:31]
	v_mfma_f32_16x16x32_bf16 v[20:23], v[146:149], v[186:189], v[20:23]
	v_mfma_f32_16x16x32_bf16 v[12:15], v[154:157], v[186:189], v[12:15]
	s_barrier
; #define PG8_STAGE(bufoff, gbase, voff) do { _Pragma("unroll") for (int _i = 0; _i < 2; ++_i) \
;         __builtin_amdgcn_global_load_lds((const unsigned*)((const char*)(gbase) + (voff)[_i]), (LAS unsigned*)(lds + (bufoff) + ldsw + _i * 8192), 16, 0, 0); } while (0)
; #define PG8_LDA(dst, b, h) do { _Pragma("unroll") for (int m = 0; m < 4; ++m) _Pragma("unroll") for (int k = 0; k < 2; ++k) dst[m][k] = *(const LAS bf16x8*)(lds + PG8_SA(b, h) + aoff + m * 2048 + k * 1024); } while (0)
; #define PG8_LDB(dst, b, h) do { _Pragma("unroll") for (int n = 0; n < 2; ++n) _Pragma("unroll") for (int k = 0; k < 2; ++k) dst[n][k] = *(const LAS bf16x8*)(lds + PG8_SB(b, h) + boff + n * 2048 + k * 1024); } while (0)
; #define PG8_MMA(ai, bj, At, Bt) do { __builtin_amdgcn_s_setprio(1); _Pragma("unroll") for (int m = 0; m < 4; ++m) _Pragma("unroll") for (int n = 0; n < 2; ++n) _Pragma("unroll") for (int k = 0; k < 2; ++k) \
;         acc[ai][bj][m][n] = __builtin_amdgcn_mfma_f32_16x16x32_bf16(Bt[n][k], At[m][k], acc[ai][bj][m][n], 0, 0, 0); __builtin_amdgcn_s_setprio(0); } while (0)
; #define PG8_WAIT_V(n) asm volatile("s_waitcnt vmcnt(" #n ")" ::: "memory")
; #define PG8_WAIT_L(n) asm volatile("s_waitcnt lgkmcnt(" #n ")" ::: "memory")
; #define PG8_BAR __builtin_amdgcn_s_barrier()
; #define PG8_SCHED __builtin_amdgcn_sched_barrier(0)
; template <class Epi>
; __device__ __forceinline__ void gemm_phase(LAS unsigned char* lds, const Gemm g, const StaticOrder& S, const Epi& E) {
;     ...
;             PG8_STAGE(PG8_SB(0, 1), b2 + hB, voffB);
;             PG8_WAIT_V(6); PG8_BAR; PG8_MMA(1, 1, At, B1); PG8_BAR;
;             PG8_LDB(B0, 1, 0); PG8_SCHED; PG8_LDA(At, 1, 0); PG8_STAGE(PG8_SA(0, 1), a2 + hA, voffA);
;             PG8_WAIT_L(8); PG8_BAR; PG8_WAIT_L(0); PG8_MMA(0, 0, At, B0); PG8_BAR; PG8_SCHED;
;             PG8_LDB(B1, 1, 1); PG8_STAGE(PG8_SB(1, 0), b3, voffB);
;             PG8_BAR; PG8_WAIT_L(0); PG8_MMA(0, 1, At, B1); PG8_BAR;
;             PG8_LDA(At, 1, 1); PG8_STAGE(PG8_SA(1, 0), a3, voffA);
	s_add_u32 s10, s16, 0xb0000
	s_addc_u32 s11, s17, 0
	s_add_i32 s26, s27, s61
	s_mov_b32 m0, s26
	v_lshl_add_u64 v[134:135], s[10:11], 0, v[144:145]
	global_load_lds_dwordx4 v[134:135], off
	s_add_i32 m0, s26, 0x2000
	v_lshl_add_u64 v[134:135], s[10:11], 0, v[128:129]
	global_load_lds_dwordx4 v[134:135], off
	s_waitcnt vmcnt(6)
	s_barrier
	v_mfma_f32_16x16x32_bf16 v[48:51], v[196:199], v[158:161], v[48:51]
	v_mfma_f32_16x16x32_bf16 v[40:43], v[204:207], v[158:161], v[40:43]
	v_mfma_f32_16x16x32_bf16 v[32:35], v[196:199], v[166:169], v[32:35]
	v_mfma_f32_16x16x32_bf16 v[24:27], v[204:207], v[166:169], v[24:27]
	v_mfma_f32_16x16x32_bf16 v[16:19], v[196:199], v[174:177], v[16:19]
	v_mfma_f32_16x16x32_bf16 v[8:11], v[204:207], v[174:177], v[8:11]
	v_mfma_f32_16x16x32_bf16 v[4:7], v[196:199], v[182:185], v[4:7]
	v_mfma_f32_16x16x32_bf16 v[0:3], v[204:207], v[182:185], v[0:3]
	v_mfma_f32_16x16x32_bf16 v[48:51], v[200:203], v[162:165], v[48:51]
	v_mfma_f32_16x16x32_bf16 v[40:43], v[214:217], v[162:165], v[40:43]
	v_mfma_f32_16x16x32_bf16 v[32:35], v[200:203], v[170:173], v[32:35]
	v_mfma_f32_16x16x32_bf16 v[24:27], v[214:217], v[170:173], v[24:27]
	v_mfma_f32_16x16x32_bf16 v[16:19], v[200:203], v[178:181], v[16:19]
	v_mfma_f32_16x16x32_bf16 v[8:11], v[214:217], v[178:181], v[8:11]
	v_mfma_f32_16x16x32_bf16 v[4:7], v[200:203], v[186:189], v[4:7]
	v_mfma_f32_16x16x32_bf16 v[0:3], v[214:217], v[186:189], v[0:3]
	s_add_i32 s26, 0, 0x18000
	v_add_u32_e32 v154, s26, v139
	s_barrier
	ds_read_b128 v[134:137], v154
	ds_read_b128 v[146:149], v154 offset:1024
	ds_read_b128 v[150:153], v154 offset:2048
	ds_read_b128 v[154:157], v154 offset:3072
	s_add_u32 s10, s20, 0xb0000
	s_addc_u32 s11, s21, 0
	s_mov_b32 m0, s65
	v_lshl_add_u64 v[196:197], s[10:11], 0, v[144:145]
	ds_read_b128 v[158:161], v141 offset:32768
	ds_read_b128 v[162:165], v141 offset:33792
	ds_read_b128 v[166:169], v141 offset:34816
	ds_read_b128 v[170:173], v141 offset:35840
	ds_read_b128 v[174:177], v141 offset:36864
	ds_read_b128 v[178:181], v141 offset:37888
	ds_read_b128 v[182:185], v141 offset:38912
	ds_read_b128 v[186:189], v141 offset:39936
	global_load_lds_dwordx4 v[196:197], off
	s_mov_b32 m0, s68
	v_lshl_add_u64 v[196:197], s[10:11], 0, v[128:129]
	global_load_lds_dwordx4 v[196:197], off
	s_waitcnt lgkmcnt(8)
	s_barrier
	s_waitcnt lgkmcnt(0)
	v_mfma_f32_16x16x32_bf16 v[124:127], v[134:137], v[158:161], v[124:127]
	v_mfma_f32_16x16x32_bf16 v[120:123], v[150:153], v[158:161], v[120:123]
	v_mfma_f32_16x16x32_bf16 v[116:119], v[134:137], v[166:169], v[116:119]
	v_mfma_f32_16x16x32_bf16 v[108:111], v[150:153], v[166:169], v[108:111]
	v_mfma_f32_16x16x32_bf16 v[100:103], v[134:137], v[174:177], v[100:103]
	v_mfma_f32_16x16x32_bf16 v[92:95], v[150:153], v[174:177], v[92:95]
	v_mfma_f32_16x16x32_bf16 v[84:87], v[134:137], v[182:185], v[84:87]
	v_mfma_f32_16x16x32_bf16 v[76:79], v[150:153], v[182:185], v[76:79]
	v_mfma_f32_16x16x32_bf16 v[124:127], v[146:149], v[162:165], v[124:127]
	v_mfma_f32_16x16x32_bf16 v[120:123], v[154:157], v[162:165], v[120:123]
	v_mfma_f32_16x16x32_bf16 v[116:119], v[146:149], v[170:173], v[116:119]
	v_mfma_f32_16x16x32_bf16 v[108:111], v[154:157], v[170:173], v[108:111]
	v_mfma_f32_16x16x32_bf16 v[100:103], v[146:149], v[178:181], v[100:103]
	v_mfma_f32_16x16x32_bf16 v[92:95], v[154:157], v[178:181], v[92:95]
	v_mfma_f32_16x16x32_bf16 v[84:87], v[146:149], v[186:189], v[84:87]
	v_mfma_f32_16x16x32_bf16 v[76:79], v[154:157], v[186:189], v[76:79]
	s_barrier
	s_add_i32 s20, 0, 0x1c000
	s_add_i32 s10, s26, s61
	v_add_u32_e32 v190, s20, v139
	v_lshl_add_u64 v[142:143], v[142:143], 0, s[88:89]
	s_mov_b32 m0, s10
	ds_read_b128 v[196:199], v190
	ds_read_b128 v[200:203], v190 offset:1024
	ds_read_b128 v[204:207], v190 offset:2048
	ds_read_b128 v[214:217], v190 offset:3072
	global_load_lds_dwordx4 v[142:143], off
	s_add_i32 m0, s10, 0x2000
	v_lshl_add_u64 v[142:143], v[192:193], 0, s[88:89]
	global_load_lds_dwordx4 v[142:143], off
	s_barrier
	s_waitcnt lgkmcnt(0)
	v_mfma_f32_16x16x32_bf16 v[112:115], v[196:199], v[158:161], v[112:115]
	v_mfma_f32_16x16x32_bf16 v[104:107], v[204:207], v[158:161], v[104:107]
	v_mfma_f32_16x16x32_bf16 v[96:99], v[196:199], v[166:169], v[96:99]
	v_mfma_f32_16x16x32_bf16 v[88:91], v[204:207], v[166:169], v[88:91]
	v_mfma_f32_16x16x32_bf16 v[80:83], v[196:199], v[174:177], v[80:83]
	v_mfma_f32_16x16x32_bf16 v[72:75], v[204:207], v[174:177], v[72:75]
	v_mfma_f32_16x16x32_bf16 v[68:71], v[196:199], v[182:185], v[68:71]
	v_mfma_f32_16x16x32_bf16 v[64:67], v[204:207], v[182:185], v[64:67]
	v_mfma_f32_16x16x32_bf16 v[112:115], v[200:203], v[162:165], v[112:115]
	v_mfma_f32_16x16x32_bf16 v[104:107], v[214:217], v[162:165], v[104:107]
	v_mfma_f32_16x16x32_bf16 v[96:99], v[200:203], v[170:173], v[96:99]
	v_mfma_f32_16x16x32_bf16 v[88:91], v[214:217], v[170:173], v[88:91]
	v_mfma_f32_16x16x32_bf16 v[80:83], v[200:203], v[178:181], v[80:83]
	v_mfma_f32_16x16x32_bf16 v[72:75], v[214:217], v[178:181], v[72:75]
	v_mfma_f32_16x16x32_bf16 v[68:71], v[200:203], v[186:189], v[68:71]
	v_mfma_f32_16x16x32_bf16 v[64:67], v[214:217], v[186:189], v[64:67]
	s_mov_b32 m0, s69
	v_lshl_add_u64 v[142:143], v[218:219], 0, s[88:89]
	s_barrier
	ds_read_b128 v[158:161], v141 offset:49152
	ds_read_b128 v[162:165], v141 offset:50176
	ds_read_b128 v[166:169], v141 offset:51200
	ds_read_b128 v[170:173], v141 offset:52224
	ds_read_b128 v[174:177], v141 offset:53248
	ds_read_b128 v[178:181], v141 offset:54272
	ds_read_b128 v[182:185], v141 offset:55296
	ds_read_b128 v[186:189], v141 offset:56320
	global_load_lds_dwordx4 v[142:143], off
	s_mov_b32 m0, s70
	v_lshl_add_u64 v[142:143], v[220:221], 0, s[88:89]
	global_load_lds_dwordx4 v[142:143], off
	s_barrier
; #define PG8_STAGE(bufoff, gbase, voff) do { _Pragma("unroll") for (int _i = 0; _i < 2; ++_i) \
;         __builtin_amdgcn_global_load_lds((const unsigned*)((const char*)(gbase) + (voff)[_i]), (LAS unsigned*)(lds + (bufoff) + ldsw + _i * 8192), 16, 0, 0); } while (0)
; #define PG8_MMA(ai, bj, At, Bt) do { __builtin_amdgcn_s_setprio(1); _Pragma("unroll") for (int m = 0; m < 4; ++m) _Pragma("unroll") for (int n = 0; n < 2; ++n) _Pragma("unroll") for (int k = 0; k < 2; ++k) \
;         acc[ai][bj][m][n] = __builtin_amdgcn_mfma_f32_16x16x32_bf16(Bt[n][k], At[m][k], acc[ai][bj][m][n], 0, 0, 0); __builtin_amdgcn_s_setprio(0); } while (0)
; #define PG8_WAIT_V(n) asm volatile("s_waitcnt vmcnt(" #n ")" ::: "memory")
; #define PG8_WAIT_L(n) asm volatile("s_waitcnt lgkmcnt(" #n ")" ::: "memory")
; #define PG8_BAR __builtin_amdgcn_s_barrier()
; #define PG8_SCHED __builtin_amdgcn_sched_barrier(0)
; template <class Epi>
; __device__ __forceinline__ void gemm_phase(LAS unsigned char* lds, const Gemm g, const StaticOrder& S, const Epi& E) {
;     ...
;             PG8_BAR; PG8_WAIT_L(0); PG8_MMA(1, 0, At, B0); PG8_BAR; PG8_SCHED;
;             PG8_STAGE(PG8_SB(1, 1), b3 + hB, voffB);
;             PG8_WAIT_V(6); PG8_BAR; PG8_MMA(1, 1, At, B1); PG8_BAR;
	s_waitcnt lgkmcnt(0)
	v_mfma_f32_16x16x32_bf16 v[60:63], v[134:137], v[158:161], v[60:63]
	v_mfma_f32_16x16x32_bf16 v[56:59], v[150:153], v[158:161], v[56:59]
	v_mfma_f32_16x16x32_bf16 v[52:55], v[134:137], v[166:169], v[52:55]
	v_mfma_f32_16x16x32_bf16 v[44:47], v[150:153], v[166:169], v[44:47]
	v_mfma_f32_16x16x32_bf16 v[36:39], v[134:137], v[174:177], v[36:39]
	v_mfma_f32_16x16x32_bf16 v[28:31], v[150:153], v[174:177], v[28:31]
	v_mfma_f32_16x16x32_bf16 v[20:23], v[134:137], v[182:185], v[20:23]
	v_mfma_f32_16x16x32_bf16 v[12:15], v[150:153], v[182:185], v[12:15]
	v_mfma_f32_16x16x32_bf16 v[60:63], v[146:149], v[162:165], v[60:63]
	v_mfma_f32_16x16x32_bf16 v[56:59], v[154:157], v[162:165], v[56:59]
	v_mfma_f32_16x16x32_bf16 v[52:55], v[146:149], v[170:173], v[52:55]
	v_mfma_f32_16x16x32_bf16 v[44:47], v[154:157], v[170:173], v[44:47]
	v_mfma_f32_16x16x32_bf16 v[36:39], v[146:149], v[178:181], v[36:39]
	v_mfma_f32_16x16x32_bf16 v[28:31], v[154:157], v[178:181], v[28:31]
	v_mfma_f32_16x16x32_bf16 v[20:23], v[146:149], v[186:189], v[20:23]
	v_mfma_f32_16x16x32_bf16 v[12:15], v[154:157], v[186:189], v[12:15]
	s_barrier
	s_add_u32 s10, s16, 0xb0080
	s_addc_u32 s11, s17, 0
	s_add_i32 s16, s20, s61
	s_mov_b32 m0, s16
	v_lshl_add_u64 v[134:135], s[10:11], 0, v[144:145]
	global_load_lds_dwordx4 v[134:135], off
	s_add_i32 m0, s16, 0x2000
	v_lshl_add_u64 v[134:135], s[10:11], 0, v[128:129]
	global_load_lds_dwordx4 v[134:135], off
	s_waitcnt vmcnt(6)
	s_barrier
	v_mfma_f32_16x16x32_bf16 v[48:51], v[196:199], v[158:161], v[48:51]
	v_mfma_f32_16x16x32_bf16 v[40:43], v[204:207], v[158:161], v[40:43]
	v_mfma_f32_16x16x32_bf16 v[32:35], v[196:199], v[166:169], v[32:35]
	v_mfma_f32_16x16x32_bf16 v[24:27], v[204:207], v[166:169], v[24:27]
	v_mfma_f32_16x16x32_bf16 v[16:19], v[196:199], v[174:177], v[16:19]
	v_mfma_f32_16x16x32_bf16 v[8:11], v[204:207], v[174:177], v[8:11]
	v_mfma_f32_16x16x32_bf16 v[4:7], v[196:199], v[182:185], v[4:7]
	v_mfma_f32_16x16x32_bf16 v[0:3], v[204:207], v[182:185], v[0:3]
	v_mfma_f32_16x16x32_bf16 v[48:51], v[200:203], v[162:165], v[48:51]
	v_mfma_f32_16x16x32_bf16 v[40:43], v[214:217], v[162:165], v[40:43]
	v_mfma_f32_16x16x32_bf16 v[32:35], v[200:203], v[170:173], v[32:35]
	v_mfma_f32_16x16x32_bf16 v[24:27], v[214:217], v[170:173], v[24:27]
	v_mfma_f32_16x16x32_bf16 v[16:19], v[200:203], v[178:181], v[16:19]
	v_mfma_f32_16x16x32_bf16 v[8:11], v[214:217], v[178:181], v[8:11]
	v_mfma_f32_16x16x32_bf16 v[4:7], v[200:203], v[186:189], v[4:7]
	v_mfma_f32_16x16x32_bf16 v[0:3], v[214:217], v[186:189], v[0:3]
	s_add_i32 s78, s78, 2
	s_add_u32 s24, s24, 0x100
	s_addc_u32 s25, s25, 0
	s_cmp_gt_u32 s78, 41
	s_mov_b64 s[10:11], s[12:13]
	s_barrier
	s_cbranch_scc0 .LBB0_1462
; __device__ __forceinline__ unsigned pk2(float lo, float hi) { unsigned r; asm("v_cvt_pk_bf16_f32 %0, %1, %2" : "=v"(r) : "v"(lo), "v"(hi)); return r; }
;     __device__ __forceinline__ void operator()(const f32x4 (&acc)[2][2][4][2], const Unit& u, int wr, int wc, int fr, int fq) const {
;     ...
;         const int row_t = rmap == 1 ? odd_phys_row0(u.pm, grp) : (rmap == 2 ? odd_phys_row0(u.pm % (BG * TPB), u.pm / (BG * TPB)) : u.pm * BM);
;         int c = col_t + 64 * wc + 16 * fq;
;         if (mode == 2) c = (c >> 6) * 96 + (c & 63);
; #pragma unroll
;         for (int ai = 0; ai < 2; ++ai)
; #pragma unroll
;             for (int m = 0; m < 4; ++m) {
;                 const int row = row_t + ai * HALF + wr * 64 + m * 16 + fr;
;                 bf16_t* rp = O + (size_t)row * ldc + c;
; #pragma unroll
;                 for (int bj = 0; bj < 2; ++bj) {
;                     const f32x4 v0 = acc[ai][bj][m][0], v1 = acc[ai][bj][m][1];
;                     u32x4 o; o.x = pk2(v0[0], v0[1]); o.y = pk2(v0[2], v0[3]); o.z = pk2(v1[0], v1[1]); o.w = pk2(v1[2], v1[3]);
;                     *(u32x4*)(rp + 8 * bj) = o;
;                 }
;             }
	v_lshl_add_u32 v134, s77, 8, v138
	v_cvt_pk_bf16_f32 v68, v68, v69
	v_cvt_pk_bf16_f32 v69, v70, v71
	v_cvt_pk_bf16_f32 v70, v64, v65
	v_add_u32_e32 v64, 0x80, v134
	v_lshl_or_b32 v136, s15, 8, v140
	v_ashrrev_i32_e32 v135, 31, v134
	v_cvt_pk_bf16_f32 v112, v112, v113
	v_cvt_pk_bf16_f32 v113, v114, v115
	v_cvt_pk_bf16_f32 v114, v104, v105
	v_or_b32_e32 v104, 16, v134
	v_ashrrev_i32_e32 v65, 31, v64
	v_cvt_pk_bf16_f32 v48, v48, v49
	v_cvt_pk_bf16_f32 v49, v50, v51
	v_cvt_pk_bf16_f32 v50, v40, v41
	v_add_u32_e32 v40, 0x90, v134
	v_ashrrev_i32_e32 v137, 31, v136
	v_lshlrev_b64 v[142:143], 11, v[134:135]
	v_ashrrev_i32_e32 v105, 31, v104
	v_cvt_pk_bf16_f32 v96, v96, v97
	v_cvt_pk_bf16_f32 v97, v98, v99
	v_cvt_pk_bf16_f32 v98, v88, v89
	v_or_b32_e32 v88, 32, v134
	v_lshlrev_b64 v[64:65], 11, v[64:65]
	v_ashrrev_i32_e32 v41, 31, v40
	v_cvt_pk_bf16_f32 v32, v32, v33
	v_cvt_pk_bf16_f32 v33, v34, v35
	v_cvt_pk_bf16_f32 v34, v24, v25
	v_add_u32_e32 v24, 0xa0, v134
	v_lshl_add_u64 v[142:143], s[8:9], 0, v[142:143]
	v_lshlrev_b64 v[136:137], 1, v[136:137]
	v_lshlrev_b64 v[104:105], 11, v[104:105]
	v_ashrrev_i32_e32 v89, 31, v88
	v_cvt_pk_bf16_f32 v80, v80, v81
	v_cvt_pk_bf16_f32 v81, v82, v83
	v_cvt_pk_bf16_f32 v82, v72, v73
	v_or_b32_e32 v72, 48, v134
	v_lshl_add_u64 v[64:65], s[8:9], 0, v[64:65]
	v_lshlrev_b64 v[40:41], 11, v[40:41]
	v_ashrrev_i32_e32 v25, 31, v24
	v_cvt_pk_bf16_f32 v16, v16, v17
	v_cvt_pk_bf16_f32 v17, v18, v19
	v_cvt_pk_bf16_f32 v18, v8, v9
	v_add_u32_e32 v8, 0xb0, v134
	v_lshl_add_u64 v[142:143], v[142:143], 0, v[136:137]
	v_lshl_add_u64 v[104:105], s[8:9], 0, v[104:105]
	v_lshlrev_b64 v[88:89], 11, v[88:89]
	v_ashrrev_i32_e32 v73, 31, v72
	v_lshl_add_u64 v[64:65], v[64:65], 0, v[136:137]
	v_lshl_add_u64 v[40:41], s[8:9], 0, v[40:41]
	v_lshlrev_b64 v[24:25], 11, v[24:25]
	v_ashrrev_i32_e32 v9, 31, v8
	v_cvt_pk_bf16_f32 v115, v106, v107
	global_store_dwordx4 v[142:143], v[112:115], off offset:16
	v_lshl_add_u64 v[88:89], s[8:9], 0, v[88:89]
	v_lshlrev_b64 v[72:73], 11, v[72:73]
	v_lshl_add_u64 v[112:113], v[104:105], 0, v[136:137]
	v_cvt_pk_bf16_f32 v51, v42, v43
	global_store_dwordx4 v[64:65], v[48:51], off offset:16
	v_lshl_add_u64 v[24:25], s[8:9], 0, v[24:25]
	v_lshlrev_b64 v[8:9], 11, v[8:9]
	v_lshl_add_u64 v[48:49], v[40:41], 0, v[136:137]
	v_cvt_pk_bf16_f32 v99, v90, v91
	global_store_dwordx4 v[112:113], v[96:99], off offset:16
	v_lshl_add_u64 v[72:73], s[8:9], 0, v[72:73]
	v_cvt_pk_bf16_f32 v35, v26, v27
	global_store_dwordx4 v[48:49], v[32:35], off offset:16
	v_lshl_add_u64 v[96:97], v[88:89], 0, v[136:137]
	v_lshl_add_u64 v[8:9], s[8:9], 0, v[8:9]
	v_lshl_add_u64 v[32:33], v[24:25], 0, v[136:137]
	v_cvt_pk_bf16_f32 v83, v74, v75
	global_store_dwordx4 v[96:97], v[80:83], off offset:16
	v_cvt_pk_bf16_f32 v19, v10, v11
	global_store_dwordx4 v[32:33], v[16:19], off offset:16
	s_and_b64 vcc, exec, s[0:1]
	v_lshl_add_u64 v[80:81], v[72:73], 0, v[136:137]
	v_lshl_add_u64 v[16:17], v[8:9], 0, v[136:137]
	s_mov_b32 s15, s72
	s_mov_b32 s77, s76
	s_mov_b64 s[12:13], s[6:7]
	s_mov_b64 s[10:11], s[4:5]
	v_cvt_pk_bf16_f32 v124, v124, v125
	v_cvt_pk_bf16_f32 v125, v126, v127
	v_cvt_pk_bf16_f32 v126, v120, v121
	v_cvt_pk_bf16_f32 v127, v122, v123
	global_store_dwordx4 v[142:143], v[124:127], off
	v_cvt_pk_bf16_f32 v104, v116, v117
	v_cvt_pk_bf16_f32 v105, v118, v119
	v_cvt_pk_bf16_f32 v106, v108, v109
	v_cvt_pk_bf16_f32 v107, v110, v111
	global_store_dwordx4 v[112:113], v[104:107], off
	v_cvt_pk_bf16_f32 v88, v100, v101
	v_cvt_pk_bf16_f32 v89, v102, v103
	v_cvt_pk_bf16_f32 v90, v92, v93
	v_cvt_pk_bf16_f32 v91, v94, v95
	global_store_dwordx4 v[96:97], v[88:91], off
	v_cvt_pk_bf16_f32 v72, v84, v85
	v_cvt_pk_bf16_f32 v73, v86, v87
	v_cvt_pk_bf16_f32 v74, v76, v77
	v_cvt_pk_bf16_f32 v75, v78, v79
	global_store_dwordx4 v[80:81], v[72:75], off
	v_cvt_pk_bf16_f32 v71, v66, v67
	global_store_dwordx4 v[80:81], v[68:71], off offset:16
	v_cvt_pk_bf16_f32 v60, v60, v61
	v_cvt_pk_bf16_f32 v61, v62, v63
	v_cvt_pk_bf16_f32 v62, v56, v57
	v_cvt_pk_bf16_f32 v63, v58, v59
	global_store_dwordx4 v[64:65], v[60:63], off
	v_cvt_pk_bf16_f32 v40, v52, v53
	v_cvt_pk_bf16_f32 v41, v54, v55
	v_cvt_pk_bf16_f32 v42, v44, v45
	v_cvt_pk_bf16_f32 v43, v46, v47
	global_store_dwordx4 v[48:49], v[40:43], off
	v_cvt_pk_bf16_f32 v24, v36, v37
	v_cvt_pk_bf16_f32 v25, v38, v39
	v_cvt_pk_bf16_f32 v26, v28, v29
	v_cvt_pk_bf16_f32 v27, v30, v31
	global_store_dwordx4 v[32:33], v[24:27], off
	v_cvt_pk_bf16_f32 v8, v20, v21
	v_cvt_pk_bf16_f32 v9, v22, v23
	v_cvt_pk_bf16_f32 v10, v12, v13
	v_cvt_pk_bf16_f32 v11, v14, v15
	global_store_dwordx4 v[16:17], v[8:11], off
	v_cvt_pk_bf16_f32 v4, v4, v5
	v_cvt_pk_bf16_f32 v5, v6, v7
	v_cvt_pk_bf16_f32 v6, v0, v1
	v_cvt_pk_bf16_f32 v7, v2, v3
	global_store_dwordx4 v[16:17], v[4:7], off offset:16
	s_cbranch_vccz .LBB0_1455
	s_waitcnt vmcnt(0)
	s_cmpk_gt_u32 s23, 0xff
	s_cbranch_scc1 .LBB0_1466
	s_barrier
